# GEMM K-loops: LDS-read wait before each load segment's closing barrier removed (the post-barrier wait remains) (on v59)
# speedup vs baseline: 1.0048x; 1.0048x over previous
; #define PG8_STAGE(bufoff, gbase, voff) do { _Pragma("unroll") for (int _i = 0; _i < 2; ++_i) \
;         __builtin_amdgcn_global_load_lds((const unsigned*)((const char*)(gbase) + (voff)[_i]), (LAS unsigned*)(lds + (bufoff) + ldsw + _i * 8192), 16, 0, 0); } while (0)
; #define PG8_LDA(dst, b, h) do { _Pragma("unroll") for (int m = 0; m < 4; ++m) _Pragma("unroll") for (int k = 0; k < 2; ++k) dst[m][k] = *(const LAS bf16x8*)(lds + PG8_SA(b, h) + aoff + m * 2048 + k * 1024); } while (0)
; #define PG8_LDB(dst, b, h) do { _Pragma("unroll") for (int n = 0; n < 2; ++n) _Pragma("unroll") for (int k = 0; k < 2; ++k) dst[n][k] = *(const LAS bf16x8*)(lds + PG8_SB(b, h) + boff + n * 2048 + k * 1024); } while (0)
; #define PG8_MMA(ai, bj, At, Bt) do { __builtin_amdgcn_s_setprio(1); _Pragma("unroll") for (int m = 0; m < 4; ++m) _Pragma("unroll") for (int n = 0; n < 2; ++n) _Pragma("unroll") for (int k = 0; k < 2; ++k) \
;         acc[ai][bj][m][n] = __builtin_amdgcn_mfma_f32_16x16x32_bf16(Bt[n][k], At[m][k], acc[ai][bj][m][n], 0, 0, 0); __builtin_amdgcn_s_setprio(0); } while (0)
; #define PG8_WAIT_V(n) asm volatile("s_waitcnt vmcnt(" #n ")" ::: "memory")
; #define PG8_WAIT_L(n) asm volatile("s_waitcnt lgkmcnt(" #n ")" ::: "memory")
; #define PG8_BAR __builtin_amdgcn_s_barrier()
; #define PG8_SCHED __builtin_amdgcn_sched_barrier(0)
; template <class Epi, bool ALIGN_EPI, int K, int LDA, int LDB>
; __device__ __forceinline__ void gemm_phase(LAS unsigned char* lds, const int wid, const Gemm g, const StaticOrder& S, const Epi& E) {
;     ...
;             const bool last = (t == nt - 2);
;             const char* a1 = cA + (size_t)(t + 1) * kstep;
;             const char* a2 = last ? nA : cA + (size_t)(t + 2) * kstep; const char* b2 = last ? nB : cB + (size_t)(t + 2) * kstep;
;             const char* a3 = a2 + kstep; const char* b3 = b2 + kstep;
;             PG8_LDB(B0, 0, 0); PG8_LDB(B1, 0, 1); PG8_SCHED; PG8_LDA(At, 0, 0); PG8_STAGE(PG8_SA(1, 1), a1 + hA, voffA);
;             PG8_WAIT_V(8); PG8_WAIT_L(0); PG8_BAR; PG8_MMA(0, 0, At, B0); PG8_MMA(0, 1, At, B1); PG8_BAR; PG8_SCHED;
;             PG8_LDA(At, 0, 1); PG8_STAGE(PG8_SB(0, 0), b2, voffB); PG8_STAGE(PG8_SB(0, 1), b2 + hB, voffB); PG8_STAGE(PG8_SA(0, 0), a2, voffA);
;             PG8_WAIT_V(8); PG8_WAIT_L(0); PG8_BAR; PG8_MMA(1, 0, At, B0); PG8_MMA(1, 1, At, B1); PG8_BAR; PG8_SCHED;
.LBB0_231:
	s_ashr_i32 s17, s16, 31
	s_lshl_b64 s[18:19], s[16:17], 19
	v_readlane_b32 s15, v254, 0
	s_add_u32 s18, s15, s18
	v_readlane_b32 s15, v254, 1
	s_addc_u32 s19, s15, s19
	s_and_b64 s[20:21], s[4:5], exec
	s_cselect_b32 s17, s19, s23
	s_cselect_b32 s48, s18, s22
	s_ashr_i32 s15, s14, 31
	s_lshl_b64 s[20:21], s[14:15], 19
	s_add_u32 s20, s0, s20
	s_addc_u32 s21, s1, s21
	s_and_b64 s[26:27], s[4:5], exec
	s_cselect_b32 s15, s21, s25
	s_cselect_b32 s49, s20, s24
	s_add_u32 s22, s22, 0x40080
	s_addc_u32 s23, s23, 0
	s_add_u32 s51, s24, 0x100
	s_addc_u32 s54, s25, 0
	s_mov_b32 s55, -2
	s_add_u32 s24, s22, 0xfffc0080
	s_addc_u32 s25, s23, -1
	s_cmp_eq_u32 s55, 12
	s_cselect_b32 s27, s17, s25
	s_cselect_b32 s26, s48, s24
	s_cselect_b32 s25, s15, s54
	s_cselect_b32 s24, s49, s51
	s_add_i32 m0, s13, 0xc000
	global_load_lds_dwordx4 v136, s[22:23]
	s_add_i32 m0, s13, 0xe000
	s_nop 0
	global_load_lds_dwordx4 v138, s[22:23]
	s_waitcnt vmcnt(8)
	s_barrier
	s_setprio 1
	s_waitcnt lgkmcnt(0)
	v_mfma_f32_16x16x32_bf16 v[124:127], v[148:151], v[180:183], 0
	v_mfma_f32_16x16x32_bf16 v[120:123], v[156:159], v[180:183], 0
	v_mfma_f32_16x16x32_bf16 v[116:119], v[148:151], v[188:191], 0
	v_mfma_f32_16x16x32_bf16 v[112:115], v[156:159], v[188:191], 0
	v_mfma_f32_16x16x32_bf16 v[100:103], v[148:151], v[196:199], 0
	v_mfma_f32_16x16x32_bf16 v[96:99], v[156:159], v[196:199], 0
	v_mfma_f32_16x16x32_bf16 v[84:87], v[148:151], v[204:207], 0
	v_mfma_f32_16x16x32_bf16 v[80:83], v[156:159], v[204:207], 0
	v_mfma_f32_16x16x32_bf16 v[124:127], v[152:155], v[184:187], v[124:127]
	v_mfma_f32_16x16x32_bf16 v[120:123], v[160:163], v[184:187], v[120:123]
	v_mfma_f32_16x16x32_bf16 v[116:119], v[152:155], v[192:195], v[116:119]
	v_mfma_f32_16x16x32_bf16 v[112:115], v[160:163], v[192:195], v[112:115]
	v_mfma_f32_16x16x32_bf16 v[100:103], v[152:155], v[200:203], v[100:103]
	v_mfma_f32_16x16x32_bf16 v[96:99], v[160:163], v[200:203], v[96:99]
	v_mfma_f32_16x16x32_bf16 v[84:87], v[152:155], v[208:211], v[84:87]
	v_mfma_f32_16x16x32_bf16 v[80:83], v[160:163], v[208:211], v[80:83]
	v_mfma_f32_16x16x32_bf16 v[108:111], v[164:167], v[180:183], 0
	v_mfma_f32_16x16x32_bf16 v[104:107], v[172:175], v[180:183], 0
	v_mfma_f32_16x16x32_bf16 v[92:95], v[164:167], v[188:191], 0
	v_mfma_f32_16x16x32_bf16 v[88:91], v[172:175], v[188:191], 0
	v_mfma_f32_16x16x32_bf16 v[76:79], v[164:167], v[196:199], 0
	v_mfma_f32_16x16x32_bf16 v[72:75], v[172:175], v[196:199], 0
	v_mfma_f32_16x16x32_bf16 v[68:71], v[164:167], v[204:207], 0
	v_mfma_f32_16x16x32_bf16 v[64:67], v[172:175], v[204:207], 0
	v_mfma_f32_16x16x32_bf16 v[108:111], v[168:171], v[184:187], v[108:111]
	v_mfma_f32_16x16x32_bf16 v[104:107], v[176:179], v[184:187], v[104:107]
	v_mfma_f32_16x16x32_bf16 v[92:95], v[168:171], v[192:195], v[92:95]
	v_mfma_f32_16x16x32_bf16 v[88:91], v[176:179], v[192:195], v[88:91]
	v_mfma_f32_16x16x32_bf16 v[76:79], v[168:171], v[200:203], v[76:79]
	v_mfma_f32_16x16x32_bf16 v[72:75], v[176:179], v[200:203], v[72:75]
	v_mfma_f32_16x16x32_bf16 v[68:71], v[168:171], v[208:211], v[68:71]
	v_mfma_f32_16x16x32_bf16 v[64:67], v[176:179], v[208:211], v[64:67]
	s_setprio 0
	s_barrier
	s_add_u32 s98, s24, s10
	s_addc_u32 s99, s25, s11
	s_add_u32 s100, s26, s10
	s_addc_u32 s101, s27, s11
	s_add_i32 s56, s40, s3
	s_mov_b32 m0, s56
	ds_read_b128 v[180:183], v147 offset:16384
	ds_read_b128 v[184:187], v147 offset:17408
	ds_read_b128 v[188:191], v147 offset:18432
	ds_read_b128 v[192:195], v147 offset:19456
	ds_read_b128 v[196:199], v147 offset:20480
	ds_read_b128 v[200:203], v147 offset:21504
	ds_read_b128 v[204:207], v147 offset:22528
	ds_read_b128 v[208:211], v147 offset:23552
	global_load_lds_dwordx4 v132, s[24:25]
	s_add_i32 m0, s56, 0x2000
	s_add_u32 s56, s24, 0x40000
	s_addc_u32 s57, s25, 0
	s_add_i32 s58, s41, s3
	global_load_lds_dwordx4 v128, s[24:25]
	s_mov_b32 m0, s58
	s_nop 0
	global_load_lds_dwordx4 v132, s[56:57]
	s_add_i32 m0, s58, 0x2000
	s_nop 0
	global_load_lds_dwordx4 v128, s[56:57]
	s_mov_b32 m0, s13
	s_nop 0
	global_load_lds_dwordx4 v134, s[26:27]
	s_mov_b32 m0, s30
	s_nop 0
	global_load_lds_dwordx4 v130, s[26:27]
	s_waitcnt vmcnt(8)
	s_barrier
	s_setprio 1
	s_waitcnt lgkmcnt(0)
	v_mfma_f32_16x16x32_bf16 v[60:63], v[148:151], v[180:183], 0
	v_mfma_f32_16x16x32_bf16 v[56:59], v[156:159], v[180:183], 0
	v_mfma_f32_16x16x32_bf16 v[52:55], v[148:151], v[188:191], 0
	v_mfma_f32_16x16x32_bf16 v[48:51], v[156:159], v[188:191], 0
	v_mfma_f32_16x16x32_bf16 v[36:39], v[148:151], v[196:199], 0
	v_mfma_f32_16x16x32_bf16 v[32:35], v[156:159], v[196:199], 0
	v_mfma_f32_16x16x32_bf16 v[20:23], v[148:151], v[204:207], 0
	v_mfma_f32_16x16x32_bf16 v[16:19], v[156:159], v[204:207], 0
	v_mfma_f32_16x16x32_bf16 v[60:63], v[152:155], v[184:187], v[60:63]
	v_mfma_f32_16x16x32_bf16 v[56:59], v[160:163], v[184:187], v[56:59]
	v_mfma_f32_16x16x32_bf16 v[52:55], v[152:155], v[192:195], v[52:55]
	v_mfma_f32_16x16x32_bf16 v[48:51], v[160:163], v[192:195], v[48:51]
	v_mfma_f32_16x16x32_bf16 v[36:39], v[152:155], v[200:203], v[36:39]
	v_mfma_f32_16x16x32_bf16 v[32:35], v[160:163], v[200:203], v[32:35]
	v_mfma_f32_16x16x32_bf16 v[20:23], v[152:155], v[208:211], v[20:23]
	v_mfma_f32_16x16x32_bf16 v[16:19], v[160:163], v[208:211], v[16:19]
	v_mfma_f32_16x16x32_bf16 v[44:47], v[164:167], v[180:183], 0
	v_mfma_f32_16x16x32_bf16 v[40:43], v[172:175], v[180:183], 0
	v_mfma_f32_16x16x32_bf16 v[28:31], v[164:167], v[188:191], 0
	v_mfma_f32_16x16x32_bf16 v[24:27], v[172:175], v[188:191], 0
	v_mfma_f32_16x16x32_bf16 v[12:15], v[164:167], v[196:199], 0
	v_mfma_f32_16x16x32_bf16 v[8:11], v[172:175], v[196:199], 0
	v_mfma_f32_16x16x32_bf16 v[4:7], v[164:167], v[204:207], 0
	v_mfma_f32_16x16x32_bf16 v[0:3], v[172:175], v[204:207], 0
	v_mfma_f32_16x16x32_bf16 v[44:47], v[168:171], v[184:187], v[44:47]
	v_mfma_f32_16x16x32_bf16 v[40:43], v[176:179], v[184:187], v[40:43]
	v_mfma_f32_16x16x32_bf16 v[28:31], v[168:171], v[192:195], v[28:31]
	v_mfma_f32_16x16x32_bf16 v[24:27], v[176:179], v[192:195], v[24:27]
	v_mfma_f32_16x16x32_bf16 v[12:15], v[168:171], v[200:203], v[12:15]
	v_mfma_f32_16x16x32_bf16 v[8:11], v[176:179], v[200:203], v[8:11]
	v_mfma_f32_16x16x32_bf16 v[4:7], v[168:171], v[208:211], v[4:7]
	v_mfma_f32_16x16x32_bf16 v[0:3], v[176:179], v[208:211], v[0:3]
	s_setprio 0
	s_barrier
; #define PG8_STAGE(bufoff, gbase, voff) do { _Pragma("unroll") for (int _i = 0; _i < 2; ++_i) \
;         __builtin_amdgcn_global_load_lds((const unsigned*)((const char*)(gbase) + (voff)[_i]), (LAS unsigned*)(lds + (bufoff) + ldsw + _i * 8192), 16, 0, 0); } while (0)
; #define PG8_LDA(dst, b, h) do { _Pragma("unroll") for (int m = 0; m < 4; ++m) _Pragma("unroll") for (int k = 0; k < 2; ++k) dst[m][k] = *(const LAS bf16x8*)(lds + PG8_SA(b, h) + aoff + m * 2048 + k * 1024); } while (0)
; #define PG8_LDB(dst, b, h) do { _Pragma("unroll") for (int n = 0; n < 2; ++n) _Pragma("unroll") for (int k = 0; k < 2; ++k) dst[n][k] = *(const LAS bf16x8*)(lds + PG8_SB(b, h) + boff + n * 2048 + k * 1024); } while (0)
; #define PG8_MMA(ai, bj, At, Bt) do { __builtin_amdgcn_s_setprio(1); _Pragma("unroll") for (int m = 0; m < 4; ++m) _Pragma("unroll") for (int n = 0; n < 2; ++n) _Pragma("unroll") for (int k = 0; k < 2; ++k) \
;         acc[ai][bj][m][n] = __builtin_amdgcn_mfma_f32_16x16x32_bf16(Bt[n][k], At[m][k], acc[ai][bj][m][n], 0, 0, 0); __builtin_amdgcn_s_setprio(0); } while (0)
; #define PG8_WAIT_V(n) asm volatile("s_waitcnt vmcnt(" #n ")" ::: "memory")
; #define PG8_WAIT_L(n) asm volatile("s_waitcnt lgkmcnt(" #n ")" ::: "memory")
; #define PG8_BAR __builtin_amdgcn_s_barrier()
; #define PG8_SCHED __builtin_amdgcn_sched_barrier(0)
; template <class Epi, bool ALIGN_EPI, int K, int LDA, int LDB>
; __device__ __forceinline__ void gemm_phase(LAS unsigned char* lds, const int wid, const Gemm g, const StaticOrder& S, const Epi& E) {
;     ...
;             PG8_LDB(B0, 1, 0); PG8_LDB(B1, 1, 1); PG8_SCHED; PG8_LDA(At, 1, 0); PG8_STAGE(PG8_SA(0, 1), a2 + hA, voffA);
;             PG8_WAIT_V(8); PG8_WAIT_L(0); PG8_BAR; PG8_MMA(0, 0, At, B0); PG8_MMA(0, 1, At, B1); PG8_BAR; PG8_SCHED;
;             PG8_LDA(At, 1, 1); PG8_STAGE(PG8_SB(1, 0), b3, voffB); PG8_STAGE(PG8_SB(1, 1), b3 + hB, voffB); PG8_STAGE(PG8_SA(1, 0), a3, voffA);
;             PG8_WAIT_V(8); PG8_WAIT_L(0); PG8_BAR; PG8_MMA(1, 0, At, B0); PG8_MMA(1, 1, At, B1); PG8_BAR; PG8_SCHED;
	s_add_i32 s56, 0, 0x18000
	s_add_i32 s57, 0, 0x1c000
	v_add_u32_e32 v160, s56, v144
	v_add_u32_e32 v176, s57, v144
	ds_read_b128 v[148:151], v160
	ds_read_b128 v[152:155], v160 offset:1024
	ds_read_b128 v[156:159], v160 offset:2048
	ds_read_b128 v[160:163], v160 offset:3072
	ds_read_b128 v[164:167], v176
	ds_read_b128 v[168:171], v176 offset:1024
	ds_read_b128 v[172:175], v176 offset:2048
	ds_read_b128 v[176:179], v176 offset:3072
	s_add_u32 s26, s26, 0x40000
	s_addc_u32 s27, s27, 0
	s_mov_b32 m0, s31
	ds_read_b128 v[180:183], v147 offset:32768
	ds_read_b128 v[184:187], v147 offset:33792
	ds_read_b128 v[188:191], v147 offset:34816
	ds_read_b128 v[192:195], v147 offset:35840
	ds_read_b128 v[196:199], v147 offset:36864
	ds_read_b128 v[200:203], v147 offset:37888
	ds_read_b128 v[204:207], v147 offset:38912
	ds_read_b128 v[208:211], v147 offset:39936
	global_load_lds_dwordx4 v134, s[26:27]
	s_mov_b32 m0, s33
	s_nop 0
	global_load_lds_dwordx4 v130, s[26:27]
	s_waitcnt vmcnt(8)
	s_barrier
	s_setprio 1
	s_waitcnt lgkmcnt(0)
	v_mfma_f32_16x16x32_bf16 v[124:127], v[148:151], v[180:183], v[124:127]
	v_mfma_f32_16x16x32_bf16 v[120:123], v[156:159], v[180:183], v[120:123]
	v_mfma_f32_16x16x32_bf16 v[116:119], v[148:151], v[188:191], v[116:119]
	v_mfma_f32_16x16x32_bf16 v[112:115], v[156:159], v[188:191], v[112:115]
	v_mfma_f32_16x16x32_bf16 v[100:103], v[148:151], v[196:199], v[100:103]
	v_mfma_f32_16x16x32_bf16 v[96:99], v[156:159], v[196:199], v[96:99]
	v_mfma_f32_16x16x32_bf16 v[84:87], v[148:151], v[204:207], v[84:87]
	v_mfma_f32_16x16x32_bf16 v[80:83], v[156:159], v[204:207], v[80:83]
	v_mfma_f32_16x16x32_bf16 v[124:127], v[152:155], v[184:187], v[124:127]
	v_mfma_f32_16x16x32_bf16 v[120:123], v[160:163], v[184:187], v[120:123]
	v_mfma_f32_16x16x32_bf16 v[116:119], v[152:155], v[192:195], v[116:119]
	v_mfma_f32_16x16x32_bf16 v[112:115], v[160:163], v[192:195], v[112:115]
	v_mfma_f32_16x16x32_bf16 v[100:103], v[152:155], v[200:203], v[100:103]
	v_mfma_f32_16x16x32_bf16 v[96:99], v[160:163], v[200:203], v[96:99]
	v_mfma_f32_16x16x32_bf16 v[84:87], v[152:155], v[208:211], v[84:87]
	v_mfma_f32_16x16x32_bf16 v[80:83], v[160:163], v[208:211], v[80:83]
	v_mfma_f32_16x16x32_bf16 v[108:111], v[164:167], v[180:183], v[108:111]
	v_mfma_f32_16x16x32_bf16 v[104:107], v[172:175], v[180:183], v[104:107]
	v_mfma_f32_16x16x32_bf16 v[92:95], v[164:167], v[188:191], v[92:95]
	v_mfma_f32_16x16x32_bf16 v[88:91], v[172:175], v[188:191], v[88:91]
	v_mfma_f32_16x16x32_bf16 v[76:79], v[164:167], v[196:199], v[76:79]
	v_mfma_f32_16x16x32_bf16 v[72:75], v[172:175], v[196:199], v[72:75]
	v_mfma_f32_16x16x32_bf16 v[68:71], v[164:167], v[204:207], v[68:71]
	v_mfma_f32_16x16x32_bf16 v[64:67], v[172:175], v[204:207], v[64:67]
	v_mfma_f32_16x16x32_bf16 v[108:111], v[168:171], v[184:187], v[108:111]
	v_mfma_f32_16x16x32_bf16 v[104:107], v[176:179], v[184:187], v[104:107]
	v_mfma_f32_16x16x32_bf16 v[92:95], v[168:171], v[192:195], v[92:95]
	v_mfma_f32_16x16x32_bf16 v[88:91], v[176:179], v[192:195], v[88:91]
	v_mfma_f32_16x16x32_bf16 v[76:79], v[168:171], v[200:203], v[76:79]
	v_mfma_f32_16x16x32_bf16 v[72:75], v[176:179], v[200:203], v[72:75]
	v_mfma_f32_16x16x32_bf16 v[68:71], v[168:171], v[208:211], v[68:71]
	v_mfma_f32_16x16x32_bf16 v[64:67], v[176:179], v[208:211], v[64:67]
	s_setprio 0
	s_barrier
	s_add_i32 s26, s56, s3
	s_mov_b32 m0, s26
	ds_read_b128 v[180:183], v147 offset:49152
	ds_read_b128 v[184:187], v147 offset:50176
	ds_read_b128 v[188:191], v147 offset:51200
	ds_read_b128 v[192:195], v147 offset:52224
	ds_read_b128 v[196:199], v147 offset:53248
	ds_read_b128 v[200:203], v147 offset:54272
	ds_read_b128 v[204:207], v147 offset:55296
	ds_read_b128 v[208:211], v147 offset:56320
	global_load_lds_dwordx4 v132, s[98:99]
	s_add_i32 m0, s26, 0x2000
	s_add_u32 s24, s24, 0x40080
	s_addc_u32 s25, s25, 0
	s_add_i32 s26, s57, s3
	global_load_lds_dwordx4 v128, s[98:99]
	s_mov_b32 m0, s26
	s_nop 0
	global_load_lds_dwordx4 v132, s[24:25]
	s_add_i32 m0, s26, 0x2000
	s_nop 0
	global_load_lds_dwordx4 v128, s[24:25]
	s_mov_b32 m0, s38
	s_nop 0
	global_load_lds_dwordx4 v134, s[100:101]
	s_mov_b32 m0, s39
	s_nop 0
	global_load_lds_dwordx4 v130, s[100:101]
	s_waitcnt vmcnt(8)
	s_barrier
	s_setprio 1
	s_waitcnt lgkmcnt(0)
	v_mfma_f32_16x16x32_bf16 v[60:63], v[148:151], v[180:183], v[60:63]
	v_mfma_f32_16x16x32_bf16 v[56:59], v[156:159], v[180:183], v[56:59]
	v_mfma_f32_16x16x32_bf16 v[52:55], v[148:151], v[188:191], v[52:55]
	v_mfma_f32_16x16x32_bf16 v[48:51], v[156:159], v[188:191], v[48:51]
	v_mfma_f32_16x16x32_bf16 v[36:39], v[148:151], v[196:199], v[36:39]
	v_mfma_f32_16x16x32_bf16 v[32:35], v[156:159], v[196:199], v[32:35]
	v_mfma_f32_16x16x32_bf16 v[20:23], v[148:151], v[204:207], v[20:23]
	v_mfma_f32_16x16x32_bf16 v[16:19], v[156:159], v[204:207], v[16:19]
	v_mfma_f32_16x16x32_bf16 v[60:63], v[152:155], v[184:187], v[60:63]
	v_mfma_f32_16x16x32_bf16 v[56:59], v[160:163], v[184:187], v[56:59]
	v_mfma_f32_16x16x32_bf16 v[52:55], v[152:155], v[192:195], v[52:55]
	v_mfma_f32_16x16x32_bf16 v[48:51], v[160:163], v[192:195], v[48:51]
	v_mfma_f32_16x16x32_bf16 v[36:39], v[152:155], v[200:203], v[36:39]
	v_mfma_f32_16x16x32_bf16 v[32:35], v[160:163], v[200:203], v[32:35]
	v_mfma_f32_16x16x32_bf16 v[20:23], v[152:155], v[208:211], v[20:23]
	v_mfma_f32_16x16x32_bf16 v[16:19], v[160:163], v[208:211], v[16:19]
	v_mfma_f32_16x16x32_bf16 v[44:47], v[164:167], v[180:183], v[44:47]
	v_mfma_f32_16x16x32_bf16 v[40:43], v[172:175], v[180:183], v[40:43]
	v_mfma_f32_16x16x32_bf16 v[28:31], v[164:167], v[188:191], v[28:31]
	v_mfma_f32_16x16x32_bf16 v[24:27], v[172:175], v[188:191], v[24:27]
	v_mfma_f32_16x16x32_bf16 v[12:15], v[164:167], v[196:199], v[12:15]
	v_mfma_f32_16x16x32_bf16 v[8:11], v[172:175], v[196:199], v[8:11]
	v_mfma_f32_16x16x32_bf16 v[4:7], v[164:167], v[204:207], v[4:7]
	v_mfma_f32_16x16x32_bf16 v[0:3], v[172:175], v[204:207], v[0:3]
	v_mfma_f32_16x16x32_bf16 v[44:47], v[168:171], v[184:187], v[44:47]
	v_mfma_f32_16x16x32_bf16 v[40:43], v[176:179], v[184:187], v[40:43]
	v_mfma_f32_16x16x32_bf16 v[28:31], v[168:171], v[192:195], v[28:31]
	v_mfma_f32_16x16x32_bf16 v[24:27], v[176:179], v[192:195], v[24:27]
	v_mfma_f32_16x16x32_bf16 v[12:15], v[168:171], v[200:203], v[12:15]
	v_mfma_f32_16x16x32_bf16 v[8:11], v[176:179], v[200:203], v[8:11]
	v_mfma_f32_16x16x32_bf16 v[4:7], v[168:171], v[208:211], v[4:7]
	v_mfma_f32_16x16x32_bf16 v[0:3], v[176:179], v[208:211], v[0:3]
	s_setprio 0
	s_barrier
	s_add_i32 s55, s55, 2
	s_add_u32 s22, s22, 0x100
	s_addc_u32 s23, s23, 0
	s_add_u32 s51, s51, 0x100
	s_addc_u32 s54, s54, 0
; #define PG8_STAGE(bufoff, gbase, voff) do { _Pragma("unroll") for (int _i = 0; _i < 2; ++_i) \
;         __builtin_amdgcn_global_load_lds((const unsigned*)((const char*)(gbase) + (voff)[_i]), (LAS unsigned*)(lds + (bufoff) + ldsw + _i * 8192), 16, 0, 0); } while (0)
; #define PG8_LDA(dst, b, h) do { _Pragma("unroll") for (int m = 0; m < 4; ++m) _Pragma("unroll") for (int k = 0; k < 2; ++k) dst[m][k] = *(const LAS bf16x8*)(lds + PG8_SA(b, h) + aoff + m * 2048 + k * 1024); } while (0)
; #define PG8_LDB(dst, b, h) do { _Pragma("unroll") for (int n = 0; n < 2; ++n) _Pragma("unroll") for (int k = 0; k < 2; ++k) dst[n][k] = *(const LAS bf16x8*)(lds + PG8_SB(b, h) + boff + n * 2048 + k * 1024); } while (0)
; #define PG8_WAIT_V(n) asm volatile("s_waitcnt vmcnt(" #n ")" ::: "memory")
; template <class Epi, bool ALIGN_EPI, int K, int LDA, int LDB>
; __device__ __forceinline__ void gemm_phase(LAS unsigned char* lds, const int wid, const Gemm g, const StaticOrder& S, const Epi& E) {
;     ...
;         for (int t = 0; t < nt; t += 2) {
;             const bool last = (t == nt - 2);
;             const char* a1 = cA + (size_t)(t + 1) * kstep;
;             const char* a2 = last ? nA : cA + (size_t)(t + 2) * kstep; const char* b2 = last ? nB : cB + (size_t)(t + 2) * kstep;
;             const char* a3 = a2 + kstep; const char* b3 = b2 + kstep;
;             PG8_LDB(B0, 0, 0); PG8_LDB(B1, 0, 1); PG8_SCHED; PG8_LDA(At, 0, 0); PG8_STAGE(PG8_SA(1, 1), a1 + hA, voffA);
;             PG8_WAIT_V(8); PG8_WAIT_L(0); PG8_BAR; PG8_MMA(0, 0, At, B0); PG8_MMA(0, 1, At, B1); PG8_BAR; PG8_SCHED;
;             PG8_LDA(At, 0, 1); PG8_STAGE(PG8_SB(0, 0), b2, voffB); PG8_STAGE(PG8_SB(0, 1), b2 + hB, voffB); PG8_STAGE(PG8_SA(0, 0), a2, voffA);
;             PG8_WAIT_V(8); PG8_WAIT_L(0); PG8_BAR; PG8_MMA(1, 0, At, B0); PG8_MMA(1, 1, At, B1); PG8_BAR; PG8_SCHED;
;             PG8_LDB(B0, 1, 0); PG8_LDB(B1, 1, 1); PG8_SCHED; PG8_LDA(At, 1, 0); PG8_STAGE(PG8_SA(0, 1), a2 + hA, voffA);
;             PG8_WAIT_V(8); PG8_WAIT_L(0); PG8_BAR; PG8_MMA(0, 0, At, B0); PG8_MMA(0, 1, At, B1); PG8_BAR; PG8_SCHED;
;             PG8_LDA(At, 1, 1); PG8_STAGE(PG8_SB(1, 0), b3, voffB); PG8_STAGE(PG8_SB(1, 1), b3 + hB, voffB); PG8_STAGE(PG8_SA(1, 0), a3, voffA);
;             PG8_WAIT_V(8); PG8_WAIT_L(0); PG8_BAR; PG8_MMA(1, 0, At, B0); PG8_MMA(1, 1, At, B1); PG8_BAR; PG8_SCHED;
.LBB0_232:
	ds_read_b128 v[148:151], v145
	ds_read_b128 v[152:155], v145 offset:1024
	ds_read_b128 v[156:159], v145 offset:2048
	ds_read_b128 v[160:163], v145 offset:3072
	ds_read_b128 v[164:167], v146
	ds_read_b128 v[168:171], v146 offset:1024
	ds_read_b128 v[172:175], v146 offset:2048
	ds_read_b128 v[176:179], v146 offset:3072
	s_add_u32 s24, s22, 0xfffc0080
	s_addc_u32 s25, s23, -1
	s_cmp_eq_u32 s55, 12
	s_cselect_b32 s27, s17, s25
	s_cselect_b32 s26, s48, s24
	s_cselect_b32 s25, s15, s54
	s_cselect_b32 s24, s49, s51
	s_add_i32 m0, s13, 0xc000
	ds_read_b128 v[180:183], v147
	ds_read_b128 v[184:187], v147 offset:1024
	ds_read_b128 v[188:191], v147 offset:2048
	ds_read_b128 v[192:195], v147 offset:3072
	ds_read_b128 v[196:199], v147 offset:4096
	ds_read_b128 v[200:203], v147 offset:5120
	ds_read_b128 v[204:207], v147 offset:6144
	ds_read_b128 v[208:211], v147 offset:7168
	global_load_lds_dwordx4 v136, s[22:23]
	s_add_i32 m0, s13, 0xe000
	s_nop 0
	global_load_lds_dwordx4 v138, s[22:23]
	s_waitcnt vmcnt(8)
	s_barrier
	s_setprio 1
	s_waitcnt lgkmcnt(0)
	v_mfma_f32_16x16x32_bf16 v[124:127], v[148:151], v[180:183], v[124:127]
	v_mfma_f32_16x16x32_bf16 v[120:123], v[156:159], v[180:183], v[120:123]
	v_mfma_f32_16x16x32_bf16 v[116:119], v[148:151], v[188:191], v[116:119]
	v_mfma_f32_16x16x32_bf16 v[112:115], v[156:159], v[188:191], v[112:115]
	v_mfma_f32_16x16x32_bf16 v[100:103], v[148:151], v[196:199], v[100:103]
	v_mfma_f32_16x16x32_bf16 v[96:99], v[156:159], v[196:199], v[96:99]
	v_mfma_f32_16x16x32_bf16 v[84:87], v[148:151], v[204:207], v[84:87]
	v_mfma_f32_16x16x32_bf16 v[80:83], v[156:159], v[204:207], v[80:83]
	v_mfma_f32_16x16x32_bf16 v[124:127], v[152:155], v[184:187], v[124:127]
	v_mfma_f32_16x16x32_bf16 v[120:123], v[160:163], v[184:187], v[120:123]
	v_mfma_f32_16x16x32_bf16 v[116:119], v[152:155], v[192:195], v[116:119]
	v_mfma_f32_16x16x32_bf16 v[112:115], v[160:163], v[192:195], v[112:115]
	v_mfma_f32_16x16x32_bf16 v[100:103], v[152:155], v[200:203], v[100:103]
	v_mfma_f32_16x16x32_bf16 v[96:99], v[160:163], v[200:203], v[96:99]
	v_mfma_f32_16x16x32_bf16 v[84:87], v[152:155], v[208:211], v[84:87]
	v_mfma_f32_16x16x32_bf16 v[80:83], v[160:163], v[208:211], v[80:83]
	v_mfma_f32_16x16x32_bf16 v[108:111], v[164:167], v[180:183], v[108:111]
	v_mfma_f32_16x16x32_bf16 v[104:107], v[172:175], v[180:183], v[104:107]
	v_mfma_f32_16x16x32_bf16 v[92:95], v[164:167], v[188:191], v[92:95]
	v_mfma_f32_16x16x32_bf16 v[88:91], v[172:175], v[188:191], v[88:91]
	v_mfma_f32_16x16x32_bf16 v[76:79], v[164:167], v[196:199], v[76:79]
	v_mfma_f32_16x16x32_bf16 v[72:75], v[172:175], v[196:199], v[72:75]
	v_mfma_f32_16x16x32_bf16 v[68:71], v[164:167], v[204:207], v[68:71]
	v_mfma_f32_16x16x32_bf16 v[64:67], v[172:175], v[204:207], v[64:67]
	v_mfma_f32_16x16x32_bf16 v[108:111], v[168:171], v[184:187], v[108:111]
	v_mfma_f32_16x16x32_bf16 v[104:107], v[176:179], v[184:187], v[104:107]
	v_mfma_f32_16x16x32_bf16 v[92:95], v[168:171], v[192:195], v[92:95]
	v_mfma_f32_16x16x32_bf16 v[88:91], v[176:179], v[192:195], v[88:91]
	v_mfma_f32_16x16x32_bf16 v[76:79], v[168:171], v[200:203], v[76:79]
	v_mfma_f32_16x16x32_bf16 v[72:75], v[176:179], v[200:203], v[72:75]
	v_mfma_f32_16x16x32_bf16 v[68:71], v[168:171], v[208:211], v[68:71]
	v_mfma_f32_16x16x32_bf16 v[64:67], v[176:179], v[208:211], v[64:67]
	s_setprio 0
	s_barrier
	s_add_u32 s98, s24, s10
	s_addc_u32 s99, s25, s11
	s_add_u32 s100, s26, s10
	s_addc_u32 s101, s27, s11
	s_add_i32 s56, s40, s3
	s_mov_b32 m0, s56
	ds_read_b128 v[180:183], v147 offset:16384
	ds_read_b128 v[184:187], v147 offset:17408
	ds_read_b128 v[188:191], v147 offset:18432
	ds_read_b128 v[192:195], v147 offset:19456
	ds_read_b128 v[196:199], v147 offset:20480
	ds_read_b128 v[200:203], v147 offset:21504
	ds_read_b128 v[204:207], v147 offset:22528
	ds_read_b128 v[208:211], v147 offset:23552
	global_load_lds_dwordx4 v132, s[24:25]
	s_add_i32 m0, s56, 0x2000
	s_add_u32 s56, s24, 0x40000
	s_addc_u32 s57, s25, 0
	s_add_i32 s58, s41, s3
	global_load_lds_dwordx4 v128, s[24:25]
	s_mov_b32 m0, s58
	s_nop 0
	global_load_lds_dwordx4 v132, s[56:57]
	s_add_i32 m0, s58, 0x2000
	s_nop 0
	global_load_lds_dwordx4 v128, s[56:57]
	s_mov_b32 m0, s13
	s_nop 0
	global_load_lds_dwordx4 v134, s[26:27]
	s_mov_b32 m0, s30
	s_nop 0
	global_load_lds_dwordx4 v130, s[26:27]
	s_waitcnt vmcnt(8)
	s_barrier
	s_setprio 1
	s_waitcnt lgkmcnt(0)
	v_mfma_f32_16x16x32_bf16 v[60:63], v[148:151], v[180:183], v[60:63]
	v_mfma_f32_16x16x32_bf16 v[56:59], v[156:159], v[180:183], v[56:59]
	v_mfma_f32_16x16x32_bf16 v[52:55], v[148:151], v[188:191], v[52:55]
	v_mfma_f32_16x16x32_bf16 v[48:51], v[156:159], v[188:191], v[48:51]
	v_mfma_f32_16x16x32_bf16 v[36:39], v[148:151], v[196:199], v[36:39]
	v_mfma_f32_16x16x32_bf16 v[32:35], v[156:159], v[196:199], v[32:35]
	v_mfma_f32_16x16x32_bf16 v[20:23], v[148:151], v[204:207], v[20:23]
	v_mfma_f32_16x16x32_bf16 v[16:19], v[156:159], v[204:207], v[16:19]
	v_mfma_f32_16x16x32_bf16 v[60:63], v[152:155], v[184:187], v[60:63]
	v_mfma_f32_16x16x32_bf16 v[56:59], v[160:163], v[184:187], v[56:59]
	v_mfma_f32_16x16x32_bf16 v[52:55], v[152:155], v[192:195], v[52:55]
	v_mfma_f32_16x16x32_bf16 v[48:51], v[160:163], v[192:195], v[48:51]
	v_mfma_f32_16x16x32_bf16 v[36:39], v[152:155], v[200:203], v[36:39]
	v_mfma_f32_16x16x32_bf16 v[32:35], v[160:163], v[200:203], v[32:35]
	v_mfma_f32_16x16x32_bf16 v[20:23], v[152:155], v[208:211], v[20:23]
	v_mfma_f32_16x16x32_bf16 v[16:19], v[160:163], v[208:211], v[16:19]
	v_mfma_f32_16x16x32_bf16 v[44:47], v[164:167], v[180:183], v[44:47]
	v_mfma_f32_16x16x32_bf16 v[40:43], v[172:175], v[180:183], v[40:43]
	v_mfma_f32_16x16x32_bf16 v[28:31], v[164:167], v[188:191], v[28:31]
	v_mfma_f32_16x16x32_bf16 v[24:27], v[172:175], v[188:191], v[24:27]
	v_mfma_f32_16x16x32_bf16 v[12:15], v[164:167], v[196:199], v[12:15]
	v_mfma_f32_16x16x32_bf16 v[8:11], v[172:175], v[196:199], v[8:11]
	v_mfma_f32_16x16x32_bf16 v[4:7], v[164:167], v[204:207], v[4:7]
	v_mfma_f32_16x16x32_bf16 v[0:3], v[172:175], v[204:207], v[0:3]
	v_mfma_f32_16x16x32_bf16 v[44:47], v[168:171], v[184:187], v[44:47]
	v_mfma_f32_16x16x32_bf16 v[40:43], v[176:179], v[184:187], v[40:43]
	v_mfma_f32_16x16x32_bf16 v[28:31], v[168:171], v[192:195], v[28:31]
	v_mfma_f32_16x16x32_bf16 v[24:27], v[176:179], v[192:195], v[24:27]
	v_mfma_f32_16x16x32_bf16 v[12:15], v[168:171], v[200:203], v[12:15]
	v_mfma_f32_16x16x32_bf16 v[8:11], v[176:179], v[200:203], v[8:11]
	v_mfma_f32_16x16x32_bf16 v[4:7], v[168:171], v[208:211], v[4:7]
	v_mfma_f32_16x16x32_bf16 v[0:3], v[176:179], v[208:211], v[0:3]
	s_setprio 0
	s_barrier
; #define PG8_STAGE(bufoff, gbase, voff) do { _Pragma("unroll") for (int _i = 0; _i < 2; ++_i) \
;         __builtin_amdgcn_global_load_lds((const unsigned*)((const char*)(gbase) + (voff)[_i]), (LAS unsigned*)(lds + (bufoff) + ldsw + _i * 8192), 16, 0, 0); } while (0)
; #define PG8_LDA(dst, b, h) do { _Pragma("unroll") for (int m = 0; m < 4; ++m) _Pragma("unroll") for (int k = 0; k < 2; ++k) dst[m][k] = *(const LAS bf16x8*)(lds + PG8_SA(b, h) + aoff + m * 2048 + k * 1024); } while (0)
; #define PG8_LDB(dst, b, h) do { _Pragma("unroll") for (int n = 0; n < 2; ++n) _Pragma("unroll") for (int k = 0; k < 2; ++k) dst[n][k] = *(const LAS bf16x8*)(lds + PG8_SB(b, h) + boff + n * 2048 + k * 1024); } while (0)
; template <class Epi, bool ALIGN_EPI, int K, int LDA, int LDB>
; __device__ __forceinline__ void gemm_phase(LAS unsigned char* lds, const int wid, const Gemm g, const StaticOrder& S, const Epi& E) {
;     ...
;         for (int t = 0; t < nt; t += 2) {
;             const bool last = (t == nt - 2);
;             const char* a1 = cA + (size_t)(t + 1) * kstep;
;             const char* a2 = last ? nA : cA + (size_t)(t + 2) * kstep; const char* b2 = last ? nB : cB + (size_t)(t + 2) * kstep;
;             const char* a3 = a2 + kstep; const char* b3 = b2 + kstep;
;             PG8_LDB(B0, 0, 0); PG8_LDB(B1, 0, 1); PG8_SCHED; PG8_LDA(At, 0, 0); PG8_STAGE(PG8_SA(1, 1), a1 + hA, voffA);
;             PG8_WAIT_V(8); PG8_WAIT_L(0); PG8_BAR; PG8_MMA(0, 0, At, B0); PG8_MMA(0, 1, At, B1); PG8_BAR; PG8_SCHED;
;             PG8_LDA(At, 0, 1); PG8_STAGE(PG8_SB(0, 0), b2, voffB); PG8_STAGE(PG8_SB(0, 1), b2 + hB, voffB); PG8_STAGE(PG8_SA(0, 0), a2, voffA);
;             PG8_WAIT_V(8); PG8_WAIT_L(0); PG8_BAR; PG8_MMA(1, 0, At, B0); PG8_MMA(1, 1, At, B1); PG8_BAR; PG8_SCHED;
;             PG8_LDB(B0, 1, 0); PG8_LDB(B1, 1, 1); PG8_SCHED; PG8_LDA(At, 1, 0); PG8_STAGE(PG8_SA(0, 1), a2 + hA, voffA);
;             PG8_WAIT_V(8); PG8_WAIT_L(0); PG8_BAR; PG8_MMA(0, 0, At, B0); PG8_MMA(0, 1, At, B1); PG8_BAR; PG8_SCHED;
;             PG8_LDA(At, 1, 1); PG8_STAGE(PG8_SB(1, 0), b3, voffB); PG8_STAGE(PG8_SB(1, 1), b3 + hB, voffB); PG8_STAGE(PG8_SA(1, 0), a3, voffA);
;             PG8_WAIT_V(8); PG8_WAIT_L(0); PG8_BAR; PG8_MMA(1, 0, At, B0); PG8_MMA(1, 1, At, B1); PG8_BAR; PG8_SCHED;
;         }
;         if constexpr (ALIGN_EPI) { if (wr == 0) PG8_BAR; }
	s_add_i32 s56, 0, 0x18000
	s_add_i32 s57, 0, 0x1c000
	v_add_u32_e32 v160, s56, v144
	v_add_u32_e32 v176, s57, v144
	ds_read_b128 v[148:151], v160
	ds_read_b128 v[152:155], v160 offset:1024
	ds_read_b128 v[156:159], v160 offset:2048
	ds_read_b128 v[160:163], v160 offset:3072
	ds_read_b128 v[164:167], v176
	ds_read_b128 v[168:171], v176 offset:1024
	ds_read_b128 v[172:175], v176 offset:2048
	ds_read_b128 v[176:179], v176 offset:3072
	s_add_u32 s26, s26, 0x40000
	s_addc_u32 s27, s27, 0
	s_mov_b32 m0, s31
	ds_read_b128 v[180:183], v147 offset:32768
	ds_read_b128 v[184:187], v147 offset:33792
	ds_read_b128 v[188:191], v147 offset:34816
	ds_read_b128 v[192:195], v147 offset:35840
	ds_read_b128 v[196:199], v147 offset:36864
	ds_read_b128 v[200:203], v147 offset:37888
	ds_read_b128 v[204:207], v147 offset:38912
	ds_read_b128 v[208:211], v147 offset:39936
	global_load_lds_dwordx4 v134, s[26:27]
	s_mov_b32 m0, s33
	s_nop 0
	global_load_lds_dwordx4 v130, s[26:27]
	s_waitcnt vmcnt(8)
	s_barrier
	s_setprio 1
	s_waitcnt lgkmcnt(0)
	v_mfma_f32_16x16x32_bf16 v[124:127], v[148:151], v[180:183], v[124:127]
	v_mfma_f32_16x16x32_bf16 v[120:123], v[156:159], v[180:183], v[120:123]
	v_mfma_f32_16x16x32_bf16 v[116:119], v[148:151], v[188:191], v[116:119]
	v_mfma_f32_16x16x32_bf16 v[112:115], v[156:159], v[188:191], v[112:115]
	v_mfma_f32_16x16x32_bf16 v[100:103], v[148:151], v[196:199], v[100:103]
	v_mfma_f32_16x16x32_bf16 v[96:99], v[156:159], v[196:199], v[96:99]
	v_mfma_f32_16x16x32_bf16 v[84:87], v[148:151], v[204:207], v[84:87]
	v_mfma_f32_16x16x32_bf16 v[80:83], v[156:159], v[204:207], v[80:83]
	v_mfma_f32_16x16x32_bf16 v[124:127], v[152:155], v[184:187], v[124:127]
	v_mfma_f32_16x16x32_bf16 v[120:123], v[160:163], v[184:187], v[120:123]
	v_mfma_f32_16x16x32_bf16 v[116:119], v[152:155], v[192:195], v[116:119]
	v_mfma_f32_16x16x32_bf16 v[112:115], v[160:163], v[192:195], v[112:115]
	v_mfma_f32_16x16x32_bf16 v[100:103], v[152:155], v[200:203], v[100:103]
	v_mfma_f32_16x16x32_bf16 v[96:99], v[160:163], v[200:203], v[96:99]
	v_mfma_f32_16x16x32_bf16 v[84:87], v[152:155], v[208:211], v[84:87]
	v_mfma_f32_16x16x32_bf16 v[80:83], v[160:163], v[208:211], v[80:83]
	v_mfma_f32_16x16x32_bf16 v[108:111], v[164:167], v[180:183], v[108:111]
	v_mfma_f32_16x16x32_bf16 v[104:107], v[172:175], v[180:183], v[104:107]
	v_mfma_f32_16x16x32_bf16 v[92:95], v[164:167], v[188:191], v[92:95]
	v_mfma_f32_16x16x32_bf16 v[88:91], v[172:175], v[188:191], v[88:91]
	v_mfma_f32_16x16x32_bf16 v[76:79], v[164:167], v[196:199], v[76:79]
	v_mfma_f32_16x16x32_bf16 v[72:75], v[172:175], v[196:199], v[72:75]
	v_mfma_f32_16x16x32_bf16 v[68:71], v[164:167], v[204:207], v[68:71]
	v_mfma_f32_16x16x32_bf16 v[64:67], v[172:175], v[204:207], v[64:67]
	v_mfma_f32_16x16x32_bf16 v[108:111], v[168:171], v[184:187], v[108:111]
	v_mfma_f32_16x16x32_bf16 v[104:107], v[176:179], v[184:187], v[104:107]
	v_mfma_f32_16x16x32_bf16 v[92:95], v[168:171], v[192:195], v[92:95]
	v_mfma_f32_16x16x32_bf16 v[88:91], v[176:179], v[192:195], v[88:91]
	v_mfma_f32_16x16x32_bf16 v[76:79], v[168:171], v[200:203], v[76:79]
	v_mfma_f32_16x16x32_bf16 v[72:75], v[176:179], v[200:203], v[72:75]
	v_mfma_f32_16x16x32_bf16 v[68:71], v[168:171], v[208:211], v[68:71]
	v_mfma_f32_16x16x32_bf16 v[64:67], v[176:179], v[208:211], v[64:67]
	s_setprio 0
	s_barrier
	s_add_i32 s26, s56, s3
	s_mov_b32 m0, s26
	ds_read_b128 v[180:183], v147 offset:49152
	ds_read_b128 v[184:187], v147 offset:50176
	ds_read_b128 v[188:191], v147 offset:51200
	ds_read_b128 v[192:195], v147 offset:52224
	ds_read_b128 v[196:199], v147 offset:53248
	ds_read_b128 v[200:203], v147 offset:54272
	ds_read_b128 v[204:207], v147 offset:55296
	ds_read_b128 v[208:211], v147 offset:56320
	global_load_lds_dwordx4 v132, s[98:99]
	s_add_i32 m0, s26, 0x2000
	s_add_u32 s24, s24, 0x40080
	s_addc_u32 s25, s25, 0
	s_add_i32 s26, s57, s3
	global_load_lds_dwordx4 v128, s[98:99]
	s_mov_b32 m0, s26
	s_nop 0
	global_load_lds_dwordx4 v132, s[24:25]
	s_add_i32 m0, s26, 0x2000
	s_nop 0
	global_load_lds_dwordx4 v128, s[24:25]
	s_mov_b32 m0, s38
	s_nop 0
	global_load_lds_dwordx4 v134, s[100:101]
	s_mov_b32 m0, s39
	s_nop 0
	global_load_lds_dwordx4 v130, s[100:101]
	s_waitcnt vmcnt(8)
	s_barrier
	s_setprio 1
	s_waitcnt lgkmcnt(0)
	v_mfma_f32_16x16x32_bf16 v[60:63], v[148:151], v[180:183], v[60:63]
	v_mfma_f32_16x16x32_bf16 v[56:59], v[156:159], v[180:183], v[56:59]
	v_mfma_f32_16x16x32_bf16 v[52:55], v[148:151], v[188:191], v[52:55]
	v_mfma_f32_16x16x32_bf16 v[48:51], v[156:159], v[188:191], v[48:51]
	v_mfma_f32_16x16x32_bf16 v[36:39], v[148:151], v[196:199], v[36:39]
	v_mfma_f32_16x16x32_bf16 v[32:35], v[156:159], v[196:199], v[32:35]
	v_mfma_f32_16x16x32_bf16 v[20:23], v[148:151], v[204:207], v[20:23]
	v_mfma_f32_16x16x32_bf16 v[16:19], v[156:159], v[204:207], v[16:19]
	v_mfma_f32_16x16x32_bf16 v[60:63], v[152:155], v[184:187], v[60:63]
	v_mfma_f32_16x16x32_bf16 v[56:59], v[160:163], v[184:187], v[56:59]
	v_mfma_f32_16x16x32_bf16 v[52:55], v[152:155], v[192:195], v[52:55]
	v_mfma_f32_16x16x32_bf16 v[48:51], v[160:163], v[192:195], v[48:51]
	v_mfma_f32_16x16x32_bf16 v[36:39], v[152:155], v[200:203], v[36:39]
	v_mfma_f32_16x16x32_bf16 v[32:35], v[160:163], v[200:203], v[32:35]
	v_mfma_f32_16x16x32_bf16 v[20:23], v[152:155], v[208:211], v[20:23]
	v_mfma_f32_16x16x32_bf16 v[16:19], v[160:163], v[208:211], v[16:19]
	v_mfma_f32_16x16x32_bf16 v[44:47], v[164:167], v[180:183], v[44:47]
	v_mfma_f32_16x16x32_bf16 v[40:43], v[172:175], v[180:183], v[40:43]
	v_mfma_f32_16x16x32_bf16 v[28:31], v[164:167], v[188:191], v[28:31]
	v_mfma_f32_16x16x32_bf16 v[24:27], v[172:175], v[188:191], v[24:27]
	v_mfma_f32_16x16x32_bf16 v[12:15], v[164:167], v[196:199], v[12:15]
	v_mfma_f32_16x16x32_bf16 v[8:11], v[172:175], v[196:199], v[8:11]
	v_mfma_f32_16x16x32_bf16 v[4:7], v[164:167], v[204:207], v[4:7]
	v_mfma_f32_16x16x32_bf16 v[0:3], v[172:175], v[204:207], v[0:3]
	v_mfma_f32_16x16x32_bf16 v[44:47], v[168:171], v[184:187], v[44:47]
	v_mfma_f32_16x16x32_bf16 v[40:43], v[176:179], v[184:187], v[40:43]
	v_mfma_f32_16x16x32_bf16 v[28:31], v[168:171], v[192:195], v[28:31]
	v_mfma_f32_16x16x32_bf16 v[24:27], v[176:179], v[192:195], v[24:27]
	v_mfma_f32_16x16x32_bf16 v[12:15], v[168:171], v[200:203], v[12:15]
	v_mfma_f32_16x16x32_bf16 v[8:11], v[176:179], v[200:203], v[8:11]
	v_mfma_f32_16x16x32_bf16 v[4:7], v[168:171], v[208:211], v[4:7]
	v_mfma_f32_16x16x32_bf16 v[0:3], v[176:179], v[208:211], v[0:3]
	s_setprio 0
	s_barrier
	s_add_i32 s55, s55, 2
	s_add_u32 s22, s22, 0x100
	s_addc_u32 s23, s23, 0
	s_add_u32 s51, s51, 0x100
	s_addc_u32 s54, s54, 0
	s_cmp_gt_u32 s55, 13
	s_cbranch_scc0 .LBB0_232
	s_and_b64 vcc, exec, s[8:9]
	s_cbranch_vccz .LBB0_235
	s_barrier

; #define PG8_STAGE(bufoff, gbase, voff) do { _Pragma("unroll") for (int _i = 0; _i < 2; ++_i) \
;         __builtin_amdgcn_global_load_lds((const unsigned*)((const char*)(gbase) + (voff)[_i]), (LAS unsigned*)(lds + (bufoff) + ldsw + _i * 8192), 16, 0, 0); } while (0)
; #define PG8_LDA(dst, b, h) do { _Pragma("unroll") for (int m = 0; m < 4; ++m) _Pragma("unroll") for (int k = 0; k < 2; ++k) dst[m][k] = *(const LAS bf16x8*)(lds + PG8_SA(b, h) + aoff + m * 2048 + k * 1024); } while (0)
; #define PG8_LDB(dst, b, h) do { _Pragma("unroll") for (int n = 0; n < 2; ++n) _Pragma("unroll") for (int k = 0; k < 2; ++k) dst[n][k] = *(const LAS bf16x8*)(lds + PG8_SB(b, h) + boff + n * 2048 + k * 1024); } while (0)
; #define PG8_MMA(ai, bj, At, Bt) do { __builtin_amdgcn_s_setprio(1); _Pragma("unroll") for (int m = 0; m < 4; ++m) _Pragma("unroll") for (int n = 0; n < 2; ++n) _Pragma("unroll") for (int k = 0; k < 2; ++k) \
;         acc[ai][bj][m][n] = __builtin_amdgcn_mfma_f32_16x16x32_bf16(Bt[n][k], At[m][k], acc[ai][bj][m][n], 0, 0, 0); __builtin_amdgcn_s_setprio(0); } while (0)
; #define PG8_WAIT_V(n) asm volatile("s_waitcnt vmcnt(" #n ")" ::: "memory")
; #define PG8_WAIT_L(n) asm volatile("s_waitcnt lgkmcnt(" #n ")" ::: "memory")
; #define PG8_BAR __builtin_amdgcn_s_barrier()
; #define PG8_SCHED __builtin_amdgcn_sched_barrier(0)
; template <class Epi, bool ALIGN_EPI, int K, int LDA, int LDB>
; __device__ __forceinline__ void gemm_phase(LAS unsigned char* lds, const int wid, const Gemm g, const StaticOrder& S, const Epi& E) {
;     ...
;             PG8_LDB(B0, 0, 0); PG8_LDB(B1, 0, 1); PG8_SCHED; PG8_LDA(At, 0, 0); PG8_STAGE(PG8_SA(1, 1), a1 + hA, voffA);
;             PG8_WAIT_V(8); PG8_WAIT_L(0); PG8_BAR; PG8_MMA(0, 0, At, B0); PG8_MMA(0, 1, At, B1); PG8_BAR; PG8_SCHED;
;             PG8_LDA(At, 0, 1); PG8_STAGE(PG8_SB(0, 0), b2, voffB); PG8_STAGE(PG8_SB(0, 1), b2 + hB, voffB); PG8_STAGE(PG8_SA(0, 0), a2, voffA);
;             PG8_WAIT_V(8); PG8_WAIT_L(0); PG8_BAR; PG8_MMA(1, 0, At, B0); PG8_MMA(1, 1, At, B1); PG8_BAR; PG8_SCHED;
.LBB0_665:
	ds_read_b128 v[8:11], v158
	ds_read_b128 v[12:15], v158 offset:1024
	ds_read_b128 v[16:19], v158 offset:2048
	ds_read_b128 v[20:23], v158 offset:3072
	ds_read_b128 v[24:27], v159
	ds_read_b128 v[28:31], v159 offset:1024
	ds_read_b128 v[32:35], v159 offset:2048
	ds_read_b128 v[36:39], v159 offset:3072
	s_add_u32 s6, s36, 0xa0080
	s_addc_u32 s7, s37, 0
	s_add_i32 s71, s42, 0xc000
	v_lshl_add_u64 v[64:65], s[6:7], 0, v[142:143]
	s_mov_b32 m0, s71
	ds_read_b128 v[0:3], v157
	ds_read_b128 v[4:7], v157 offset:1024
	ds_read_b128 v[40:43], v157 offset:2048
	ds_read_b128 v[44:47], v157 offset:3072
	ds_read_b128 v[48:51], v157 offset:4096
	ds_read_b128 v[52:55], v157 offset:5120
	ds_read_b128 v[56:59], v157 offset:6144
	ds_read_b128 v[60:63], v157 offset:7168
	global_load_lds_dwordx4 v[64:65], off
	v_lshl_add_u64 v[64:65], s[6:7], 0, v[138:139]
	s_add_i32 s6, s42, 0xe000
	s_mov_b32 m0, s6
	s_nop 0
	global_load_lds_dwordx4 v[64:65], off
	s_waitcnt vmcnt(8)
	s_barrier
	s_setprio 1
	s_waitcnt lgkmcnt(0)
	v_mfma_f32_16x16x32_bf16 v[64:67], v[8:11], v[0:3], 0
	v_mfma_f32_16x16x32_bf16 v[68:71], v[16:19], v[0:3], 0
	v_mfma_f32_16x16x32_bf16 v[72:75], v[8:11], v[40:43], 0
	v_mfma_f32_16x16x32_bf16 v[76:79], v[16:19], v[40:43], 0
	v_mfma_f32_16x16x32_bf16 v[80:83], v[8:11], v[48:51], 0
	v_mfma_f32_16x16x32_bf16 v[84:87], v[16:19], v[48:51], 0
	s_waitcnt vmcnt(0)
	v_mfma_f32_16x16x32_bf16 v[88:91], v[8:11], v[56:59], 0
	v_mfma_f32_16x16x32_bf16 v[92:95], v[16:19], v[56:59], 0
	v_mfma_f32_16x16x32_bf16 v[64:67], v[12:15], v[4:7], v[64:67]
	v_mfma_f32_16x16x32_bf16 v[68:71], v[20:23], v[4:7], v[68:71]
	v_mfma_f32_16x16x32_bf16 v[72:75], v[12:15], v[44:47], v[72:75]
	v_mfma_f32_16x16x32_bf16 v[76:79], v[20:23], v[44:47], v[76:79]
	v_mfma_f32_16x16x32_bf16 v[80:83], v[12:15], v[52:55], v[80:83]
	v_mfma_f32_16x16x32_bf16 v[84:87], v[20:23], v[52:55], v[84:87]
	v_mfma_f32_16x16x32_bf16 v[88:91], v[12:15], v[60:63], v[88:91]
	v_mfma_f32_16x16x32_bf16 v[92:95], v[20:23], v[60:63], v[92:95]
	v_mfma_f32_16x16x32_bf16 v[96:99], v[24:27], v[0:3], 0
	v_mfma_f32_16x16x32_bf16 v[0:3], v[32:35], v[0:3], 0
	v_mfma_f32_16x16x32_bf16 v[100:103], v[36:39], v[4:7], v[0:3]
	v_mfma_f32_16x16x32_bf16 v[0:3], v[24:27], v[40:43], 0
	v_mfma_f32_16x16x32_bf16 v[104:107], v[28:31], v[44:47], v[0:3]
	v_mfma_f32_16x16x32_bf16 v[0:3], v[32:35], v[40:43], 0
	v_mfma_f32_16x16x32_bf16 v[40:43], v[36:39], v[44:47], v[0:3]
	v_mfma_f32_16x16x32_bf16 v[0:3], v[24:27], v[48:51], 0
	v_mfma_f32_16x16x32_bf16 v[44:47], v[28:31], v[52:55], v[0:3]
	v_mfma_f32_16x16x32_bf16 v[0:3], v[32:35], v[48:51], 0
	v_mfma_f32_16x16x32_bf16 v[48:51], v[36:39], v[52:55], v[0:3]
	v_mfma_f32_16x16x32_bf16 v[0:3], v[24:27], v[56:59], 0
	v_mfma_f32_16x16x32_bf16 v[52:55], v[28:31], v[60:63], v[0:3]
	v_mfma_f32_16x16x32_bf16 v[0:3], v[32:35], v[56:59], 0
	v_mfma_f32_16x16x32_bf16 v[96:99], v[28:31], v[4:7], v[96:99]
	v_mfma_f32_16x16x32_bf16 v[56:59], v[36:39], v[60:63], v[0:3]
	s_setprio 0
	s_barrier
	s_nop 3
	v_lshl_add_u64 v[0:1], s[38:39], 0, v[140:141]
	s_add_i32 s68, s59, s0
	v_lshl_add_u64 v[2:3], v[0:1], 0, s[22:23]
	s_mov_b32 m0, s68
	s_add_i32 s7, s68, 0x2000
	ds_read_b128 v[60:63], v157 offset:16384
	ds_read_b128 v[108:111], v157 offset:17408
	ds_read_b128 v[112:115], v157 offset:18432
	ds_read_b128 v[116:119], v157 offset:19456
	ds_read_b128 v[120:123], v157 offset:20480
	ds_read_b128 v[124:127], v157 offset:21504
	ds_read_b128 v[128:131], v157 offset:22528
	ds_read_b128 v[132:135], v157 offset:23552
	global_load_lds_dwordx4 v[2:3], off
	v_lshl_add_u64 v[2:3], s[38:39], 0, v[136:137]
	s_add_u32 s72, s38, 0x18100
	v_lshl_add_u64 v[4:5], v[2:3], 0, s[22:23]
	s_mov_b32 m0, s7
	s_addc_u32 s73, s39, 0
	s_add_i32 s66, s60, s0
	global_load_lds_dwordx4 v[4:5], off
	v_lshl_add_u64 v[4:5], s[72:73], 0, v[140:141]
	s_mov_b32 m0, s66
	s_add_i32 s67, s66, 0x2000
	global_load_lds_dwordx4 v[4:5], off
	v_lshl_add_u64 v[4:5], s[72:73], 0, v[136:137]
	s_mov_b32 m0, s67
	s_nop 0
	global_load_lds_dwordx4 v[4:5], off
	v_lshl_add_u64 v[4:5], s[36:37], 0, v[142:143]
	v_lshl_add_u64 v[6:7], v[4:5], 0, s[22:23]
	s_mov_b32 m0, s42
	s_nop 0
	global_load_lds_dwordx4 v[6:7], off
	v_lshl_add_u64 v[6:7], s[36:37], 0, v[138:139]
	v_lshl_add_u64 v[148:149], v[6:7], 0, s[22:23]
	s_mov_b32 m0, s51
	s_nop 0
	global_load_lds_dwordx4 v[148:149], off
	s_waitcnt vmcnt(8)
	s_barrier
	s_setprio 1
	s_waitcnt lgkmcnt(0)
	v_mfma_f32_16x16x32_bf16 v[148:151], v[8:11], v[60:63], 0
	v_mfma_f32_16x16x32_bf16 v[160:163], v[8:11], v[112:115], 0
	v_mfma_f32_16x16x32_bf16 v[168:171], v[8:11], v[120:123], 0
	v_mfma_f32_16x16x32_bf16 v[8:11], v[8:11], v[128:131], 0
	v_mfma_f32_16x16x32_bf16 v[148:151], v[12:15], v[108:111], v[148:151]
	v_mfma_f32_16x16x32_bf16 v[152:155], v[16:19], v[60:63], 0
	v_mfma_f32_16x16x32_bf16 v[160:163], v[12:15], v[116:119], v[160:163]
	v_mfma_f32_16x16x32_bf16 v[164:167], v[16:19], v[112:115], 0
	v_mfma_f32_16x16x32_bf16 v[168:171], v[12:15], v[124:127], v[168:171]
	v_mfma_f32_16x16x32_bf16 v[172:175], v[16:19], v[120:123], 0
	v_mfma_f32_16x16x32_bf16 v[10:13], v[12:15], v[132:135], v[8:11]
	v_mfma_f32_16x16x32_bf16 v[14:17], v[16:19], v[128:131], 0
	v_mfma_f32_16x16x32_bf16 v[14:17], v[20:23], v[132:135], v[14:17]
	v_mfma_f32_16x16x32_bf16 v[152:155], v[20:23], v[108:111], v[152:155]
	v_mfma_f32_16x16x32_bf16 v[164:167], v[20:23], v[116:119], v[164:167]
	v_mfma_f32_16x16x32_bf16 v[172:175], v[20:23], v[124:127], v[172:175]
	v_mfma_f32_16x16x32_bf16 v[18:21], v[24:27], v[60:63], 0
	v_mfma_f32_16x16x32_bf16 v[60:63], v[32:35], v[60:63], 0
	v_mfma_f32_16x16x32_bf16 v[18:21], v[28:31], v[108:111], v[18:21]
	v_mfma_f32_16x16x32_bf16 v[60:63], v[36:39], v[108:111], v[60:63]
	v_mfma_f32_16x16x32_bf16 v[108:111], v[24:27], v[112:115], 0
	v_mfma_f32_16x16x32_bf16 v[112:115], v[32:35], v[112:115], 0
	v_mfma_f32_16x16x32_bf16 v[108:111], v[28:31], v[116:119], v[108:111]
	v_mfma_f32_16x16x32_bf16 v[112:115], v[36:39], v[116:119], v[112:115]
	v_mfma_f32_16x16x32_bf16 v[116:119], v[24:27], v[120:123], 0
	v_mfma_f32_16x16x32_bf16 v[22:25], v[24:27], v[128:131], 0
	v_mfma_f32_16x16x32_bf16 v[116:119], v[28:31], v[124:127], v[116:119]
	v_mfma_f32_16x16x32_bf16 v[22:25], v[28:31], v[132:135], v[22:25]
	v_mfma_f32_16x16x32_bf16 v[26:29], v[32:35], v[128:131], 0
	v_mfma_f32_16x16x32_bf16 v[120:123], v[32:35], v[120:123], 0
	v_mfma_f32_16x16x32_bf16 v[26:29], v[36:39], v[132:135], v[26:29]
	v_mfma_f32_16x16x32_bf16 v[120:123], v[36:39], v[124:127], v[120:123]
	s_setprio 0
	s_barrier
; #define PG8_STAGE(bufoff, gbase, voff) do { _Pragma("unroll") for (int _i = 0; _i < 2; ++_i) \
;         __builtin_amdgcn_global_load_lds((const unsigned*)((const char*)(gbase) + (voff)[_i]), (LAS unsigned*)(lds + (bufoff) + ldsw + _i * 8192), 16, 0, 0); } while (0)
; #define PG8_LDA(dst, b, h) do { _Pragma("unroll") for (int m = 0; m < 4; ++m) _Pragma("unroll") for (int k = 0; k < 2; ++k) dst[m][k] = *(const LAS bf16x8*)(lds + PG8_SA(b, h) + aoff + m * 2048 + k * 1024); } while (0)
; #define PG8_LDB(dst, b, h) do { _Pragma("unroll") for (int n = 0; n < 2; ++n) _Pragma("unroll") for (int k = 0; k < 2; ++k) dst[n][k] = *(const LAS bf16x8*)(lds + PG8_SB(b, h) + boff + n * 2048 + k * 1024); } while (0)
; #define PG8_MMA(ai, bj, At, Bt) do { __builtin_amdgcn_s_setprio(1); _Pragma("unroll") for (int m = 0; m < 4; ++m) _Pragma("unroll") for (int n = 0; n < 2; ++n) _Pragma("unroll") for (int k = 0; k < 2; ++k) \
;         acc[ai][bj][m][n] = __builtin_amdgcn_mfma_f32_16x16x32_bf16(Bt[n][k], At[m][k], acc[ai][bj][m][n], 0, 0, 0); __builtin_amdgcn_s_setprio(0); } while (0)
; #define PG8_WAIT_V(n) asm volatile("s_waitcnt vmcnt(" #n ")" ::: "memory")
; #define PG8_WAIT_L(n) asm volatile("s_waitcnt lgkmcnt(" #n ")" ::: "memory")
; #define PG8_BAR __builtin_amdgcn_s_barrier()
; #define PG8_SCHED __builtin_amdgcn_sched_barrier(0)
; template <class Epi, bool ALIGN_EPI, int K, int LDA, int LDB>
; __device__ __forceinline__ void gemm_phase(LAS unsigned char* lds, const int wid, const Gemm g, const StaticOrder& S, const Epi& E) {
;     ...
;             PG8_LDB(B0, 1, 0); PG8_LDB(B1, 1, 1); PG8_SCHED; PG8_LDA(At, 1, 0); PG8_STAGE(PG8_SA(0, 1), a2 + hA, voffA);
;             PG8_WAIT_V(8); PG8_WAIT_L(0); PG8_BAR; PG8_MMA(0, 0, At, B0); PG8_MMA(0, 1, At, B1); PG8_BAR; PG8_SCHED;
;             PG8_LDA(At, 1, 1); PG8_STAGE(PG8_SB(1, 0), b3, voffB); PG8_STAGE(PG8_SB(1, 1), b3 + hB, voffB); PG8_STAGE(PG8_SA(1, 0), a3, voffA);
;             PG8_WAIT_V(8); PG8_WAIT_L(0); PG8_BAR; PG8_MMA(1, 0, At, B0); PG8_MMA(1, 1, At, B1); PG8_BAR; PG8_SCHED;
	s_add_i32 s69, 0, 0x18000
	s_add_i32 s70, 0, 0x1c000
	v_add_u32_e32 v8, s69, v156
	v_add_u32_e32 v9, s70, v156
	ds_read_b128 v[30:33], v8
	ds_read_b128 v[34:37], v8 offset:1024
	ds_read_b128 v[124:127], v8 offset:2048
	ds_read_b128 v[128:131], v8 offset:3072
	ds_read_b128 v[132:135], v9
	ds_read_b128 v[176:179], v9 offset:1024
	ds_read_b128 v[180:183], v9 offset:2048
	ds_read_b128 v[184:187], v9 offset:3072
	s_add_u32 s72, s36, 0xa0100
	s_addc_u32 s73, s37, 0
	s_mov_b32 m0, s54
	v_lshl_add_u64 v[38:39], s[72:73], 0, v[142:143]
	ds_read_b128 v[188:191], v157 offset:32768
	ds_read_b128 v[192:195], v157 offset:33792
	ds_read_b128 v[196:199], v157 offset:34816
	ds_read_b128 v[200:203], v157 offset:35840
	ds_read_b128 v[204:207], v157 offset:36864
	ds_read_b128 v[208:211], v157 offset:37888
	ds_read_b128 v[212:215], v157 offset:38912
	ds_read_b128 v[216:219], v157 offset:39936
	global_load_lds_dwordx4 v[38:39], off
	v_lshl_add_u64 v[38:39], s[72:73], 0, v[138:139]
	s_mov_b32 m0, s55
	s_nop 0
	global_load_lds_dwordx4 v[38:39], off
	s_waitcnt vmcnt(8)
	s_barrier
	s_setprio 1
	s_waitcnt lgkmcnt(0)
	v_mfma_f32_16x16x32_bf16 v[64:67], v[30:33], v[188:191], v[64:67]
	v_mfma_f32_16x16x32_bf16 v[68:71], v[124:127], v[188:191], v[68:71]
	v_mfma_f32_16x16x32_bf16 v[72:75], v[30:33], v[196:199], v[72:75]
	v_mfma_f32_16x16x32_bf16 v[76:79], v[124:127], v[196:199], v[76:79]
	v_mfma_f32_16x16x32_bf16 v[80:83], v[30:33], v[204:207], v[80:83]
	v_mfma_f32_16x16x32_bf16 v[84:87], v[124:127], v[204:207], v[84:87]
	v_mfma_f32_16x16x32_bf16 v[88:91], v[30:33], v[212:215], v[88:91]
	v_mfma_f32_16x16x32_bf16 v[92:95], v[124:127], v[212:215], v[92:95]
	v_mfma_f32_16x16x32_bf16 v[64:67], v[34:37], v[192:195], v[64:67]
	v_mfma_f32_16x16x32_bf16 v[68:71], v[128:131], v[192:195], v[68:71]
	v_mfma_f32_16x16x32_bf16 v[72:75], v[34:37], v[200:203], v[72:75]
	v_mfma_f32_16x16x32_bf16 v[76:79], v[128:131], v[200:203], v[76:79]
	v_mfma_f32_16x16x32_bf16 v[80:83], v[34:37], v[208:211], v[80:83]
	v_mfma_f32_16x16x32_bf16 v[84:87], v[128:131], v[208:211], v[84:87]
	v_mfma_f32_16x16x32_bf16 v[88:91], v[34:37], v[216:219], v[88:91]
	v_mfma_f32_16x16x32_bf16 v[92:95], v[128:131], v[216:219], v[92:95]
	v_mfma_f32_16x16x32_bf16 v[96:99], v[132:135], v[188:191], v[96:99]
	v_mfma_f32_16x16x32_bf16 v[100:103], v[180:183], v[188:191], v[100:103]
	v_mfma_f32_16x16x32_bf16 v[104:107], v[132:135], v[196:199], v[104:107]
	v_mfma_f32_16x16x32_bf16 v[38:41], v[180:183], v[196:199], v[40:43]
	v_mfma_f32_16x16x32_bf16 v[42:45], v[132:135], v[204:207], v[44:47]
	v_mfma_f32_16x16x32_bf16 v[46:49], v[180:183], v[204:207], v[48:51]
	v_mfma_f32_16x16x32_bf16 v[50:53], v[132:135], v[212:215], v[52:55]
	v_mfma_f32_16x16x32_bf16 v[54:57], v[180:183], v[212:215], v[56:59]
	v_mfma_f32_16x16x32_bf16 v[96:99], v[176:179], v[192:195], v[96:99]
	v_mfma_f32_16x16x32_bf16 v[100:103], v[184:187], v[192:195], v[100:103]
	v_mfma_f32_16x16x32_bf16 v[104:107], v[176:179], v[200:203], v[104:107]
	v_mfma_f32_16x16x32_bf16 v[38:41], v[184:187], v[200:203], v[38:41]
	v_mfma_f32_16x16x32_bf16 v[42:45], v[176:179], v[208:211], v[42:45]
	v_mfma_f32_16x16x32_bf16 v[46:49], v[184:187], v[208:211], v[46:49]
	v_mfma_f32_16x16x32_bf16 v[50:53], v[176:179], v[216:219], v[50:53]
	v_mfma_f32_16x16x32_bf16 v[54:57], v[184:187], v[216:219], v[54:57]
	s_setprio 0
	s_barrier
	s_add_i32 s73, s69, s0
	s_add_i32 s69, s73, 0x2000
	v_lshl_add_u64 v[58:59], v[0:1], 0, s[24:25]
	s_mov_b32 m0, s73
	s_add_u32 s74, s38, 0x18180
	ds_read_b128 v[188:191], v157 offset:49152
	ds_read_b128 v[192:195], v157 offset:50176
	ds_read_b128 v[196:199], v157 offset:51200
	ds_read_b128 v[200:203], v157 offset:52224
	ds_read_b128 v[204:207], v157 offset:53248
	ds_read_b128 v[208:211], v157 offset:54272
	ds_read_b128 v[212:215], v157 offset:55296
	ds_read_b128 v[216:219], v157 offset:56320
	global_load_lds_dwordx4 v[58:59], off
	v_lshl_add_u64 v[58:59], v[2:3], 0, s[24:25]
	s_mov_b32 m0, s69
	s_addc_u32 s75, s39, 0
	s_add_i32 s70, s70, s0
	global_load_lds_dwordx4 v[58:59], off
	v_lshl_add_u64 v[58:59], s[74:75], 0, v[140:141]
	s_mov_b32 m0, s70
	s_add_i32 s72, s70, 0x2000
	global_load_lds_dwordx4 v[58:59], off
	v_lshl_add_u64 v[58:59], s[74:75], 0, v[136:137]
	s_mov_b32 m0, s72
	s_nop 0
	global_load_lds_dwordx4 v[58:59], off
	v_lshl_add_u64 v[58:59], v[4:5], 0, s[24:25]
	s_mov_b32 m0, s56
	s_nop 0
	global_load_lds_dwordx4 v[58:59], off
	v_lshl_add_u64 v[58:59], v[6:7], 0, s[24:25]
	s_mov_b32 m0, s57
	s_nop 0
	global_load_lds_dwordx4 v[58:59], off
	s_waitcnt vmcnt(8)
	s_barrier
; #define PG8_STAGE(bufoff, gbase, voff) do { _Pragma("unroll") for (int _i = 0; _i < 2; ++_i) \
;         __builtin_amdgcn_global_load_lds((const unsigned*)((const char*)(gbase) + (voff)[_i]), (LAS unsigned*)(lds + (bufoff) + ldsw + _i * 8192), 16, 0, 0); } while (0)
; #define PG8_LDA(dst, b, h) do { _Pragma("unroll") for (int m = 0; m < 4; ++m) _Pragma("unroll") for (int k = 0; k < 2; ++k) dst[m][k] = *(const LAS bf16x8*)(lds + PG8_SA(b, h) + aoff + m * 2048 + k * 1024); } while (0)
; #define PG8_MMA(ai, bj, At, Bt) do { __builtin_amdgcn_s_setprio(1); _Pragma("unroll") for (int m = 0; m < 4; ++m) _Pragma("unroll") for (int n = 0; n < 2; ++n) _Pragma("unroll") for (int k = 0; k < 2; ++k) \
;         acc[ai][bj][m][n] = __builtin_amdgcn_mfma_f32_16x16x32_bf16(Bt[n][k], At[m][k], acc[ai][bj][m][n], 0, 0, 0); __builtin_amdgcn_s_setprio(0); } while (0)
; #define PG8_WAIT_V(n) asm volatile("s_waitcnt vmcnt(" #n ")" ::: "memory")
; #define PG8_WAIT_L(n) asm volatile("s_waitcnt lgkmcnt(" #n ")" ::: "memory")
; #define PG8_BAR __builtin_amdgcn_s_barrier()
; #define PG8_SCHED __builtin_amdgcn_sched_barrier(0)
; template <class Epi, bool ALIGN_EPI, int K, int LDA, int LDB>
; __device__ __forceinline__ void gemm_phase(LAS unsigned char* lds, const int wid, const Gemm g, const StaticOrder& S, const Epi& E) {
;     ...
;             PG8_WAIT_V(8); PG8_WAIT_L(0); PG8_BAR; PG8_MMA(0, 0, At, B0); PG8_MMA(0, 1, At, B1); PG8_BAR; PG8_SCHED;
;             PG8_LDA(At, 0, 1); PG8_STAGE(PG8_SB(0, 0), b2, voffB); PG8_STAGE(PG8_SB(0, 1), b2 + hB, voffB); PG8_STAGE(PG8_SA(0, 0), a2, voffA);
;             PG8_WAIT_V(8); PG8_WAIT_L(0); PG8_BAR; PG8_MMA(1, 0, At, B0); PG8_MMA(1, 1, At, B1); PG8_BAR; PG8_SCHED;
	s_setprio 1
	s_waitcnt lgkmcnt(0)
	v_mfma_f32_16x16x32_bf16 v[10:13], v[30:33], v[212:215], v[10:13]
	v_mfma_f32_16x16x32_bf16 v[14:17], v[124:127], v[212:215], v[14:17]
	v_mfma_f32_16x16x32_bf16 v[148:151], v[30:33], v[188:191], v[148:151]
	v_mfma_f32_16x16x32_bf16 v[152:155], v[124:127], v[188:191], v[152:155]
	v_mfma_f32_16x16x32_bf16 v[160:163], v[30:33], v[196:199], v[160:163]
	v_mfma_f32_16x16x32_bf16 v[164:167], v[124:127], v[196:199], v[164:167]
	v_mfma_f32_16x16x32_bf16 v[168:171], v[30:33], v[204:207], v[168:171]
	v_mfma_f32_16x16x32_bf16 v[172:175], v[124:127], v[204:207], v[172:175]
	v_mfma_f32_16x16x32_bf16 v[10:13], v[34:37], v[216:219], v[10:13]
	v_mfma_f32_16x16x32_bf16 v[14:17], v[128:131], v[216:219], v[14:17]
	v_mfma_f32_16x16x32_bf16 v[148:151], v[34:37], v[192:195], v[148:151]
	v_mfma_f32_16x16x32_bf16 v[152:155], v[128:131], v[192:195], v[152:155]
	v_mfma_f32_16x16x32_bf16 v[160:163], v[34:37], v[200:203], v[160:163]
	v_mfma_f32_16x16x32_bf16 v[164:167], v[128:131], v[200:203], v[164:167]
	v_mfma_f32_16x16x32_bf16 v[168:171], v[34:37], v[208:211], v[168:171]
	v_mfma_f32_16x16x32_bf16 v[172:175], v[128:131], v[208:211], v[172:175]
	v_mfma_f32_16x16x32_bf16 v[18:21], v[132:135], v[188:191], v[18:21]
	v_mfma_f32_16x16x32_bf16 v[30:33], v[180:183], v[188:191], v[60:63]
	v_mfma_f32_16x16x32_bf16 v[34:37], v[132:135], v[196:199], v[108:111]
	v_mfma_f32_16x16x32_bf16 v[58:61], v[180:183], v[196:199], v[112:115]
	v_mfma_f32_16x16x32_bf16 v[108:111], v[132:135], v[204:207], v[116:119]
	v_mfma_f32_16x16x32_bf16 v[112:115], v[180:183], v[204:207], v[120:123]
	v_mfma_f32_16x16x32_bf16 v[22:25], v[132:135], v[212:215], v[22:25]
	v_mfma_f32_16x16x32_bf16 v[26:29], v[180:183], v[212:215], v[26:29]
	v_mfma_f32_16x16x32_bf16 v[18:21], v[176:179], v[192:195], v[18:21]
	v_mfma_f32_16x16x32_bf16 v[30:33], v[184:187], v[192:195], v[30:33]
	v_mfma_f32_16x16x32_bf16 v[34:37], v[176:179], v[200:203], v[34:37]
	v_mfma_f32_16x16x32_bf16 v[58:61], v[184:187], v[200:203], v[58:61]
	v_mfma_f32_16x16x32_bf16 v[108:111], v[176:179], v[208:211], v[108:111]
	v_mfma_f32_16x16x32_bf16 v[112:115], v[184:187], v[208:211], v[112:115]
	v_mfma_f32_16x16x32_bf16 v[22:25], v[176:179], v[216:219], v[22:25]
	v_mfma_f32_16x16x32_bf16 v[26:29], v[184:187], v[216:219], v[26:29]
	s_setprio 0
	s_barrier
	ds_read_b128 v[116:119], v158
	ds_read_b128 v[120:123], v158 offset:1024
	ds_read_b128 v[124:127], v158 offset:2048
	ds_read_b128 v[128:131], v158 offset:3072
	ds_read_b128 v[132:135], v159
	ds_read_b128 v[176:179], v159 offset:1024
	ds_read_b128 v[180:183], v159 offset:2048
	ds_read_b128 v[184:187], v159 offset:3072
	s_add_u32 s74, s36, 0xa0180
	s_addc_u32 s75, s37, 0
	s_mov_b32 m0, s71
	v_lshl_add_u64 v[62:63], s[74:75], 0, v[142:143]
	ds_read_b128 v[188:191], v157
	ds_read_b128 v[192:195], v157 offset:1024
	ds_read_b128 v[196:199], v157 offset:2048
	ds_read_b128 v[200:203], v157 offset:3072
	ds_read_b128 v[204:207], v157 offset:4096
	ds_read_b128 v[208:211], v157 offset:5120
	ds_read_b128 v[212:215], v157 offset:6144
	ds_read_b128 v[216:219], v157 offset:7168
	global_load_lds_dwordx4 v[62:63], off
	v_lshl_add_u64 v[62:63], s[74:75], 0, v[138:139]
	s_mov_b32 m0, s6
	s_nop 0
	global_load_lds_dwordx4 v[62:63], off
	s_waitcnt vmcnt(8)
	s_barrier
	s_setprio 1
	s_waitcnt lgkmcnt(0)
	v_mfma_f32_16x16x32_bf16 v[62:65], v[116:119], v[188:191], v[64:67]
	v_mfma_f32_16x16x32_bf16 v[66:69], v[124:127], v[188:191], v[68:71]
	v_mfma_f32_16x16x32_bf16 v[70:73], v[116:119], v[196:199], v[72:75]
	v_mfma_f32_16x16x32_bf16 v[74:77], v[124:127], v[196:199], v[76:79]
	v_mfma_f32_16x16x32_bf16 v[78:81], v[116:119], v[204:207], v[80:83]
	v_mfma_f32_16x16x32_bf16 v[82:85], v[124:127], v[204:207], v[84:87]
	v_mfma_f32_16x16x32_bf16 v[86:89], v[116:119], v[212:215], v[88:91]
	v_mfma_f32_16x16x32_bf16 v[90:93], v[124:127], v[212:215], v[92:95]
	v_mfma_f32_16x16x32_bf16 v[62:65], v[120:123], v[192:195], v[62:65]
	v_mfma_f32_16x16x32_bf16 v[66:69], v[128:131], v[192:195], v[66:69]
	v_mfma_f32_16x16x32_bf16 v[70:73], v[120:123], v[200:203], v[70:73]
	v_mfma_f32_16x16x32_bf16 v[74:77], v[128:131], v[200:203], v[74:77]
	v_mfma_f32_16x16x32_bf16 v[78:81], v[120:123], v[208:211], v[78:81]
	v_mfma_f32_16x16x32_bf16 v[82:85], v[128:131], v[208:211], v[82:85]
	v_mfma_f32_16x16x32_bf16 v[86:89], v[120:123], v[216:219], v[86:89]
	v_mfma_f32_16x16x32_bf16 v[90:93], v[128:131], v[216:219], v[90:93]
	v_mfma_f32_16x16x32_bf16 v[94:97], v[132:135], v[188:191], v[96:99]
	v_mfma_f32_16x16x32_bf16 v[98:101], v[180:183], v[188:191], v[100:103]
	v_mfma_f32_16x16x32_bf16 v[102:105], v[132:135], v[196:199], v[104:107]
	v_mfma_f32_16x16x32_bf16 v[38:41], v[180:183], v[196:199], v[38:41]
	v_mfma_f32_16x16x32_bf16 v[42:45], v[132:135], v[204:207], v[42:45]
	v_mfma_f32_16x16x32_bf16 v[46:49], v[180:183], v[204:207], v[46:49]
	v_mfma_f32_16x16x32_bf16 v[50:53], v[132:135], v[212:215], v[50:53]
	v_mfma_f32_16x16x32_bf16 v[54:57], v[180:183], v[212:215], v[54:57]
	v_mfma_f32_16x16x32_bf16 v[94:97], v[176:179], v[192:195], v[94:97]
	v_mfma_f32_16x16x32_bf16 v[98:101], v[184:187], v[192:195], v[98:101]
	v_mfma_f32_16x16x32_bf16 v[102:105], v[176:179], v[200:203], v[102:105]
	v_mfma_f32_16x16x32_bf16 v[38:41], v[184:187], v[200:203], v[38:41]
	v_mfma_f32_16x16x32_bf16 v[42:45], v[176:179], v[208:211], v[42:45]
	v_mfma_f32_16x16x32_bf16 v[46:49], v[184:187], v[208:211], v[46:49]
	v_mfma_f32_16x16x32_bf16 v[50:53], v[176:179], v[216:219], v[50:53]
	v_mfma_f32_16x16x32_bf16 v[54:57], v[184:187], v[216:219], v[54:57]
	s_setprio 0
	s_barrier
; #define PG8_STAGE(bufoff, gbase, voff) do { _Pragma("unroll") for (int _i = 0; _i < 2; ++_i) \
;         __builtin_amdgcn_global_load_lds((const unsigned*)((const char*)(gbase) + (voff)[_i]), (LAS unsigned*)(lds + (bufoff) + ldsw + _i * 8192), 16, 0, 0); } while (0)
; #define PG8_LDA(dst, b, h) do { _Pragma("unroll") for (int m = 0; m < 4; ++m) _Pragma("unroll") for (int k = 0; k < 2; ++k) dst[m][k] = *(const LAS bf16x8*)(lds + PG8_SA(b, h) + aoff + m * 2048 + k * 1024); } while (0)
; #define PG8_LDB(dst, b, h) do { _Pragma("unroll") for (int n = 0; n < 2; ++n) _Pragma("unroll") for (int k = 0; k < 2; ++k) dst[n][k] = *(const LAS bf16x8*)(lds + PG8_SB(b, h) + boff + n * 2048 + k * 1024); } while (0)
; #define PG8_MMA(ai, bj, At, Bt) do { __builtin_amdgcn_s_setprio(1); _Pragma("unroll") for (int m = 0; m < 4; ++m) _Pragma("unroll") for (int n = 0; n < 2; ++n) _Pragma("unroll") for (int k = 0; k < 2; ++k) \
;         acc[ai][bj][m][n] = __builtin_amdgcn_mfma_f32_16x16x32_bf16(Bt[n][k], At[m][k], acc[ai][bj][m][n], 0, 0, 0); __builtin_amdgcn_s_setprio(0); } while (0)
; #define PG8_WAIT_V(n) asm volatile("s_waitcnt vmcnt(" #n ")" ::: "memory")
; #define PG8_WAIT_L(n) asm volatile("s_waitcnt lgkmcnt(" #n ")" ::: "memory")
; #define PG8_BAR __builtin_amdgcn_s_barrier()
; #define PG8_SCHED __builtin_amdgcn_sched_barrier(0)
; template <class Epi, bool ALIGN_EPI, int K, int LDA, int LDB>
; __device__ __forceinline__ void gemm_phase(LAS unsigned char* lds, const int wid, const Gemm g, const StaticOrder& S, const Epi& E) {
;     ...
;             PG8_LDA(At, 0, 1); PG8_STAGE(PG8_SB(0, 0), b2, voffB); PG8_STAGE(PG8_SB(0, 1), b2 + hB, voffB); PG8_STAGE(PG8_SA(0, 0), a2, voffA);
;             PG8_WAIT_V(8); PG8_WAIT_L(0); PG8_BAR; PG8_MMA(1, 0, At, B0); PG8_MMA(1, 1, At, B1); PG8_BAR; PG8_SCHED;
;             PG8_LDB(B0, 1, 0); PG8_LDB(B1, 1, 1); PG8_SCHED; PG8_LDA(At, 1, 0); PG8_STAGE(PG8_SA(0, 1), a2 + hA, voffA);
;             PG8_WAIT_V(8); PG8_WAIT_L(0); PG8_BAR; PG8_MMA(0, 0, At, B0); PG8_MMA(0, 1, At, B1); PG8_BAR; PG8_SCHED;
	s_mov_b32 m0, s68
	v_lshl_add_u64 v[106:107], v[0:1], 0, s[26:27]
	s_add_u32 s74, s38, 0x18200
	ds_read_b128 v[188:191], v157 offset:16384
	ds_read_b128 v[192:195], v157 offset:17408
	ds_read_b128 v[196:199], v157 offset:18432
	ds_read_b128 v[200:203], v157 offset:19456
	ds_read_b128 v[204:207], v157 offset:20480
	ds_read_b128 v[208:211], v157 offset:21504
	ds_read_b128 v[212:215], v157 offset:22528
	ds_read_b128 v[216:219], v157 offset:23552
	global_load_lds_dwordx4 v[106:107], off
	v_lshl_add_u64 v[106:107], v[2:3], 0, s[26:27]
	s_mov_b32 m0, s7
	s_addc_u32 s75, s39, 0
	global_load_lds_dwordx4 v[106:107], off
	v_lshl_add_u64 v[106:107], s[74:75], 0, v[140:141]
	s_mov_b32 m0, s66
	s_nop 0
	global_load_lds_dwordx4 v[106:107], off
	v_lshl_add_u64 v[106:107], s[74:75], 0, v[136:137]
	s_mov_b32 m0, s67
	s_nop 0
	global_load_lds_dwordx4 v[106:107], off
	v_lshl_add_u64 v[106:107], v[4:5], 0, s[26:27]
	s_mov_b32 m0, s42
	s_nop 0
	global_load_lds_dwordx4 v[106:107], off
	v_lshl_add_u64 v[106:107], v[6:7], 0, s[26:27]
	s_mov_b32 m0, s51
	s_nop 0
	global_load_lds_dwordx4 v[106:107], off
	s_waitcnt vmcnt(8)
	s_barrier
	s_setprio 1
	s_waitcnt lgkmcnt(0)
	v_mfma_f32_16x16x32_bf16 v[10:13], v[116:119], v[212:215], v[10:13]
	v_mfma_f32_16x16x32_bf16 v[14:17], v[124:127], v[212:215], v[14:17]
	v_mfma_f32_16x16x32_bf16 v[148:151], v[116:119], v[188:191], v[148:151]
	v_mfma_f32_16x16x32_bf16 v[152:155], v[124:127], v[188:191], v[152:155]
	v_mfma_f32_16x16x32_bf16 v[160:163], v[116:119], v[196:199], v[160:163]
	v_mfma_f32_16x16x32_bf16 v[164:167], v[124:127], v[196:199], v[164:167]
	v_mfma_f32_16x16x32_bf16 v[168:171], v[116:119], v[204:207], v[168:171]
	v_mfma_f32_16x16x32_bf16 v[172:175], v[124:127], v[204:207], v[172:175]
	v_mfma_f32_16x16x32_bf16 v[10:13], v[120:123], v[216:219], v[10:13]
	v_mfma_f32_16x16x32_bf16 v[14:17], v[128:131], v[216:219], v[14:17]
	v_mfma_f32_16x16x32_bf16 v[148:151], v[120:123], v[192:195], v[148:151]
	v_mfma_f32_16x16x32_bf16 v[152:155], v[128:131], v[192:195], v[152:155]
	v_mfma_f32_16x16x32_bf16 v[160:163], v[120:123], v[200:203], v[160:163]
	v_mfma_f32_16x16x32_bf16 v[164:167], v[128:131], v[200:203], v[164:167]
	v_mfma_f32_16x16x32_bf16 v[168:171], v[120:123], v[208:211], v[168:171]
	v_mfma_f32_16x16x32_bf16 v[172:175], v[128:131], v[208:211], v[172:175]
	v_mfma_f32_16x16x32_bf16 v[18:21], v[132:135], v[188:191], v[18:21]
	v_mfma_f32_16x16x32_bf16 v[30:33], v[180:183], v[188:191], v[30:33]
	v_mfma_f32_16x16x32_bf16 v[34:37], v[132:135], v[196:199], v[34:37]
	v_mfma_f32_16x16x32_bf16 v[58:61], v[180:183], v[196:199], v[58:61]
	v_mfma_f32_16x16x32_bf16 v[106:109], v[132:135], v[204:207], v[108:111]
	v_mfma_f32_16x16x32_bf16 v[110:113], v[180:183], v[204:207], v[112:115]
	v_mfma_f32_16x16x32_bf16 v[22:25], v[132:135], v[212:215], v[22:25]
	v_mfma_f32_16x16x32_bf16 v[26:29], v[180:183], v[212:215], v[26:29]
	v_mfma_f32_16x16x32_bf16 v[18:21], v[176:179], v[192:195], v[18:21]
	v_mfma_f32_16x16x32_bf16 v[30:33], v[184:187], v[192:195], v[30:33]
	v_mfma_f32_16x16x32_bf16 v[34:37], v[176:179], v[200:203], v[34:37]
	v_mfma_f32_16x16x32_bf16 v[58:61], v[184:187], v[200:203], v[58:61]
	v_mfma_f32_16x16x32_bf16 v[106:109], v[176:179], v[208:211], v[106:109]
	v_mfma_f32_16x16x32_bf16 v[110:113], v[184:187], v[208:211], v[110:113]
	v_mfma_f32_16x16x32_bf16 v[22:25], v[176:179], v[216:219], v[22:25]
	v_mfma_f32_16x16x32_bf16 v[26:29], v[184:187], v[216:219], v[26:29]
	s_setprio 0
	s_barrier
	ds_read_b128 v[114:117], v8
	ds_read_b128 v[118:121], v8 offset:1024
	ds_read_b128 v[122:125], v8 offset:2048
	ds_read_b128 v[126:129], v8 offset:3072
	ds_read_b128 v[130:133], v9
	ds_read_b128 v[176:179], v9 offset:1024
	ds_read_b128 v[180:183], v9 offset:2048
	ds_read_b128 v[184:187], v9 offset:3072
	s_add_u32 s74, s36, 0xa0200
	s_addc_u32 s75, s37, 0
	s_mov_b32 m0, s54
	v_lshl_add_u64 v[134:135], s[74:75], 0, v[142:143]
	ds_read_b128 v[188:191], v157 offset:32768
	ds_read_b128 v[192:195], v157 offset:33792
	ds_read_b128 v[196:199], v157 offset:34816
	ds_read_b128 v[200:203], v157 offset:35840
	ds_read_b128 v[204:207], v157 offset:36864
	ds_read_b128 v[208:211], v157 offset:37888
	ds_read_b128 v[212:215], v157 offset:38912
	ds_read_b128 v[216:219], v157 offset:39936
	global_load_lds_dwordx4 v[134:135], off
	v_lshl_add_u64 v[134:135], s[74:75], 0, v[138:139]
	s_mov_b32 m0, s55
	s_nop 0
	global_load_lds_dwordx4 v[134:135], off
	s_waitcnt vmcnt(8)
	s_barrier
	s_setprio 1
	s_waitcnt lgkmcnt(0)
	v_mfma_f32_16x16x32_bf16 v[62:65], v[114:117], v[188:191], v[62:65]
	v_mfma_f32_16x16x32_bf16 v[66:69], v[122:125], v[188:191], v[66:69]
	v_mfma_f32_16x16x32_bf16 v[70:73], v[114:117], v[196:199], v[70:73]
	v_mfma_f32_16x16x32_bf16 v[74:77], v[122:125], v[196:199], v[74:77]
	v_mfma_f32_16x16x32_bf16 v[78:81], v[114:117], v[204:207], v[78:81]
	v_mfma_f32_16x16x32_bf16 v[82:85], v[122:125], v[204:207], v[82:85]
	v_mfma_f32_16x16x32_bf16 v[86:89], v[114:117], v[212:215], v[86:89]
	v_mfma_f32_16x16x32_bf16 v[90:93], v[122:125], v[212:215], v[90:93]
	v_mfma_f32_16x16x32_bf16 v[62:65], v[118:121], v[192:195], v[62:65]
	v_mfma_f32_16x16x32_bf16 v[66:69], v[126:129], v[192:195], v[66:69]
	v_mfma_f32_16x16x32_bf16 v[70:73], v[118:121], v[200:203], v[70:73]
	v_mfma_f32_16x16x32_bf16 v[74:77], v[126:129], v[200:203], v[74:77]
	v_mfma_f32_16x16x32_bf16 v[78:81], v[118:121], v[208:211], v[78:81]
	v_mfma_f32_16x16x32_bf16 v[82:85], v[126:129], v[208:211], v[82:85]
	v_mfma_f32_16x16x32_bf16 v[86:89], v[118:121], v[216:219], v[86:89]
	v_mfma_f32_16x16x32_bf16 v[90:93], v[126:129], v[216:219], v[90:93]
	v_mfma_f32_16x16x32_bf16 v[94:97], v[130:133], v[188:191], v[94:97]
	v_mfma_f32_16x16x32_bf16 v[98:101], v[180:183], v[188:191], v[98:101]
	v_mfma_f32_16x16x32_bf16 v[102:105], v[130:133], v[196:199], v[102:105]
	v_mfma_f32_16x16x32_bf16 v[38:41], v[180:183], v[196:199], v[38:41]
	v_mfma_f32_16x16x32_bf16 v[42:45], v[130:133], v[204:207], v[42:45]
	v_mfma_f32_16x16x32_bf16 v[46:49], v[180:183], v[204:207], v[46:49]
	v_mfma_f32_16x16x32_bf16 v[50:53], v[130:133], v[212:215], v[50:53]
	v_mfma_f32_16x16x32_bf16 v[54:57], v[180:183], v[212:215], v[54:57]
	v_mfma_f32_16x16x32_bf16 v[94:97], v[176:179], v[192:195], v[94:97]
	v_mfma_f32_16x16x32_bf16 v[98:101], v[184:187], v[192:195], v[98:101]
	v_mfma_f32_16x16x32_bf16 v[102:105], v[176:179], v[200:203], v[102:105]
	v_mfma_f32_16x16x32_bf16 v[38:41], v[184:187], v[200:203], v[38:41]
	v_mfma_f32_16x16x32_bf16 v[42:45], v[176:179], v[208:211], v[42:45]
	v_mfma_f32_16x16x32_bf16 v[46:49], v[184:187], v[208:211], v[46:49]
	v_mfma_f32_16x16x32_bf16 v[50:53], v[176:179], v[216:219], v[50:53]
	v_mfma_f32_16x16x32_bf16 v[54:57], v[184:187], v[216:219], v[54:57]
	s_setprio 0
	s_barrier
; #define PG8_STAGE(bufoff, gbase, voff) do { _Pragma("unroll") for (int _i = 0; _i < 2; ++_i) \
;         __builtin_amdgcn_global_load_lds((const unsigned*)((const char*)(gbase) + (voff)[_i]), (LAS unsigned*)(lds + (bufoff) + ldsw + _i * 8192), 16, 0, 0); } while (0)
; #define PG8_LDA(dst, b, h) do { _Pragma("unroll") for (int m = 0; m < 4; ++m) _Pragma("unroll") for (int k = 0; k < 2; ++k) dst[m][k] = *(const LAS bf16x8*)(lds + PG8_SA(b, h) + aoff + m * 2048 + k * 1024); } while (0)
; #define PG8_LDB(dst, b, h) do { _Pragma("unroll") for (int n = 0; n < 2; ++n) _Pragma("unroll") for (int k = 0; k < 2; ++k) dst[n][k] = *(const LAS bf16x8*)(lds + PG8_SB(b, h) + boff + n * 2048 + k * 1024); } while (0)
; #define PG8_MMA(ai, bj, At, Bt) do { __builtin_amdgcn_s_setprio(1); _Pragma("unroll") for (int m = 0; m < 4; ++m) _Pragma("unroll") for (int n = 0; n < 2; ++n) _Pragma("unroll") for (int k = 0; k < 2; ++k) \
;         acc[ai][bj][m][n] = __builtin_amdgcn_mfma_f32_16x16x32_bf16(Bt[n][k], At[m][k], acc[ai][bj][m][n], 0, 0, 0); __builtin_amdgcn_s_setprio(0); } while (0)
; #define PG8_WAIT_V(n) asm volatile("s_waitcnt vmcnt(" #n ")" ::: "memory")
; #define PG8_WAIT_L(n) asm volatile("s_waitcnt lgkmcnt(" #n ")" ::: "memory")
; #define PG8_BAR __builtin_amdgcn_s_barrier()
; #define PG8_SCHED __builtin_amdgcn_sched_barrier(0)
; template <class Epi, bool ALIGN_EPI, int K, int LDA, int LDB>
; __device__ __forceinline__ void gemm_phase(LAS unsigned char* lds, const int wid, const Gemm g, const StaticOrder& S, const Epi& E) {
;     ...
;             PG8_LDB(B0, 1, 0); PG8_LDB(B1, 1, 1); PG8_SCHED; PG8_LDA(At, 1, 0); PG8_STAGE(PG8_SA(0, 1), a2 + hA, voffA);
;             PG8_WAIT_V(8); PG8_WAIT_L(0); PG8_BAR; PG8_MMA(0, 0, At, B0); PG8_MMA(0, 1, At, B1); PG8_BAR; PG8_SCHED;
;             PG8_LDA(At, 1, 1); PG8_STAGE(PG8_SB(1, 0), b3, voffB); PG8_STAGE(PG8_SB(1, 1), b3 + hB, voffB); PG8_STAGE(PG8_SA(1, 0), a3, voffA);
;             PG8_WAIT_V(8); PG8_WAIT_L(0); PG8_BAR; PG8_MMA(1, 0, At, B0); PG8_MMA(1, 1, At, B1); PG8_BAR; PG8_SCHED;
	s_mov_b32 m0, s73
	v_lshl_add_u64 v[0:1], v[0:1], 0, s[28:29]
	s_add_u32 s38, s38, 0x18280
	ds_read_b128 v[188:191], v157 offset:49152
	ds_read_b128 v[192:195], v157 offset:50176
	ds_read_b128 v[196:199], v157 offset:51200
	ds_read_b128 v[200:203], v157 offset:52224
	ds_read_b128 v[204:207], v157 offset:53248
	ds_read_b128 v[208:211], v157 offset:54272
	ds_read_b128 v[212:215], v157 offset:55296
	ds_read_b128 v[216:219], v157 offset:56320
	global_load_lds_dwordx4 v[0:1], off
	v_lshl_add_u64 v[0:1], v[2:3], 0, s[28:29]
	s_mov_b32 m0, s69
	s_addc_u32 s39, s39, 0
	global_load_lds_dwordx4 v[0:1], off
	v_lshl_add_u64 v[0:1], s[38:39], 0, v[140:141]
	s_mov_b32 m0, s70
	s_nop 0
	global_load_lds_dwordx4 v[0:1], off
	v_lshl_add_u64 v[0:1], s[38:39], 0, v[136:137]
	s_mov_b32 m0, s72
	s_nop 0
	global_load_lds_dwordx4 v[0:1], off
	v_lshl_add_u64 v[0:1], v[4:5], 0, s[28:29]
	s_mov_b32 m0, s56
	s_nop 0
	global_load_lds_dwordx4 v[0:1], off
	v_lshl_add_u64 v[0:1], v[6:7], 0, s[28:29]
	s_mov_b32 m0, s57
	s_nop 0
	global_load_lds_dwordx4 v[0:1], off
	s_waitcnt vmcnt(8)
	s_barrier
	s_setprio 1
	s_waitcnt lgkmcnt(0)
	v_mfma_f32_16x16x32_bf16 v[0:3], v[114:117], v[188:191], v[148:151]
	v_mfma_f32_16x16x32_bf16 v[4:7], v[122:125], v[188:191], v[152:155]
	v_mfma_f32_16x16x32_bf16 v[10:13], v[114:117], v[212:215], v[10:13]
	v_mfma_f32_16x16x32_bf16 v[14:17], v[122:125], v[212:215], v[14:17]
	v_mfma_f32_16x16x32_bf16 v[0:3], v[118:121], v[192:195], v[0:3]
	v_mfma_f32_16x16x32_bf16 v[4:7], v[126:129], v[192:195], v[4:7]
	v_mfma_f32_16x16x32_bf16 v[148:151], v[114:117], v[196:199], v[160:163]
	v_mfma_f32_16x16x32_bf16 v[152:155], v[122:125], v[196:199], v[164:167]
	v_mfma_f32_16x16x32_bf16 v[160:163], v[114:117], v[204:207], v[168:171]
	v_mfma_f32_16x16x32_bf16 v[164:167], v[122:125], v[204:207], v[172:175]
	v_mfma_f32_16x16x32_bf16 v[10:13], v[118:121], v[216:219], v[10:13]
	v_mfma_f32_16x16x32_bf16 v[14:17], v[126:129], v[216:219], v[14:17]
	v_mfma_f32_16x16x32_bf16 v[148:151], v[118:121], v[200:203], v[148:151]
	v_mfma_f32_16x16x32_bf16 v[152:155], v[126:129], v[200:203], v[152:155]
	v_mfma_f32_16x16x32_bf16 v[160:163], v[118:121], v[208:211], v[160:163]
	v_mfma_f32_16x16x32_bf16 v[164:167], v[126:129], v[208:211], v[164:167]
	v_mfma_f32_16x16x32_bf16 v[18:21], v[130:133], v[188:191], v[18:21]
	v_mfma_f32_16x16x32_bf16 v[30:33], v[180:183], v[188:191], v[30:33]
	v_mfma_f32_16x16x32_bf16 v[34:37], v[130:133], v[196:199], v[34:37]
	v_mfma_f32_16x16x32_bf16 v[58:61], v[180:183], v[196:199], v[58:61]
	v_mfma_f32_16x16x32_bf16 v[106:109], v[130:133], v[204:207], v[106:109]
	v_mfma_f32_16x16x32_bf16 v[110:113], v[180:183], v[204:207], v[110:113]
	v_mfma_f32_16x16x32_bf16 v[22:25], v[130:133], v[212:215], v[22:25]
	v_mfma_f32_16x16x32_bf16 v[26:29], v[180:183], v[212:215], v[26:29]
	v_mfma_f32_16x16x32_bf16 v[18:21], v[176:179], v[192:195], v[18:21]
	v_mfma_f32_16x16x32_bf16 v[30:33], v[184:187], v[192:195], v[30:33]
	v_mfma_f32_16x16x32_bf16 v[34:37], v[176:179], v[200:203], v[34:37]
	v_mfma_f32_16x16x32_bf16 v[58:61], v[184:187], v[200:203], v[58:61]
	v_mfma_f32_16x16x32_bf16 v[106:109], v[176:179], v[208:211], v[106:109]
	v_mfma_f32_16x16x32_bf16 v[110:113], v[184:187], v[208:211], v[110:113]
	v_mfma_f32_16x16x32_bf16 v[22:25], v[176:179], v[216:219], v[22:25]
	v_mfma_f32_16x16x32_bf16 v[26:29], v[184:187], v[216:219], v[26:29]
	s_setprio 0
	s_barrier
	ds_read_b128 v[114:117], v158
	ds_read_b128 v[118:121], v158 offset:1024
	ds_read_b128 v[122:125], v158 offset:2048
	ds_read_b128 v[126:129], v158 offset:3072
	ds_read_b128 v[130:133], v159
	ds_read_b128 v[168:171], v159 offset:1024
	ds_read_b128 v[172:175], v159 offset:2048
	ds_read_b128 v[176:179], v159 offset:3072
	s_add_u32 s36, s36, 0xa0280
	s_addc_u32 s37, s37, 0
	s_mov_b32 m0, s71
	v_lshl_add_u64 v[134:135], s[36:37], 0, v[142:143]
	ds_read_b128 v[180:183], v157
	ds_read_b128 v[184:187], v157 offset:1024
	ds_read_b128 v[188:191], v157 offset:2048
	ds_read_b128 v[192:195], v157 offset:3072
	ds_read_b128 v[196:199], v157 offset:4096
	ds_read_b128 v[200:203], v157 offset:5120
	ds_read_b128 v[204:207], v157 offset:6144
	ds_read_b128 v[208:211], v157 offset:7168
	global_load_lds_dwordx4 v[134:135], off
	v_lshl_add_u64 v[134:135], s[36:37], 0, v[138:139]
	s_mov_b32 m0, s6
	s_nop 0
	global_load_lds_dwordx4 v[134:135], off
	s_waitcnt vmcnt(8)
	s_barrier
	s_setprio 1
	s_waitcnt lgkmcnt(0)
	v_mfma_f32_16x16x32_bf16 v[62:65], v[114:117], v[180:183], v[62:65]
	v_mfma_f32_16x16x32_bf16 v[66:69], v[122:125], v[180:183], v[66:69]
	v_mfma_f32_16x16x32_bf16 v[70:73], v[114:117], v[188:191], v[70:73]
	v_mfma_f32_16x16x32_bf16 v[74:77], v[122:125], v[188:191], v[74:77]
	v_mfma_f32_16x16x32_bf16 v[78:81], v[114:117], v[196:199], v[78:81]
	v_mfma_f32_16x16x32_bf16 v[82:85], v[122:125], v[196:199], v[82:85]
	v_mfma_f32_16x16x32_bf16 v[86:89], v[114:117], v[204:207], v[86:89]
	v_mfma_f32_16x16x32_bf16 v[62:65], v[118:121], v[184:187], v[62:65]
	v_mfma_f32_16x16x32_bf16 v[66:69], v[126:129], v[184:187], v[66:69]
	v_mfma_f32_16x16x32_bf16 v[70:73], v[118:121], v[192:195], v[70:73]
	v_mfma_f32_16x16x32_bf16 v[74:77], v[126:129], v[192:195], v[74:77]
	v_mfma_f32_16x16x32_bf16 v[78:81], v[118:121], v[200:203], v[78:81]
	v_mfma_f32_16x16x32_bf16 v[82:85], v[126:129], v[200:203], v[82:85]
	v_mfma_f32_16x16x32_bf16 v[212:215], v[118:121], v[208:211], v[86:89]
	v_mfma_f32_16x16x32_bf16 v[86:89], v[122:125], v[204:207], v[90:93]
	v_mfma_f32_16x16x32_bf16 v[216:219], v[126:129], v[208:211], v[86:89]
	v_mfma_f32_16x16x32_bf16 v[86:89], v[130:133], v[180:183], v[94:97]
	v_mfma_f32_16x16x32_bf16 v[220:223], v[168:171], v[184:187], v[86:89]
	v_mfma_f32_16x16x32_bf16 v[86:89], v[172:175], v[180:183], v[98:101]
	v_mfma_f32_16x16x32_bf16 v[96:99], v[176:179], v[184:187], v[86:89]
	v_mfma_f32_16x16x32_bf16 v[86:89], v[130:133], v[188:191], v[102:105]
	v_mfma_f32_16x16x32_bf16 v[38:41], v[172:175], v[188:191], v[38:41]
	v_mfma_f32_16x16x32_bf16 v[42:45], v[130:133], v[196:199], v[42:45]
	v_mfma_f32_16x16x32_bf16 v[46:49], v[172:175], v[196:199], v[46:49]
	v_mfma_f32_16x16x32_bf16 v[50:53], v[130:133], v[204:207], v[50:53]
	v_mfma_f32_16x16x32_bf16 v[54:57], v[172:175], v[204:207], v[54:57]
	v_mfma_f32_16x16x32_bf16 v[100:103], v[168:171], v[192:195], v[86:89]
	v_mfma_f32_16x16x32_bf16 v[38:41], v[176:179], v[192:195], v[38:41]
	v_mfma_f32_16x16x32_bf16 v[42:45], v[168:171], v[200:203], v[42:45]
	v_mfma_f32_16x16x32_bf16 v[46:49], v[176:179], v[200:203], v[46:49]
	v_mfma_f32_16x16x32_bf16 v[50:53], v[168:171], v[208:211], v[50:53]
	v_mfma_f32_16x16x32_bf16 v[54:57], v[176:179], v[208:211], v[54:57]
	s_setprio 0
	s_barrier
; #define PG8_STAGE(bufoff, gbase, voff) do { _Pragma("unroll") for (int _i = 0; _i < 2; ++_i) \
;         __builtin_amdgcn_global_load_lds((const unsigned*)((const char*)(gbase) + (voff)[_i]), (LAS unsigned*)(lds + (bufoff) + ldsw + _i * 8192), 16, 0, 0); } while (0)
; #define PG8_LDA(dst, b, h) do { _Pragma("unroll") for (int m = 0; m < 4; ++m) _Pragma("unroll") for (int k = 0; k < 2; ++k) dst[m][k] = *(const LAS bf16x8*)(lds + PG8_SA(b, h) + aoff + m * 2048 + k * 1024); } while (0)
; #define PG8_LDB(dst, b, h) do { _Pragma("unroll") for (int n = 0; n < 2; ++n) _Pragma("unroll") for (int k = 0; k < 2; ++k) dst[n][k] = *(const LAS bf16x8*)(lds + PG8_SB(b, h) + boff + n * 2048 + k * 1024); } while (0)
; #define PG8_MMA(ai, bj, At, Bt) do { __builtin_amdgcn_s_setprio(1); _Pragma("unroll") for (int m = 0; m < 4; ++m) _Pragma("unroll") for (int n = 0; n < 2; ++n) _Pragma("unroll") for (int k = 0; k < 2; ++k) \
;         acc[ai][bj][m][n] = __builtin_amdgcn_mfma_f32_16x16x32_bf16(Bt[n][k], At[m][k], acc[ai][bj][m][n], 0, 0, 0); __builtin_amdgcn_s_setprio(0); } while (0)
; #define PG8_WAIT_V(n) asm volatile("s_waitcnt vmcnt(" #n ")" ::: "memory")
; #define PG8_WAIT_L(n) asm volatile("s_waitcnt lgkmcnt(" #n ")" ::: "memory")
; #define PG8_BAR __builtin_amdgcn_s_barrier()
; #define PG8_SCHED __builtin_amdgcn_sched_barrier(0)
; template <class Epi, bool ALIGN_EPI, int K, int LDA, int LDB>
; __device__ __forceinline__ void gemm_phase(LAS unsigned char* lds, const int wid, const Gemm g, const StaticOrder& S, const Epi& E) {
;     ...
;             PG8_LDA(At, 0, 1); PG8_STAGE(PG8_SB(0, 0), b2, voffB); PG8_STAGE(PG8_SB(0, 1), b2 + hB, voffB); PG8_STAGE(PG8_SA(0, 0), a2, voffA);
;             PG8_WAIT_V(8); PG8_WAIT_L(0); PG8_BAR; PG8_MMA(1, 0, At, B0); PG8_MMA(1, 1, At, B1); PG8_BAR; PG8_SCHED;
;             PG8_LDB(B0, 1, 0); PG8_LDB(B1, 1, 1); PG8_SCHED; PG8_LDA(At, 1, 0); PG8_STAGE(PG8_SA(0, 1), a2 + hA, voffA);
;             PG8_WAIT_V(8); PG8_WAIT_L(0); PG8_BAR; PG8_MMA(0, 0, At, B0); PG8_MMA(0, 1, At, B1); PG8_BAR; PG8_SCHED;
;             PG8_LDA(At, 1, 1); PG8_STAGE(PG8_SB(1, 0), b3, voffB); PG8_STAGE(PG8_SB(1, 1), b3 + hB, voffB); PG8_STAGE(PG8_SA(1, 0), a3, voffA);
	s_mov_b32 m0, s68
	v_lshl_add_u64 v[248:249], s[34:35], 0, v[140:141]
	s_add_u32 s6, s34, 0x18000
	ds_read_b128 v[86:89], v157 offset:16384
	ds_read_b128 v[90:93], v157 offset:17408
	ds_read_b128 v[180:183], v157 offset:18432
	ds_read_b128 v[184:187], v157 offset:19456
	ds_read_b128 v[188:191], v157 offset:20480
	ds_read_b128 v[192:195], v157 offset:21504
	ds_read_b128 v[196:199], v157 offset:22528
	ds_read_b128 v[200:203], v157 offset:23552
	global_load_lds_dwordx4 v[248:249], off
	v_lshl_add_u64 v[250:251], s[34:35], 0, v[136:137]
	s_mov_b32 m0, s7
	s_addc_u32 s7, s35, 0
	global_load_lds_dwordx4 v[250:251], off
	v_lshl_add_u64 v[94:95], s[6:7], 0, v[140:141]
	s_mov_b32 m0, s66
	v_lshl_add_u64 v[252:253], s[30:31], 0, v[142:143]
	global_load_lds_dwordx4 v[94:95], off
	v_lshl_add_u64 v[94:95], s[6:7], 0, v[136:137]
	s_mov_b32 m0, s67
	v_lshl_add_u64 v[144:145], s[30:31], 0, v[138:139]
	global_load_lds_dwordx4 v[94:95], off
	s_mov_b32 m0, s42
	s_nop 0
	global_load_lds_dwordx4 v[252:253], off
	s_mov_b32 m0, s51
	s_nop 0
	global_load_lds_dwordx4 v[144:145], off
	s_waitcnt vmcnt(8)
	s_barrier
	s_setprio 1
	s_waitcnt lgkmcnt(0)
	v_mfma_f32_16x16x32_bf16 v[0:3], v[114:117], v[86:89], v[0:3]
	v_mfma_f32_16x16x32_bf16 v[4:7], v[122:125], v[86:89], v[4:7]
	v_mfma_f32_16x16x32_bf16 v[10:13], v[114:117], v[196:199], v[10:13]
	v_mfma_f32_16x16x32_bf16 v[0:3], v[118:121], v[90:93], v[0:3]
	v_mfma_f32_16x16x32_bf16 v[4:7], v[126:129], v[90:93], v[4:7]
	v_mfma_f32_16x16x32_bf16 v[148:151], v[114:117], v[180:183], v[148:151]
	v_mfma_f32_16x16x32_bf16 v[152:155], v[122:125], v[180:183], v[152:155]
	v_mfma_f32_16x16x32_bf16 v[160:163], v[114:117], v[188:191], v[160:163]
	v_mfma_f32_16x16x32_bf16 v[164:167], v[122:125], v[188:191], v[164:167]
	v_mfma_f32_16x16x32_bf16 v[10:13], v[118:121], v[200:203], v[10:13]
	v_mfma_f32_16x16x32_bf16 v[14:17], v[122:125], v[196:199], v[14:17]
	v_mfma_f32_16x16x32_bf16 v[148:151], v[118:121], v[184:187], v[148:151]
	v_mfma_f32_16x16x32_bf16 v[152:155], v[126:129], v[184:187], v[152:155]
	v_mfma_f32_16x16x32_bf16 v[160:163], v[118:121], v[192:195], v[160:163]
	v_mfma_f32_16x16x32_bf16 v[164:167], v[126:129], v[192:195], v[164:167]
	v_mfma_f32_16x16x32_bf16 v[120:123], v[126:129], v[200:203], v[14:17]
	v_mfma_f32_16x16x32_bf16 v[30:33], v[172:175], v[86:89], v[30:33]
	v_mfma_f32_16x16x32_bf16 v[58:61], v[172:175], v[180:183], v[58:61]
	v_mfma_f32_16x16x32_bf16 v[14:17], v[130:133], v[86:89], v[18:21]
	v_mfma_f32_16x16x32_bf16 v[124:127], v[176:179], v[90:93], v[30:33]
	v_mfma_f32_16x16x32_bf16 v[30:33], v[130:133], v[180:183], v[34:37]
	v_mfma_f32_16x16x32_bf16 v[180:183], v[176:179], v[184:187], v[58:61]
	v_mfma_f32_16x16x32_bf16 v[58:61], v[130:133], v[188:191], v[106:109]
	v_mfma_f32_16x16x32_bf16 v[20:23], v[130:133], v[196:199], v[22:25]
	v_mfma_f32_16x16x32_bf16 v[16:19], v[168:171], v[90:93], v[14:17]
	v_mfma_f32_16x16x32_bf16 v[32:35], v[168:171], v[184:187], v[30:33]
	v_mfma_f32_16x16x32_bf16 v[184:187], v[168:171], v[192:195], v[58:61]
	v_mfma_f32_16x16x32_bf16 v[58:61], v[172:175], v[188:191], v[110:113]
	v_mfma_f32_16x16x32_bf16 v[168:171], v[168:171], v[200:203], v[20:23]
	v_mfma_f32_16x16x32_bf16 v[20:23], v[172:175], v[196:199], v[26:29]
	v_mfma_f32_16x16x32_bf16 v[188:191], v[176:179], v[192:195], v[58:61]
	v_mfma_f32_16x16x32_bf16 v[172:175], v[176:179], v[200:203], v[20:23]
	s_setprio 0
	s_barrier
	s_nop 3
	ds_read_b128 v[20:23], v8
	ds_read_b128 v[176:179], v8 offset:1024
	ds_read_b128 v[192:195], v8 offset:2048
	ds_read_b128 v[196:199], v8 offset:3072
	ds_read_b128 v[200:203], v9
	ds_read_b128 v[204:207], v9 offset:1024
	ds_read_b128 v[208:211], v9 offset:2048
	ds_read_b128 v[224:227], v9 offset:3072
	s_add_u32 s6, s30, 0xa0000
	s_addc_u32 s7, s31, 0
	s_mov_b32 m0, s54
	v_lshl_add_u64 v[8:9], s[6:7], 0, v[142:143]
	ds_read_b128 v[24:27], v157 offset:32768
	ds_read_b128 v[28:31], v157 offset:33792
	ds_read_b128 v[58:61], v157 offset:34816
	ds_read_b128 v[228:231], v157 offset:35840
	ds_read_b128 v[232:235], v157 offset:36864
	ds_read_b128 v[236:239], v157 offset:37888
	ds_read_b128 v[240:243], v157 offset:38912
	ds_read_b128 v[244:247], v157 offset:39936
	global_load_lds_dwordx4 v[8:9], off
	v_lshl_add_u64 v[8:9], s[6:7], 0, v[138:139]
	s_mov_b32 m0, s55
	s_nop 0
	global_load_lds_dwordx4 v[8:9], off
	s_waitcnt vmcnt(8)
	s_barrier
; #define PG8_STAGE(bufoff, gbase, voff) do { _Pragma("unroll") for (int _i = 0; _i < 2; ++_i) \
;         __builtin_amdgcn_global_load_lds((const unsigned*)((const char*)(gbase) + (voff)[_i]), (LAS unsigned*)(lds + (bufoff) + ldsw + _i * 8192), 16, 0, 0); } while (0)
; #define PG8_LDA(dst, b, h) do { _Pragma("unroll") for (int m = 0; m < 4; ++m) _Pragma("unroll") for (int k = 0; k < 2; ++k) dst[m][k] = *(const LAS bf16x8*)(lds + PG8_SA(b, h) + aoff + m * 2048 + k * 1024); } while (0)
; #define PG8_LDB(dst, b, h) do { _Pragma("unroll") for (int n = 0; n < 2; ++n) _Pragma("unroll") for (int k = 0; k < 2; ++k) dst[n][k] = *(const LAS bf16x8*)(lds + PG8_SB(b, h) + boff + n * 2048 + k * 1024); } while (0)
; #define PG8_MMA(ai, bj, At, Bt) do { __builtin_amdgcn_s_setprio(1); _Pragma("unroll") for (int m = 0; m < 4; ++m) _Pragma("unroll") for (int n = 0; n < 2; ++n) _Pragma("unroll") for (int k = 0; k < 2; ++k) \
;         acc[ai][bj][m][n] = __builtin_amdgcn_mfma_f32_16x16x32_bf16(Bt[n][k], At[m][k], acc[ai][bj][m][n], 0, 0, 0); __builtin_amdgcn_s_setprio(0); } while (0)
; #define PG8_WAIT_V(n) asm volatile("s_waitcnt vmcnt(" #n ")" ::: "memory")
; #define PG8_BAR __builtin_amdgcn_s_barrier()
; template <class Epi, bool ALIGN_EPI, int K, int LDA, int LDB>
; __device__ __forceinline__ void gemm_phase(LAS unsigned char* lds, const int wid, const Gemm g, const StaticOrder& S, const Epi& E) {
;     ...
;             PG8_WAIT_V(8); PG8_WAIT_L(0); PG8_BAR; PG8_MMA(0, 0, At, B0); PG8_MMA(0, 1, At, B1); PG8_BAR; PG8_SCHED;
;             PG8_LDA(At, 0, 1); PG8_STAGE(PG8_SB(0, 0), b2, voffB); PG8_STAGE(PG8_SB(0, 1), b2 + hB, voffB); PG8_STAGE(PG8_SA(0, 0), a2, voffA);
;             PG8_WAIT_V(8); PG8_WAIT_L(0); PG8_BAR; PG8_MMA(1, 0, At, B0); PG8_MMA(1, 1, At, B1); PG8_BAR; PG8_SCHED;
;             PG8_LDB(B0, 1, 0); PG8_LDB(B1, 1, 1); PG8_SCHED; PG8_LDA(At, 1, 0); PG8_STAGE(PG8_SA(0, 1), a2 + hA, voffA);
;             PG8_WAIT_V(8); PG8_WAIT_L(0); PG8_BAR; PG8_MMA(0, 0, At, B0); PG8_MMA(0, 1, At, B1); PG8_BAR; PG8_SCHED;
;             PG8_LDA(At, 1, 1); PG8_STAGE(PG8_SB(1, 0), b3, voffB); PG8_STAGE(PG8_SB(1, 1), b3 + hB, voffB); PG8_STAGE(PG8_SA(1, 0), a3, voffA);
;             PG8_WAIT_V(8); PG8_WAIT_L(0); PG8_BAR; PG8_MMA(1, 0, At, B0); PG8_MMA(1, 1, At, B1); PG8_BAR; PG8_SCHED;
;         }
;         if constexpr (ALIGN_EPI) { if (wr == 0) PG8_BAR; }
	s_setprio 1
	s_waitcnt lgkmcnt(0)
	v_mfma_f32_16x16x32_bf16 v[62:65], v[20:23], v[24:27], v[62:65]
	v_mfma_f32_16x16x32_bf16 v[128:131], v[176:179], v[28:31], v[62:65]
	v_mfma_f32_16x16x32_bf16 v[62:65], v[192:195], v[24:27], v[66:69]
	v_mfma_f32_16x16x32_bf16 v[132:135], v[196:199], v[28:31], v[62:65]
	v_mfma_f32_16x16x32_bf16 v[62:65], v[20:23], v[58:61], v[70:73]
	v_mfma_f32_16x16x32_bf16 v[108:111], v[176:179], v[228:231], v[62:65]
	v_mfma_f32_16x16x32_bf16 v[62:65], v[192:195], v[58:61], v[74:77]
	v_mfma_f32_16x16x32_bf16 v[104:107], v[196:199], v[228:231], v[62:65]
	v_mfma_f32_16x16x32_bf16 v[62:65], v[20:23], v[232:235], v[78:81]
	v_mfma_f32_16x16x32_bf16 v[92:95], v[176:179], v[236:239], v[62:65]
	v_mfma_f32_16x16x32_bf16 v[62:65], v[192:195], v[232:235], v[82:85]
	v_mfma_f32_16x16x32_bf16 v[88:91], v[196:199], v[236:239], v[62:65]
	v_mfma_f32_16x16x32_bf16 v[62:65], v[20:23], v[240:243], v[212:215]
	v_mfma_f32_16x16x32_bf16 v[76:79], v[176:179], v[244:247], v[62:65]
	v_mfma_f32_16x16x32_bf16 v[62:65], v[192:195], v[240:243], v[216:219]
	v_mfma_f32_16x16x32_bf16 v[72:75], v[196:199], v[244:247], v[62:65]
	v_mfma_f32_16x16x32_bf16 v[62:65], v[200:203], v[24:27], v[220:223]
	v_mfma_f32_16x16x32_bf16 v[24:27], v[208:211], v[24:27], v[96:99]
	v_mfma_f32_16x16x32_bf16 v[112:115], v[224:227], v[28:31], v[24:27]
	v_mfma_f32_16x16x32_bf16 v[24:27], v[200:203], v[58:61], v[100:103]
	v_mfma_f32_16x16x32_bf16 v[100:103], v[204:207], v[228:231], v[24:27]
	v_mfma_f32_16x16x32_bf16 v[24:27], v[208:211], v[58:61], v[38:41]
	v_mfma_f32_16x16x32_bf16 v[96:99], v[224:227], v[228:231], v[24:27]
	v_mfma_f32_16x16x32_bf16 v[24:27], v[200:203], v[232:235], v[42:45]
	v_mfma_f32_16x16x32_bf16 v[84:87], v[204:207], v[236:239], v[24:27]
	v_mfma_f32_16x16x32_bf16 v[24:27], v[208:211], v[232:235], v[46:49]
	v_mfma_f32_16x16x32_bf16 v[80:83], v[224:227], v[236:239], v[24:27]
	v_mfma_f32_16x16x32_bf16 v[24:27], v[200:203], v[240:243], v[50:53]
	v_mfma_f32_16x16x32_bf16 v[68:71], v[204:207], v[244:247], v[24:27]
	v_mfma_f32_16x16x32_bf16 v[24:27], v[208:211], v[240:243], v[54:57]
	v_mfma_f32_16x16x32_bf16 v[116:119], v[204:207], v[28:31], v[62:65]
	v_mfma_f32_16x16x32_bf16 v[64:67], v[224:227], v[244:247], v[24:27]
	s_setprio 0
	s_barrier
	s_mov_b32 m0, s73
	v_lshl_add_u64 v[8:9], v[248:249], 0, s[16:17]
	s_add_u32 s6, s34, 0x18080
	ds_read_b128 v[36:39], v157 offset:49152
	ds_read_b128 v[48:51], v157 offset:50176
	ds_read_b128 v[212:215], v157 offset:51200
	ds_read_b128 v[216:219], v157 offset:52224
	ds_read_b128 v[220:223], v157 offset:53248
	ds_read_b128 v[228:231], v157 offset:54272
	ds_read_b128 v[232:235], v157 offset:55296
	ds_read_b128 v[236:239], v157 offset:56320
	global_load_lds_dwordx4 v[8:9], off
	v_lshl_add_u64 v[8:9], v[250:251], 0, s[16:17]
	s_mov_b32 m0, s69
	s_addc_u32 s7, s35, 0
	global_load_lds_dwordx4 v[8:9], off
	v_lshl_add_u64 v[8:9], s[6:7], 0, v[140:141]
	s_mov_b32 m0, s70
	s_nop 0
	global_load_lds_dwordx4 v[8:9], off
	v_lshl_add_u64 v[8:9], s[6:7], 0, v[136:137]
	s_mov_b32 m0, s72
	s_nop 0
	global_load_lds_dwordx4 v[8:9], off
	v_lshl_add_u64 v[8:9], v[252:253], 0, s[16:17]
	s_mov_b32 m0, s56
	s_nop 0
	global_load_lds_dwordx4 v[8:9], off
	v_lshl_add_u64 v[8:9], v[144:145], 0, s[16:17]
	s_mov_b32 m0, s57
	s_nop 0
	global_load_lds_dwordx4 v[8:9], off
	s_waitcnt vmcnt(8)
	s_barrier
	s_setprio 1
	s_waitcnt lgkmcnt(0)
	v_mfma_f32_16x16x32_bf16 v[0:3], v[20:23], v[36:39], v[0:3]
	v_mfma_f32_16x16x32_bf16 v[60:63], v[176:179], v[48:51], v[0:3]
	v_mfma_f32_16x16x32_bf16 v[0:3], v[192:195], v[36:39], v[4:7]
	v_mfma_f32_16x16x32_bf16 v[56:59], v[196:199], v[48:51], v[0:3]
	v_mfma_f32_16x16x32_bf16 v[0:3], v[20:23], v[212:215], v[148:151]
	v_mfma_f32_16x16x32_bf16 v[44:47], v[176:179], v[216:219], v[0:3]
	v_mfma_f32_16x16x32_bf16 v[0:3], v[192:195], v[212:215], v[152:155]
	v_mfma_f32_16x16x32_bf16 v[40:43], v[196:199], v[216:219], v[0:3]
	v_mfma_f32_16x16x32_bf16 v[0:3], v[20:23], v[220:223], v[160:163]
	v_mfma_f32_16x16x32_bf16 v[28:31], v[176:179], v[228:231], v[0:3]
	v_mfma_f32_16x16x32_bf16 v[0:3], v[192:195], v[220:223], v[164:167]
	v_mfma_f32_16x16x32_bf16 v[24:27], v[196:199], v[228:231], v[0:3]
	v_mfma_f32_16x16x32_bf16 v[0:3], v[20:23], v[232:235], v[10:13]
	v_mfma_f32_16x16x32_bf16 v[12:15], v[176:179], v[236:239], v[0:3]
	v_mfma_f32_16x16x32_bf16 v[0:3], v[192:195], v[232:235], v[120:123]
	v_mfma_f32_16x16x32_bf16 v[8:11], v[196:199], v[236:239], v[0:3]
	v_mfma_f32_16x16x32_bf16 v[0:3], v[200:203], v[36:39], v[16:19]
	v_mfma_f32_16x16x32_bf16 v[52:55], v[204:207], v[48:51], v[0:3]
	v_mfma_f32_16x16x32_bf16 v[0:3], v[208:211], v[36:39], v[124:127]
	v_mfma_f32_16x16x32_bf16 v[48:51], v[224:227], v[48:51], v[0:3]
	v_mfma_f32_16x16x32_bf16 v[0:3], v[200:203], v[212:215], v[32:35]
	v_mfma_f32_16x16x32_bf16 v[36:39], v[204:207], v[216:219], v[0:3]
	v_mfma_f32_16x16x32_bf16 v[0:3], v[208:211], v[212:215], v[180:183]
	v_mfma_f32_16x16x32_bf16 v[32:35], v[224:227], v[216:219], v[0:3]
	v_mfma_f32_16x16x32_bf16 v[0:3], v[200:203], v[220:223], v[184:187]
	v_mfma_f32_16x16x32_bf16 v[20:23], v[204:207], v[228:231], v[0:3]
	v_mfma_f32_16x16x32_bf16 v[0:3], v[208:211], v[220:223], v[188:191]
	v_mfma_f32_16x16x32_bf16 v[16:19], v[224:227], v[228:231], v[0:3]
	v_mfma_f32_16x16x32_bf16 v[0:3], v[200:203], v[232:235], v[168:171]
	v_mfma_f32_16x16x32_bf16 v[4:7], v[204:207], v[236:239], v[0:3]
	v_mfma_f32_16x16x32_bf16 v[0:3], v[208:211], v[232:235], v[172:175]
	v_mfma_f32_16x16x32_bf16 v[0:3], v[224:227], v[236:239], v[0:3]
	s_setprio 0
	s_barrier
	s_andn2_b64 vcc, exec, s[18:19]
	s_cbranch_vccnz .LBB0_667
	s_barrier

; #define PG8_STAGE(bufoff, gbase, voff) do { _Pragma("unroll") for (int _i = 0; _i < 2; ++_i) \
;         __builtin_amdgcn_global_load_lds((const unsigned*)((const char*)(gbase) + (voff)[_i]), (LAS unsigned*)(lds + (bufoff) + ldsw + _i * 8192), 16, 0, 0); } while (0)
; #define PG8_LDA(dst, b, h) do { _Pragma("unroll") for (int m = 0; m < 4; ++m) _Pragma("unroll") for (int k = 0; k < 2; ++k) dst[m][k] = *(const LAS bf16x8*)(lds + PG8_SA(b, h) + aoff + m * 2048 + k * 1024); } while (0)
; #define PG8_LDB(dst, b, h) do { _Pragma("unroll") for (int n = 0; n < 2; ++n) _Pragma("unroll") for (int k = 0; k < 2; ++k) dst[n][k] = *(const LAS bf16x8*)(lds + PG8_SB(b, h) + boff + n * 2048 + k * 1024); } while (0)
; #define PG8_MMA(ai, bj, At, Bt) do { __builtin_amdgcn_s_setprio(1); _Pragma("unroll") for (int m = 0; m < 4; ++m) _Pragma("unroll") for (int n = 0; n < 2; ++n) _Pragma("unroll") for (int k = 0; k < 2; ++k) \
;         acc[ai][bj][m][n] = __builtin_amdgcn_mfma_f32_16x16x32_bf16(Bt[n][k], At[m][k], acc[ai][bj][m][n], 0, 0, 0); __builtin_amdgcn_s_setprio(0); } while (0)
; template <class Epi, bool ALIGN_EPI, int K, int LDA, int LDB>
; __device__ __forceinline__ void gemm_phase(LAS unsigned char* lds, const int wid, const Gemm g, const StaticOrder& S, const Epi& E) {
;     ...
;         const bool has_next = S.next(ui + 1, nxt);
;         const char* nA = has_next ? (const char*)g.A + (size_t)nxt.pm * tA : cA; const char* nB = has_next ? (const char*)g.Bt + (size_t)nxt.pn * tB : cB;
;         for (int t = 0; t < nt; t += 2) {
;             const bool last = (t == nt - 2);
;             const char* a1 = cA + (size_t)(t + 1) * kstep;
;             const char* a2 = last ? nA : cA + (size_t)(t + 2) * kstep; const char* b2 = last ? nB : cB + (size_t)(t + 2) * kstep;
;             const char* a3 = a2 + kstep; const char* b3 = b2 + kstep;
;             PG8_LDB(B0, 0, 0); PG8_LDB(B1, 0, 1); PG8_SCHED; PG8_LDA(At, 0, 0); PG8_STAGE(PG8_SA(1, 1), a1 + hA, voffA);
;             PG8_WAIT_V(8); PG8_WAIT_L(0); PG8_BAR; PG8_MMA(0, 0, At, B0); PG8_MMA(0, 1, At, B1); PG8_BAR; PG8_SCHED;
;             PG8_LDA(At, 0, 1); PG8_STAGE(PG8_SB(0, 0), b2, voffB); PG8_STAGE(PG8_SB(0, 1), b2 + hB, voffB); PG8_STAGE(PG8_SA(0, 0), a2, voffA);
;             PG8_WAIT_V(8); PG8_WAIT_L(0); PG8_BAR; PG8_MMA(1, 0, At, B0); PG8_MMA(1, 1, At, B1); PG8_BAR; PG8_SCHED;
.LBB0_689:
	ds_read_b128 v[0:3], v145
	ds_read_b128 v[4:7], v145 offset:1024
	ds_read_b128 v[8:11], v145 offset:2048
	ds_read_b128 v[12:15], v145 offset:3072
	ds_read_b128 v[16:19], v147
	ds_read_b128 v[20:23], v147 offset:1024
	ds_read_b128 v[24:27], v147 offset:2048
	ds_read_b128 v[28:31], v147 offset:3072
	s_ashr_i32 s31, s30, 31
	s_lshl_b64 s[36:37], s[30:31], 17
	s_add_u32 s36, s51, s36
	s_addc_u32 s37, s54, s37
	s_and_b64 s[8:9], s[8:9], exec
	s_cselect_b32 s9, s37, s41
	s_cselect_b32 s8, s36, s40
	s_add_u32 s66, s38, 0xa0080
	s_addc_u32 s67, s39, 0
	s_add_i32 s70, s55, 0xc000
	v_lshl_add_u64 v[64:65], s[66:67], 0, v[128:129]
	s_mov_b32 m0, s70
	s_add_i32 s31, s55, 0xe000
	ds_read_b128 v[32:35], v149
	ds_read_b128 v[36:39], v149 offset:1024
	ds_read_b128 v[40:43], v149 offset:2048
	ds_read_b128 v[44:47], v149 offset:3072
	ds_read_b128 v[48:51], v149 offset:4096
	ds_read_b128 v[52:55], v149 offset:5120
	ds_read_b128 v[56:59], v149 offset:6144
	ds_read_b128 v[60:63], v149 offset:7168
	global_load_lds_dwordx4 v[64:65], off
	v_lshl_add_u64 v[64:65], s[66:67], 0, v[132:133]
	s_mov_b32 m0, s31
	s_nop 0
	global_load_lds_dwordx4 v[64:65], off
	s_waitcnt vmcnt(8)
	s_barrier
	s_setprio 1
	s_waitcnt lgkmcnt(0)
	v_mfma_f32_16x16x32_bf16 v[64:67], v[0:3], v[32:35], 0
	v_mfma_f32_16x16x32_bf16 v[68:71], v[8:11], v[32:35], 0
	v_mfma_f32_16x16x32_bf16 v[72:75], v[0:3], v[40:43], 0
	v_mfma_f32_16x16x32_bf16 v[76:79], v[8:11], v[40:43], 0
	v_mfma_f32_16x16x32_bf16 v[80:83], v[0:3], v[48:51], 0
	v_mfma_f32_16x16x32_bf16 v[84:87], v[8:11], v[48:51], 0
	s_waitcnt vmcnt(0)
	v_mfma_f32_16x16x32_bf16 v[88:91], v[0:3], v[56:59], 0
	v_mfma_f32_16x16x32_bf16 v[92:95], v[8:11], v[56:59], 0
	v_mfma_f32_16x16x32_bf16 v[64:67], v[4:7], v[36:39], v[64:67]
	v_mfma_f32_16x16x32_bf16 v[68:71], v[12:15], v[36:39], v[68:71]
	v_mfma_f32_16x16x32_bf16 v[72:75], v[4:7], v[44:47], v[72:75]
	v_mfma_f32_16x16x32_bf16 v[76:79], v[12:15], v[44:47], v[76:79]
	v_mfma_f32_16x16x32_bf16 v[80:83], v[4:7], v[52:55], v[80:83]
	v_mfma_f32_16x16x32_bf16 v[84:87], v[12:15], v[52:55], v[84:87]
	v_mfma_f32_16x16x32_bf16 v[88:91], v[4:7], v[60:63], v[88:91]
	v_mfma_f32_16x16x32_bf16 v[92:95], v[12:15], v[60:63], v[92:95]
	v_mfma_f32_16x16x32_bf16 v[96:99], v[16:19], v[32:35], 0
	v_mfma_f32_16x16x32_bf16 v[32:35], v[24:27], v[32:35], 0
	v_mfma_f32_16x16x32_bf16 v[96:99], v[20:23], v[36:39], v[96:99]
	v_mfma_f32_16x16x32_bf16 v[32:35], v[28:31], v[36:39], v[32:35]
	v_mfma_f32_16x16x32_bf16 v[36:39], v[16:19], v[40:43], 0
	v_mfma_f32_16x16x32_bf16 v[40:43], v[24:27], v[40:43], 0
	v_mfma_f32_16x16x32_bf16 v[36:39], v[20:23], v[44:47], v[36:39]
	v_mfma_f32_16x16x32_bf16 v[40:43], v[28:31], v[44:47], v[40:43]
	v_mfma_f32_16x16x32_bf16 v[44:47], v[16:19], v[48:51], 0
	v_mfma_f32_16x16x32_bf16 v[48:51], v[24:27], v[48:51], 0
	v_mfma_f32_16x16x32_bf16 v[44:47], v[20:23], v[52:55], v[44:47]
	v_mfma_f32_16x16x32_bf16 v[48:51], v[28:31], v[52:55], v[48:51]
	v_mfma_f32_16x16x32_bf16 v[52:55], v[16:19], v[56:59], 0
	v_mfma_f32_16x16x32_bf16 v[56:59], v[24:27], v[56:59], 0
	v_mfma_f32_16x16x32_bf16 v[52:55], v[20:23], v[60:63], v[52:55]
	v_mfma_f32_16x16x32_bf16 v[56:59], v[28:31], v[60:63], v[56:59]
	s_setprio 0
	s_barrier
	s_add_i32 s68, s43, s0
	v_lshl_add_u64 v[140:141], s[40:41], 0, v[130:131]
	s_add_i32 s65, s68, 0x2000
	v_lshl_add_u64 v[150:151], v[140:141], 0, s[24:25]
	s_mov_b32 m0, s68
	v_lshl_add_u64 v[214:215], s[40:41], 0, v[134:135]
	s_add_u32 s72, s40, 0x10100
	ds_read_b128 v[60:63], v149 offset:16384
	ds_read_b128 v[100:103], v149 offset:17408
	ds_read_b128 v[104:107], v149 offset:18432
	ds_read_b128 v[108:111], v149 offset:19456
	ds_read_b128 v[112:115], v149 offset:20480
	ds_read_b128 v[116:119], v149 offset:21504
	ds_read_b128 v[120:123], v149 offset:22528
	ds_read_b128 v[124:127], v149 offset:23552
	global_load_lds_dwordx4 v[150:151], off
	v_lshl_add_u64 v[150:151], v[214:215], 0, s[24:25]
	s_mov_b32 m0, s65
	s_addc_u32 s73, s41, 0
	s_add_i32 s66, s61, s0
	global_load_lds_dwordx4 v[150:151], off
	v_lshl_add_u64 v[150:151], s[72:73], 0, v[130:131]
	s_mov_b32 m0, s66
	s_add_i32 s67, s66, 0x2000
	global_load_lds_dwordx4 v[150:151], off
	v_lshl_add_u64 v[150:151], s[72:73], 0, v[134:135]
	s_mov_b32 m0, s67
	v_lshl_add_u64 v[216:217], s[38:39], 0, v[128:129]
	global_load_lds_dwordx4 v[150:151], off
	v_lshl_add_u64 v[150:151], v[216:217], 0, s[24:25]
	s_mov_b32 m0, s55
	v_lshl_add_u64 v[218:219], s[38:39], 0, v[132:133]
	global_load_lds_dwordx4 v[150:151], off
	v_lshl_add_u64 v[150:151], v[218:219], 0, s[24:25]
	s_mov_b32 m0, s56
	s_nop 0
	global_load_lds_dwordx4 v[150:151], off
	s_waitcnt vmcnt(8)
	s_barrier
; #define PG8_STAGE(bufoff, gbase, voff) do { _Pragma("unroll") for (int _i = 0; _i < 2; ++_i) \
;         __builtin_amdgcn_global_load_lds((const unsigned*)((const char*)(gbase) + (voff)[_i]), (LAS unsigned*)(lds + (bufoff) + ldsw + _i * 8192), 16, 0, 0); } while (0)
; #define PG8_LDA(dst, b, h) do { _Pragma("unroll") for (int m = 0; m < 4; ++m) _Pragma("unroll") for (int k = 0; k < 2; ++k) dst[m][k] = *(const LAS bf16x8*)(lds + PG8_SA(b, h) + aoff + m * 2048 + k * 1024); } while (0)
; #define PG8_LDB(dst, b, h) do { _Pragma("unroll") for (int n = 0; n < 2; ++n) _Pragma("unroll") for (int k = 0; k < 2; ++k) dst[n][k] = *(const LAS bf16x8*)(lds + PG8_SB(b, h) + boff + n * 2048 + k * 1024); } while (0)
; #define PG8_MMA(ai, bj, At, Bt) do { __builtin_amdgcn_s_setprio(1); _Pragma("unroll") for (int m = 0; m < 4; ++m) _Pragma("unroll") for (int n = 0; n < 2; ++n) _Pragma("unroll") for (int k = 0; k < 2; ++k) \
;         acc[ai][bj][m][n] = __builtin_amdgcn_mfma_f32_16x16x32_bf16(Bt[n][k], At[m][k], acc[ai][bj][m][n], 0, 0, 0); __builtin_amdgcn_s_setprio(0); } while (0)
; #define PG8_WAIT_V(n) asm volatile("s_waitcnt vmcnt(" #n ")" ::: "memory")
; #define PG8_WAIT_L(n) asm volatile("s_waitcnt lgkmcnt(" #n ")" ::: "memory")
; #define PG8_BAR __builtin_amdgcn_s_barrier()
; #define PG8_SCHED __builtin_amdgcn_sched_barrier(0)
; template <class Epi, bool ALIGN_EPI, int K, int LDA, int LDB>
; __device__ __forceinline__ void gemm_phase(LAS unsigned char* lds, const int wid, const Gemm g, const StaticOrder& S, const Epi& E) {
;     ...
;             PG8_WAIT_V(8); PG8_WAIT_L(0); PG8_BAR; PG8_MMA(0, 0, At, B0); PG8_MMA(0, 1, At, B1); PG8_BAR; PG8_SCHED;
;             PG8_LDA(At, 0, 1); PG8_STAGE(PG8_SB(0, 0), b2, voffB); PG8_STAGE(PG8_SB(0, 1), b2 + hB, voffB); PG8_STAGE(PG8_SA(0, 0), a2, voffA);
;             PG8_WAIT_V(8); PG8_WAIT_L(0); PG8_BAR; PG8_MMA(1, 0, At, B0); PG8_MMA(1, 1, At, B1); PG8_BAR; PG8_SCHED;
;             PG8_LDB(B0, 1, 0); PG8_LDB(B1, 1, 1); PG8_SCHED; PG8_LDA(At, 1, 0); PG8_STAGE(PG8_SA(0, 1), a2 + hA, voffA);
;             PG8_WAIT_V(8); PG8_WAIT_L(0); PG8_BAR; PG8_MMA(0, 0, At, B0); PG8_MMA(0, 1, At, B1); PG8_BAR; PG8_SCHED;
	s_setprio 1
	s_waitcnt lgkmcnt(0)
	v_mfma_f32_16x16x32_bf16 v[150:153], v[0:3], v[60:63], 0
	v_mfma_f32_16x16x32_bf16 v[158:161], v[0:3], v[104:107], 0
	v_mfma_f32_16x16x32_bf16 v[166:169], v[0:3], v[112:115], 0
	v_mfma_f32_16x16x32_bf16 v[0:3], v[0:3], v[120:123], 0
	v_mfma_f32_16x16x32_bf16 v[150:153], v[4:7], v[100:103], v[150:153]
	v_mfma_f32_16x16x32_bf16 v[158:161], v[4:7], v[108:111], v[158:161]
	v_mfma_f32_16x16x32_bf16 v[166:169], v[4:7], v[116:119], v[166:169]
	v_mfma_f32_16x16x32_bf16 v[0:3], v[4:7], v[124:127], v[0:3]
	v_mfma_f32_16x16x32_bf16 v[4:7], v[8:11], v[120:123], 0
	v_mfma_f32_16x16x32_bf16 v[154:157], v[8:11], v[60:63], 0
	v_mfma_f32_16x16x32_bf16 v[162:165], v[8:11], v[104:107], 0
	v_mfma_f32_16x16x32_bf16 v[170:173], v[8:11], v[112:115], 0
	v_mfma_f32_16x16x32_bf16 v[4:7], v[12:15], v[124:127], v[4:7]
	v_mfma_f32_16x16x32_bf16 v[154:157], v[12:15], v[100:103], v[154:157]
	v_mfma_f32_16x16x32_bf16 v[162:165], v[12:15], v[108:111], v[162:165]
	v_mfma_f32_16x16x32_bf16 v[170:173], v[12:15], v[116:119], v[170:173]
	v_mfma_f32_16x16x32_bf16 v[8:11], v[16:19], v[60:63], 0
	v_mfma_f32_16x16x32_bf16 v[12:15], v[24:27], v[60:63], 0
	v_mfma_f32_16x16x32_bf16 v[8:11], v[20:23], v[100:103], v[8:11]
	v_mfma_f32_16x16x32_bf16 v[12:15], v[28:31], v[100:103], v[12:15]
	v_mfma_f32_16x16x32_bf16 v[60:63], v[16:19], v[104:107], 0
	v_mfma_f32_16x16x32_bf16 v[100:103], v[24:27], v[104:107], 0
	v_mfma_f32_16x16x32_bf16 v[104:107], v[16:19], v[112:115], 0
	v_mfma_f32_16x16x32_bf16 v[16:19], v[16:19], v[120:123], 0
	v_mfma_f32_16x16x32_bf16 v[60:63], v[20:23], v[108:111], v[60:63]
	v_mfma_f32_16x16x32_bf16 v[100:103], v[28:31], v[108:111], v[100:103]
	v_mfma_f32_16x16x32_bf16 v[104:107], v[20:23], v[116:119], v[104:107]
	v_mfma_f32_16x16x32_bf16 v[108:111], v[24:27], v[112:115], 0
	v_mfma_f32_16x16x32_bf16 v[16:19], v[20:23], v[124:127], v[16:19]
	v_mfma_f32_16x16x32_bf16 v[20:23], v[24:27], v[120:123], 0
	v_mfma_f32_16x16x32_bf16 v[108:111], v[28:31], v[116:119], v[108:111]
	v_mfma_f32_16x16x32_bf16 v[20:23], v[28:31], v[124:127], v[20:23]
	s_setprio 0
	s_barrier
	s_add_i32 s71, 0, 0x18000
	s_add_i32 s74, 0, 0x1c000
	v_add_u32_e32 v142, s71, v143
	v_add_u32_e32 v144, s74, v143
	ds_read_b128 v[24:27], v142
	ds_read_b128 v[28:31], v142 offset:1024
	ds_read_b128 v[112:115], v142 offset:2048
	ds_read_b128 v[116:119], v142 offset:3072
	ds_read_b128 v[120:123], v144
	ds_read_b128 v[124:127], v144 offset:1024
	ds_read_b128 v[174:177], v144 offset:2048
	ds_read_b128 v[178:181], v144 offset:3072
	s_add_u32 s72, s38, 0xa0100
	s_addc_u32 s73, s39, 0
	s_mov_b32 m0, s57
	v_lshl_add_u64 v[220:221], s[72:73], 0, v[128:129]
	ds_read_b128 v[182:185], v149 offset:32768
	ds_read_b128 v[186:189], v149 offset:33792
	ds_read_b128 v[190:193], v149 offset:34816
	ds_read_b128 v[194:197], v149 offset:35840
	ds_read_b128 v[198:201], v149 offset:36864
	ds_read_b128 v[202:205], v149 offset:37888
	ds_read_b128 v[206:209], v149 offset:38912
	ds_read_b128 v[210:213], v149 offset:39936
	global_load_lds_dwordx4 v[220:221], off
	v_lshl_add_u64 v[220:221], s[72:73], 0, v[132:133]
	s_mov_b32 m0, s58
	s_nop 0
	global_load_lds_dwordx4 v[220:221], off
	s_waitcnt vmcnt(8)
	s_barrier
	s_setprio 1
	s_waitcnt lgkmcnt(0)
	v_mfma_f32_16x16x32_bf16 v[64:67], v[24:27], v[182:185], v[64:67]
	v_mfma_f32_16x16x32_bf16 v[68:71], v[112:115], v[182:185], v[68:71]
	v_mfma_f32_16x16x32_bf16 v[72:75], v[24:27], v[190:193], v[72:75]
	v_mfma_f32_16x16x32_bf16 v[76:79], v[112:115], v[190:193], v[76:79]
	v_mfma_f32_16x16x32_bf16 v[80:83], v[24:27], v[198:201], v[80:83]
	v_mfma_f32_16x16x32_bf16 v[84:87], v[112:115], v[198:201], v[84:87]
	v_mfma_f32_16x16x32_bf16 v[88:91], v[24:27], v[206:209], v[88:91]
	v_mfma_f32_16x16x32_bf16 v[92:95], v[112:115], v[206:209], v[92:95]
	v_mfma_f32_16x16x32_bf16 v[64:67], v[28:31], v[186:189], v[64:67]
	v_mfma_f32_16x16x32_bf16 v[68:71], v[116:119], v[186:189], v[68:71]
	v_mfma_f32_16x16x32_bf16 v[72:75], v[28:31], v[194:197], v[72:75]
	v_mfma_f32_16x16x32_bf16 v[76:79], v[116:119], v[194:197], v[76:79]
	v_mfma_f32_16x16x32_bf16 v[80:83], v[28:31], v[202:205], v[80:83]
	v_mfma_f32_16x16x32_bf16 v[84:87], v[116:119], v[202:205], v[84:87]
	v_mfma_f32_16x16x32_bf16 v[88:91], v[28:31], v[210:213], v[88:91]
	v_mfma_f32_16x16x32_bf16 v[92:95], v[116:119], v[210:213], v[92:95]
	v_mfma_f32_16x16x32_bf16 v[96:99], v[120:123], v[182:185], v[96:99]
	v_mfma_f32_16x16x32_bf16 v[32:35], v[174:177], v[182:185], v[32:35]
	v_mfma_f32_16x16x32_bf16 v[36:39], v[120:123], v[190:193], v[36:39]
	v_mfma_f32_16x16x32_bf16 v[40:43], v[174:177], v[190:193], v[40:43]
	v_mfma_f32_16x16x32_bf16 v[44:47], v[120:123], v[198:201], v[44:47]
	v_mfma_f32_16x16x32_bf16 v[48:51], v[174:177], v[198:201], v[48:51]
	v_mfma_f32_16x16x32_bf16 v[52:55], v[120:123], v[206:209], v[52:55]
	v_mfma_f32_16x16x32_bf16 v[56:59], v[174:177], v[206:209], v[56:59]
	v_mfma_f32_16x16x32_bf16 v[96:99], v[124:127], v[186:189], v[96:99]
	v_mfma_f32_16x16x32_bf16 v[32:35], v[178:181], v[186:189], v[32:35]
	v_mfma_f32_16x16x32_bf16 v[36:39], v[124:127], v[194:197], v[36:39]
	v_mfma_f32_16x16x32_bf16 v[40:43], v[178:181], v[194:197], v[40:43]
	v_mfma_f32_16x16x32_bf16 v[44:47], v[124:127], v[202:205], v[44:47]
	v_mfma_f32_16x16x32_bf16 v[48:51], v[178:181], v[202:205], v[48:51]
	v_mfma_f32_16x16x32_bf16 v[52:55], v[124:127], v[210:213], v[52:55]
	v_mfma_f32_16x16x32_bf16 v[56:59], v[178:181], v[210:213], v[56:59]
	s_setprio 0
	s_barrier
; #define PG8_STAGE(bufoff, gbase, voff) do { _Pragma("unroll") for (int _i = 0; _i < 2; ++_i) \
;         __builtin_amdgcn_global_load_lds((const unsigned*)((const char*)(gbase) + (voff)[_i]), (LAS unsigned*)(lds + (bufoff) + ldsw + _i * 8192), 16, 0, 0); } while (0)
; #define PG8_LDA(dst, b, h) do { _Pragma("unroll") for (int m = 0; m < 4; ++m) _Pragma("unroll") for (int k = 0; k < 2; ++k) dst[m][k] = *(const LAS bf16x8*)(lds + PG8_SA(b, h) + aoff + m * 2048 + k * 1024); } while (0)
; #define PG8_LDB(dst, b, h) do { _Pragma("unroll") for (int n = 0; n < 2; ++n) _Pragma("unroll") for (int k = 0; k < 2; ++k) dst[n][k] = *(const LAS bf16x8*)(lds + PG8_SB(b, h) + boff + n * 2048 + k * 1024); } while (0)
; #define PG8_MMA(ai, bj, At, Bt) do { __builtin_amdgcn_s_setprio(1); _Pragma("unroll") for (int m = 0; m < 4; ++m) _Pragma("unroll") for (int n = 0; n < 2; ++n) _Pragma("unroll") for (int k = 0; k < 2; ++k) \
;         acc[ai][bj][m][n] = __builtin_amdgcn_mfma_f32_16x16x32_bf16(Bt[n][k], At[m][k], acc[ai][bj][m][n], 0, 0, 0); __builtin_amdgcn_s_setprio(0); } while (0)
; #define PG8_WAIT_V(n) asm volatile("s_waitcnt vmcnt(" #n ")" ::: "memory")
; #define PG8_WAIT_L(n) asm volatile("s_waitcnt lgkmcnt(" #n ")" ::: "memory")
; #define PG8_BAR __builtin_amdgcn_s_barrier()
; #define PG8_SCHED __builtin_amdgcn_sched_barrier(0)
; template <class Epi, bool ALIGN_EPI, int K, int LDA, int LDB>
; __device__ __forceinline__ void gemm_phase(LAS unsigned char* lds, const int wid, const Gemm g, const StaticOrder& S, const Epi& E) {
;     ...
;             PG8_LDB(B0, 1, 0); PG8_LDB(B1, 1, 1); PG8_SCHED; PG8_LDA(At, 1, 0); PG8_STAGE(PG8_SA(0, 1), a2 + hA, voffA);
;             PG8_WAIT_V(8); PG8_WAIT_L(0); PG8_BAR; PG8_MMA(0, 0, At, B0); PG8_MMA(0, 1, At, B1); PG8_BAR; PG8_SCHED;
;             PG8_LDA(At, 1, 1); PG8_STAGE(PG8_SB(1, 0), b3, voffB); PG8_STAGE(PG8_SB(1, 1), b3 + hB, voffB); PG8_STAGE(PG8_SA(1, 0), a3, voffA);
;             PG8_WAIT_V(8); PG8_WAIT_L(0); PG8_BAR; PG8_MMA(1, 0, At, B0); PG8_MMA(1, 1, At, B1); PG8_BAR; PG8_SCHED;
	s_add_i32 s71, s71, s0
	s_add_i32 s69, s71, 0x2000
	v_lshl_add_u64 v[140:141], v[140:141], 0, s[26:27]
	s_mov_b32 m0, s71
	s_add_u32 s72, s40, 0x10180
	ds_read_b128 v[182:185], v149 offset:49152
	ds_read_b128 v[186:189], v149 offset:50176
	ds_read_b128 v[190:193], v149 offset:51200
	ds_read_b128 v[194:197], v149 offset:52224
	ds_read_b128 v[198:201], v149 offset:53248
	ds_read_b128 v[202:205], v149 offset:54272
	ds_read_b128 v[206:209], v149 offset:55296
	ds_read_b128 v[210:213], v149 offset:56320
	global_load_lds_dwordx4 v[140:141], off
	v_lshl_add_u64 v[140:141], v[214:215], 0, s[26:27]
	s_mov_b32 m0, s69
	s_addc_u32 s73, s41, 0
	s_add_i32 s40, s74, s0
	global_load_lds_dwordx4 v[140:141], off
	v_lshl_add_u64 v[140:141], s[72:73], 0, v[130:131]
	s_mov_b32 m0, s40
	s_add_i32 s41, s40, 0x2000
	global_load_lds_dwordx4 v[140:141], off
	v_lshl_add_u64 v[140:141], s[72:73], 0, v[134:135]
	s_mov_b32 m0, s41
	s_nop 0
	global_load_lds_dwordx4 v[140:141], off
	v_lshl_add_u64 v[140:141], v[216:217], 0, s[26:27]
	s_mov_b32 m0, s59
	s_nop 0
	global_load_lds_dwordx4 v[140:141], off
	v_lshl_add_u64 v[140:141], v[218:219], 0, s[26:27]
	s_mov_b32 m0, s60
	s_nop 0
	global_load_lds_dwordx4 v[140:141], off
	s_waitcnt vmcnt(8)
	s_barrier
	s_setprio 1
	s_waitcnt lgkmcnt(0)
	v_mfma_f32_16x16x32_bf16 v[0:3], v[24:27], v[206:209], v[0:3]
	v_mfma_f32_16x16x32_bf16 v[4:7], v[112:115], v[206:209], v[4:7]
	v_mfma_f32_16x16x32_bf16 v[150:153], v[24:27], v[182:185], v[150:153]
	v_mfma_f32_16x16x32_bf16 v[154:157], v[112:115], v[182:185], v[154:157]
	v_mfma_f32_16x16x32_bf16 v[158:161], v[24:27], v[190:193], v[158:161]
	v_mfma_f32_16x16x32_bf16 v[162:165], v[112:115], v[190:193], v[162:165]
	v_mfma_f32_16x16x32_bf16 v[166:169], v[24:27], v[198:201], v[166:169]
	v_mfma_f32_16x16x32_bf16 v[170:173], v[112:115], v[198:201], v[170:173]
	v_mfma_f32_16x16x32_bf16 v[0:3], v[28:31], v[210:213], v[0:3]
	v_mfma_f32_16x16x32_bf16 v[4:7], v[116:119], v[210:213], v[4:7]
	v_mfma_f32_16x16x32_bf16 v[150:153], v[28:31], v[186:189], v[150:153]
	v_mfma_f32_16x16x32_bf16 v[154:157], v[116:119], v[186:189], v[154:157]
	v_mfma_f32_16x16x32_bf16 v[158:161], v[28:31], v[194:197], v[158:161]
	v_mfma_f32_16x16x32_bf16 v[162:165], v[116:119], v[194:197], v[162:165]
	v_mfma_f32_16x16x32_bf16 v[166:169], v[28:31], v[202:205], v[166:169]
	v_mfma_f32_16x16x32_bf16 v[170:173], v[116:119], v[202:205], v[170:173]
	v_mfma_f32_16x16x32_bf16 v[8:11], v[120:123], v[182:185], v[8:11]
	v_mfma_f32_16x16x32_bf16 v[12:15], v[174:177], v[182:185], v[12:15]
	v_mfma_f32_16x16x32_bf16 v[24:27], v[120:123], v[190:193], v[60:63]
	v_mfma_f32_16x16x32_bf16 v[28:31], v[174:177], v[190:193], v[100:103]
	v_mfma_f32_16x16x32_bf16 v[60:63], v[120:123], v[198:201], v[104:107]
	v_mfma_f32_16x16x32_bf16 v[100:103], v[174:177], v[198:201], v[108:111]
	v_mfma_f32_16x16x32_bf16 v[16:19], v[120:123], v[206:209], v[16:19]
	v_mfma_f32_16x16x32_bf16 v[20:23], v[174:177], v[206:209], v[20:23]
	v_mfma_f32_16x16x32_bf16 v[8:11], v[124:127], v[186:189], v[8:11]
	v_mfma_f32_16x16x32_bf16 v[12:15], v[178:181], v[186:189], v[12:15]
	v_mfma_f32_16x16x32_bf16 v[24:27], v[124:127], v[194:197], v[24:27]
	v_mfma_f32_16x16x32_bf16 v[28:31], v[178:181], v[194:197], v[28:31]
	v_mfma_f32_16x16x32_bf16 v[60:63], v[124:127], v[202:205], v[60:63]
	v_mfma_f32_16x16x32_bf16 v[100:103], v[178:181], v[202:205], v[100:103]
	v_mfma_f32_16x16x32_bf16 v[16:19], v[124:127], v[210:213], v[16:19]
	v_mfma_f32_16x16x32_bf16 v[20:23], v[178:181], v[210:213], v[20:23]
	s_setprio 0
	s_barrier
	ds_read_b128 v[104:107], v145
	ds_read_b128 v[108:111], v145 offset:1024
	ds_read_b128 v[112:115], v145 offset:2048
	ds_read_b128 v[116:119], v145 offset:3072
	ds_read_b128 v[120:123], v147
	ds_read_b128 v[124:127], v147 offset:1024
	ds_read_b128 v[174:177], v147 offset:2048
	ds_read_b128 v[178:181], v147 offset:3072
	s_add_u32 s38, s38, 0xa0180
	s_addc_u32 s39, s39, 0
	s_mov_b32 m0, s70
	v_lshl_add_u64 v[140:141], s[38:39], 0, v[128:129]
	ds_read_b128 v[182:185], v149
	ds_read_b128 v[186:189], v149 offset:1024
	ds_read_b128 v[190:193], v149 offset:2048
	ds_read_b128 v[194:197], v149 offset:3072
	ds_read_b128 v[198:201], v149 offset:4096
	ds_read_b128 v[202:205], v149 offset:5120
	ds_read_b128 v[206:209], v149 offset:6144
	ds_read_b128 v[210:213], v149 offset:7168
	global_load_lds_dwordx4 v[140:141], off
	v_lshl_add_u64 v[140:141], s[38:39], 0, v[132:133]
	s_mov_b32 m0, s31
	s_nop 0
	global_load_lds_dwordx4 v[140:141], off
	s_waitcnt vmcnt(8)
	s_barrier
	s_setprio 1
	s_waitcnt lgkmcnt(0)
	v_mfma_f32_16x16x32_bf16 v[64:67], v[104:107], v[182:185], v[64:67]
	v_mfma_f32_16x16x32_bf16 v[68:71], v[112:115], v[182:185], v[68:71]
	v_mfma_f32_16x16x32_bf16 v[72:75], v[104:107], v[190:193], v[72:75]
	v_mfma_f32_16x16x32_bf16 v[76:79], v[112:115], v[190:193], v[76:79]
	v_mfma_f32_16x16x32_bf16 v[80:83], v[104:107], v[198:201], v[80:83]
	v_mfma_f32_16x16x32_bf16 v[84:87], v[112:115], v[198:201], v[84:87]
	v_mfma_f32_16x16x32_bf16 v[88:91], v[104:107], v[206:209], v[88:91]
	v_mfma_f32_16x16x32_bf16 v[64:67], v[108:111], v[186:189], v[64:67]
	v_mfma_f32_16x16x32_bf16 v[68:71], v[116:119], v[186:189], v[68:71]
	v_mfma_f32_16x16x32_bf16 v[72:75], v[108:111], v[194:197], v[72:75]
	v_mfma_f32_16x16x32_bf16 v[76:79], v[116:119], v[194:197], v[76:79]
	v_mfma_f32_16x16x32_bf16 v[80:83], v[108:111], v[202:205], v[80:83]
	v_mfma_f32_16x16x32_bf16 v[84:87], v[116:119], v[202:205], v[84:87]
	v_mfma_f32_16x16x32_bf16 v[214:217], v[108:111], v[210:213], v[88:91]
	v_mfma_f32_16x16x32_bf16 v[88:91], v[112:115], v[206:209], v[92:95]
	v_mfma_f32_16x16x32_bf16 v[218:221], v[116:119], v[210:213], v[88:91]
	v_mfma_f32_16x16x32_bf16 v[88:91], v[120:123], v[182:185], v[96:99]
	v_mfma_f32_16x16x32_bf16 v[32:35], v[174:177], v[182:185], v[32:35]
	v_mfma_f32_16x16x32_bf16 v[36:39], v[120:123], v[190:193], v[36:39]
	v_mfma_f32_16x16x32_bf16 v[40:43], v[174:177], v[190:193], v[40:43]
	v_mfma_f32_16x16x32_bf16 v[44:47], v[120:123], v[198:201], v[44:47]
	v_mfma_f32_16x16x32_bf16 v[48:51], v[174:177], v[198:201], v[48:51]
	v_mfma_f32_16x16x32_bf16 v[52:55], v[120:123], v[206:209], v[52:55]
	v_mfma_f32_16x16x32_bf16 v[56:59], v[174:177], v[206:209], v[56:59]
	v_mfma_f32_16x16x32_bf16 v[96:99], v[124:127], v[186:189], v[88:91]
	v_mfma_f32_16x16x32_bf16 v[32:35], v[178:181], v[186:189], v[32:35]
	v_mfma_f32_16x16x32_bf16 v[36:39], v[124:127], v[194:197], v[36:39]
	v_mfma_f32_16x16x32_bf16 v[40:43], v[178:181], v[194:197], v[40:43]
	v_mfma_f32_16x16x32_bf16 v[44:47], v[124:127], v[202:205], v[44:47]
	v_mfma_f32_16x16x32_bf16 v[48:51], v[178:181], v[202:205], v[48:51]
	v_mfma_f32_16x16x32_bf16 v[52:55], v[124:127], v[210:213], v[52:55]
	v_mfma_f32_16x16x32_bf16 v[56:59], v[178:181], v[210:213], v[56:59]
	s_setprio 0
	s_barrier
; #define PG8_STAGE(bufoff, gbase, voff) do { _Pragma("unroll") for (int _i = 0; _i < 2; ++_i) \
;         __builtin_amdgcn_global_load_lds((const unsigned*)((const char*)(gbase) + (voff)[_i]), (LAS unsigned*)(lds + (bufoff) + ldsw + _i * 8192), 16, 0, 0); } while (0)
; #define PG8_LDA(dst, b, h) do { _Pragma("unroll") for (int m = 0; m < 4; ++m) _Pragma("unroll") for (int k = 0; k < 2; ++k) dst[m][k] = *(const LAS bf16x8*)(lds + PG8_SA(b, h) + aoff + m * 2048 + k * 1024); } while (0)
; #define PG8_LDB(dst, b, h) do { _Pragma("unroll") for (int n = 0; n < 2; ++n) _Pragma("unroll") for (int k = 0; k < 2; ++k) dst[n][k] = *(const LAS bf16x8*)(lds + PG8_SB(b, h) + boff + n * 2048 + k * 1024); } while (0)
; #define PG8_MMA(ai, bj, At, Bt) do { __builtin_amdgcn_s_setprio(1); _Pragma("unroll") for (int m = 0; m < 4; ++m) _Pragma("unroll") for (int n = 0; n < 2; ++n) _Pragma("unroll") for (int k = 0; k < 2; ++k) \
;         acc[ai][bj][m][n] = __builtin_amdgcn_mfma_f32_16x16x32_bf16(Bt[n][k], At[m][k], acc[ai][bj][m][n], 0, 0, 0); __builtin_amdgcn_s_setprio(0); } while (0)
; #define PG8_WAIT_V(n) asm volatile("s_waitcnt vmcnt(" #n ")" ::: "memory")
; #define PG8_WAIT_L(n) asm volatile("s_waitcnt lgkmcnt(" #n ")" ::: "memory")
; #define PG8_BAR __builtin_amdgcn_s_barrier()
; #define PG8_SCHED __builtin_amdgcn_sched_barrier(0)
; template <class Epi, bool ALIGN_EPI, int K, int LDA, int LDB>
; __device__ __forceinline__ void gemm_phase(LAS unsigned char* lds, const int wid, const Gemm g, const StaticOrder& S, const Epi& E) {
;     ...
;             PG8_LDA(At, 0, 1); PG8_STAGE(PG8_SB(0, 0), b2, voffB); PG8_STAGE(PG8_SB(0, 1), b2 + hB, voffB); PG8_STAGE(PG8_SA(0, 0), a2, voffA);
;             PG8_WAIT_V(8); PG8_WAIT_L(0); PG8_BAR; PG8_MMA(1, 0, At, B0); PG8_MMA(1, 1, At, B1); PG8_BAR; PG8_SCHED;
;             PG8_LDB(B0, 1, 0); PG8_LDB(B1, 1, 1); PG8_SCHED; PG8_LDA(At, 1, 0); PG8_STAGE(PG8_SA(0, 1), a2 + hA, voffA);
;             PG8_WAIT_V(8); PG8_WAIT_L(0); PG8_BAR; PG8_MMA(0, 0, At, B0); PG8_MMA(0, 1, At, B1); PG8_BAR; PG8_SCHED;
;             PG8_LDA(At, 1, 1); PG8_STAGE(PG8_SB(1, 0), b3, voffB); PG8_STAGE(PG8_SB(1, 1), b3 + hB, voffB); PG8_STAGE(PG8_SA(1, 0), a3, voffA);
	s_mov_b32 m0, s68
	v_lshl_add_u64 v[140:141], s[8:9], 0, v[130:131]
	s_add_u32 s38, s8, 0x10000
	ds_read_b128 v[88:91], v149 offset:16384
	ds_read_b128 v[92:95], v149 offset:17408
	ds_read_b128 v[182:185], v149 offset:18432
	ds_read_b128 v[186:189], v149 offset:19456
	ds_read_b128 v[190:193], v149 offset:20480
	ds_read_b128 v[194:197], v149 offset:21504
	ds_read_b128 v[198:201], v149 offset:22528
	ds_read_b128 v[202:205], v149 offset:23552
	global_load_lds_dwordx4 v[140:141], off
	v_lshl_add_u64 v[250:251], s[8:9], 0, v[134:135]
	s_mov_b32 m0, s65
	s_addc_u32 s39, s9, 0
	global_load_lds_dwordx4 v[250:251], off
	v_lshl_add_u64 v[206:207], s[38:39], 0, v[130:131]
	s_mov_b32 m0, s66
	v_lshl_add_u64 v[252:253], s[34:35], 0, v[128:129]
	global_load_lds_dwordx4 v[206:207], off
	v_lshl_add_u64 v[206:207], s[38:39], 0, v[134:135]
	s_mov_b32 m0, s67
	v_lshl_add_u64 v[136:137], s[34:35], 0, v[132:133]
	global_load_lds_dwordx4 v[206:207], off
	s_mov_b32 m0, s55
	s_nop 0
	global_load_lds_dwordx4 v[252:253], off
	s_mov_b32 m0, s56
	s_nop 0
	global_load_lds_dwordx4 v[136:137], off
	s_waitcnt vmcnt(8)
	s_barrier
	s_setprio 1
	s_waitcnt lgkmcnt(0)
	v_mfma_f32_16x16x32_bf16 v[0:3], v[104:107], v[198:201], v[0:3]
	v_mfma_f32_16x16x32_bf16 v[4:7], v[112:115], v[198:201], v[4:7]
	v_mfma_f32_16x16x32_bf16 v[150:153], v[104:107], v[88:91], v[150:153]
	v_mfma_f32_16x16x32_bf16 v[154:157], v[112:115], v[88:91], v[154:157]
	v_mfma_f32_16x16x32_bf16 v[158:161], v[104:107], v[182:185], v[158:161]
	v_mfma_f32_16x16x32_bf16 v[162:165], v[112:115], v[182:185], v[162:165]
	v_mfma_f32_16x16x32_bf16 v[166:169], v[104:107], v[190:193], v[166:169]
	v_mfma_f32_16x16x32_bf16 v[170:173], v[112:115], v[190:193], v[170:173]
	v_mfma_f32_16x16x32_bf16 v[0:3], v[108:111], v[202:205], v[0:3]
	v_mfma_f32_16x16x32_bf16 v[4:7], v[116:119], v[202:205], v[4:7]
	v_mfma_f32_16x16x32_bf16 v[150:153], v[108:111], v[92:95], v[150:153]
	v_mfma_f32_16x16x32_bf16 v[154:157], v[116:119], v[92:95], v[154:157]
	v_mfma_f32_16x16x32_bf16 v[158:161], v[108:111], v[186:189], v[158:161]
	v_mfma_f32_16x16x32_bf16 v[162:165], v[116:119], v[186:189], v[162:165]
	v_mfma_f32_16x16x32_bf16 v[166:169], v[108:111], v[194:197], v[166:169]
	v_mfma_f32_16x16x32_bf16 v[170:173], v[116:119], v[194:197], v[170:173]
	v_mfma_f32_16x16x32_bf16 v[8:11], v[120:123], v[88:91], v[8:11]
	v_mfma_f32_16x16x32_bf16 v[206:209], v[124:127], v[92:95], v[8:11]
	v_mfma_f32_16x16x32_bf16 v[8:11], v[174:177], v[88:91], v[12:15]
	v_mfma_f32_16x16x32_bf16 v[210:213], v[178:181], v[92:95], v[8:11]
	v_mfma_f32_16x16x32_bf16 v[8:11], v[120:123], v[182:185], v[24:27]
	v_mfma_f32_16x16x32_bf16 v[222:225], v[124:127], v[186:189], v[8:11]
	v_mfma_f32_16x16x32_bf16 v[8:11], v[174:177], v[182:185], v[28:31]
	v_mfma_f32_16x16x32_bf16 v[182:185], v[178:181], v[186:189], v[8:11]
	v_mfma_f32_16x16x32_bf16 v[8:11], v[120:123], v[190:193], v[60:63]
	v_mfma_f32_16x16x32_bf16 v[186:189], v[124:127], v[194:197], v[8:11]
	v_mfma_f32_16x16x32_bf16 v[8:11], v[174:177], v[190:193], v[100:103]
	v_mfma_f32_16x16x32_bf16 v[190:193], v[178:181], v[194:197], v[8:11]
	v_mfma_f32_16x16x32_bf16 v[8:11], v[120:123], v[198:201], v[16:19]
	v_mfma_f32_16x16x32_bf16 v[194:197], v[124:127], v[202:205], v[8:11]
	v_mfma_f32_16x16x32_bf16 v[8:11], v[174:177], v[198:201], v[20:23]
	v_mfma_f32_16x16x32_bf16 v[174:177], v[178:181], v[202:205], v[8:11]
	s_setprio 0
	s_barrier
	s_nop 4
	ds_read_b128 v[8:11], v142
	ds_read_b128 v[12:15], v142 offset:1024
	ds_read_b128 v[16:19], v142 offset:2048
	ds_read_b128 v[20:23], v142 offset:3072
	ds_read_b128 v[178:181], v144
	ds_read_b128 v[198:201], v144 offset:1024
	ds_read_b128 v[202:205], v144 offset:2048
	ds_read_b128 v[226:229], v144 offset:3072
	s_add_u32 s38, s34, 0xa0000
	s_addc_u32 s39, s35, 0
	s_mov_b32 m0, s57
	v_lshl_add_u64 v[88:89], s[38:39], 0, v[128:129]
	ds_read_b128 v[24:27], v149 offset:32768
	ds_read_b128 v[28:31], v149 offset:33792
	ds_read_b128 v[60:63], v149 offset:34816
	ds_read_b128 v[230:233], v149 offset:35840
	ds_read_b128 v[234:237], v149 offset:36864
	ds_read_b128 v[238:241], v149 offset:37888
	ds_read_b128 v[242:245], v149 offset:38912
	ds_read_b128 v[246:249], v149 offset:39936
	global_load_lds_dwordx4 v[88:89], off
	v_lshl_add_u64 v[88:89], s[38:39], 0, v[132:133]
	s_mov_b32 m0, s58
	s_nop 0
	global_load_lds_dwordx4 v[88:89], off
	s_waitcnt vmcnt(8)
	s_barrier
; #define PG8_STAGE(bufoff, gbase, voff) do { _Pragma("unroll") for (int _i = 0; _i < 2; ++_i) \
;         __builtin_amdgcn_global_load_lds((const unsigned*)((const char*)(gbase) + (voff)[_i]), (LAS unsigned*)(lds + (bufoff) + ldsw + _i * 8192), 16, 0, 0); } while (0)
; #define PG8_LDA(dst, b, h) do { _Pragma("unroll") for (int m = 0; m < 4; ++m) _Pragma("unroll") for (int k = 0; k < 2; ++k) dst[m][k] = *(const LAS bf16x8*)(lds + PG8_SA(b, h) + aoff + m * 2048 + k * 1024); } while (0)
; #define PG8_LDB(dst, b, h) do { _Pragma("unroll") for (int n = 0; n < 2; ++n) _Pragma("unroll") for (int k = 0; k < 2; ++k) dst[n][k] = *(const LAS bf16x8*)(lds + PG8_SB(b, h) + boff + n * 2048 + k * 1024); } while (0)
; #define PG8_MMA(ai, bj, At, Bt) do { __builtin_amdgcn_s_setprio(1); _Pragma("unroll") for (int m = 0; m < 4; ++m) _Pragma("unroll") for (int n = 0; n < 2; ++n) _Pragma("unroll") for (int k = 0; k < 2; ++k) \
;         acc[ai][bj][m][n] = __builtin_amdgcn_mfma_f32_16x16x32_bf16(Bt[n][k], At[m][k], acc[ai][bj][m][n], 0, 0, 0); __builtin_amdgcn_s_setprio(0); } while (0)
; #define PG8_WAIT_V(n) asm volatile("s_waitcnt vmcnt(" #n ")" ::: "memory")
; #define PG8_BAR __builtin_amdgcn_s_barrier()
; template <class Epi, bool ALIGN_EPI, int K, int LDA, int LDB>
; __device__ __forceinline__ void gemm_phase(LAS unsigned char* lds, const int wid, const Gemm g, const StaticOrder& S, const Epi& E) {
;     ...
;             PG8_WAIT_V(8); PG8_WAIT_L(0); PG8_BAR; PG8_MMA(0, 0, At, B0); PG8_MMA(0, 1, At, B1); PG8_BAR; PG8_SCHED;
;             PG8_LDA(At, 0, 1); PG8_STAGE(PG8_SB(0, 0), b2, voffB); PG8_STAGE(PG8_SB(0, 1), b2 + hB, voffB); PG8_STAGE(PG8_SA(0, 0), a2, voffA);
;             PG8_WAIT_V(8); PG8_WAIT_L(0); PG8_BAR; PG8_MMA(1, 0, At, B0); PG8_MMA(1, 1, At, B1); PG8_BAR; PG8_SCHED;
;             PG8_LDB(B0, 1, 0); PG8_LDB(B1, 1, 1); PG8_SCHED; PG8_LDA(At, 1, 0); PG8_STAGE(PG8_SA(0, 1), a2 + hA, voffA);
;             PG8_WAIT_V(8); PG8_WAIT_L(0); PG8_BAR; PG8_MMA(0, 0, At, B0); PG8_MMA(0, 1, At, B1); PG8_BAR; PG8_SCHED;
;             PG8_LDA(At, 1, 1); PG8_STAGE(PG8_SB(1, 0), b3, voffB); PG8_STAGE(PG8_SB(1, 1), b3 + hB, voffB); PG8_STAGE(PG8_SA(1, 0), a3, voffA);
;             PG8_WAIT_V(8); PG8_WAIT_L(0); PG8_BAR; PG8_MMA(1, 0, At, B0); PG8_MMA(1, 1, At, B1); PG8_BAR; PG8_SCHED;
;         }
;         if constexpr (ALIGN_EPI) { if (wr == 0) PG8_BAR; }
	s_setprio 1
	s_waitcnt lgkmcnt(0)
	v_mfma_f32_16x16x32_bf16 v[64:67], v[8:11], v[24:27], v[64:67]
	v_mfma_f32_16x16x32_bf16 v[112:115], v[12:15], v[28:31], v[64:67]
	v_mfma_f32_16x16x32_bf16 v[64:67], v[16:19], v[24:27], v[68:71]
	v_mfma_f32_16x16x32_bf16 v[116:119], v[20:23], v[28:31], v[64:67]
	v_mfma_f32_16x16x32_bf16 v[64:67], v[8:11], v[60:63], v[72:75]
	v_mfma_f32_16x16x32_bf16 v[108:111], v[12:15], v[230:233], v[64:67]
	v_mfma_f32_16x16x32_bf16 v[64:67], v[16:19], v[60:63], v[76:79]
	v_mfma_f32_16x16x32_bf16 v[104:107], v[20:23], v[230:233], v[64:67]
	v_mfma_f32_16x16x32_bf16 v[64:67], v[8:11], v[234:237], v[80:83]
	v_mfma_f32_16x16x32_bf16 v[92:95], v[12:15], v[238:241], v[64:67]
	v_mfma_f32_16x16x32_bf16 v[64:67], v[16:19], v[234:237], v[84:87]
	v_mfma_f32_16x16x32_bf16 v[88:91], v[20:23], v[238:241], v[64:67]
	v_mfma_f32_16x16x32_bf16 v[64:67], v[8:11], v[242:245], v[214:217]
	v_mfma_f32_16x16x32_bf16 v[76:79], v[12:15], v[246:249], v[64:67]
	v_mfma_f32_16x16x32_bf16 v[64:67], v[16:19], v[242:245], v[218:221]
	v_mfma_f32_16x16x32_bf16 v[72:75], v[20:23], v[246:249], v[64:67]
	v_mfma_f32_16x16x32_bf16 v[64:67], v[178:181], v[24:27], v[96:99]
	v_mfma_f32_16x16x32_bf16 v[24:27], v[202:205], v[24:27], v[32:35]
	v_mfma_f32_16x16x32_bf16 v[124:127], v[226:229], v[28:31], v[24:27]
	v_mfma_f32_16x16x32_bf16 v[24:27], v[178:181], v[60:63], v[36:39]
	v_mfma_f32_16x16x32_bf16 v[100:103], v[198:201], v[230:233], v[24:27]
	v_mfma_f32_16x16x32_bf16 v[24:27], v[202:205], v[60:63], v[40:43]
	v_mfma_f32_16x16x32_bf16 v[96:99], v[226:229], v[230:233], v[24:27]
	v_mfma_f32_16x16x32_bf16 v[24:27], v[178:181], v[234:237], v[44:47]
	v_mfma_f32_16x16x32_bf16 v[84:87], v[198:201], v[238:241], v[24:27]
	v_mfma_f32_16x16x32_bf16 v[24:27], v[202:205], v[234:237], v[48:51]
	v_mfma_f32_16x16x32_bf16 v[80:83], v[226:229], v[238:241], v[24:27]
	v_mfma_f32_16x16x32_bf16 v[24:27], v[178:181], v[242:245], v[52:55]
	v_mfma_f32_16x16x32_bf16 v[68:71], v[198:201], v[246:249], v[24:27]
	v_mfma_f32_16x16x32_bf16 v[24:27], v[202:205], v[242:245], v[56:59]
	v_mfma_f32_16x16x32_bf16 v[120:123], v[198:201], v[28:31], v[64:67]
	v_mfma_f32_16x16x32_bf16 v[60:63], v[226:229], v[246:249], v[24:27]
	s_setprio 0
	s_barrier
	s_mov_b32 m0, s71
	s_nop 2
	v_lshl_add_u64 v[24:25], v[140:141], 0, s[14:15]
	s_add_u32 s8, s8, 0x10080
	ds_read_b128 v[32:35], v149 offset:49152
	ds_read_b128 v[36:39], v149 offset:50176
	ds_read_b128 v[214:217], v149 offset:51200
	ds_read_b128 v[218:221], v149 offset:52224
	ds_read_b128 v[230:233], v149 offset:53248
	ds_read_b128 v[234:237], v149 offset:54272
	ds_read_b128 v[238:241], v149 offset:55296
	ds_read_b128 v[242:245], v149 offset:56320
	global_load_lds_dwordx4 v[24:25], off
	v_lshl_add_u64 v[24:25], v[250:251], 0, s[14:15]
	s_mov_b32 m0, s69
	s_addc_u32 s9, s9, 0
	global_load_lds_dwordx4 v[24:25], off
	v_lshl_add_u64 v[24:25], s[8:9], 0, v[130:131]
	s_mov_b32 m0, s40
	s_nop 0
	global_load_lds_dwordx4 v[24:25], off
	v_lshl_add_u64 v[24:25], s[8:9], 0, v[134:135]
	s_mov_b32 m0, s41
	s_nop 0
	global_load_lds_dwordx4 v[24:25], off
	v_lshl_add_u64 v[24:25], v[252:253], 0, s[14:15]
	s_mov_b32 m0, s59
	s_nop 0
	global_load_lds_dwordx4 v[24:25], off
	v_lshl_add_u64 v[24:25], v[136:137], 0, s[14:15]
	s_mov_b32 m0, s60
	s_nop 0
	global_load_lds_dwordx4 v[24:25], off
	s_waitcnt vmcnt(8)
	s_barrier
	s_setprio 1
	s_waitcnt lgkmcnt(0)
	v_mfma_f32_16x16x32_bf16 v[24:27], v[8:11], v[32:35], v[150:153]
	v_mfma_f32_16x16x32_bf16 v[64:67], v[12:15], v[36:39], v[24:27]
	v_mfma_f32_16x16x32_bf16 v[24:27], v[16:19], v[32:35], v[154:157]
	v_mfma_f32_16x16x32_bf16 v[56:59], v[20:23], v[36:39], v[24:27]
	v_mfma_f32_16x16x32_bf16 v[24:27], v[8:11], v[214:217], v[158:161]
	v_mfma_f32_16x16x32_bf16 v[44:47], v[12:15], v[218:221], v[24:27]
	v_mfma_f32_16x16x32_bf16 v[24:27], v[16:19], v[214:217], v[162:165]
	v_mfma_f32_16x16x32_bf16 v[40:43], v[20:23], v[218:221], v[24:27]
	v_mfma_f32_16x16x32_bf16 v[24:27], v[8:11], v[230:233], v[166:169]
	v_mfma_f32_16x16x32_bf16 v[0:3], v[8:11], v[238:241], v[0:3]
	v_mfma_f32_16x16x32_bf16 v[28:31], v[12:15], v[234:237], v[24:27]
	v_mfma_f32_16x16x32_bf16 v[24:27], v[16:19], v[230:233], v[170:173]
	v_mfma_f32_16x16x32_bf16 v[12:15], v[12:15], v[242:245], v[0:3]
	v_mfma_f32_16x16x32_bf16 v[0:3], v[16:19], v[238:241], v[4:7]
	v_mfma_f32_16x16x32_bf16 v[24:27], v[20:23], v[234:237], v[24:27]
	v_mfma_f32_16x16x32_bf16 v[8:11], v[20:23], v[242:245], v[0:3]
	v_mfma_f32_16x16x32_bf16 v[0:3], v[178:181], v[32:35], v[206:209]
	v_mfma_f32_16x16x32_bf16 v[52:55], v[198:201], v[36:39], v[0:3]
	v_mfma_f32_16x16x32_bf16 v[0:3], v[202:205], v[32:35], v[210:213]
	v_mfma_f32_16x16x32_bf16 v[48:51], v[226:229], v[36:39], v[0:3]
	v_mfma_f32_16x16x32_bf16 v[0:3], v[178:181], v[214:217], v[222:225]
	v_mfma_f32_16x16x32_bf16 v[36:39], v[198:201], v[218:221], v[0:3]
	v_mfma_f32_16x16x32_bf16 v[0:3], v[202:205], v[214:217], v[182:185]
	v_mfma_f32_16x16x32_bf16 v[32:35], v[226:229], v[218:221], v[0:3]
	v_mfma_f32_16x16x32_bf16 v[0:3], v[178:181], v[230:233], v[186:189]
	v_mfma_f32_16x16x32_bf16 v[20:23], v[198:201], v[234:237], v[0:3]
	v_mfma_f32_16x16x32_bf16 v[0:3], v[202:205], v[230:233], v[190:193]
	v_mfma_f32_16x16x32_bf16 v[16:19], v[226:229], v[234:237], v[0:3]
	v_mfma_f32_16x16x32_bf16 v[0:3], v[178:181], v[238:241], v[194:197]
	v_mfma_f32_16x16x32_bf16 v[4:7], v[198:201], v[242:245], v[0:3]
	v_mfma_f32_16x16x32_bf16 v[0:3], v[202:205], v[238:241], v[174:177]
	v_mfma_f32_16x16x32_bf16 v[0:3], v[226:229], v[242:245], v[0:3]
	s_setprio 0
	s_barrier
	s_andn2_b64 vcc, exec, s[16:17]
	s_cbranch_vccnz .LBB0_691
	s_barrier

; #define PG8_STAGE(bufoff, gbase, voff) do { _Pragma("unroll") for (int _i = 0; _i < 2; ++_i) \
;         __builtin_amdgcn_global_load_lds((const unsigned*)((const char*)(gbase) + (voff)[_i]), (LAS unsigned*)(lds + (bufoff) + ldsw + _i * 8192), 16, 0, 0); } while (0)
; #define PG8_LDA(dst, b, h) do { _Pragma("unroll") for (int m = 0; m < 4; ++m) _Pragma("unroll") for (int k = 0; k < 2; ++k) dst[m][k] = *(const LAS bf16x8*)(lds + PG8_SA(b, h) + aoff + m * 2048 + k * 1024); } while (0)
; #define PG8_LDB(dst, b, h) do { _Pragma("unroll") for (int n = 0; n < 2; ++n) _Pragma("unroll") for (int k = 0; k < 2; ++k) dst[n][k] = *(const LAS bf16x8*)(lds + PG8_SB(b, h) + boff + n * 2048 + k * 1024); } while (0)
; #define PG8_MMA(ai, bj, At, Bt) do { __builtin_amdgcn_s_setprio(1); _Pragma("unroll") for (int m = 0; m < 4; ++m) _Pragma("unroll") for (int n = 0; n < 2; ++n) _Pragma("unroll") for (int k = 0; k < 2; ++k) \
;         acc[ai][bj][m][n] = __builtin_amdgcn_mfma_f32_16x16x32_bf16(Bt[n][k], At[m][k], acc[ai][bj][m][n], 0, 0, 0); __builtin_amdgcn_s_setprio(0); } while (0)
; template <class Epi, bool ALIGN_EPI, int K, int LDA, int LDB>
; __device__ __forceinline__ void gemm_phase(LAS unsigned char* lds, const int wid, const Gemm g, const StaticOrder& S, const Epi& E) {
;     ...
;         const bool has_next = S.next(ui + 1, nxt);
;         const char* nA = has_next ? (const char*)g.A + (size_t)nxt.pm * tA : cA; const char* nB = has_next ? (const char*)g.Bt + (size_t)nxt.pn * tB : cB;
;         for (int t = 0; t < nt; t += 2) {
;             const bool last = (t == nt - 2);
;             const char* a1 = cA + (size_t)(t + 1) * kstep;
;             const char* a2 = last ? nA : cA + (size_t)(t + 2) * kstep; const char* b2 = last ? nB : cB + (size_t)(t + 2) * kstep;
;             const char* a3 = a2 + kstep; const char* b3 = b2 + kstep;
;             PG8_LDB(B0, 0, 0); PG8_LDB(B1, 0, 1); PG8_SCHED; PG8_LDA(At, 0, 0); PG8_STAGE(PG8_SA(1, 1), a1 + hA, voffA);
;             PG8_WAIT_V(8); PG8_WAIT_L(0); PG8_BAR; PG8_MMA(0, 0, At, B0); PG8_MMA(0, 1, At, B1); PG8_BAR; PG8_SCHED;
;             PG8_LDA(At, 0, 1); PG8_STAGE(PG8_SB(0, 0), b2, voffB); PG8_STAGE(PG8_SB(0, 1), b2 + hB, voffB); PG8_STAGE(PG8_SA(0, 0), a2, voffA);
;             PG8_WAIT_V(8); PG8_WAIT_L(0); PG8_BAR; PG8_MMA(1, 0, At, B0); PG8_MMA(1, 1, At, B1); PG8_BAR; PG8_SCHED;
.LBB0_703:
	ds_read_b128 v[0:3], v140
	ds_read_b128 v[4:7], v140 offset:1024
	ds_read_b128 v[8:11], v140 offset:2048
	ds_read_b128 v[12:15], v140 offset:3072
	ds_read_b128 v[16:19], v141
	ds_read_b128 v[20:23], v141 offset:1024
	ds_read_b128 v[24:27], v141 offset:2048
	ds_read_b128 v[28:31], v141 offset:3072
	s_ashr_i32 s25, s24, 31
	s_lshl_b64 s[26:27], s[24:25], 17
	s_add_u32 s26, s40, s26
	s_addc_u32 s27, s41, s27
	s_and_b64 s[28:29], s[4:5], exec
	s_cselect_b32 s39, s27, s31
	s_cselect_b32 s38, s26, s30
	s_ashr_i32 s23, s22, 31
	s_lshl_b64 s[28:29], s[22:23], 17
	s_add_u32 s28, s42, s28
	s_addc_u32 s29, s43, s29
	s_and_b64 s[36:37], s[4:5], exec
	s_cselect_b32 s37, s29, s35
	s_cselect_b32 s36, s28, s34
	s_add_u32 s68, s30, 0x10080
	s_addc_u32 s69, s31, 0
	s_mov_b32 m0, s58
	v_lshl_add_u64 v[64:65], s[68:69], 0, v[134:135]
	ds_read_b128 v[32:35], v142
	ds_read_b128 v[36:39], v142 offset:1024
	ds_read_b128 v[40:43], v142 offset:2048
	ds_read_b128 v[44:47], v142 offset:3072
	ds_read_b128 v[48:51], v142 offset:4096
	ds_read_b128 v[52:55], v142 offset:5120
	ds_read_b128 v[56:59], v142 offset:6144
	ds_read_b128 v[60:63], v142 offset:7168
	global_load_lds_dwordx4 v[64:65], off
	v_lshl_add_u64 v[64:65], s[68:69], 0, v[130:131]
	s_mov_b32 m0, s59
	s_nop 0
	global_load_lds_dwordx4 v[64:65], off
	s_waitcnt vmcnt(8)
	s_barrier
	s_setprio 1
	s_waitcnt lgkmcnt(0)
	v_mfma_f32_16x16x32_bf16 v[64:67], v[0:3], v[32:35], 0
	v_mfma_f32_16x16x32_bf16 v[68:71], v[8:11], v[32:35], 0
	v_mfma_f32_16x16x32_bf16 v[72:75], v[0:3], v[40:43], 0
	v_mfma_f32_16x16x32_bf16 v[76:79], v[8:11], v[40:43], 0
	v_mfma_f32_16x16x32_bf16 v[80:83], v[0:3], v[48:51], 0
	v_mfma_f32_16x16x32_bf16 v[84:87], v[8:11], v[48:51], 0
	v_mfma_f32_16x16x32_bf16 v[88:91], v[0:3], v[56:59], 0
	v_mfma_f32_16x16x32_bf16 v[92:95], v[8:11], v[56:59], 0
	v_mfma_f32_16x16x32_bf16 v[64:67], v[4:7], v[36:39], v[64:67]
	v_mfma_f32_16x16x32_bf16 v[68:71], v[12:15], v[36:39], v[68:71]
	v_mfma_f32_16x16x32_bf16 v[72:75], v[4:7], v[44:47], v[72:75]
	v_mfma_f32_16x16x32_bf16 v[76:79], v[12:15], v[44:47], v[76:79]
	v_mfma_f32_16x16x32_bf16 v[80:83], v[4:7], v[52:55], v[80:83]
	v_mfma_f32_16x16x32_bf16 v[84:87], v[12:15], v[52:55], v[84:87]
	v_mfma_f32_16x16x32_bf16 v[88:91], v[4:7], v[60:63], v[88:91]
	v_mfma_f32_16x16x32_bf16 v[92:95], v[12:15], v[60:63], v[92:95]
	v_mfma_f32_16x16x32_bf16 v[96:99], v[16:19], v[32:35], 0
	v_mfma_f32_16x16x32_bf16 v[32:35], v[24:27], v[32:35], 0
	v_mfma_f32_16x16x32_bf16 v[96:99], v[20:23], v[36:39], v[96:99]
	v_mfma_f32_16x16x32_bf16 v[32:35], v[28:31], v[36:39], v[32:35]
	v_mfma_f32_16x16x32_bf16 v[36:39], v[16:19], v[40:43], 0
	v_mfma_f32_16x16x32_bf16 v[40:43], v[24:27], v[40:43], 0
	v_mfma_f32_16x16x32_bf16 v[36:39], v[20:23], v[44:47], v[36:39]
	v_mfma_f32_16x16x32_bf16 v[40:43], v[28:31], v[44:47], v[40:43]
	v_mfma_f32_16x16x32_bf16 v[44:47], v[16:19], v[48:51], 0
	v_mfma_f32_16x16x32_bf16 v[48:51], v[24:27], v[48:51], 0
	v_mfma_f32_16x16x32_bf16 v[44:47], v[20:23], v[52:55], v[44:47]
	v_mfma_f32_16x16x32_bf16 v[48:51], v[28:31], v[52:55], v[48:51]
	v_mfma_f32_16x16x32_bf16 v[52:55], v[16:19], v[56:59], 0
	v_mfma_f32_16x16x32_bf16 v[56:59], v[24:27], v[56:59], 0
	v_mfma_f32_16x16x32_bf16 v[52:55], v[20:23], v[60:63], v[52:55]
	v_mfma_f32_16x16x32_bf16 v[56:59], v[28:31], v[60:63], v[56:59]
	s_setprio 0
	s_barrier
	v_lshl_add_u64 v[210:211], s[34:35], 0, v[132:133]
	s_mov_b32 m0, s60
	v_lshl_add_u64 v[146:147], v[210:211], 0, s[16:17]
	v_lshl_add_u64 v[212:213], s[34:35], 0, v[128:129]
	s_add_u32 s68, s34, 0x10100
	ds_read_b128 v[60:63], v142 offset:16384
	ds_read_b128 v[100:103], v142 offset:17408
	ds_read_b128 v[104:107], v142 offset:18432
	ds_read_b128 v[108:111], v142 offset:19456
	ds_read_b128 v[112:115], v142 offset:20480
	ds_read_b128 v[116:119], v142 offset:21504
	ds_read_b128 v[120:123], v142 offset:22528
	ds_read_b128 v[124:127], v142 offset:23552
	global_load_lds_dwordx4 v[146:147], off
	v_lshl_add_u64 v[146:147], v[212:213], 0, s[16:17]
	s_mov_b32 m0, s61
	s_addc_u32 s69, s35, 0
	global_load_lds_dwordx4 v[146:147], off
	v_lshl_add_u64 v[146:147], s[68:69], 0, v[132:133]
	s_mov_b32 m0, s62
	v_lshl_add_u64 v[214:215], s[30:31], 0, v[134:135]
	global_load_lds_dwordx4 v[146:147], off
	v_lshl_add_u64 v[146:147], s[68:69], 0, v[128:129]
	s_mov_b32 m0, s63
	v_lshl_add_u64 v[216:217], s[30:31], 0, v[130:131]
	global_load_lds_dwordx4 v[146:147], off
	v_lshl_add_u64 v[146:147], v[214:215], 0, s[16:17]
	s_mov_b32 m0, s21
	s_nop 0
	global_load_lds_dwordx4 v[146:147], off
	v_lshl_add_u64 v[146:147], v[216:217], 0, s[16:17]
	s_mov_b32 m0, s49
	s_nop 0
	global_load_lds_dwordx4 v[146:147], off
	s_waitcnt vmcnt(8)
	s_barrier
; #define PG8_STAGE(bufoff, gbase, voff) do { _Pragma("unroll") for (int _i = 0; _i < 2; ++_i) \
;         __builtin_amdgcn_global_load_lds((const unsigned*)((const char*)(gbase) + (voff)[_i]), (LAS unsigned*)(lds + (bufoff) + ldsw + _i * 8192), 16, 0, 0); } while (0)
; #define PG8_LDA(dst, b, h) do { _Pragma("unroll") for (int m = 0; m < 4; ++m) _Pragma("unroll") for (int k = 0; k < 2; ++k) dst[m][k] = *(const LAS bf16x8*)(lds + PG8_SA(b, h) + aoff + m * 2048 + k * 1024); } while (0)
; #define PG8_LDB(dst, b, h) do { _Pragma("unroll") for (int n = 0; n < 2; ++n) _Pragma("unroll") for (int k = 0; k < 2; ++k) dst[n][k] = *(const LAS bf16x8*)(lds + PG8_SB(b, h) + boff + n * 2048 + k * 1024); } while (0)
; #define PG8_MMA(ai, bj, At, Bt) do { __builtin_amdgcn_s_setprio(1); _Pragma("unroll") for (int m = 0; m < 4; ++m) _Pragma("unroll") for (int n = 0; n < 2; ++n) _Pragma("unroll") for (int k = 0; k < 2; ++k) \
;         acc[ai][bj][m][n] = __builtin_amdgcn_mfma_f32_16x16x32_bf16(Bt[n][k], At[m][k], acc[ai][bj][m][n], 0, 0, 0); __builtin_amdgcn_s_setprio(0); } while (0)
; #define PG8_WAIT_V(n) asm volatile("s_waitcnt vmcnt(" #n ")" ::: "memory")
; #define PG8_WAIT_L(n) asm volatile("s_waitcnt lgkmcnt(" #n ")" ::: "memory")
; #define PG8_BAR __builtin_amdgcn_s_barrier()
; #define PG8_SCHED __builtin_amdgcn_sched_barrier(0)
; template <class Epi, bool ALIGN_EPI, int K, int LDA, int LDB>
; __device__ __forceinline__ void gemm_phase(LAS unsigned char* lds, const int wid, const Gemm g, const StaticOrder& S, const Epi& E) {
;     ...
;             PG8_WAIT_V(8); PG8_WAIT_L(0); PG8_BAR; PG8_MMA(0, 0, At, B0); PG8_MMA(0, 1, At, B1); PG8_BAR; PG8_SCHED;
;             PG8_LDA(At, 0, 1); PG8_STAGE(PG8_SB(0, 0), b2, voffB); PG8_STAGE(PG8_SB(0, 1), b2 + hB, voffB); PG8_STAGE(PG8_SA(0, 0), a2, voffA);
;             PG8_WAIT_V(8); PG8_WAIT_L(0); PG8_BAR; PG8_MMA(1, 0, At, B0); PG8_MMA(1, 1, At, B1); PG8_BAR; PG8_SCHED;
;             PG8_LDB(B0, 1, 0); PG8_LDB(B1, 1, 1); PG8_SCHED; PG8_LDA(At, 1, 0); PG8_STAGE(PG8_SA(0, 1), a2 + hA, voffA);
;             PG8_WAIT_V(8); PG8_WAIT_L(0); PG8_BAR; PG8_MMA(0, 0, At, B0); PG8_MMA(0, 1, At, B1); PG8_BAR; PG8_SCHED;
	s_setprio 1
	s_waitcnt lgkmcnt(0)
	v_mfma_f32_16x16x32_bf16 v[146:149], v[0:3], v[60:63], 0
	v_mfma_f32_16x16x32_bf16 v[154:157], v[0:3], v[104:107], 0
	v_mfma_f32_16x16x32_bf16 v[162:165], v[0:3], v[112:115], 0
	v_mfma_f32_16x16x32_bf16 v[0:3], v[0:3], v[120:123], 0
	v_mfma_f32_16x16x32_bf16 v[146:149], v[4:7], v[100:103], v[146:149]
	v_mfma_f32_16x16x32_bf16 v[154:157], v[4:7], v[108:111], v[154:157]
	v_mfma_f32_16x16x32_bf16 v[162:165], v[4:7], v[116:119], v[162:165]
	v_mfma_f32_16x16x32_bf16 v[0:3], v[4:7], v[124:127], v[0:3]
	v_mfma_f32_16x16x32_bf16 v[4:7], v[8:11], v[120:123], 0
	v_mfma_f32_16x16x32_bf16 v[150:153], v[8:11], v[60:63], 0
	v_mfma_f32_16x16x32_bf16 v[158:161], v[8:11], v[104:107], 0
	v_mfma_f32_16x16x32_bf16 v[166:169], v[8:11], v[112:115], 0
	v_mfma_f32_16x16x32_bf16 v[4:7], v[12:15], v[124:127], v[4:7]
	v_mfma_f32_16x16x32_bf16 v[150:153], v[12:15], v[100:103], v[150:153]
	v_mfma_f32_16x16x32_bf16 v[158:161], v[12:15], v[108:111], v[158:161]
	v_mfma_f32_16x16x32_bf16 v[166:169], v[12:15], v[116:119], v[166:169]
	v_mfma_f32_16x16x32_bf16 v[8:11], v[16:19], v[60:63], 0
	v_mfma_f32_16x16x32_bf16 v[12:15], v[24:27], v[60:63], 0
	v_mfma_f32_16x16x32_bf16 v[8:11], v[20:23], v[100:103], v[8:11]
	v_mfma_f32_16x16x32_bf16 v[12:15], v[28:31], v[100:103], v[12:15]
	v_mfma_f32_16x16x32_bf16 v[60:63], v[16:19], v[104:107], 0
	v_mfma_f32_16x16x32_bf16 v[100:103], v[24:27], v[104:107], 0
	v_mfma_f32_16x16x32_bf16 v[104:107], v[16:19], v[112:115], 0
	v_mfma_f32_16x16x32_bf16 v[16:19], v[16:19], v[120:123], 0
	v_mfma_f32_16x16x32_bf16 v[60:63], v[20:23], v[108:111], v[60:63]
	v_mfma_f32_16x16x32_bf16 v[100:103], v[28:31], v[108:111], v[100:103]
	v_mfma_f32_16x16x32_bf16 v[104:107], v[20:23], v[116:119], v[104:107]
	v_mfma_f32_16x16x32_bf16 v[108:111], v[24:27], v[112:115], 0
	v_mfma_f32_16x16x32_bf16 v[16:19], v[20:23], v[124:127], v[16:19]
	v_mfma_f32_16x16x32_bf16 v[20:23], v[24:27], v[120:123], 0
	v_mfma_f32_16x16x32_bf16 v[108:111], v[28:31], v[116:119], v[108:111]
	v_mfma_f32_16x16x32_bf16 v[20:23], v[28:31], v[124:127], v[20:23]
	s_setprio 0
	s_barrier
	ds_read_b128 v[24:27], v143
	ds_read_b128 v[28:31], v143 offset:1024
	ds_read_b128 v[112:115], v143 offset:2048
	ds_read_b128 v[116:119], v143 offset:3072
	ds_read_b128 v[120:123], v144
	ds_read_b128 v[124:127], v144 offset:1024
	ds_read_b128 v[170:173], v144 offset:2048
	ds_read_b128 v[174:177], v144 offset:3072
	s_add_u32 s68, s30, 0x10100
	s_addc_u32 s69, s31, 0
	s_mov_b32 m0, s51
	v_lshl_add_u64 v[218:219], s[68:69], 0, v[134:135]
	ds_read_b128 v[178:181], v142 offset:32768
	ds_read_b128 v[182:185], v142 offset:33792
	ds_read_b128 v[186:189], v142 offset:34816
	ds_read_b128 v[190:193], v142 offset:35840
	ds_read_b128 v[194:197], v142 offset:36864
	ds_read_b128 v[198:201], v142 offset:37888
	ds_read_b128 v[202:205], v142 offset:38912
	ds_read_b128 v[206:209], v142 offset:39936
	global_load_lds_dwordx4 v[218:219], off
	v_lshl_add_u64 v[218:219], s[68:69], 0, v[130:131]
	s_mov_b32 m0, s54
	s_nop 0
	global_load_lds_dwordx4 v[218:219], off
	s_waitcnt vmcnt(8)
	s_barrier
	s_setprio 1
	s_waitcnt lgkmcnt(0)
	v_mfma_f32_16x16x32_bf16 v[64:67], v[24:27], v[178:181], v[64:67]
	v_mfma_f32_16x16x32_bf16 v[68:71], v[112:115], v[178:181], v[68:71]
	v_mfma_f32_16x16x32_bf16 v[72:75], v[24:27], v[186:189], v[72:75]
	v_mfma_f32_16x16x32_bf16 v[76:79], v[112:115], v[186:189], v[76:79]
	v_mfma_f32_16x16x32_bf16 v[80:83], v[24:27], v[194:197], v[80:83]
	v_mfma_f32_16x16x32_bf16 v[84:87], v[112:115], v[194:197], v[84:87]
	v_mfma_f32_16x16x32_bf16 v[88:91], v[24:27], v[202:205], v[88:91]
	v_mfma_f32_16x16x32_bf16 v[92:95], v[112:115], v[202:205], v[92:95]
	v_mfma_f32_16x16x32_bf16 v[64:67], v[28:31], v[182:185], v[64:67]
	v_mfma_f32_16x16x32_bf16 v[68:71], v[116:119], v[182:185], v[68:71]
	v_mfma_f32_16x16x32_bf16 v[72:75], v[28:31], v[190:193], v[72:75]
	v_mfma_f32_16x16x32_bf16 v[76:79], v[116:119], v[190:193], v[76:79]
	v_mfma_f32_16x16x32_bf16 v[80:83], v[28:31], v[198:201], v[80:83]
	v_mfma_f32_16x16x32_bf16 v[84:87], v[116:119], v[198:201], v[84:87]
	v_mfma_f32_16x16x32_bf16 v[88:91], v[28:31], v[206:209], v[88:91]
	v_mfma_f32_16x16x32_bf16 v[92:95], v[116:119], v[206:209], v[92:95]
	v_mfma_f32_16x16x32_bf16 v[96:99], v[120:123], v[178:181], v[96:99]
	v_mfma_f32_16x16x32_bf16 v[32:35], v[170:173], v[178:181], v[32:35]
	v_mfma_f32_16x16x32_bf16 v[36:39], v[120:123], v[186:189], v[36:39]
	v_mfma_f32_16x16x32_bf16 v[40:43], v[170:173], v[186:189], v[40:43]
	v_mfma_f32_16x16x32_bf16 v[44:47], v[120:123], v[194:197], v[44:47]
	v_mfma_f32_16x16x32_bf16 v[48:51], v[170:173], v[194:197], v[48:51]
	v_mfma_f32_16x16x32_bf16 v[52:55], v[120:123], v[202:205], v[52:55]
	v_mfma_f32_16x16x32_bf16 v[56:59], v[170:173], v[202:205], v[56:59]
	v_mfma_f32_16x16x32_bf16 v[96:99], v[124:127], v[182:185], v[96:99]
	v_mfma_f32_16x16x32_bf16 v[32:35], v[174:177], v[182:185], v[32:35]
	v_mfma_f32_16x16x32_bf16 v[36:39], v[124:127], v[190:193], v[36:39]
	v_mfma_f32_16x16x32_bf16 v[40:43], v[174:177], v[190:193], v[40:43]
	v_mfma_f32_16x16x32_bf16 v[44:47], v[124:127], v[198:201], v[44:47]
	v_mfma_f32_16x16x32_bf16 v[48:51], v[174:177], v[198:201], v[48:51]
	v_mfma_f32_16x16x32_bf16 v[52:55], v[124:127], v[206:209], v[52:55]
	v_mfma_f32_16x16x32_bf16 v[56:59], v[174:177], v[206:209], v[56:59]
	s_setprio 0
	s_barrier
; #define PG8_STAGE(bufoff, gbase, voff) do { _Pragma("unroll") for (int _i = 0; _i < 2; ++_i) \
;         __builtin_amdgcn_global_load_lds((const unsigned*)((const char*)(gbase) + (voff)[_i]), (LAS unsigned*)(lds + (bufoff) + ldsw + _i * 8192), 16, 0, 0); } while (0)
; #define PG8_LDA(dst, b, h) do { _Pragma("unroll") for (int m = 0; m < 4; ++m) _Pragma("unroll") for (int k = 0; k < 2; ++k) dst[m][k] = *(const LAS bf16x8*)(lds + PG8_SA(b, h) + aoff + m * 2048 + k * 1024); } while (0)
; #define PG8_LDB(dst, b, h) do { _Pragma("unroll") for (int n = 0; n < 2; ++n) _Pragma("unroll") for (int k = 0; k < 2; ++k) dst[n][k] = *(const LAS bf16x8*)(lds + PG8_SB(b, h) + boff + n * 2048 + k * 1024); } while (0)
; #define PG8_MMA(ai, bj, At, Bt) do { __builtin_amdgcn_s_setprio(1); _Pragma("unroll") for (int m = 0; m < 4; ++m) _Pragma("unroll") for (int n = 0; n < 2; ++n) _Pragma("unroll") for (int k = 0; k < 2; ++k) \
;         acc[ai][bj][m][n] = __builtin_amdgcn_mfma_f32_16x16x32_bf16(Bt[n][k], At[m][k], acc[ai][bj][m][n], 0, 0, 0); __builtin_amdgcn_s_setprio(0); } while (0)
; #define PG8_WAIT_V(n) asm volatile("s_waitcnt vmcnt(" #n ")" ::: "memory")
; #define PG8_WAIT_L(n) asm volatile("s_waitcnt lgkmcnt(" #n ")" ::: "memory")
; #define PG8_BAR __builtin_amdgcn_s_barrier()
; #define PG8_SCHED __builtin_amdgcn_sched_barrier(0)
; template <class Epi, bool ALIGN_EPI, int K, int LDA, int LDB>
; __device__ __forceinline__ void gemm_phase(LAS unsigned char* lds, const int wid, const Gemm g, const StaticOrder& S, const Epi& E) {
;     ...
;             PG8_LDB(B0, 1, 0); PG8_LDB(B1, 1, 1); PG8_SCHED; PG8_LDA(At, 1, 0); PG8_STAGE(PG8_SA(0, 1), a2 + hA, voffA);
;             PG8_WAIT_V(8); PG8_WAIT_L(0); PG8_BAR; PG8_MMA(0, 0, At, B0); PG8_MMA(0, 1, At, B1); PG8_BAR; PG8_SCHED;
;             PG8_LDA(At, 1, 1); PG8_STAGE(PG8_SB(1, 0), b3, voffB); PG8_STAGE(PG8_SB(1, 1), b3 + hB, voffB); PG8_STAGE(PG8_SA(1, 0), a3, voffA);
;             PG8_WAIT_V(8); PG8_WAIT_L(0); PG8_BAR; PG8_MMA(1, 0, At, B0); PG8_MMA(1, 1, At, B1); PG8_BAR; PG8_SCHED;
	s_add_i32 s23, s65, 0x2000
	s_mov_b32 m0, s65
	v_lshl_add_u64 v[210:211], v[210:211], 0, s[18:19]
	s_add_u32 s34, s34, 0x10180
	ds_read_b128 v[178:181], v142 offset:49152
	ds_read_b128 v[182:185], v142 offset:50176
	ds_read_b128 v[186:189], v142 offset:51200
	ds_read_b128 v[190:193], v142 offset:52224
	ds_read_b128 v[194:197], v142 offset:53248
	ds_read_b128 v[198:201], v142 offset:54272
	ds_read_b128 v[202:205], v142 offset:55296
	ds_read_b128 v[206:209], v142 offset:56320
	global_load_lds_dwordx4 v[210:211], off
	v_lshl_add_u64 v[210:211], v[212:213], 0, s[18:19]
	s_mov_b32 m0, s23
	s_addc_u32 s35, s35, 0
	s_add_i32 s25, s64, s0
	global_load_lds_dwordx4 v[210:211], off
	v_lshl_add_u64 v[210:211], s[34:35], 0, v[132:133]
	s_mov_b32 m0, s25
	s_nop 0
	global_load_lds_dwordx4 v[210:211], off
	v_lshl_add_u64 v[210:211], s[34:35], 0, v[128:129]
	s_add_i32 s34, s25, 0x2000
	s_mov_b32 m0, s34
	s_nop 0
	global_load_lds_dwordx4 v[210:211], off
	v_lshl_add_u64 v[210:211], v[214:215], 0, s[18:19]
	s_mov_b32 m0, s55
	s_nop 0
	global_load_lds_dwordx4 v[210:211], off
	v_lshl_add_u64 v[210:211], v[216:217], 0, s[18:19]
	s_mov_b32 m0, s56
	s_nop 0
	global_load_lds_dwordx4 v[210:211], off
	s_waitcnt vmcnt(8)
	s_barrier
	s_setprio 1
	s_waitcnt lgkmcnt(0)
	v_mfma_f32_16x16x32_bf16 v[0:3], v[24:27], v[202:205], v[0:3]
	v_mfma_f32_16x16x32_bf16 v[4:7], v[112:115], v[202:205], v[4:7]
	v_mfma_f32_16x16x32_bf16 v[146:149], v[24:27], v[178:181], v[146:149]
	v_mfma_f32_16x16x32_bf16 v[150:153], v[112:115], v[178:181], v[150:153]
	v_mfma_f32_16x16x32_bf16 v[154:157], v[24:27], v[186:189], v[154:157]
	v_mfma_f32_16x16x32_bf16 v[158:161], v[112:115], v[186:189], v[158:161]
	v_mfma_f32_16x16x32_bf16 v[162:165], v[24:27], v[194:197], v[162:165]
	v_mfma_f32_16x16x32_bf16 v[166:169], v[112:115], v[194:197], v[166:169]
	v_mfma_f32_16x16x32_bf16 v[0:3], v[28:31], v[206:209], v[0:3]
	v_mfma_f32_16x16x32_bf16 v[4:7], v[116:119], v[206:209], v[4:7]
	v_mfma_f32_16x16x32_bf16 v[146:149], v[28:31], v[182:185], v[146:149]
	v_mfma_f32_16x16x32_bf16 v[150:153], v[116:119], v[182:185], v[150:153]
	v_mfma_f32_16x16x32_bf16 v[154:157], v[28:31], v[190:193], v[154:157]
	v_mfma_f32_16x16x32_bf16 v[158:161], v[116:119], v[190:193], v[158:161]
	v_mfma_f32_16x16x32_bf16 v[162:165], v[28:31], v[198:201], v[162:165]
	v_mfma_f32_16x16x32_bf16 v[166:169], v[116:119], v[198:201], v[166:169]
	v_mfma_f32_16x16x32_bf16 v[8:11], v[120:123], v[178:181], v[8:11]
	v_mfma_f32_16x16x32_bf16 v[12:15], v[170:173], v[178:181], v[12:15]
	v_mfma_f32_16x16x32_bf16 v[24:27], v[120:123], v[186:189], v[60:63]
	v_mfma_f32_16x16x32_bf16 v[28:31], v[170:173], v[186:189], v[100:103]
	v_mfma_f32_16x16x32_bf16 v[60:63], v[120:123], v[194:197], v[104:107]
	v_mfma_f32_16x16x32_bf16 v[100:103], v[170:173], v[194:197], v[108:111]
	v_mfma_f32_16x16x32_bf16 v[16:19], v[120:123], v[202:205], v[16:19]
	v_mfma_f32_16x16x32_bf16 v[20:23], v[170:173], v[202:205], v[20:23]
	v_mfma_f32_16x16x32_bf16 v[8:11], v[124:127], v[182:185], v[8:11]
	v_mfma_f32_16x16x32_bf16 v[12:15], v[174:177], v[182:185], v[12:15]
	v_mfma_f32_16x16x32_bf16 v[24:27], v[124:127], v[190:193], v[24:27]
	v_mfma_f32_16x16x32_bf16 v[28:31], v[174:177], v[190:193], v[28:31]
	v_mfma_f32_16x16x32_bf16 v[60:63], v[124:127], v[198:201], v[60:63]
	v_mfma_f32_16x16x32_bf16 v[100:103], v[174:177], v[198:201], v[100:103]
	v_mfma_f32_16x16x32_bf16 v[16:19], v[124:127], v[206:209], v[16:19]
	v_mfma_f32_16x16x32_bf16 v[20:23], v[174:177], v[206:209], v[20:23]
	s_setprio 0
	s_barrier
	ds_read_b128 v[104:107], v140
	ds_read_b128 v[108:111], v140 offset:1024
	ds_read_b128 v[112:115], v140 offset:2048
	ds_read_b128 v[116:119], v140 offset:3072
	ds_read_b128 v[120:123], v141
	ds_read_b128 v[124:127], v141 offset:1024
	ds_read_b128 v[170:173], v141 offset:2048
	ds_read_b128 v[174:177], v141 offset:3072
	s_add_u32 s30, s30, 0x10180
	s_addc_u32 s31, s31, 0
	s_mov_b32 m0, s58
	v_lshl_add_u64 v[210:211], s[30:31], 0, v[134:135]
	ds_read_b128 v[178:181], v142
	ds_read_b128 v[182:185], v142 offset:1024
	ds_read_b128 v[186:189], v142 offset:2048
	ds_read_b128 v[190:193], v142 offset:3072
	ds_read_b128 v[194:197], v142 offset:4096
	ds_read_b128 v[198:201], v142 offset:5120
	ds_read_b128 v[202:205], v142 offset:6144
	ds_read_b128 v[206:209], v142 offset:7168
	global_load_lds_dwordx4 v[210:211], off
	v_lshl_add_u64 v[210:211], s[30:31], 0, v[130:131]
	s_mov_b32 m0, s59
	s_nop 0
	global_load_lds_dwordx4 v[210:211], off
	s_waitcnt vmcnt(8)
	s_barrier
	s_setprio 1
	s_waitcnt lgkmcnt(0)
	v_mfma_f32_16x16x32_bf16 v[80:83], v[104:107], v[194:197], v[80:83]
	v_mfma_f32_16x16x32_bf16 v[210:213], v[108:111], v[198:201], v[80:83]
	v_mfma_f32_16x16x32_bf16 v[80:83], v[112:115], v[194:197], v[84:87]
	v_mfma_f32_16x16x32_bf16 v[214:217], v[116:119], v[198:201], v[80:83]
	v_mfma_f32_16x16x32_bf16 v[80:83], v[104:107], v[202:205], v[88:91]
	v_mfma_f32_16x16x32_bf16 v[64:67], v[104:107], v[178:181], v[64:67]
	v_mfma_f32_16x16x32_bf16 v[68:71], v[112:115], v[178:181], v[68:71]
	v_mfma_f32_16x16x32_bf16 v[72:75], v[104:107], v[186:189], v[72:75]
	v_mfma_f32_16x16x32_bf16 v[76:79], v[112:115], v[186:189], v[76:79]
	v_mfma_f32_16x16x32_bf16 v[88:91], v[108:111], v[206:209], v[80:83]
	v_mfma_f32_16x16x32_bf16 v[80:83], v[112:115], v[202:205], v[92:95]
	v_mfma_f32_16x16x32_bf16 v[64:67], v[108:111], v[182:185], v[64:67]
	v_mfma_f32_16x16x32_bf16 v[68:71], v[116:119], v[182:185], v[68:71]
	v_mfma_f32_16x16x32_bf16 v[72:75], v[108:111], v[190:193], v[72:75]
	v_mfma_f32_16x16x32_bf16 v[76:79], v[116:119], v[190:193], v[76:79]
	v_mfma_f32_16x16x32_bf16 v[92:95], v[116:119], v[206:209], v[80:83]
	v_mfma_f32_16x16x32_bf16 v[48:51], v[170:173], v[194:197], v[48:51]
	v_mfma_f32_16x16x32_bf16 v[80:83], v[120:123], v[178:181], v[96:99]
	v_mfma_f32_16x16x32_bf16 v[32:35], v[170:173], v[178:181], v[32:35]
	v_mfma_f32_16x16x32_bf16 v[178:181], v[174:177], v[198:201], v[48:51]
	v_mfma_f32_16x16x32_bf16 v[48:51], v[120:123], v[202:205], v[52:55]
	v_mfma_f32_16x16x32_bf16 v[96:99], v[124:127], v[182:185], v[80:83]
	v_mfma_f32_16x16x32_bf16 v[32:35], v[174:177], v[182:185], v[32:35]
	v_mfma_f32_16x16x32_bf16 v[36:39], v[120:123], v[186:189], v[36:39]
	v_mfma_f32_16x16x32_bf16 v[40:43], v[170:173], v[186:189], v[40:43]
	v_mfma_f32_16x16x32_bf16 v[44:47], v[120:123], v[194:197], v[44:47]
	v_mfma_f32_16x16x32_bf16 v[182:185], v[124:127], v[206:209], v[48:51]
	v_mfma_f32_16x16x32_bf16 v[48:51], v[170:173], v[202:205], v[56:59]
	v_mfma_f32_16x16x32_bf16 v[36:39], v[124:127], v[190:193], v[36:39]
	v_mfma_f32_16x16x32_bf16 v[40:43], v[174:177], v[190:193], v[40:43]
	v_mfma_f32_16x16x32_bf16 v[44:47], v[124:127], v[198:201], v[44:47]
	v_mfma_f32_16x16x32_bf16 v[56:59], v[174:177], v[206:209], v[48:51]
	s_setprio 0
	s_barrier
; #define PG8_STAGE(bufoff, gbase, voff) do { _Pragma("unroll") for (int _i = 0; _i < 2; ++_i) \
;         __builtin_amdgcn_global_load_lds((const unsigned*)((const char*)(gbase) + (voff)[_i]), (LAS unsigned*)(lds + (bufoff) + ldsw + _i * 8192), 16, 0, 0); } while (0)
; #define PG8_LDA(dst, b, h) do { _Pragma("unroll") for (int m = 0; m < 4; ++m) _Pragma("unroll") for (int k = 0; k < 2; ++k) dst[m][k] = *(const LAS bf16x8*)(lds + PG8_SA(b, h) + aoff + m * 2048 + k * 1024); } while (0)
; #define PG8_LDB(dst, b, h) do { _Pragma("unroll") for (int n = 0; n < 2; ++n) _Pragma("unroll") for (int k = 0; k < 2; ++k) dst[n][k] = *(const LAS bf16x8*)(lds + PG8_SB(b, h) + boff + n * 2048 + k * 1024); } while (0)
; #define PG8_MMA(ai, bj, At, Bt) do { __builtin_amdgcn_s_setprio(1); _Pragma("unroll") for (int m = 0; m < 4; ++m) _Pragma("unroll") for (int n = 0; n < 2; ++n) _Pragma("unroll") for (int k = 0; k < 2; ++k) \
;         acc[ai][bj][m][n] = __builtin_amdgcn_mfma_f32_16x16x32_bf16(Bt[n][k], At[m][k], acc[ai][bj][m][n], 0, 0, 0); __builtin_amdgcn_s_setprio(0); } while (0)
; #define PG8_WAIT_V(n) asm volatile("s_waitcnt vmcnt(" #n ")" ::: "memory")
; #define PG8_WAIT_L(n) asm volatile("s_waitcnt lgkmcnt(" #n ")" ::: "memory")
; #define PG8_BAR __builtin_amdgcn_s_barrier()
; #define PG8_SCHED __builtin_amdgcn_sched_barrier(0)
; template <class Epi, bool ALIGN_EPI, int K, int LDA, int LDB>
; __device__ __forceinline__ void gemm_phase(LAS unsigned char* lds, const int wid, const Gemm g, const StaticOrder& S, const Epi& E) {
;     ...
;             PG8_LDA(At, 0, 1); PG8_STAGE(PG8_SB(0, 0), b2, voffB); PG8_STAGE(PG8_SB(0, 1), b2 + hB, voffB); PG8_STAGE(PG8_SA(0, 0), a2, voffA);
;             PG8_WAIT_V(8); PG8_WAIT_L(0); PG8_BAR; PG8_MMA(1, 0, At, B0); PG8_MMA(1, 1, At, B1); PG8_BAR; PG8_SCHED;
;             PG8_LDB(B0, 1, 0); PG8_LDB(B1, 1, 1); PG8_SCHED; PG8_LDA(At, 1, 0); PG8_STAGE(PG8_SA(0, 1), a2 + hA, voffA);
;             PG8_WAIT_V(8); PG8_WAIT_L(0); PG8_BAR; PG8_MMA(0, 0, At, B0); PG8_MMA(0, 1, At, B1); PG8_BAR; PG8_SCHED;
;             PG8_LDA(At, 1, 1); PG8_STAGE(PG8_SB(1, 0), b3, voffB); PG8_STAGE(PG8_SB(1, 1), b3 + hB, voffB); PG8_STAGE(PG8_SA(1, 0), a3, voffA);
	s_mov_b32 m0, s60
	v_lshl_add_u64 v[250:251], s[36:37], 0, v[132:133]
	s_add_u32 s30, s36, 0x10000
	ds_read_b128 v[48:51], v142 offset:16384
	ds_read_b128 v[52:55], v142 offset:17408
	ds_read_b128 v[80:83], v142 offset:18432
	ds_read_b128 v[84:87], v142 offset:19456
	ds_read_b128 v[186:189], v142 offset:20480
	ds_read_b128 v[190:193], v142 offset:21504
	ds_read_b128 v[194:197], v142 offset:22528
	ds_read_b128 v[198:201], v142 offset:23552
	global_load_lds_dwordx4 v[250:251], off
	v_lshl_add_u64 v[252:253], s[36:37], 0, v[128:129]
	s_mov_b32 m0, s61
	s_addc_u32 s31, s37, 0
	global_load_lds_dwordx4 v[252:253], off
	v_lshl_add_u64 v[202:203], s[30:31], 0, v[132:133]
	s_mov_b32 m0, s62
	v_lshl_add_u64 v[136:137], s[38:39], 0, v[134:135]
	global_load_lds_dwordx4 v[202:203], off
	v_lshl_add_u64 v[202:203], s[30:31], 0, v[128:129]
	s_mov_b32 m0, s63
	v_lshl_add_u64 v[138:139], s[38:39], 0, v[130:131]
	global_load_lds_dwordx4 v[202:203], off
	s_mov_b32 m0, s21
	s_nop 0
	global_load_lds_dwordx4 v[136:137], off
	s_mov_b32 m0, s49
	s_nop 0
	global_load_lds_dwordx4 v[138:139], off
	s_waitcnt vmcnt(8)
	s_barrier
	s_setprio 1
	s_waitcnt lgkmcnt(0)
	v_mfma_f32_16x16x32_bf16 v[0:3], v[104:107], v[194:197], v[0:3]
	v_mfma_f32_16x16x32_bf16 v[4:7], v[112:115], v[194:197], v[4:7]
	v_mfma_f32_16x16x32_bf16 v[146:149], v[104:107], v[48:51], v[146:149]
	v_mfma_f32_16x16x32_bf16 v[150:153], v[112:115], v[48:51], v[150:153]
	v_mfma_f32_16x16x32_bf16 v[154:157], v[104:107], v[80:83], v[154:157]
	v_mfma_f32_16x16x32_bf16 v[158:161], v[112:115], v[80:83], v[158:161]
	v_mfma_f32_16x16x32_bf16 v[162:165], v[104:107], v[186:189], v[162:165]
	v_mfma_f32_16x16x32_bf16 v[166:169], v[112:115], v[186:189], v[166:169]
	v_mfma_f32_16x16x32_bf16 v[0:3], v[108:111], v[198:201], v[0:3]
	v_mfma_f32_16x16x32_bf16 v[4:7], v[116:119], v[198:201], v[4:7]
	v_mfma_f32_16x16x32_bf16 v[146:149], v[108:111], v[52:55], v[146:149]
	v_mfma_f32_16x16x32_bf16 v[150:153], v[116:119], v[52:55], v[150:153]
	v_mfma_f32_16x16x32_bf16 v[154:157], v[108:111], v[84:87], v[154:157]
	v_mfma_f32_16x16x32_bf16 v[158:161], v[116:119], v[84:87], v[158:161]
	v_mfma_f32_16x16x32_bf16 v[162:165], v[108:111], v[190:193], v[162:165]
	v_mfma_f32_16x16x32_bf16 v[166:169], v[116:119], v[190:193], v[166:169]
	v_mfma_f32_16x16x32_bf16 v[24:27], v[120:123], v[80:83], v[24:27]
	v_mfma_f32_16x16x32_bf16 v[202:205], v[124:127], v[84:87], v[24:27]
	v_mfma_f32_16x16x32_bf16 v[24:27], v[170:173], v[80:83], v[28:31]
	v_mfma_f32_16x16x32_bf16 v[206:209], v[174:177], v[84:87], v[24:27]
	v_mfma_f32_16x16x32_bf16 v[24:27], v[120:123], v[186:189], v[60:63]
	v_mfma_f32_16x16x32_bf16 v[8:11], v[120:123], v[48:51], v[8:11]
	v_mfma_f32_16x16x32_bf16 v[12:15], v[170:173], v[48:51], v[12:15]
	v_mfma_f32_16x16x32_bf16 v[218:221], v[124:127], v[190:193], v[24:27]
	v_mfma_f32_16x16x32_bf16 v[24:27], v[170:173], v[186:189], v[100:103]
	v_mfma_f32_16x16x32_bf16 v[16:19], v[120:123], v[194:197], v[16:19]
	v_mfma_f32_16x16x32_bf16 v[8:11], v[124:127], v[52:55], v[8:11]
	v_mfma_f32_16x16x32_bf16 v[12:15], v[174:177], v[52:55], v[12:15]
	v_mfma_f32_16x16x32_bf16 v[186:189], v[174:177], v[190:193], v[24:27]
	v_mfma_f32_16x16x32_bf16 v[190:193], v[124:127], v[198:201], v[16:19]
	v_mfma_f32_16x16x32_bf16 v[16:19], v[170:173], v[194:197], v[20:23]
	v_mfma_f32_16x16x32_bf16 v[170:173], v[174:177], v[198:201], v[16:19]
	s_setprio 0
	s_barrier
	ds_read_b128 v[104:107], v143
	ds_read_b128 v[108:111], v143 offset:1024
	ds_read_b128 v[174:177], v143 offset:2048
	ds_read_b128 v[194:197], v143 offset:3072
	ds_read_b128 v[198:201], v144
	ds_read_b128 v[222:225], v144 offset:1024
	ds_read_b128 v[226:229], v144 offset:2048
	ds_read_b128 v[230:233], v144 offset:3072
	s_add_u32 s30, s38, 0x10000
	s_addc_u32 s31, s39, 0
	s_mov_b32 m0, s51
	v_lshl_add_u64 v[16:17], s[30:31], 0, v[134:135]
	ds_read_b128 v[24:27], v142 offset:32768
	ds_read_b128 v[28:31], v142 offset:33792
	ds_read_b128 v[60:63], v142 offset:34816
	ds_read_b128 v[100:103], v142 offset:35840
	ds_read_b128 v[234:237], v142 offset:36864
	ds_read_b128 v[238:241], v142 offset:37888
	ds_read_b128 v[242:245], v142 offset:38912
	ds_read_b128 v[246:249], v142 offset:39936
	global_load_lds_dwordx4 v[16:17], off
	v_lshl_add_u64 v[16:17], s[30:31], 0, v[130:131]
	s_mov_b32 m0, s54
	s_nop 0
	global_load_lds_dwordx4 v[16:17], off
	s_waitcnt vmcnt(8)
	s_barrier
; #define PG8_STAGE(bufoff, gbase, voff) do { _Pragma("unroll") for (int _i = 0; _i < 2; ++_i) \
;         __builtin_amdgcn_global_load_lds((const unsigned*)((const char*)(gbase) + (voff)[_i]), (LAS unsigned*)(lds + (bufoff) + ldsw + _i * 8192), 16, 0, 0); } while (0)
; #define PG8_LDA(dst, b, h) do { _Pragma("unroll") for (int m = 0; m < 4; ++m) _Pragma("unroll") for (int k = 0; k < 2; ++k) dst[m][k] = *(const LAS bf16x8*)(lds + PG8_SA(b, h) + aoff + m * 2048 + k * 1024); } while (0)
; #define PG8_LDB(dst, b, h) do { _Pragma("unroll") for (int n = 0; n < 2; ++n) _Pragma("unroll") for (int k = 0; k < 2; ++k) dst[n][k] = *(const LAS bf16x8*)(lds + PG8_SB(b, h) + boff + n * 2048 + k * 1024); } while (0)
; #define PG8_MMA(ai, bj, At, Bt) do { __builtin_amdgcn_s_setprio(1); _Pragma("unroll") for (int m = 0; m < 4; ++m) _Pragma("unroll") for (int n = 0; n < 2; ++n) _Pragma("unroll") for (int k = 0; k < 2; ++k) \
;         acc[ai][bj][m][n] = __builtin_amdgcn_mfma_f32_16x16x32_bf16(Bt[n][k], At[m][k], acc[ai][bj][m][n], 0, 0, 0); __builtin_amdgcn_s_setprio(0); } while (0)
; #define PG8_WAIT_V(n) asm volatile("s_waitcnt vmcnt(" #n ")" ::: "memory")
; #define PG8_BAR __builtin_amdgcn_s_barrier()
; template <class Epi, bool ALIGN_EPI, int K, int LDA, int LDB>
; __device__ __forceinline__ void gemm_phase(LAS unsigned char* lds, const int wid, const Gemm g, const StaticOrder& S, const Epi& E) {
;     ...
;             PG8_WAIT_V(8); PG8_WAIT_L(0); PG8_BAR; PG8_MMA(0, 0, At, B0); PG8_MMA(0, 1, At, B1); PG8_BAR; PG8_SCHED;
;             PG8_LDA(At, 0, 1); PG8_STAGE(PG8_SB(0, 0), b2, voffB); PG8_STAGE(PG8_SB(0, 1), b2 + hB, voffB); PG8_STAGE(PG8_SA(0, 0), a2, voffA);
;             PG8_WAIT_V(8); PG8_WAIT_L(0); PG8_BAR; PG8_MMA(1, 0, At, B0); PG8_MMA(1, 1, At, B1); PG8_BAR; PG8_SCHED;
;             PG8_LDB(B0, 1, 0); PG8_LDB(B1, 1, 1); PG8_SCHED; PG8_LDA(At, 1, 0); PG8_STAGE(PG8_SA(0, 1), a2 + hA, voffA);
;             PG8_WAIT_V(8); PG8_WAIT_L(0); PG8_BAR; PG8_MMA(0, 0, At, B0); PG8_MMA(0, 1, At, B1); PG8_BAR; PG8_SCHED;
;             PG8_LDA(At, 1, 1); PG8_STAGE(PG8_SB(1, 0), b3, voffB); PG8_STAGE(PG8_SB(1, 1), b3 + hB, voffB); PG8_STAGE(PG8_SA(1, 0), a3, voffA);
;             PG8_WAIT_V(8); PG8_WAIT_L(0); PG8_BAR; PG8_MMA(1, 0, At, B0); PG8_MMA(1, 1, At, B1); PG8_BAR; PG8_SCHED;
;         }
;         if constexpr (ALIGN_EPI) { if (wr == 0) PG8_BAR; }
	s_setprio 1
	s_waitcnt lgkmcnt(0)
	v_mfma_f32_16x16x32_bf16 v[16:19], v[104:107], v[24:27], v[64:67]
	v_mfma_f32_16x16x32_bf16 v[112:115], v[108:111], v[28:31], v[16:19]
	v_mfma_f32_16x16x32_bf16 v[16:19], v[174:177], v[24:27], v[68:71]
	v_mfma_f32_16x16x32_bf16 v[116:119], v[194:197], v[28:31], v[16:19]
	v_mfma_f32_16x16x32_bf16 v[16:19], v[104:107], v[60:63], v[72:75]
	v_mfma_f32_16x16x32_bf16 v[80:83], v[108:111], v[100:103], v[16:19]
	v_mfma_f32_16x16x32_bf16 v[16:19], v[174:177], v[60:63], v[76:79]
	v_mfma_f32_16x16x32_bf16 v[84:87], v[194:197], v[100:103], v[16:19]
	v_mfma_f32_16x16x32_bf16 v[16:19], v[104:107], v[234:237], v[210:213]
	v_mfma_f32_16x16x32_bf16 v[48:51], v[108:111], v[238:241], v[16:19]
	v_mfma_f32_16x16x32_bf16 v[16:19], v[174:177], v[234:237], v[214:217]
	v_mfma_f32_16x16x32_bf16 v[52:55], v[194:197], v[238:241], v[16:19]
	v_mfma_f32_16x16x32_bf16 v[16:19], v[104:107], v[242:245], v[88:91]
	v_mfma_f32_16x16x32_bf16 v[20:23], v[174:177], v[242:245], v[92:95]
	v_mfma_f32_16x16x32_bf16 v[16:19], v[108:111], v[246:249], v[16:19]
	v_mfma_f32_16x16x32_bf16 v[20:23], v[194:197], v[246:249], v[20:23]
	v_mfma_f32_16x16x32_bf16 v[64:67], v[198:201], v[24:27], v[96:99]
	v_mfma_f32_16x16x32_bf16 v[24:27], v[226:229], v[24:27], v[32:35]
	v_mfma_f32_16x16x32_bf16 v[124:127], v[230:233], v[28:31], v[24:27]
	v_mfma_f32_16x16x32_bf16 v[24:27], v[198:201], v[60:63], v[36:39]
	v_mfma_f32_16x16x32_bf16 v[96:99], v[222:225], v[100:103], v[24:27]
	v_mfma_f32_16x16x32_bf16 v[24:27], v[226:229], v[60:63], v[40:43]
	v_mfma_f32_16x16x32_bf16 v[100:103], v[230:233], v[100:103], v[24:27]
	v_mfma_f32_16x16x32_bf16 v[24:27], v[198:201], v[234:237], v[44:47]
	v_mfma_f32_16x16x32_bf16 v[120:123], v[222:225], v[28:31], v[64:67]
	v_mfma_f32_16x16x32_bf16 v[64:67], v[222:225], v[238:241], v[24:27]
	v_mfma_f32_16x16x32_bf16 v[24:27], v[226:229], v[234:237], v[178:181]
	v_mfma_f32_16x16x32_bf16 v[68:71], v[230:233], v[238:241], v[24:27]
	v_mfma_f32_16x16x32_bf16 v[24:27], v[198:201], v[242:245], v[182:185]
	v_mfma_f32_16x16x32_bf16 v[32:35], v[222:225], v[246:249], v[24:27]
	v_mfma_f32_16x16x32_bf16 v[24:27], v[226:229], v[242:245], v[56:59]
	v_mfma_f32_16x16x32_bf16 v[36:39], v[230:233], v[246:249], v[24:27]
	s_setprio 0
	s_barrier
	s_mov_b32 m0, s65
	s_nop 3
	v_lshl_add_u64 v[24:25], v[250:251], 0, s[10:11]
	s_add_u32 s30, s36, 0x10080
	ds_read_b128 v[40:43], v142 offset:49152
	ds_read_b128 v[44:47], v142 offset:50176
	ds_read_b128 v[76:79], v142 offset:51200
	ds_read_b128 v[178:181], v142 offset:52224
	ds_read_b128 v[182:185], v142 offset:53248
	ds_read_b128 v[210:213], v142 offset:54272
	ds_read_b128 v[214:217], v142 offset:55296
	ds_read_b128 v[234:237], v142 offset:56320
	global_load_lds_dwordx4 v[24:25], off
	v_lshl_add_u64 v[24:25], v[252:253], 0, s[10:11]
	s_mov_b32 m0, s23
	s_addc_u32 s31, s37, 0
	global_load_lds_dwordx4 v[24:25], off
	v_lshl_add_u64 v[24:25], s[30:31], 0, v[132:133]
	s_mov_b32 m0, s25
	s_nop 0
	global_load_lds_dwordx4 v[24:25], off
	v_lshl_add_u64 v[24:25], s[30:31], 0, v[128:129]
	s_mov_b32 m0, s34
	s_nop 0
	global_load_lds_dwordx4 v[24:25], off
	v_lshl_add_u64 v[24:25], v[136:137], 0, s[10:11]
	s_mov_b32 m0, s55
	s_nop 0
	global_load_lds_dwordx4 v[24:25], off
	v_lshl_add_u64 v[24:25], v[138:139], 0, s[10:11]
	s_mov_b32 m0, s56
	s_nop 0
	global_load_lds_dwordx4 v[24:25], off
	s_waitcnt vmcnt(8)
	s_barrier
	s_setprio 1
	s_waitcnt lgkmcnt(0)
	v_mfma_f32_16x16x32_bf16 v[24:27], v[104:107], v[40:43], v[146:149]
	v_mfma_f32_16x16x32_bf16 v[88:91], v[108:111], v[44:47], v[24:27]
	v_mfma_f32_16x16x32_bf16 v[24:27], v[174:177], v[40:43], v[150:153]
	v_mfma_f32_16x16x32_bf16 v[92:95], v[194:197], v[44:47], v[24:27]
	v_mfma_f32_16x16x32_bf16 v[24:27], v[104:107], v[76:79], v[154:157]
	v_mfma_f32_16x16x32_bf16 v[56:59], v[108:111], v[178:181], v[24:27]
	v_mfma_f32_16x16x32_bf16 v[24:27], v[174:177], v[76:79], v[158:161]
	v_mfma_f32_16x16x32_bf16 v[60:63], v[194:197], v[178:181], v[24:27]
	v_mfma_f32_16x16x32_bf16 v[24:27], v[104:107], v[182:185], v[162:165]
	v_mfma_f32_16x16x32_bf16 v[28:31], v[174:177], v[182:185], v[166:169]
	v_mfma_f32_16x16x32_bf16 v[0:3], v[104:107], v[214:217], v[0:3]
	v_mfma_f32_16x16x32_bf16 v[4:7], v[174:177], v[214:217], v[4:7]
	v_mfma_f32_16x16x32_bf16 v[24:27], v[108:111], v[210:213], v[24:27]
	v_mfma_f32_16x16x32_bf16 v[28:31], v[194:197], v[210:213], v[28:31]
	v_mfma_f32_16x16x32_bf16 v[0:3], v[108:111], v[234:237], v[0:3]
	v_mfma_f32_16x16x32_bf16 v[4:7], v[194:197], v[234:237], v[4:7]
	v_mfma_f32_16x16x32_bf16 v[8:11], v[198:201], v[40:43], v[8:11]
	v_mfma_f32_16x16x32_bf16 v[104:107], v[222:225], v[44:47], v[8:11]
	v_mfma_f32_16x16x32_bf16 v[8:11], v[226:229], v[40:43], v[12:15]
	v_mfma_f32_16x16x32_bf16 v[108:111], v[230:233], v[44:47], v[8:11]
	v_mfma_f32_16x16x32_bf16 v[8:11], v[198:201], v[76:79], v[202:205]
	v_mfma_f32_16x16x32_bf16 v[72:75], v[222:225], v[178:181], v[8:11]
	v_mfma_f32_16x16x32_bf16 v[8:11], v[226:229], v[76:79], v[206:209]
	v_mfma_f32_16x16x32_bf16 v[76:79], v[230:233], v[178:181], v[8:11]
	v_mfma_f32_16x16x32_bf16 v[8:11], v[198:201], v[182:185], v[218:221]
	v_mfma_f32_16x16x32_bf16 v[40:43], v[222:225], v[210:213], v[8:11]
	v_mfma_f32_16x16x32_bf16 v[8:11], v[226:229], v[182:185], v[186:189]
	v_mfma_f32_16x16x32_bf16 v[44:47], v[230:233], v[210:213], v[8:11]
	v_mfma_f32_16x16x32_bf16 v[8:11], v[198:201], v[214:217], v[190:193]
	v_mfma_f32_16x16x32_bf16 v[12:15], v[226:229], v[214:217], v[170:173]
	v_mfma_f32_16x16x32_bf16 v[8:11], v[222:225], v[234:237], v[8:11]
	v_mfma_f32_16x16x32_bf16 v[12:15], v[230:233], v[234:237], v[12:15]
	s_setprio 0
	s_barrier
	s_andn2_b64 vcc, exec, s[12:13]
	s_cbranch_vccnz .LBB0_705
	s_barrier

; #define PG8_STAGE(bufoff, gbase, voff) do { _Pragma("unroll") for (int _i = 0; _i < 2; ++_i) \
;         __builtin_amdgcn_global_load_lds((const unsigned*)((const char*)(gbase) + (voff)[_i]), (LAS unsigned*)(lds + (bufoff) + ldsw + _i * 8192), 16, 0, 0); } while (0)
; #define PG8_LDA(dst, b, h) do { _Pragma("unroll") for (int m = 0; m < 4; ++m) _Pragma("unroll") for (int k = 0; k < 2; ++k) dst[m][k] = *(const LAS bf16x8*)(lds + PG8_SA(b, h) + aoff + m * 2048 + k * 1024); } while (0)
; #define PG8_WAIT_V(n) asm volatile("s_waitcnt vmcnt(" #n ")" ::: "memory")
; #define PG8_BAR __builtin_amdgcn_s_barrier()
; template <class Epi, bool ALIGN_EPI, int K, int LDA, int LDB>
; __device__ __forceinline__ void gemm_phase(LAS unsigned char* lds, const int wid, const Gemm g, const StaticOrder& S, const Epi& E) {
;     ...
;         const bool has_next = S.next(ui + 1, nxt);
;         const char* nA = has_next ? (const char*)g.A + (size_t)nxt.pm * tA : cA; const char* nB = has_next ? (const char*)g.Bt + (size_t)nxt.pn * tB : cB;
;         for (int t = 0; t < nt; t += 2) {
;             const bool last = (t == nt - 2);
;             const char* a1 = cA + (size_t)(t + 1) * kstep;
;             const char* a2 = last ? nA : cA + (size_t)(t + 2) * kstep; const char* b2 = last ? nB : cB + (size_t)(t + 2) * kstep;
;             const char* a3 = a2 + kstep; const char* b3 = b2 + kstep;
;             PG8_LDB(B0, 0, 0); PG8_LDB(B1, 0, 1); PG8_SCHED; PG8_LDA(At, 0, 0); PG8_STAGE(PG8_SA(1, 1), a1 + hA, voffA);
;             PG8_WAIT_V(8); PG8_WAIT_L(0); PG8_BAR; PG8_MMA(0, 0, At, B0); PG8_MMA(0, 1, At, B1); PG8_BAR; PG8_SCHED;
;             PG8_LDA(At, 0, 1); PG8_STAGE(PG8_SB(0, 0), b2, voffB); PG8_STAGE(PG8_SB(0, 1), b2 + hB, voffB); PG8_STAGE(PG8_SA(0, 0), a2, voffA);
;             PG8_WAIT_V(8); PG8_WAIT_L(0); PG8_BAR; PG8_MMA(1, 0, At, B0); PG8_MMA(1, 1, At, B1); PG8_BAR; PG8_SCHED;
;             PG8_LDB(B0, 1, 0); PG8_LDB(B1, 1, 1); PG8_SCHED; PG8_LDA(At, 1, 0); PG8_STAGE(PG8_SA(0, 1), a2 + hA, voffA);
;             PG8_WAIT_V(8); PG8_WAIT_L(0); PG8_BAR; PG8_MMA(0, 0, At, B0); PG8_MMA(0, 1, At, B1); PG8_BAR; PG8_SCHED;
;             PG8_LDA(At, 1, 1); PG8_STAGE(PG8_SB(1, 0), b3, voffB); PG8_STAGE(PG8_SB(1, 1), b3 + hB, voffB); PG8_STAGE(PG8_SA(1, 0), a3, voffA);
;             PG8_WAIT_V(8); PG8_WAIT_L(0); PG8_BAR; PG8_MMA(1, 0, At, B0); PG8_MMA(1, 1, At, B1); PG8_BAR; PG8_SCHED;
.LBB0_916:
	s_ashr_i32 s27, s26, 31
	s_lshl_b64 s[28:29], s[26:27], 19
	v_readlane_b32 s25, v254, 0
	s_add_u32 s28, s25, s28
	v_readlane_b32 s25, v254, 1
	s_addc_u32 s29, s25, s29
	s_and_b64 s[30:31], s[4:5], exec
	s_cselect_b32 s27, s29, s37
	s_cselect_b32 s63, s28, s36
	s_ashr_i32 s25, s24, 31
	s_lshl_b64 s[30:31], s[24:25], 19
	s_add_u32 s30, s1, s30
	s_addc_u32 s31, s3, s31
	s_and_b64 s[40:41], s[4:5], exec
	s_cselect_b32 s25, s31, s39
	s_cselect_b32 s64, s30, s38
	s_add_u32 s36, s36, 0x40080
	s_addc_u32 s37, s37, 0
	s_add_u32 s65, s38, 0x100
	s_addc_u32 s66, s39, 0
	s_mov_b32 s67, -2
	s_add_u32 s38, s36, 0xfffc0080
	s_addc_u32 s39, s37, -1
	s_cmp_eq_u32 s67, 12
	s_cselect_b32 s41, s27, s39
	s_cselect_b32 s40, s63, s38
	s_cselect_b32 s39, s25, s66
	s_cselect_b32 s38, s64, s65
	s_add_i32 m0, s35, 0xc000
	global_load_lds_dwordx4 v152, s[36:37]
	s_add_i32 m0, s35, 0xe000
	s_nop 0
	global_load_lds_dwordx4 v154, s[36:37]
	s_waitcnt vmcnt(8)
	s_barrier
	s_setprio 1
	s_waitcnt lgkmcnt(0)
	v_mfma_f32_16x16x32_bf16 v[124:127], v[128:131], v[182:185], 0
	v_mfma_f32_16x16x32_bf16 v[120:123], v[136:139], v[182:185], 0
	v_mfma_f32_16x16x32_bf16 v[108:111], v[128:131], v[190:193], 0
	v_mfma_f32_16x16x32_bf16 v[104:107], v[136:139], v[190:193], 0
	v_mfma_f32_16x16x32_bf16 v[92:95], v[128:131], v[198:201], 0
	v_mfma_f32_16x16x32_bf16 v[88:91], v[136:139], v[198:201], 0
	v_mfma_f32_16x16x32_bf16 v[76:79], v[128:131], v[206:209], 0
	v_mfma_f32_16x16x32_bf16 v[72:75], v[136:139], v[206:209], 0
	v_mfma_f32_16x16x32_bf16 v[124:127], v[132:135], v[186:189], v[124:127]
	v_mfma_f32_16x16x32_bf16 v[120:123], v[140:143], v[186:189], v[120:123]
	v_mfma_f32_16x16x32_bf16 v[108:111], v[132:135], v[194:197], v[108:111]
	v_mfma_f32_16x16x32_bf16 v[104:107], v[140:143], v[194:197], v[104:107]
	v_mfma_f32_16x16x32_bf16 v[92:95], v[132:135], v[202:205], v[92:95]
	v_mfma_f32_16x16x32_bf16 v[88:91], v[140:143], v[202:205], v[88:91]
	v_mfma_f32_16x16x32_bf16 v[76:79], v[132:135], v[210:213], v[76:79]
	v_mfma_f32_16x16x32_bf16 v[72:75], v[140:143], v[210:213], v[72:75]
	v_mfma_f32_16x16x32_bf16 v[116:119], v[166:169], v[182:185], 0
	v_mfma_f32_16x16x32_bf16 v[112:115], v[174:177], v[182:185], 0
	v_mfma_f32_16x16x32_bf16 v[100:103], v[166:169], v[190:193], 0
	v_mfma_f32_16x16x32_bf16 v[96:99], v[174:177], v[190:193], 0
	v_mfma_f32_16x16x32_bf16 v[84:87], v[166:169], v[198:201], 0
	v_mfma_f32_16x16x32_bf16 v[80:83], v[174:177], v[198:201], 0
	v_mfma_f32_16x16x32_bf16 v[68:71], v[166:169], v[206:209], 0
	v_mfma_f32_16x16x32_bf16 v[64:67], v[174:177], v[206:209], 0
	v_mfma_f32_16x16x32_bf16 v[116:119], v[170:173], v[186:189], v[116:119]
	v_mfma_f32_16x16x32_bf16 v[112:115], v[178:181], v[186:189], v[112:115]
	v_mfma_f32_16x16x32_bf16 v[100:103], v[170:173], v[194:197], v[100:103]
	v_mfma_f32_16x16x32_bf16 v[96:99], v[178:181], v[194:197], v[96:99]
	v_mfma_f32_16x16x32_bf16 v[84:87], v[170:173], v[202:205], v[84:87]
	v_mfma_f32_16x16x32_bf16 v[80:83], v[178:181], v[202:205], v[80:83]
	v_mfma_f32_16x16x32_bf16 v[68:71], v[170:173], v[210:213], v[68:71]
	v_mfma_f32_16x16x32_bf16 v[64:67], v[178:181], v[210:213], v[64:67]
	s_setprio 0
	s_barrier
	s_add_u32 s98, s38, s12
	s_addc_u32 s99, s39, s13
	s_add_u32 s100, s40, s12
	s_addc_u32 s101, s41, s13
	s_add_i32 s52, s58, s33
	s_mov_b32 m0, s52
	ds_read_b128 v[182:185], v165 offset:16384
	ds_read_b128 v[186:189], v165 offset:17408
	ds_read_b128 v[190:193], v165 offset:18432
	ds_read_b128 v[194:197], v165 offset:19456
	ds_read_b128 v[198:201], v165 offset:20480
	ds_read_b128 v[202:205], v165 offset:21504
	ds_read_b128 v[206:209], v165 offset:22528
	ds_read_b128 v[210:213], v165 offset:23552
	global_load_lds_dwordx4 v146, s[38:39]
	s_add_i32 m0, s52, 0x2000
	s_add_u32 s68, s38, 0x40000
	s_addc_u32 s69, s39, 0
	s_add_i32 s52, s59, s33
	global_load_lds_dwordx4 v150, s[38:39]
	s_mov_b32 m0, s52
	s_nop 0
	global_load_lds_dwordx4 v146, s[68:69]
	s_add_i32 m0, s52, 0x2000
	s_nop 0
	global_load_lds_dwordx4 v150, s[68:69]
	s_mov_b32 m0, s35
	s_nop 0
	global_load_lds_dwordx4 v144, s[40:41]
	s_mov_b32 m0, s42
	s_nop 0
	global_load_lds_dwordx4 v148, s[40:41]
	s_waitcnt vmcnt(8)
	s_barrier
	s_setprio 1
	s_waitcnt lgkmcnt(0)
	v_mfma_f32_16x16x32_bf16 v[60:63], v[128:131], v[182:185], 0
	v_mfma_f32_16x16x32_bf16 v[56:59], v[136:139], v[182:185], 0
	v_mfma_f32_16x16x32_bf16 v[44:47], v[128:131], v[190:193], 0
	v_mfma_f32_16x16x32_bf16 v[40:43], v[136:139], v[190:193], 0
	v_mfma_f32_16x16x32_bf16 v[28:31], v[128:131], v[198:201], 0
	v_mfma_f32_16x16x32_bf16 v[24:27], v[136:139], v[198:201], 0
	v_mfma_f32_16x16x32_bf16 v[12:15], v[128:131], v[206:209], 0
	v_mfma_f32_16x16x32_bf16 v[8:11], v[136:139], v[206:209], 0
	v_mfma_f32_16x16x32_bf16 v[60:63], v[132:135], v[186:189], v[60:63]
	v_mfma_f32_16x16x32_bf16 v[56:59], v[140:143], v[186:189], v[56:59]
	v_mfma_f32_16x16x32_bf16 v[44:47], v[132:135], v[194:197], v[44:47]
	v_mfma_f32_16x16x32_bf16 v[40:43], v[140:143], v[194:197], v[40:43]
	v_mfma_f32_16x16x32_bf16 v[28:31], v[132:135], v[202:205], v[28:31]
	v_mfma_f32_16x16x32_bf16 v[24:27], v[140:143], v[202:205], v[24:27]
	v_mfma_f32_16x16x32_bf16 v[12:15], v[132:135], v[210:213], v[12:15]
	v_mfma_f32_16x16x32_bf16 v[8:11], v[140:143], v[210:213], v[8:11]
	v_mfma_f32_16x16x32_bf16 v[52:55], v[166:169], v[182:185], 0
	v_mfma_f32_16x16x32_bf16 v[48:51], v[174:177], v[182:185], 0
	v_mfma_f32_16x16x32_bf16 v[36:39], v[166:169], v[190:193], 0
	v_mfma_f32_16x16x32_bf16 v[32:35], v[174:177], v[190:193], 0
	v_mfma_f32_16x16x32_bf16 v[20:23], v[166:169], v[198:201], 0
	v_mfma_f32_16x16x32_bf16 v[16:19], v[174:177], v[198:201], 0
	v_mfma_f32_16x16x32_bf16 v[4:7], v[166:169], v[206:209], 0
	v_mfma_f32_16x16x32_bf16 v[0:3], v[174:177], v[206:209], 0
	v_mfma_f32_16x16x32_bf16 v[52:55], v[170:173], v[186:189], v[52:55]
	v_mfma_f32_16x16x32_bf16 v[48:51], v[178:181], v[186:189], v[48:51]
	v_mfma_f32_16x16x32_bf16 v[36:39], v[170:173], v[194:197], v[36:39]
	v_mfma_f32_16x16x32_bf16 v[32:35], v[178:181], v[194:197], v[32:35]
	v_mfma_f32_16x16x32_bf16 v[20:23], v[170:173], v[202:205], v[20:23]
	v_mfma_f32_16x16x32_bf16 v[16:19], v[178:181], v[202:205], v[16:19]
	v_mfma_f32_16x16x32_bf16 v[4:7], v[170:173], v[210:213], v[4:7]
	v_mfma_f32_16x16x32_bf16 v[0:3], v[178:181], v[210:213], v[0:3]
	s_setprio 0
	s_barrier
; #define PG8_STAGE(bufoff, gbase, voff) do { _Pragma("unroll") for (int _i = 0; _i < 2; ++_i) \
;         __builtin_amdgcn_global_load_lds((const unsigned*)((const char*)(gbase) + (voff)[_i]), (LAS unsigned*)(lds + (bufoff) + ldsw + _i * 8192), 16, 0, 0); } while (0)
; #define PG8_LDA(dst, b, h) do { _Pragma("unroll") for (int m = 0; m < 4; ++m) _Pragma("unroll") for (int k = 0; k < 2; ++k) dst[m][k] = *(const LAS bf16x8*)(lds + PG8_SA(b, h) + aoff + m * 2048 + k * 1024); } while (0)
; #define PG8_LDB(dst, b, h) do { _Pragma("unroll") for (int n = 0; n < 2; ++n) _Pragma("unroll") for (int k = 0; k < 2; ++k) dst[n][k] = *(const LAS bf16x8*)(lds + PG8_SB(b, h) + boff + n * 2048 + k * 1024); } while (0)
; #define PG8_MMA(ai, bj, At, Bt) do { __builtin_amdgcn_s_setprio(1); _Pragma("unroll") for (int m = 0; m < 4; ++m) _Pragma("unroll") for (int n = 0; n < 2; ++n) _Pragma("unroll") for (int k = 0; k < 2; ++k) \
;         acc[ai][bj][m][n] = __builtin_amdgcn_mfma_f32_16x16x32_bf16(Bt[n][k], At[m][k], acc[ai][bj][m][n], 0, 0, 0); __builtin_amdgcn_s_setprio(0); } while (0)
; #define PG8_WAIT_V(n) asm volatile("s_waitcnt vmcnt(" #n ")" ::: "memory")
; #define PG8_WAIT_L(n) asm volatile("s_waitcnt lgkmcnt(" #n ")" ::: "memory")
; #define PG8_BAR __builtin_amdgcn_s_barrier()
; #define PG8_SCHED __builtin_amdgcn_sched_barrier(0)
; template <class Epi, bool ALIGN_EPI, int K, int LDA, int LDB>
; __device__ __forceinline__ void gemm_phase(LAS unsigned char* lds, const int wid, const Gemm g, const StaticOrder& S, const Epi& E) {
;     ...
;             PG8_LDB(B0, 1, 0); PG8_LDB(B1, 1, 1); PG8_SCHED; PG8_LDA(At, 1, 0); PG8_STAGE(PG8_SA(0, 1), a2 + hA, voffA);
;             PG8_WAIT_V(8); PG8_WAIT_L(0); PG8_BAR; PG8_MMA(0, 0, At, B0); PG8_MMA(0, 1, At, B1); PG8_BAR; PG8_SCHED;
;             PG8_LDA(At, 1, 1); PG8_STAGE(PG8_SB(1, 0), b3, voffB); PG8_STAGE(PG8_SB(1, 1), b3 + hB, voffB); PG8_STAGE(PG8_SA(1, 0), a3, voffA);
;             PG8_WAIT_V(8); PG8_WAIT_L(0); PG8_BAR; PG8_MMA(1, 0, At, B0); PG8_MMA(1, 1, At, B1); PG8_BAR; PG8_SCHED;
	s_add_i32 s52, 0, 0x18000
	s_add_i32 s53, 0, 0x1c000
	v_add_u32_e32 v140, s52, v162
	v_add_u32_e32 v178, s53, v162
	ds_read_b128 v[128:131], v140
	ds_read_b128 v[132:135], v140 offset:1024
	ds_read_b128 v[136:139], v140 offset:2048
	ds_read_b128 v[140:143], v140 offset:3072
	ds_read_b128 v[166:169], v178
	ds_read_b128 v[170:173], v178 offset:1024
	ds_read_b128 v[174:177], v178 offset:2048
	ds_read_b128 v[178:181], v178 offset:3072
	s_add_u32 s40, s40, 0x40000
	s_addc_u32 s41, s41, 0
	s_mov_b32 m0, s43
	ds_read_b128 v[182:185], v165 offset:32768
	ds_read_b128 v[186:189], v165 offset:33792
	ds_read_b128 v[190:193], v165 offset:34816
	ds_read_b128 v[194:197], v165 offset:35840
	ds_read_b128 v[198:201], v165 offset:36864
	ds_read_b128 v[202:205], v165 offset:37888
	ds_read_b128 v[206:209], v165 offset:38912
	ds_read_b128 v[210:213], v165 offset:39936
	global_load_lds_dwordx4 v144, s[40:41]
	s_mov_b32 m0, s48
	s_nop 0
	global_load_lds_dwordx4 v148, s[40:41]
	s_waitcnt vmcnt(8)
	s_barrier
	s_setprio 1
	s_waitcnt lgkmcnt(0)
	v_mfma_f32_16x16x32_bf16 v[124:127], v[128:131], v[182:185], v[124:127]
	v_mfma_f32_16x16x32_bf16 v[120:123], v[136:139], v[182:185], v[120:123]
	v_mfma_f32_16x16x32_bf16 v[108:111], v[128:131], v[190:193], v[108:111]
	v_mfma_f32_16x16x32_bf16 v[104:107], v[136:139], v[190:193], v[104:107]
	v_mfma_f32_16x16x32_bf16 v[92:95], v[128:131], v[198:201], v[92:95]
	v_mfma_f32_16x16x32_bf16 v[88:91], v[136:139], v[198:201], v[88:91]
	v_mfma_f32_16x16x32_bf16 v[76:79], v[128:131], v[206:209], v[76:79]
	v_mfma_f32_16x16x32_bf16 v[72:75], v[136:139], v[206:209], v[72:75]
	v_mfma_f32_16x16x32_bf16 v[124:127], v[132:135], v[186:189], v[124:127]
	v_mfma_f32_16x16x32_bf16 v[120:123], v[140:143], v[186:189], v[120:123]
	v_mfma_f32_16x16x32_bf16 v[108:111], v[132:135], v[194:197], v[108:111]
	v_mfma_f32_16x16x32_bf16 v[104:107], v[140:143], v[194:197], v[104:107]
	v_mfma_f32_16x16x32_bf16 v[92:95], v[132:135], v[202:205], v[92:95]
	v_mfma_f32_16x16x32_bf16 v[88:91], v[140:143], v[202:205], v[88:91]
	v_mfma_f32_16x16x32_bf16 v[76:79], v[132:135], v[210:213], v[76:79]
	v_mfma_f32_16x16x32_bf16 v[72:75], v[140:143], v[210:213], v[72:75]
	v_mfma_f32_16x16x32_bf16 v[116:119], v[166:169], v[182:185], v[116:119]
	v_mfma_f32_16x16x32_bf16 v[112:115], v[174:177], v[182:185], v[112:115]
	v_mfma_f32_16x16x32_bf16 v[100:103], v[166:169], v[190:193], v[100:103]
	v_mfma_f32_16x16x32_bf16 v[96:99], v[174:177], v[190:193], v[96:99]
	v_mfma_f32_16x16x32_bf16 v[84:87], v[166:169], v[198:201], v[84:87]
	v_mfma_f32_16x16x32_bf16 v[80:83], v[174:177], v[198:201], v[80:83]
	v_mfma_f32_16x16x32_bf16 v[68:71], v[166:169], v[206:209], v[68:71]
	v_mfma_f32_16x16x32_bf16 v[64:67], v[174:177], v[206:209], v[64:67]
	v_mfma_f32_16x16x32_bf16 v[116:119], v[170:173], v[186:189], v[116:119]
	v_mfma_f32_16x16x32_bf16 v[112:115], v[178:181], v[186:189], v[112:115]
	v_mfma_f32_16x16x32_bf16 v[100:103], v[170:173], v[194:197], v[100:103]
	v_mfma_f32_16x16x32_bf16 v[96:99], v[178:181], v[194:197], v[96:99]
	v_mfma_f32_16x16x32_bf16 v[84:87], v[170:173], v[202:205], v[84:87]
	v_mfma_f32_16x16x32_bf16 v[80:83], v[178:181], v[202:205], v[80:83]
	v_mfma_f32_16x16x32_bf16 v[68:71], v[170:173], v[210:213], v[68:71]
	v_mfma_f32_16x16x32_bf16 v[64:67], v[178:181], v[210:213], v[64:67]
	s_setprio 0
	s_barrier
	s_add_i32 s40, s52, s33
	s_mov_b32 m0, s40
	ds_read_b128 v[182:185], v165 offset:49152
	ds_read_b128 v[186:189], v165 offset:50176
	ds_read_b128 v[190:193], v165 offset:51200
	ds_read_b128 v[194:197], v165 offset:52224
	ds_read_b128 v[198:201], v165 offset:53248
	ds_read_b128 v[202:205], v165 offset:54272
	ds_read_b128 v[206:209], v165 offset:55296
	ds_read_b128 v[210:213], v165 offset:56320
	global_load_lds_dwordx4 v146, s[98:99]
	s_add_i32 m0, s40, 0x2000
	s_add_u32 s38, s38, 0x40080
	s_addc_u32 s39, s39, 0
	s_add_i32 s40, s53, s33
	global_load_lds_dwordx4 v150, s[98:99]
	s_mov_b32 m0, s40
	s_nop 0
	global_load_lds_dwordx4 v146, s[38:39]
	s_add_i32 m0, s40, 0x2000
	s_nop 0
	global_load_lds_dwordx4 v150, s[38:39]
	s_mov_b32 m0, s55
	s_nop 0
	global_load_lds_dwordx4 v144, s[100:101]
	s_mov_b32 m0, s56
	s_nop 0
	global_load_lds_dwordx4 v148, s[100:101]
	s_waitcnt vmcnt(8)
	s_barrier
	s_setprio 1
	s_waitcnt lgkmcnt(0)
	v_mfma_f32_16x16x32_bf16 v[60:63], v[128:131], v[182:185], v[60:63]
	v_mfma_f32_16x16x32_bf16 v[56:59], v[136:139], v[182:185], v[56:59]
	v_mfma_f32_16x16x32_bf16 v[44:47], v[128:131], v[190:193], v[44:47]
	v_mfma_f32_16x16x32_bf16 v[40:43], v[136:139], v[190:193], v[40:43]
	v_mfma_f32_16x16x32_bf16 v[28:31], v[128:131], v[198:201], v[28:31]
	v_mfma_f32_16x16x32_bf16 v[24:27], v[136:139], v[198:201], v[24:27]
	v_mfma_f32_16x16x32_bf16 v[12:15], v[128:131], v[206:209], v[12:15]
	v_mfma_f32_16x16x32_bf16 v[8:11], v[136:139], v[206:209], v[8:11]
	v_mfma_f32_16x16x32_bf16 v[60:63], v[132:135], v[186:189], v[60:63]
	v_mfma_f32_16x16x32_bf16 v[56:59], v[140:143], v[186:189], v[56:59]
	v_mfma_f32_16x16x32_bf16 v[44:47], v[132:135], v[194:197], v[44:47]
	v_mfma_f32_16x16x32_bf16 v[40:43], v[140:143], v[194:197], v[40:43]
	v_mfma_f32_16x16x32_bf16 v[28:31], v[132:135], v[202:205], v[28:31]
	v_mfma_f32_16x16x32_bf16 v[24:27], v[140:143], v[202:205], v[24:27]
	v_mfma_f32_16x16x32_bf16 v[12:15], v[132:135], v[210:213], v[12:15]
	v_mfma_f32_16x16x32_bf16 v[8:11], v[140:143], v[210:213], v[8:11]
	v_mfma_f32_16x16x32_bf16 v[52:55], v[166:169], v[182:185], v[52:55]
	v_mfma_f32_16x16x32_bf16 v[48:51], v[174:177], v[182:185], v[48:51]
	v_mfma_f32_16x16x32_bf16 v[36:39], v[166:169], v[190:193], v[36:39]
	v_mfma_f32_16x16x32_bf16 v[32:35], v[174:177], v[190:193], v[32:35]
	v_mfma_f32_16x16x32_bf16 v[20:23], v[166:169], v[198:201], v[20:23]
	v_mfma_f32_16x16x32_bf16 v[16:19], v[174:177], v[198:201], v[16:19]
	v_mfma_f32_16x16x32_bf16 v[4:7], v[166:169], v[206:209], v[4:7]
	v_mfma_f32_16x16x32_bf16 v[0:3], v[174:177], v[206:209], v[0:3]
	v_mfma_f32_16x16x32_bf16 v[52:55], v[170:173], v[186:189], v[52:55]
	v_mfma_f32_16x16x32_bf16 v[48:51], v[178:181], v[186:189], v[48:51]
	v_mfma_f32_16x16x32_bf16 v[36:39], v[170:173], v[194:197], v[36:39]
	v_mfma_f32_16x16x32_bf16 v[32:35], v[178:181], v[194:197], v[32:35]
	v_mfma_f32_16x16x32_bf16 v[20:23], v[170:173], v[202:205], v[20:23]
	v_mfma_f32_16x16x32_bf16 v[16:19], v[178:181], v[202:205], v[16:19]
	v_mfma_f32_16x16x32_bf16 v[4:7], v[170:173], v[210:213], v[4:7]
	v_mfma_f32_16x16x32_bf16 v[0:3], v[178:181], v[210:213], v[0:3]
	s_setprio 0
	s_barrier
	s_add_i32 s67, s67, 2
	s_add_u32 s36, s36, 0x100
	s_addc_u32 s37, s37, 0
	s_add_u32 s65, s65, 0x100
	s_addc_u32 s66, s66, 0
; #define PG8_STAGE(bufoff, gbase, voff) do { _Pragma("unroll") for (int _i = 0; _i < 2; ++_i) \
;         __builtin_amdgcn_global_load_lds((const unsigned*)((const char*)(gbase) + (voff)[_i]), (LAS unsigned*)(lds + (bufoff) + ldsw + _i * 8192), 16, 0, 0); } while (0)
; #define PG8_LDA(dst, b, h) do { _Pragma("unroll") for (int m = 0; m < 4; ++m) _Pragma("unroll") for (int k = 0; k < 2; ++k) dst[m][k] = *(const LAS bf16x8*)(lds + PG8_SA(b, h) + aoff + m * 2048 + k * 1024); } while (0)
; #define PG8_LDB(dst, b, h) do { _Pragma("unroll") for (int n = 0; n < 2; ++n) _Pragma("unroll") for (int k = 0; k < 2; ++k) dst[n][k] = *(const LAS bf16x8*)(lds + PG8_SB(b, h) + boff + n * 2048 + k * 1024); } while (0)
; #define PG8_MMA(ai, bj, At, Bt) do { __builtin_amdgcn_s_setprio(1); _Pragma("unroll") for (int m = 0; m < 4; ++m) _Pragma("unroll") for (int n = 0; n < 2; ++n) _Pragma("unroll") for (int k = 0; k < 2; ++k) \
;         acc[ai][bj][m][n] = __builtin_amdgcn_mfma_f32_16x16x32_bf16(Bt[n][k], At[m][k], acc[ai][bj][m][n], 0, 0, 0); __builtin_amdgcn_s_setprio(0); } while (0)
; #define PG8_WAIT_V(n) asm volatile("s_waitcnt vmcnt(" #n ")" ::: "memory")
; #define PG8_WAIT_L(n) asm volatile("s_waitcnt lgkmcnt(" #n ")" ::: "memory")
; #define PG8_BAR __builtin_amdgcn_s_barrier()
; template <class Epi, bool ALIGN_EPI, int K, int LDA, int LDB>
; __device__ __forceinline__ void gemm_phase(LAS unsigned char* lds, const int wid, const Gemm g, const StaticOrder& S, const Epi& E) {
;     ...
;         for (int t = 0; t < nt; t += 2) {
;             const bool last = (t == nt - 2);
;             const char* a1 = cA + (size_t)(t + 1) * kstep;
;             const char* a2 = last ? nA : cA + (size_t)(t + 2) * kstep; const char* b2 = last ? nB : cB + (size_t)(t + 2) * kstep;
;             const char* a3 = a2 + kstep; const char* b3 = b2 + kstep;
;             PG8_LDB(B0, 0, 0); PG8_LDB(B1, 0, 1); PG8_SCHED; PG8_LDA(At, 0, 0); PG8_STAGE(PG8_SA(1, 1), a1 + hA, voffA);
;             PG8_WAIT_V(8); PG8_WAIT_L(0); PG8_BAR; PG8_MMA(0, 0, At, B0); PG8_MMA(0, 1, At, B1); PG8_BAR; PG8_SCHED;
;             PG8_LDA(At, 0, 1); PG8_STAGE(PG8_SB(0, 0), b2, voffB); PG8_STAGE(PG8_SB(0, 1), b2 + hB, voffB); PG8_STAGE(PG8_SA(0, 0), a2, voffA);
;             PG8_WAIT_V(8); PG8_WAIT_L(0); PG8_BAR; PG8_MMA(1, 0, At, B0); PG8_MMA(1, 1, At, B1); PG8_BAR; PG8_SCHED;
.LBB0_917:
	ds_read_b128 v[128:131], v163
	ds_read_b128 v[132:135], v163 offset:1024
	ds_read_b128 v[136:139], v163 offset:2048
	ds_read_b128 v[140:143], v163 offset:3072
	ds_read_b128 v[166:169], v164
	ds_read_b128 v[170:173], v164 offset:1024
	ds_read_b128 v[174:177], v164 offset:2048
	ds_read_b128 v[178:181], v164 offset:3072
	s_add_u32 s38, s36, 0xfffc0080
	s_addc_u32 s39, s37, -1
	s_cmp_eq_u32 s67, 12
	s_cselect_b32 s41, s27, s39
	s_cselect_b32 s40, s63, s38
	s_cselect_b32 s39, s25, s66
	s_cselect_b32 s38, s64, s65
	s_add_i32 m0, s35, 0xc000
	ds_read_b128 v[182:185], v165
	ds_read_b128 v[186:189], v165 offset:1024
	ds_read_b128 v[190:193], v165 offset:2048
	ds_read_b128 v[194:197], v165 offset:3072
	ds_read_b128 v[198:201], v165 offset:4096
	ds_read_b128 v[202:205], v165 offset:5120
	ds_read_b128 v[206:209], v165 offset:6144
	ds_read_b128 v[210:213], v165 offset:7168
	global_load_lds_dwordx4 v152, s[36:37]
	s_add_i32 m0, s35, 0xe000
	s_nop 0
	global_load_lds_dwordx4 v154, s[36:37]
	s_waitcnt vmcnt(8)
	s_barrier
	s_setprio 1
	s_waitcnt lgkmcnt(0)
	v_mfma_f32_16x16x32_bf16 v[124:127], v[128:131], v[182:185], v[124:127]
	v_mfma_f32_16x16x32_bf16 v[120:123], v[136:139], v[182:185], v[120:123]
	v_mfma_f32_16x16x32_bf16 v[108:111], v[128:131], v[190:193], v[108:111]
	v_mfma_f32_16x16x32_bf16 v[104:107], v[136:139], v[190:193], v[104:107]
	v_mfma_f32_16x16x32_bf16 v[92:95], v[128:131], v[198:201], v[92:95]
	v_mfma_f32_16x16x32_bf16 v[88:91], v[136:139], v[198:201], v[88:91]
	v_mfma_f32_16x16x32_bf16 v[76:79], v[128:131], v[206:209], v[76:79]
	v_mfma_f32_16x16x32_bf16 v[72:75], v[136:139], v[206:209], v[72:75]
	v_mfma_f32_16x16x32_bf16 v[124:127], v[132:135], v[186:189], v[124:127]
	v_mfma_f32_16x16x32_bf16 v[120:123], v[140:143], v[186:189], v[120:123]
	v_mfma_f32_16x16x32_bf16 v[108:111], v[132:135], v[194:197], v[108:111]
	v_mfma_f32_16x16x32_bf16 v[104:107], v[140:143], v[194:197], v[104:107]
	v_mfma_f32_16x16x32_bf16 v[92:95], v[132:135], v[202:205], v[92:95]
	v_mfma_f32_16x16x32_bf16 v[88:91], v[140:143], v[202:205], v[88:91]
	v_mfma_f32_16x16x32_bf16 v[76:79], v[132:135], v[210:213], v[76:79]
	v_mfma_f32_16x16x32_bf16 v[72:75], v[140:143], v[210:213], v[72:75]
	v_mfma_f32_16x16x32_bf16 v[116:119], v[166:169], v[182:185], v[116:119]
	v_mfma_f32_16x16x32_bf16 v[112:115], v[174:177], v[182:185], v[112:115]
	v_mfma_f32_16x16x32_bf16 v[100:103], v[166:169], v[190:193], v[100:103]
	v_mfma_f32_16x16x32_bf16 v[96:99], v[174:177], v[190:193], v[96:99]
	v_mfma_f32_16x16x32_bf16 v[84:87], v[166:169], v[198:201], v[84:87]
	v_mfma_f32_16x16x32_bf16 v[80:83], v[174:177], v[198:201], v[80:83]
	v_mfma_f32_16x16x32_bf16 v[68:71], v[166:169], v[206:209], v[68:71]
	v_mfma_f32_16x16x32_bf16 v[64:67], v[174:177], v[206:209], v[64:67]
	v_mfma_f32_16x16x32_bf16 v[116:119], v[170:173], v[186:189], v[116:119]
	v_mfma_f32_16x16x32_bf16 v[112:115], v[178:181], v[186:189], v[112:115]
	v_mfma_f32_16x16x32_bf16 v[100:103], v[170:173], v[194:197], v[100:103]
	v_mfma_f32_16x16x32_bf16 v[96:99], v[178:181], v[194:197], v[96:99]
	v_mfma_f32_16x16x32_bf16 v[84:87], v[170:173], v[202:205], v[84:87]
	v_mfma_f32_16x16x32_bf16 v[80:83], v[178:181], v[202:205], v[80:83]
	v_mfma_f32_16x16x32_bf16 v[68:71], v[170:173], v[210:213], v[68:71]
	v_mfma_f32_16x16x32_bf16 v[64:67], v[178:181], v[210:213], v[64:67]
	s_setprio 0
	s_barrier
	s_add_u32 s98, s38, s12
	s_addc_u32 s99, s39, s13
	s_add_u32 s100, s40, s12
	s_addc_u32 s101, s41, s13
	s_add_i32 s52, s58, s33
	s_mov_b32 m0, s52
	ds_read_b128 v[182:185], v165 offset:16384
	ds_read_b128 v[186:189], v165 offset:17408
	ds_read_b128 v[190:193], v165 offset:18432
	ds_read_b128 v[194:197], v165 offset:19456
	ds_read_b128 v[198:201], v165 offset:20480
	ds_read_b128 v[202:205], v165 offset:21504
	ds_read_b128 v[206:209], v165 offset:22528
	ds_read_b128 v[210:213], v165 offset:23552
	global_load_lds_dwordx4 v146, s[38:39]
	s_add_i32 m0, s52, 0x2000
	s_add_u32 s68, s38, 0x40000
	s_addc_u32 s69, s39, 0
	s_add_i32 s52, s59, s33
	global_load_lds_dwordx4 v150, s[38:39]
	s_mov_b32 m0, s52
	s_nop 0
	global_load_lds_dwordx4 v146, s[68:69]
	s_add_i32 m0, s52, 0x2000
	s_nop 0
	global_load_lds_dwordx4 v150, s[68:69]
	s_mov_b32 m0, s35
	s_nop 0
	global_load_lds_dwordx4 v144, s[40:41]
	s_mov_b32 m0, s42
	s_nop 0
	global_load_lds_dwordx4 v148, s[40:41]
	s_waitcnt vmcnt(8)
	s_barrier
	s_setprio 1
	s_waitcnt lgkmcnt(0)
	v_mfma_f32_16x16x32_bf16 v[60:63], v[128:131], v[182:185], v[60:63]
	v_mfma_f32_16x16x32_bf16 v[56:59], v[136:139], v[182:185], v[56:59]
	v_mfma_f32_16x16x32_bf16 v[44:47], v[128:131], v[190:193], v[44:47]
	v_mfma_f32_16x16x32_bf16 v[40:43], v[136:139], v[190:193], v[40:43]
	v_mfma_f32_16x16x32_bf16 v[28:31], v[128:131], v[198:201], v[28:31]
	v_mfma_f32_16x16x32_bf16 v[24:27], v[136:139], v[198:201], v[24:27]
	v_mfma_f32_16x16x32_bf16 v[12:15], v[128:131], v[206:209], v[12:15]
	v_mfma_f32_16x16x32_bf16 v[8:11], v[136:139], v[206:209], v[8:11]
	v_mfma_f32_16x16x32_bf16 v[60:63], v[132:135], v[186:189], v[60:63]
	v_mfma_f32_16x16x32_bf16 v[56:59], v[140:143], v[186:189], v[56:59]
	v_mfma_f32_16x16x32_bf16 v[44:47], v[132:135], v[194:197], v[44:47]
	v_mfma_f32_16x16x32_bf16 v[40:43], v[140:143], v[194:197], v[40:43]
	v_mfma_f32_16x16x32_bf16 v[28:31], v[132:135], v[202:205], v[28:31]
	v_mfma_f32_16x16x32_bf16 v[24:27], v[140:143], v[202:205], v[24:27]
	v_mfma_f32_16x16x32_bf16 v[12:15], v[132:135], v[210:213], v[12:15]
	v_mfma_f32_16x16x32_bf16 v[8:11], v[140:143], v[210:213], v[8:11]
	v_mfma_f32_16x16x32_bf16 v[52:55], v[166:169], v[182:185], v[52:55]
	v_mfma_f32_16x16x32_bf16 v[48:51], v[174:177], v[182:185], v[48:51]
	v_mfma_f32_16x16x32_bf16 v[36:39], v[166:169], v[190:193], v[36:39]
	v_mfma_f32_16x16x32_bf16 v[32:35], v[174:177], v[190:193], v[32:35]
	v_mfma_f32_16x16x32_bf16 v[20:23], v[166:169], v[198:201], v[20:23]
	v_mfma_f32_16x16x32_bf16 v[16:19], v[174:177], v[198:201], v[16:19]
	v_mfma_f32_16x16x32_bf16 v[4:7], v[166:169], v[206:209], v[4:7]
	v_mfma_f32_16x16x32_bf16 v[0:3], v[174:177], v[206:209], v[0:3]
	v_mfma_f32_16x16x32_bf16 v[52:55], v[170:173], v[186:189], v[52:55]
	v_mfma_f32_16x16x32_bf16 v[48:51], v[178:181], v[186:189], v[48:51]
	v_mfma_f32_16x16x32_bf16 v[36:39], v[170:173], v[194:197], v[36:39]
	v_mfma_f32_16x16x32_bf16 v[32:35], v[178:181], v[194:197], v[32:35]
	v_mfma_f32_16x16x32_bf16 v[20:23], v[170:173], v[202:205], v[20:23]
	v_mfma_f32_16x16x32_bf16 v[16:19], v[178:181], v[202:205], v[16:19]
	v_mfma_f32_16x16x32_bf16 v[4:7], v[170:173], v[210:213], v[4:7]
	v_mfma_f32_16x16x32_bf16 v[0:3], v[178:181], v[210:213], v[0:3]
	s_setprio 0
	s_barrier
; #define PG8_STAGE(bufoff, gbase, voff) do { _Pragma("unroll") for (int _i = 0; _i < 2; ++_i) \
;         __builtin_amdgcn_global_load_lds((const unsigned*)((const char*)(gbase) + (voff)[_i]), (LAS unsigned*)(lds + (bufoff) + ldsw + _i * 8192), 16, 0, 0); } while (0)
; #define PG8_LDA(dst, b, h) do { _Pragma("unroll") for (int m = 0; m < 4; ++m) _Pragma("unroll") for (int k = 0; k < 2; ++k) dst[m][k] = *(const LAS bf16x8*)(lds + PG8_SA(b, h) + aoff + m * 2048 + k * 1024); } while (0)
; #define PG8_LDB(dst, b, h) do { _Pragma("unroll") for (int n = 0; n < 2; ++n) _Pragma("unroll") for (int k = 0; k < 2; ++k) dst[n][k] = *(const LAS bf16x8*)(lds + PG8_SB(b, h) + boff + n * 2048 + k * 1024); } while (0)
; #define PG8_MMA(ai, bj, At, Bt) do { __builtin_amdgcn_s_setprio(1); _Pragma("unroll") for (int m = 0; m < 4; ++m) _Pragma("unroll") for (int n = 0; n < 2; ++n) _Pragma("unroll") for (int k = 0; k < 2; ++k) \
;         acc[ai][bj][m][n] = __builtin_amdgcn_mfma_f32_16x16x32_bf16(Bt[n][k], At[m][k], acc[ai][bj][m][n], 0, 0, 0); __builtin_amdgcn_s_setprio(0); } while (0)
; #define PG8_WAIT_V(n) asm volatile("s_waitcnt vmcnt(" #n ")" ::: "memory")
; #define PG8_WAIT_L(n) asm volatile("s_waitcnt lgkmcnt(" #n ")" ::: "memory")
; #define PG8_BAR __builtin_amdgcn_s_barrier()
; #define PG8_SCHED __builtin_amdgcn_sched_barrier(0)
; template <class Epi, bool ALIGN_EPI, int K, int LDA, int LDB>
; __device__ __forceinline__ void gemm_phase(LAS unsigned char* lds, const int wid, const Gemm g, const StaticOrder& S, const Epi& E) {
;     ...
;         for (int t = 0; t < nt; t += 2) {
;             const bool last = (t == nt - 2);
;     ...
;             PG8_LDB(B0, 1, 0); PG8_LDB(B1, 1, 1); PG8_SCHED; PG8_LDA(At, 1, 0); PG8_STAGE(PG8_SA(0, 1), a2 + hA, voffA);
;             PG8_WAIT_V(8); PG8_WAIT_L(0); PG8_BAR; PG8_MMA(0, 0, At, B0); PG8_MMA(0, 1, At, B1); PG8_BAR; PG8_SCHED;
;             PG8_LDA(At, 1, 1); PG8_STAGE(PG8_SB(1, 0), b3, voffB); PG8_STAGE(PG8_SB(1, 1), b3 + hB, voffB); PG8_STAGE(PG8_SA(1, 0), a3, voffA);
;             PG8_WAIT_V(8); PG8_WAIT_L(0); PG8_BAR; PG8_MMA(1, 0, At, B0); PG8_MMA(1, 1, At, B1); PG8_BAR; PG8_SCHED;
	s_add_i32 s52, 0, 0x18000
	s_add_i32 s53, 0, 0x1c000
	v_add_u32_e32 v140, s52, v162
	v_add_u32_e32 v178, s53, v162
	ds_read_b128 v[128:131], v140
	ds_read_b128 v[132:135], v140 offset:1024
	ds_read_b128 v[136:139], v140 offset:2048
	ds_read_b128 v[140:143], v140 offset:3072
	ds_read_b128 v[166:169], v178
	ds_read_b128 v[170:173], v178 offset:1024
	ds_read_b128 v[174:177], v178 offset:2048
	ds_read_b128 v[178:181], v178 offset:3072
	s_add_u32 s40, s40, 0x40000
	s_addc_u32 s41, s41, 0
	s_mov_b32 m0, s43
	ds_read_b128 v[182:185], v165 offset:32768
	ds_read_b128 v[186:189], v165 offset:33792
	ds_read_b128 v[190:193], v165 offset:34816
	ds_read_b128 v[194:197], v165 offset:35840
	ds_read_b128 v[198:201], v165 offset:36864
	ds_read_b128 v[202:205], v165 offset:37888
	ds_read_b128 v[206:209], v165 offset:38912
	ds_read_b128 v[210:213], v165 offset:39936
	global_load_lds_dwordx4 v144, s[40:41]
	s_mov_b32 m0, s48
	s_nop 0
	global_load_lds_dwordx4 v148, s[40:41]
	s_waitcnt vmcnt(8)
	s_barrier
	s_setprio 1
	s_waitcnt lgkmcnt(0)
	v_mfma_f32_16x16x32_bf16 v[124:127], v[128:131], v[182:185], v[124:127]
	v_mfma_f32_16x16x32_bf16 v[120:123], v[136:139], v[182:185], v[120:123]
	v_mfma_f32_16x16x32_bf16 v[108:111], v[128:131], v[190:193], v[108:111]
	v_mfma_f32_16x16x32_bf16 v[104:107], v[136:139], v[190:193], v[104:107]
	v_mfma_f32_16x16x32_bf16 v[92:95], v[128:131], v[198:201], v[92:95]
	v_mfma_f32_16x16x32_bf16 v[88:91], v[136:139], v[198:201], v[88:91]
	v_mfma_f32_16x16x32_bf16 v[76:79], v[128:131], v[206:209], v[76:79]
	v_mfma_f32_16x16x32_bf16 v[72:75], v[136:139], v[206:209], v[72:75]
	v_mfma_f32_16x16x32_bf16 v[124:127], v[132:135], v[186:189], v[124:127]
	v_mfma_f32_16x16x32_bf16 v[120:123], v[140:143], v[186:189], v[120:123]
	v_mfma_f32_16x16x32_bf16 v[108:111], v[132:135], v[194:197], v[108:111]
	v_mfma_f32_16x16x32_bf16 v[104:107], v[140:143], v[194:197], v[104:107]
	v_mfma_f32_16x16x32_bf16 v[92:95], v[132:135], v[202:205], v[92:95]
	v_mfma_f32_16x16x32_bf16 v[88:91], v[140:143], v[202:205], v[88:91]
	v_mfma_f32_16x16x32_bf16 v[76:79], v[132:135], v[210:213], v[76:79]
	v_mfma_f32_16x16x32_bf16 v[72:75], v[140:143], v[210:213], v[72:75]
	v_mfma_f32_16x16x32_bf16 v[116:119], v[166:169], v[182:185], v[116:119]
	v_mfma_f32_16x16x32_bf16 v[112:115], v[174:177], v[182:185], v[112:115]
	v_mfma_f32_16x16x32_bf16 v[100:103], v[166:169], v[190:193], v[100:103]
	v_mfma_f32_16x16x32_bf16 v[96:99], v[174:177], v[190:193], v[96:99]
	v_mfma_f32_16x16x32_bf16 v[84:87], v[166:169], v[198:201], v[84:87]
	v_mfma_f32_16x16x32_bf16 v[80:83], v[174:177], v[198:201], v[80:83]
	v_mfma_f32_16x16x32_bf16 v[68:71], v[166:169], v[206:209], v[68:71]
	v_mfma_f32_16x16x32_bf16 v[64:67], v[174:177], v[206:209], v[64:67]
	v_mfma_f32_16x16x32_bf16 v[116:119], v[170:173], v[186:189], v[116:119]
	v_mfma_f32_16x16x32_bf16 v[112:115], v[178:181], v[186:189], v[112:115]
	v_mfma_f32_16x16x32_bf16 v[100:103], v[170:173], v[194:197], v[100:103]
	v_mfma_f32_16x16x32_bf16 v[96:99], v[178:181], v[194:197], v[96:99]
	v_mfma_f32_16x16x32_bf16 v[84:87], v[170:173], v[202:205], v[84:87]
	v_mfma_f32_16x16x32_bf16 v[80:83], v[178:181], v[202:205], v[80:83]
	v_mfma_f32_16x16x32_bf16 v[68:71], v[170:173], v[210:213], v[68:71]
	v_mfma_f32_16x16x32_bf16 v[64:67], v[178:181], v[210:213], v[64:67]
	s_setprio 0
	s_barrier
	s_add_i32 s40, s52, s33
	s_mov_b32 m0, s40
	ds_read_b128 v[182:185], v165 offset:49152
	ds_read_b128 v[186:189], v165 offset:50176
	ds_read_b128 v[190:193], v165 offset:51200
	ds_read_b128 v[194:197], v165 offset:52224
	ds_read_b128 v[198:201], v165 offset:53248
	ds_read_b128 v[202:205], v165 offset:54272
	ds_read_b128 v[206:209], v165 offset:55296
	ds_read_b128 v[210:213], v165 offset:56320
	global_load_lds_dwordx4 v146, s[98:99]
	s_add_i32 m0, s40, 0x2000
	s_add_u32 s38, s38, 0x40080
	s_addc_u32 s39, s39, 0
	s_add_i32 s40, s53, s33
	global_load_lds_dwordx4 v150, s[98:99]
	s_mov_b32 m0, s40
	s_nop 0
	global_load_lds_dwordx4 v146, s[38:39]
	s_add_i32 m0, s40, 0x2000
	s_nop 0
	global_load_lds_dwordx4 v150, s[38:39]
	s_mov_b32 m0, s55
	s_nop 0
	global_load_lds_dwordx4 v144, s[100:101]
	s_mov_b32 m0, s56
	s_nop 0
	global_load_lds_dwordx4 v148, s[100:101]
	s_waitcnt vmcnt(8)
	s_barrier
	s_setprio 1
	s_waitcnt lgkmcnt(0)
	v_mfma_f32_16x16x32_bf16 v[60:63], v[128:131], v[182:185], v[60:63]
	v_mfma_f32_16x16x32_bf16 v[56:59], v[136:139], v[182:185], v[56:59]
	v_mfma_f32_16x16x32_bf16 v[44:47], v[128:131], v[190:193], v[44:47]
	v_mfma_f32_16x16x32_bf16 v[40:43], v[136:139], v[190:193], v[40:43]
	v_mfma_f32_16x16x32_bf16 v[28:31], v[128:131], v[198:201], v[28:31]
	v_mfma_f32_16x16x32_bf16 v[24:27], v[136:139], v[198:201], v[24:27]
	v_mfma_f32_16x16x32_bf16 v[12:15], v[128:131], v[206:209], v[12:15]
	v_mfma_f32_16x16x32_bf16 v[8:11], v[136:139], v[206:209], v[8:11]
	v_mfma_f32_16x16x32_bf16 v[60:63], v[132:135], v[186:189], v[60:63]
	v_mfma_f32_16x16x32_bf16 v[56:59], v[140:143], v[186:189], v[56:59]
	v_mfma_f32_16x16x32_bf16 v[44:47], v[132:135], v[194:197], v[44:47]
	v_mfma_f32_16x16x32_bf16 v[40:43], v[140:143], v[194:197], v[40:43]
	v_mfma_f32_16x16x32_bf16 v[28:31], v[132:135], v[202:205], v[28:31]
	v_mfma_f32_16x16x32_bf16 v[24:27], v[140:143], v[202:205], v[24:27]
	v_mfma_f32_16x16x32_bf16 v[12:15], v[132:135], v[210:213], v[12:15]
	v_mfma_f32_16x16x32_bf16 v[8:11], v[140:143], v[210:213], v[8:11]
	v_mfma_f32_16x16x32_bf16 v[52:55], v[166:169], v[182:185], v[52:55]
	v_mfma_f32_16x16x32_bf16 v[48:51], v[174:177], v[182:185], v[48:51]
	v_mfma_f32_16x16x32_bf16 v[36:39], v[166:169], v[190:193], v[36:39]
	v_mfma_f32_16x16x32_bf16 v[32:35], v[174:177], v[190:193], v[32:35]
	v_mfma_f32_16x16x32_bf16 v[20:23], v[166:169], v[198:201], v[20:23]
	v_mfma_f32_16x16x32_bf16 v[16:19], v[174:177], v[198:201], v[16:19]
	v_mfma_f32_16x16x32_bf16 v[4:7], v[166:169], v[206:209], v[4:7]
	v_mfma_f32_16x16x32_bf16 v[0:3], v[174:177], v[206:209], v[0:3]
	v_mfma_f32_16x16x32_bf16 v[52:55], v[170:173], v[186:189], v[52:55]
	v_mfma_f32_16x16x32_bf16 v[48:51], v[178:181], v[186:189], v[48:51]
	v_mfma_f32_16x16x32_bf16 v[36:39], v[170:173], v[194:197], v[36:39]
	v_mfma_f32_16x16x32_bf16 v[32:35], v[178:181], v[194:197], v[32:35]
	v_mfma_f32_16x16x32_bf16 v[20:23], v[170:173], v[202:205], v[20:23]
	v_mfma_f32_16x16x32_bf16 v[16:19], v[178:181], v[202:205], v[16:19]
	v_mfma_f32_16x16x32_bf16 v[4:7], v[170:173], v[210:213], v[4:7]
	v_mfma_f32_16x16x32_bf16 v[0:3], v[178:181], v[210:213], v[0:3]
	s_setprio 0
	s_barrier
	s_add_i32 s67, s67, 2
	s_add_u32 s36, s36, 0x100
	s_addc_u32 s37, s37, 0
	s_add_u32 s65, s65, 0x100
	s_addc_u32 s66, s66, 0
	s_cmp_gt_u32 s67, 13
	s_cbranch_scc0 .LBB0_917
	s_and_b64 vcc, exec, s[14:15]
	s_cbranch_vccz .LBB0_920
	s_barrier

; #define PG8_STAGE(bufoff, gbase, voff) do { _Pragma("unroll") for (int _i = 0; _i < 2; ++_i) \
;         __builtin_amdgcn_global_load_lds((const unsigned*)((const char*)(gbase) + (voff)[_i]), (LAS unsigned*)(lds + (bufoff) + ldsw + _i * 8192), 16, 0, 0); } while (0)
; #define PG8_LDA(dst, b, h) do { _Pragma("unroll") for (int m = 0; m < 4; ++m) _Pragma("unroll") for (int k = 0; k < 2; ++k) dst[m][k] = *(const LAS bf16x8*)(lds + PG8_SA(b, h) + aoff + m * 2048 + k * 1024); } while (0)
; #define PG8_LDB(dst, b, h) do { _Pragma("unroll") for (int n = 0; n < 2; ++n) _Pragma("unroll") for (int k = 0; k < 2; ++k) dst[n][k] = *(const LAS bf16x8*)(lds + PG8_SB(b, h) + boff + n * 2048 + k * 1024); } while (0)
; #define PG8_MMA(ai, bj, At, Bt) do { __builtin_amdgcn_s_setprio(1); _Pragma("unroll") for (int m = 0; m < 4; ++m) _Pragma("unroll") for (int n = 0; n < 2; ++n) _Pragma("unroll") for (int k = 0; k < 2; ++k) \
;         acc[ai][bj][m][n] = __builtin_amdgcn_mfma_f32_16x16x32_bf16(Bt[n][k], At[m][k], acc[ai][bj][m][n], 0, 0, 0); __builtin_amdgcn_s_setprio(0); } while (0)
; template <class Epi, bool ALIGN_EPI, int K, int LDA, int LDB>
; __device__ __forceinline__ void gemm_phase(LAS unsigned char* lds, const int wid, const Gemm g, const StaticOrder& S, const Epi& E) {
;     ...
;         const bool has_next = S.next(ui + 1, nxt);
;         const char* nA = has_next ? (const char*)g.A + (size_t)nxt.pm * tA : cA; const char* nB = has_next ? (const char*)g.Bt + (size_t)nxt.pn * tB : cB;
;         for (int t = 0; t < nt; t += 2) {
;             const bool last = (t == nt - 2);
;             const char* a1 = cA + (size_t)(t + 1) * kstep;
;             const char* a2 = last ? nA : cA + (size_t)(t + 2) * kstep; const char* b2 = last ? nB : cB + (size_t)(t + 2) * kstep;
;             const char* a3 = a2 + kstep; const char* b3 = b2 + kstep;
;             PG8_LDB(B0, 0, 0); PG8_LDB(B1, 0, 1); PG8_SCHED; PG8_LDA(At, 0, 0); PG8_STAGE(PG8_SA(1, 1), a1 + hA, voffA);
;             PG8_WAIT_V(8); PG8_WAIT_L(0); PG8_BAR; PG8_MMA(0, 0, At, B0); PG8_MMA(0, 1, At, B1); PG8_BAR; PG8_SCHED;
;             PG8_LDA(At, 0, 1); PG8_STAGE(PG8_SB(0, 0), b2, voffB); PG8_STAGE(PG8_SB(0, 1), b2 + hB, voffB); PG8_STAGE(PG8_SA(0, 0), a2, voffA);
;             PG8_WAIT_V(8); PG8_WAIT_L(0); PG8_BAR; PG8_MMA(1, 0, At, B0); PG8_MMA(1, 1, At, B1); PG8_BAR; PG8_SCHED;
.LBB0_1051:
	s_ashr_i32 s15, s14, 31
	s_lshl_b64 s[16:17], s[14:15], 19
	v_readlane_b32 s13, v254, 0
	s_add_u32 s16, s13, s16
	v_readlane_b32 s13, v254, 1
	s_addc_u32 s17, s13, s17
	s_and_b64 s[18:19], s[4:5], exec
	s_cselect_b32 s15, s17, s23
	s_cselect_b32 s48, s16, s22
	s_ashr_i32 s13, s12, 31
	s_lshl_b64 s[18:19], s[12:13], 19
	s_add_u32 s18, s0, s18
	s_addc_u32 s19, s1, s19
	s_and_b64 s[26:27], s[4:5], exec
	s_cselect_b32 s13, s19, s25
	s_cselect_b32 s49, s18, s24
	s_add_u32 s22, s22, 0x40080
	s_addc_u32 s23, s23, 0
	s_add_u32 s51, s24, 0x100
	s_addc_u32 s54, s25, 0
	s_mov_b32 s55, -2
	s_add_u32 s24, s22, 0xfffc0080
	s_addc_u32 s25, s23, -1
	s_cmp_eq_u32 s55, 12
	s_cselect_b32 s27, s15, s25
	s_cselect_b32 s26, s48, s24
	s_cselect_b32 s25, s13, s54
	s_cselect_b32 s24, s49, s51
	s_add_i32 m0, s21, 0xc000
	global_load_lds_dwordx4 v136, s[22:23]
	s_add_i32 m0, s21, 0xe000
	s_nop 0
	global_load_lds_dwordx4 v138, s[22:23]
	s_waitcnt vmcnt(8)
	s_barrier
	s_setprio 1
	s_waitcnt lgkmcnt(0)
	v_mfma_f32_16x16x32_bf16 v[124:127], v[148:151], v[180:183], 0
	v_mfma_f32_16x16x32_bf16 v[120:123], v[156:159], v[180:183], 0
	v_mfma_f32_16x16x32_bf16 v[108:111], v[148:151], v[188:191], 0
	v_mfma_f32_16x16x32_bf16 v[104:107], v[156:159], v[188:191], 0
	v_mfma_f32_16x16x32_bf16 v[92:95], v[148:151], v[196:199], 0
	v_mfma_f32_16x16x32_bf16 v[88:91], v[156:159], v[196:199], 0
	v_mfma_f32_16x16x32_bf16 v[76:79], v[148:151], v[204:207], 0
	v_mfma_f32_16x16x32_bf16 v[72:75], v[156:159], v[204:207], 0
	v_mfma_f32_16x16x32_bf16 v[124:127], v[152:155], v[184:187], v[124:127]
	v_mfma_f32_16x16x32_bf16 v[120:123], v[160:163], v[184:187], v[120:123]
	v_mfma_f32_16x16x32_bf16 v[108:111], v[152:155], v[192:195], v[108:111]
	v_mfma_f32_16x16x32_bf16 v[104:107], v[160:163], v[192:195], v[104:107]
	v_mfma_f32_16x16x32_bf16 v[92:95], v[152:155], v[200:203], v[92:95]
	v_mfma_f32_16x16x32_bf16 v[88:91], v[160:163], v[200:203], v[88:91]
	v_mfma_f32_16x16x32_bf16 v[76:79], v[152:155], v[208:211], v[76:79]
	v_mfma_f32_16x16x32_bf16 v[72:75], v[160:163], v[208:211], v[72:75]
	v_mfma_f32_16x16x32_bf16 v[116:119], v[164:167], v[180:183], 0
	v_mfma_f32_16x16x32_bf16 v[112:115], v[172:175], v[180:183], 0
	v_mfma_f32_16x16x32_bf16 v[100:103], v[164:167], v[188:191], 0
	v_mfma_f32_16x16x32_bf16 v[96:99], v[172:175], v[188:191], 0
	v_mfma_f32_16x16x32_bf16 v[84:87], v[164:167], v[196:199], 0
	v_mfma_f32_16x16x32_bf16 v[80:83], v[172:175], v[196:199], 0
	v_mfma_f32_16x16x32_bf16 v[68:71], v[164:167], v[204:207], 0
	v_mfma_f32_16x16x32_bf16 v[64:67], v[172:175], v[204:207], 0
	v_mfma_f32_16x16x32_bf16 v[116:119], v[168:171], v[184:187], v[116:119]
	v_mfma_f32_16x16x32_bf16 v[112:115], v[176:179], v[184:187], v[112:115]
	v_mfma_f32_16x16x32_bf16 v[100:103], v[168:171], v[192:195], v[100:103]
	v_mfma_f32_16x16x32_bf16 v[96:99], v[176:179], v[192:195], v[96:99]
	v_mfma_f32_16x16x32_bf16 v[84:87], v[168:171], v[200:203], v[84:87]
	v_mfma_f32_16x16x32_bf16 v[80:83], v[176:179], v[200:203], v[80:83]
	v_mfma_f32_16x16x32_bf16 v[68:71], v[168:171], v[208:211], v[68:71]
	v_mfma_f32_16x16x32_bf16 v[64:67], v[176:179], v[208:211], v[64:67]
	s_setprio 0
	s_barrier
	s_add_u32 s98, s24, s10
	s_addc_u32 s99, s25, s11
	s_add_u32 s100, s26, s10
	s_addc_u32 s101, s27, s11
	s_add_i32 s52, s40, s3
	s_mov_b32 m0, s52
	ds_read_b128 v[180:183], v147 offset:16384
	ds_read_b128 v[184:187], v147 offset:17408
	ds_read_b128 v[188:191], v147 offset:18432
	ds_read_b128 v[192:195], v147 offset:19456
	ds_read_b128 v[196:199], v147 offset:20480
	ds_read_b128 v[200:203], v147 offset:21504
	ds_read_b128 v[204:207], v147 offset:22528
	ds_read_b128 v[208:211], v147 offset:23552
	global_load_lds_dwordx4 v132, s[24:25]
	s_add_i32 m0, s52, 0x2000
	s_add_u32 s56, s24, 0x40000
	s_addc_u32 s57, s25, 0
	s_add_i32 s52, s41, s3
	global_load_lds_dwordx4 v128, s[24:25]
	s_mov_b32 m0, s52
	s_nop 0
	global_load_lds_dwordx4 v132, s[56:57]
	s_add_i32 m0, s52, 0x2000
	s_nop 0
	global_load_lds_dwordx4 v128, s[56:57]
	s_mov_b32 m0, s21
	s_nop 0
	global_load_lds_dwordx4 v134, s[26:27]
	s_mov_b32 m0, s30
	s_nop 0
	global_load_lds_dwordx4 v130, s[26:27]
	s_waitcnt vmcnt(8)
	s_barrier
	s_setprio 1
	s_waitcnt lgkmcnt(0)
	v_mfma_f32_16x16x32_bf16 v[60:63], v[148:151], v[180:183], 0
	v_mfma_f32_16x16x32_bf16 v[56:59], v[156:159], v[180:183], 0
	v_mfma_f32_16x16x32_bf16 v[44:47], v[148:151], v[188:191], 0
	v_mfma_f32_16x16x32_bf16 v[40:43], v[156:159], v[188:191], 0
	v_mfma_f32_16x16x32_bf16 v[28:31], v[148:151], v[196:199], 0
	v_mfma_f32_16x16x32_bf16 v[24:27], v[156:159], v[196:199], 0
	v_mfma_f32_16x16x32_bf16 v[12:15], v[148:151], v[204:207], 0
	v_mfma_f32_16x16x32_bf16 v[8:11], v[156:159], v[204:207], 0
	v_mfma_f32_16x16x32_bf16 v[60:63], v[152:155], v[184:187], v[60:63]
	v_mfma_f32_16x16x32_bf16 v[56:59], v[160:163], v[184:187], v[56:59]
	v_mfma_f32_16x16x32_bf16 v[44:47], v[152:155], v[192:195], v[44:47]
	v_mfma_f32_16x16x32_bf16 v[40:43], v[160:163], v[192:195], v[40:43]
	v_mfma_f32_16x16x32_bf16 v[28:31], v[152:155], v[200:203], v[28:31]
	v_mfma_f32_16x16x32_bf16 v[24:27], v[160:163], v[200:203], v[24:27]
	v_mfma_f32_16x16x32_bf16 v[12:15], v[152:155], v[208:211], v[12:15]
	v_mfma_f32_16x16x32_bf16 v[8:11], v[160:163], v[208:211], v[8:11]
	v_mfma_f32_16x16x32_bf16 v[52:55], v[164:167], v[180:183], 0
	v_mfma_f32_16x16x32_bf16 v[48:51], v[172:175], v[180:183], 0
	v_mfma_f32_16x16x32_bf16 v[36:39], v[164:167], v[188:191], 0
	v_mfma_f32_16x16x32_bf16 v[32:35], v[172:175], v[188:191], 0
	v_mfma_f32_16x16x32_bf16 v[20:23], v[164:167], v[196:199], 0
	v_mfma_f32_16x16x32_bf16 v[16:19], v[172:175], v[196:199], 0
	v_mfma_f32_16x16x32_bf16 v[4:7], v[164:167], v[204:207], 0
	v_mfma_f32_16x16x32_bf16 v[0:3], v[172:175], v[204:207], 0
	v_mfma_f32_16x16x32_bf16 v[52:55], v[168:171], v[184:187], v[52:55]
	v_mfma_f32_16x16x32_bf16 v[48:51], v[176:179], v[184:187], v[48:51]
	v_mfma_f32_16x16x32_bf16 v[36:39], v[168:171], v[192:195], v[36:39]
	v_mfma_f32_16x16x32_bf16 v[32:35], v[176:179], v[192:195], v[32:35]
	v_mfma_f32_16x16x32_bf16 v[20:23], v[168:171], v[200:203], v[20:23]
	v_mfma_f32_16x16x32_bf16 v[16:19], v[176:179], v[200:203], v[16:19]
	v_mfma_f32_16x16x32_bf16 v[4:7], v[168:171], v[208:211], v[4:7]
	v_mfma_f32_16x16x32_bf16 v[0:3], v[176:179], v[208:211], v[0:3]
	s_setprio 0
	s_barrier
; #define PG8_STAGE(bufoff, gbase, voff) do { _Pragma("unroll") for (int _i = 0; _i < 2; ++_i) \
;         __builtin_amdgcn_global_load_lds((const unsigned*)((const char*)(gbase) + (voff)[_i]), (LAS unsigned*)(lds + (bufoff) + ldsw + _i * 8192), 16, 0, 0); } while (0)
; #define PG8_LDA(dst, b, h) do { _Pragma("unroll") for (int m = 0; m < 4; ++m) _Pragma("unroll") for (int k = 0; k < 2; ++k) dst[m][k] = *(const LAS bf16x8*)(lds + PG8_SA(b, h) + aoff + m * 2048 + k * 1024); } while (0)
; #define PG8_LDB(dst, b, h) do { _Pragma("unroll") for (int n = 0; n < 2; ++n) _Pragma("unroll") for (int k = 0; k < 2; ++k) dst[n][k] = *(const LAS bf16x8*)(lds + PG8_SB(b, h) + boff + n * 2048 + k * 1024); } while (0)
; #define PG8_MMA(ai, bj, At, Bt) do { __builtin_amdgcn_s_setprio(1); _Pragma("unroll") for (int m = 0; m < 4; ++m) _Pragma("unroll") for (int n = 0; n < 2; ++n) _Pragma("unroll") for (int k = 0; k < 2; ++k) \
;         acc[ai][bj][m][n] = __builtin_amdgcn_mfma_f32_16x16x32_bf16(Bt[n][k], At[m][k], acc[ai][bj][m][n], 0, 0, 0); __builtin_amdgcn_s_setprio(0); } while (0)
; #define PG8_WAIT_V(n) asm volatile("s_waitcnt vmcnt(" #n ")" ::: "memory")
; #define PG8_WAIT_L(n) asm volatile("s_waitcnt lgkmcnt(" #n ")" ::: "memory")
; #define PG8_BAR __builtin_amdgcn_s_barrier()
; #define PG8_SCHED __builtin_amdgcn_sched_barrier(0)
; template <class Epi, bool ALIGN_EPI, int K, int LDA, int LDB>
; __device__ __forceinline__ void gemm_phase(LAS unsigned char* lds, const int wid, const Gemm g, const StaticOrder& S, const Epi& E) {
;     ...
;             PG8_LDB(B0, 1, 0); PG8_LDB(B1, 1, 1); PG8_SCHED; PG8_LDA(At, 1, 0); PG8_STAGE(PG8_SA(0, 1), a2 + hA, voffA);
;             PG8_WAIT_V(8); PG8_WAIT_L(0); PG8_BAR; PG8_MMA(0, 0, At, B0); PG8_MMA(0, 1, At, B1); PG8_BAR; PG8_SCHED;
;             PG8_LDA(At, 1, 1); PG8_STAGE(PG8_SB(1, 0), b3, voffB); PG8_STAGE(PG8_SB(1, 1), b3 + hB, voffB); PG8_STAGE(PG8_SA(1, 0), a3, voffA);
;             PG8_WAIT_V(8); PG8_WAIT_L(0); PG8_BAR; PG8_MMA(1, 0, At, B0); PG8_MMA(1, 1, At, B1); PG8_BAR; PG8_SCHED;
	s_add_i32 s52, 0, 0x18000
	s_add_i32 s53, 0, 0x1c000
	v_add_u32_e32 v160, s52, v144
	v_add_u32_e32 v176, s53, v144
	ds_read_b128 v[148:151], v160
	ds_read_b128 v[152:155], v160 offset:1024
	ds_read_b128 v[156:159], v160 offset:2048
	ds_read_b128 v[160:163], v160 offset:3072
	ds_read_b128 v[164:167], v176
	ds_read_b128 v[168:171], v176 offset:1024
	ds_read_b128 v[172:175], v176 offset:2048
	ds_read_b128 v[176:179], v176 offset:3072
	s_add_u32 s26, s26, 0x40000
	s_addc_u32 s27, s27, 0
	s_mov_b32 m0, s31
	ds_read_b128 v[180:183], v147 offset:32768
	ds_read_b128 v[184:187], v147 offset:33792
	ds_read_b128 v[188:191], v147 offset:34816
	ds_read_b128 v[192:195], v147 offset:35840
	ds_read_b128 v[196:199], v147 offset:36864
	ds_read_b128 v[200:203], v147 offset:37888
	ds_read_b128 v[204:207], v147 offset:38912
	ds_read_b128 v[208:211], v147 offset:39936
	global_load_lds_dwordx4 v134, s[26:27]
	s_mov_b32 m0, s33
	s_nop 0
	global_load_lds_dwordx4 v130, s[26:27]
	s_waitcnt vmcnt(8)
	s_barrier
	s_setprio 1
	s_waitcnt lgkmcnt(0)
	v_mfma_f32_16x16x32_bf16 v[124:127], v[148:151], v[180:183], v[124:127]
	v_mfma_f32_16x16x32_bf16 v[120:123], v[156:159], v[180:183], v[120:123]
	v_mfma_f32_16x16x32_bf16 v[108:111], v[148:151], v[188:191], v[108:111]
	v_mfma_f32_16x16x32_bf16 v[104:107], v[156:159], v[188:191], v[104:107]
	v_mfma_f32_16x16x32_bf16 v[92:95], v[148:151], v[196:199], v[92:95]
	v_mfma_f32_16x16x32_bf16 v[88:91], v[156:159], v[196:199], v[88:91]
	v_mfma_f32_16x16x32_bf16 v[76:79], v[148:151], v[204:207], v[76:79]
	v_mfma_f32_16x16x32_bf16 v[72:75], v[156:159], v[204:207], v[72:75]
	v_mfma_f32_16x16x32_bf16 v[124:127], v[152:155], v[184:187], v[124:127]
	v_mfma_f32_16x16x32_bf16 v[120:123], v[160:163], v[184:187], v[120:123]
	v_mfma_f32_16x16x32_bf16 v[108:111], v[152:155], v[192:195], v[108:111]
	v_mfma_f32_16x16x32_bf16 v[104:107], v[160:163], v[192:195], v[104:107]
	v_mfma_f32_16x16x32_bf16 v[92:95], v[152:155], v[200:203], v[92:95]
	v_mfma_f32_16x16x32_bf16 v[88:91], v[160:163], v[200:203], v[88:91]
	v_mfma_f32_16x16x32_bf16 v[76:79], v[152:155], v[208:211], v[76:79]
	v_mfma_f32_16x16x32_bf16 v[72:75], v[160:163], v[208:211], v[72:75]
	v_mfma_f32_16x16x32_bf16 v[116:119], v[164:167], v[180:183], v[116:119]
	v_mfma_f32_16x16x32_bf16 v[112:115], v[172:175], v[180:183], v[112:115]
	v_mfma_f32_16x16x32_bf16 v[100:103], v[164:167], v[188:191], v[100:103]
	v_mfma_f32_16x16x32_bf16 v[96:99], v[172:175], v[188:191], v[96:99]
	v_mfma_f32_16x16x32_bf16 v[84:87], v[164:167], v[196:199], v[84:87]
	v_mfma_f32_16x16x32_bf16 v[80:83], v[172:175], v[196:199], v[80:83]
	v_mfma_f32_16x16x32_bf16 v[68:71], v[164:167], v[204:207], v[68:71]
	v_mfma_f32_16x16x32_bf16 v[64:67], v[172:175], v[204:207], v[64:67]
	v_mfma_f32_16x16x32_bf16 v[116:119], v[168:171], v[184:187], v[116:119]
	v_mfma_f32_16x16x32_bf16 v[112:115], v[176:179], v[184:187], v[112:115]
	v_mfma_f32_16x16x32_bf16 v[100:103], v[168:171], v[192:195], v[100:103]
	v_mfma_f32_16x16x32_bf16 v[96:99], v[176:179], v[192:195], v[96:99]
	v_mfma_f32_16x16x32_bf16 v[84:87], v[168:171], v[200:203], v[84:87]
	v_mfma_f32_16x16x32_bf16 v[80:83], v[176:179], v[200:203], v[80:83]
	v_mfma_f32_16x16x32_bf16 v[68:71], v[168:171], v[208:211], v[68:71]
	v_mfma_f32_16x16x32_bf16 v[64:67], v[176:179], v[208:211], v[64:67]
	s_setprio 0
	s_barrier
	s_add_i32 s26, s52, s3
	s_mov_b32 m0, s26
	ds_read_b128 v[180:183], v147 offset:49152
	ds_read_b128 v[184:187], v147 offset:50176
	ds_read_b128 v[188:191], v147 offset:51200
	ds_read_b128 v[192:195], v147 offset:52224
	ds_read_b128 v[196:199], v147 offset:53248
	ds_read_b128 v[200:203], v147 offset:54272
	ds_read_b128 v[204:207], v147 offset:55296
	ds_read_b128 v[208:211], v147 offset:56320
	global_load_lds_dwordx4 v132, s[98:99]
	s_add_i32 m0, s26, 0x2000
	s_add_u32 s24, s24, 0x40080
	s_addc_u32 s25, s25, 0
	s_add_i32 s26, s53, s3
	global_load_lds_dwordx4 v128, s[98:99]
	s_mov_b32 m0, s26
	s_nop 0
	global_load_lds_dwordx4 v132, s[24:25]
	s_add_i32 m0, s26, 0x2000
	s_nop 0
	global_load_lds_dwordx4 v128, s[24:25]
	s_mov_b32 m0, s38
	s_nop 0
	global_load_lds_dwordx4 v134, s[100:101]
	s_mov_b32 m0, s39
	s_nop 0
	global_load_lds_dwordx4 v130, s[100:101]
	s_waitcnt vmcnt(8)
	s_barrier
	s_setprio 1
	s_waitcnt lgkmcnt(0)
	v_mfma_f32_16x16x32_bf16 v[60:63], v[148:151], v[180:183], v[60:63]
	v_mfma_f32_16x16x32_bf16 v[56:59], v[156:159], v[180:183], v[56:59]
	v_mfma_f32_16x16x32_bf16 v[44:47], v[148:151], v[188:191], v[44:47]
	v_mfma_f32_16x16x32_bf16 v[40:43], v[156:159], v[188:191], v[40:43]
	v_mfma_f32_16x16x32_bf16 v[28:31], v[148:151], v[196:199], v[28:31]
	v_mfma_f32_16x16x32_bf16 v[24:27], v[156:159], v[196:199], v[24:27]
	v_mfma_f32_16x16x32_bf16 v[12:15], v[148:151], v[204:207], v[12:15]
	v_mfma_f32_16x16x32_bf16 v[8:11], v[156:159], v[204:207], v[8:11]
	v_mfma_f32_16x16x32_bf16 v[60:63], v[152:155], v[184:187], v[60:63]
	v_mfma_f32_16x16x32_bf16 v[56:59], v[160:163], v[184:187], v[56:59]
	v_mfma_f32_16x16x32_bf16 v[44:47], v[152:155], v[192:195], v[44:47]
	v_mfma_f32_16x16x32_bf16 v[40:43], v[160:163], v[192:195], v[40:43]
	v_mfma_f32_16x16x32_bf16 v[28:31], v[152:155], v[200:203], v[28:31]
	v_mfma_f32_16x16x32_bf16 v[24:27], v[160:163], v[200:203], v[24:27]
	v_mfma_f32_16x16x32_bf16 v[12:15], v[152:155], v[208:211], v[12:15]
	v_mfma_f32_16x16x32_bf16 v[8:11], v[160:163], v[208:211], v[8:11]
	v_mfma_f32_16x16x32_bf16 v[52:55], v[164:167], v[180:183], v[52:55]
	v_mfma_f32_16x16x32_bf16 v[48:51], v[172:175], v[180:183], v[48:51]
	v_mfma_f32_16x16x32_bf16 v[36:39], v[164:167], v[188:191], v[36:39]
	v_mfma_f32_16x16x32_bf16 v[32:35], v[172:175], v[188:191], v[32:35]
	v_mfma_f32_16x16x32_bf16 v[20:23], v[164:167], v[196:199], v[20:23]
	v_mfma_f32_16x16x32_bf16 v[16:19], v[172:175], v[196:199], v[16:19]
	v_mfma_f32_16x16x32_bf16 v[4:7], v[164:167], v[204:207], v[4:7]
	v_mfma_f32_16x16x32_bf16 v[0:3], v[172:175], v[204:207], v[0:3]
	v_mfma_f32_16x16x32_bf16 v[52:55], v[168:171], v[184:187], v[52:55]
	v_mfma_f32_16x16x32_bf16 v[48:51], v[176:179], v[184:187], v[48:51]
	v_mfma_f32_16x16x32_bf16 v[36:39], v[168:171], v[192:195], v[36:39]
	v_mfma_f32_16x16x32_bf16 v[32:35], v[176:179], v[192:195], v[32:35]
	v_mfma_f32_16x16x32_bf16 v[20:23], v[168:171], v[200:203], v[20:23]
	v_mfma_f32_16x16x32_bf16 v[16:19], v[176:179], v[200:203], v[16:19]
	v_mfma_f32_16x16x32_bf16 v[4:7], v[168:171], v[208:211], v[4:7]
	v_mfma_f32_16x16x32_bf16 v[0:3], v[176:179], v[208:211], v[0:3]
	s_setprio 0
	s_barrier
	s_add_i32 s55, s55, 2
	s_add_u32 s22, s22, 0x100
	s_addc_u32 s23, s23, 0
	s_add_u32 s51, s51, 0x100
	s_addc_u32 s54, s54, 0
; #define PG8_STAGE(bufoff, gbase, voff) do { _Pragma("unroll") for (int _i = 0; _i < 2; ++_i) \
;         __builtin_amdgcn_global_load_lds((const unsigned*)((const char*)(gbase) + (voff)[_i]), (LAS unsigned*)(lds + (bufoff) + ldsw + _i * 8192), 16, 0, 0); } while (0)
; #define PG8_LDA(dst, b, h) do { _Pragma("unroll") for (int m = 0; m < 4; ++m) _Pragma("unroll") for (int k = 0; k < 2; ++k) dst[m][k] = *(const LAS bf16x8*)(lds + PG8_SA(b, h) + aoff + m * 2048 + k * 1024); } while (0)
; #define PG8_LDB(dst, b, h) do { _Pragma("unroll") for (int n = 0; n < 2; ++n) _Pragma("unroll") for (int k = 0; k < 2; ++k) dst[n][k] = *(const LAS bf16x8*)(lds + PG8_SB(b, h) + boff + n * 2048 + k * 1024); } while (0)
; #define PG8_MMA(ai, bj, At, Bt) do { __builtin_amdgcn_s_setprio(1); _Pragma("unroll") for (int m = 0; m < 4; ++m) _Pragma("unroll") for (int n = 0; n < 2; ++n) _Pragma("unroll") for (int k = 0; k < 2; ++k) \
;         acc[ai][bj][m][n] = __builtin_amdgcn_mfma_f32_16x16x32_bf16(Bt[n][k], At[m][k], acc[ai][bj][m][n], 0, 0, 0); __builtin_amdgcn_s_setprio(0); } while (0)
; #define PG8_WAIT_V(n) asm volatile("s_waitcnt vmcnt(" #n ")" ::: "memory")
; #define PG8_WAIT_L(n) asm volatile("s_waitcnt lgkmcnt(" #n ")" ::: "memory")
; #define PG8_BAR __builtin_amdgcn_s_barrier()
; template <class Epi, bool ALIGN_EPI, int K, int LDA, int LDB>
; __device__ __forceinline__ void gemm_phase(LAS unsigned char* lds, const int wid, const Gemm g, const StaticOrder& S, const Epi& E) {
;     ...
;         for (int t = 0; t < nt; t += 2) {
;             const bool last = (t == nt - 2);
;             const char* a1 = cA + (size_t)(t + 1) * kstep;
;             const char* a2 = last ? nA : cA + (size_t)(t + 2) * kstep; const char* b2 = last ? nB : cB + (size_t)(t + 2) * kstep;
;             const char* a3 = a2 + kstep; const char* b3 = b2 + kstep;
;             PG8_LDB(B0, 0, 0); PG8_LDB(B1, 0, 1); PG8_SCHED; PG8_LDA(At, 0, 0); PG8_STAGE(PG8_SA(1, 1), a1 + hA, voffA);
;             PG8_WAIT_V(8); PG8_WAIT_L(0); PG8_BAR; PG8_MMA(0, 0, At, B0); PG8_MMA(0, 1, At, B1); PG8_BAR; PG8_SCHED;
;             PG8_LDA(At, 0, 1); PG8_STAGE(PG8_SB(0, 0), b2, voffB); PG8_STAGE(PG8_SB(0, 1), b2 + hB, voffB); PG8_STAGE(PG8_SA(0, 0), a2, voffA);
;             PG8_WAIT_V(8); PG8_WAIT_L(0); PG8_BAR; PG8_MMA(1, 0, At, B0); PG8_MMA(1, 1, At, B1); PG8_BAR; PG8_SCHED;
.LBB0_1052:
	ds_read_b128 v[148:151], v145
	ds_read_b128 v[152:155], v145 offset:1024
	ds_read_b128 v[156:159], v145 offset:2048
	ds_read_b128 v[160:163], v145 offset:3072
	ds_read_b128 v[164:167], v146
	ds_read_b128 v[168:171], v146 offset:1024
	ds_read_b128 v[172:175], v146 offset:2048
	ds_read_b128 v[176:179], v146 offset:3072
	s_add_u32 s24, s22, 0xfffc0080
	s_addc_u32 s25, s23, -1
	s_cmp_eq_u32 s55, 12
	s_cselect_b32 s27, s15, s25
	s_cselect_b32 s26, s48, s24
	s_cselect_b32 s25, s13, s54
	s_cselect_b32 s24, s49, s51
	s_add_i32 m0, s21, 0xc000
	ds_read_b128 v[180:183], v147
	ds_read_b128 v[184:187], v147 offset:1024
	ds_read_b128 v[188:191], v147 offset:2048
	ds_read_b128 v[192:195], v147 offset:3072
	ds_read_b128 v[196:199], v147 offset:4096
	ds_read_b128 v[200:203], v147 offset:5120
	ds_read_b128 v[204:207], v147 offset:6144
	ds_read_b128 v[208:211], v147 offset:7168
	global_load_lds_dwordx4 v136, s[22:23]
	s_add_i32 m0, s21, 0xe000
	s_nop 0
	global_load_lds_dwordx4 v138, s[22:23]
	s_waitcnt vmcnt(8)
	s_barrier
	s_setprio 1
	s_waitcnt lgkmcnt(0)
	v_mfma_f32_16x16x32_bf16 v[124:127], v[148:151], v[180:183], v[124:127]
	v_mfma_f32_16x16x32_bf16 v[120:123], v[156:159], v[180:183], v[120:123]
	v_mfma_f32_16x16x32_bf16 v[108:111], v[148:151], v[188:191], v[108:111]
	v_mfma_f32_16x16x32_bf16 v[104:107], v[156:159], v[188:191], v[104:107]
	v_mfma_f32_16x16x32_bf16 v[92:95], v[148:151], v[196:199], v[92:95]
	v_mfma_f32_16x16x32_bf16 v[88:91], v[156:159], v[196:199], v[88:91]
	v_mfma_f32_16x16x32_bf16 v[76:79], v[148:151], v[204:207], v[76:79]
	v_mfma_f32_16x16x32_bf16 v[72:75], v[156:159], v[204:207], v[72:75]
	v_mfma_f32_16x16x32_bf16 v[124:127], v[152:155], v[184:187], v[124:127]
	v_mfma_f32_16x16x32_bf16 v[120:123], v[160:163], v[184:187], v[120:123]
	v_mfma_f32_16x16x32_bf16 v[108:111], v[152:155], v[192:195], v[108:111]
	v_mfma_f32_16x16x32_bf16 v[104:107], v[160:163], v[192:195], v[104:107]
	v_mfma_f32_16x16x32_bf16 v[92:95], v[152:155], v[200:203], v[92:95]
	v_mfma_f32_16x16x32_bf16 v[88:91], v[160:163], v[200:203], v[88:91]
	v_mfma_f32_16x16x32_bf16 v[76:79], v[152:155], v[208:211], v[76:79]
	v_mfma_f32_16x16x32_bf16 v[72:75], v[160:163], v[208:211], v[72:75]
	v_mfma_f32_16x16x32_bf16 v[116:119], v[164:167], v[180:183], v[116:119]
	v_mfma_f32_16x16x32_bf16 v[112:115], v[172:175], v[180:183], v[112:115]
	v_mfma_f32_16x16x32_bf16 v[100:103], v[164:167], v[188:191], v[100:103]
	v_mfma_f32_16x16x32_bf16 v[96:99], v[172:175], v[188:191], v[96:99]
	v_mfma_f32_16x16x32_bf16 v[84:87], v[164:167], v[196:199], v[84:87]
	v_mfma_f32_16x16x32_bf16 v[80:83], v[172:175], v[196:199], v[80:83]
	v_mfma_f32_16x16x32_bf16 v[68:71], v[164:167], v[204:207], v[68:71]
	v_mfma_f32_16x16x32_bf16 v[64:67], v[172:175], v[204:207], v[64:67]
	v_mfma_f32_16x16x32_bf16 v[116:119], v[168:171], v[184:187], v[116:119]
	v_mfma_f32_16x16x32_bf16 v[112:115], v[176:179], v[184:187], v[112:115]
	v_mfma_f32_16x16x32_bf16 v[100:103], v[168:171], v[192:195], v[100:103]
	v_mfma_f32_16x16x32_bf16 v[96:99], v[176:179], v[192:195], v[96:99]
	v_mfma_f32_16x16x32_bf16 v[84:87], v[168:171], v[200:203], v[84:87]
	v_mfma_f32_16x16x32_bf16 v[80:83], v[176:179], v[200:203], v[80:83]
	v_mfma_f32_16x16x32_bf16 v[68:71], v[168:171], v[208:211], v[68:71]
	v_mfma_f32_16x16x32_bf16 v[64:67], v[176:179], v[208:211], v[64:67]
	s_setprio 0
	s_barrier
	s_add_u32 s98, s24, s10
	s_addc_u32 s99, s25, s11
	s_add_u32 s100, s26, s10
	s_addc_u32 s101, s27, s11
	s_add_i32 s52, s40, s3
	s_mov_b32 m0, s52
	ds_read_b128 v[180:183], v147 offset:16384
	ds_read_b128 v[184:187], v147 offset:17408
	ds_read_b128 v[188:191], v147 offset:18432
	ds_read_b128 v[192:195], v147 offset:19456
	ds_read_b128 v[196:199], v147 offset:20480
	ds_read_b128 v[200:203], v147 offset:21504
	ds_read_b128 v[204:207], v147 offset:22528
	ds_read_b128 v[208:211], v147 offset:23552
	global_load_lds_dwordx4 v132, s[24:25]
	s_add_i32 m0, s52, 0x2000
	s_add_u32 s56, s24, 0x40000
	s_addc_u32 s57, s25, 0
	s_add_i32 s52, s41, s3
	global_load_lds_dwordx4 v128, s[24:25]
	s_mov_b32 m0, s52
	s_nop 0
	global_load_lds_dwordx4 v132, s[56:57]
	s_add_i32 m0, s52, 0x2000
	s_nop 0
	global_load_lds_dwordx4 v128, s[56:57]
	s_mov_b32 m0, s21
	s_nop 0
	global_load_lds_dwordx4 v134, s[26:27]
	s_mov_b32 m0, s30
	s_nop 0
	global_load_lds_dwordx4 v130, s[26:27]
	s_waitcnt vmcnt(8)
	s_barrier
	s_setprio 1
	s_waitcnt lgkmcnt(0)
	v_mfma_f32_16x16x32_bf16 v[60:63], v[148:151], v[180:183], v[60:63]
	v_mfma_f32_16x16x32_bf16 v[56:59], v[156:159], v[180:183], v[56:59]
	v_mfma_f32_16x16x32_bf16 v[44:47], v[148:151], v[188:191], v[44:47]
	v_mfma_f32_16x16x32_bf16 v[40:43], v[156:159], v[188:191], v[40:43]
	v_mfma_f32_16x16x32_bf16 v[28:31], v[148:151], v[196:199], v[28:31]
	v_mfma_f32_16x16x32_bf16 v[24:27], v[156:159], v[196:199], v[24:27]
	v_mfma_f32_16x16x32_bf16 v[12:15], v[148:151], v[204:207], v[12:15]
	v_mfma_f32_16x16x32_bf16 v[8:11], v[156:159], v[204:207], v[8:11]
	v_mfma_f32_16x16x32_bf16 v[60:63], v[152:155], v[184:187], v[60:63]
	v_mfma_f32_16x16x32_bf16 v[56:59], v[160:163], v[184:187], v[56:59]
	v_mfma_f32_16x16x32_bf16 v[44:47], v[152:155], v[192:195], v[44:47]
	v_mfma_f32_16x16x32_bf16 v[40:43], v[160:163], v[192:195], v[40:43]
	v_mfma_f32_16x16x32_bf16 v[28:31], v[152:155], v[200:203], v[28:31]
	v_mfma_f32_16x16x32_bf16 v[24:27], v[160:163], v[200:203], v[24:27]
	v_mfma_f32_16x16x32_bf16 v[12:15], v[152:155], v[208:211], v[12:15]
	v_mfma_f32_16x16x32_bf16 v[8:11], v[160:163], v[208:211], v[8:11]
	v_mfma_f32_16x16x32_bf16 v[52:55], v[164:167], v[180:183], v[52:55]
	v_mfma_f32_16x16x32_bf16 v[48:51], v[172:175], v[180:183], v[48:51]
	v_mfma_f32_16x16x32_bf16 v[36:39], v[164:167], v[188:191], v[36:39]
	v_mfma_f32_16x16x32_bf16 v[32:35], v[172:175], v[188:191], v[32:35]
	v_mfma_f32_16x16x32_bf16 v[20:23], v[164:167], v[196:199], v[20:23]
	v_mfma_f32_16x16x32_bf16 v[16:19], v[172:175], v[196:199], v[16:19]
	v_mfma_f32_16x16x32_bf16 v[4:7], v[164:167], v[204:207], v[4:7]
	v_mfma_f32_16x16x32_bf16 v[0:3], v[172:175], v[204:207], v[0:3]
	v_mfma_f32_16x16x32_bf16 v[52:55], v[168:171], v[184:187], v[52:55]
	v_mfma_f32_16x16x32_bf16 v[48:51], v[176:179], v[184:187], v[48:51]
	v_mfma_f32_16x16x32_bf16 v[36:39], v[168:171], v[192:195], v[36:39]
	v_mfma_f32_16x16x32_bf16 v[32:35], v[176:179], v[192:195], v[32:35]
	v_mfma_f32_16x16x32_bf16 v[20:23], v[168:171], v[200:203], v[20:23]
	v_mfma_f32_16x16x32_bf16 v[16:19], v[176:179], v[200:203], v[16:19]
	v_mfma_f32_16x16x32_bf16 v[4:7], v[168:171], v[208:211], v[4:7]
	v_mfma_f32_16x16x32_bf16 v[0:3], v[176:179], v[208:211], v[0:3]
	s_setprio 0
	s_barrier
; #define PG8_STAGE(bufoff, gbase, voff) do { _Pragma("unroll") for (int _i = 0; _i < 2; ++_i) \
;         __builtin_amdgcn_global_load_lds((const unsigned*)((const char*)(gbase) + (voff)[_i]), (LAS unsigned*)(lds + (bufoff) + ldsw + _i * 8192), 16, 0, 0); } while (0)
; #define PG8_LDA(dst, b, h) do { _Pragma("unroll") for (int m = 0; m < 4; ++m) _Pragma("unroll") for (int k = 0; k < 2; ++k) dst[m][k] = *(const LAS bf16x8*)(lds + PG8_SA(b, h) + aoff + m * 2048 + k * 1024); } while (0)
; #define PG8_LDB(dst, b, h) do { _Pragma("unroll") for (int n = 0; n < 2; ++n) _Pragma("unroll") for (int k = 0; k < 2; ++k) dst[n][k] = *(const LAS bf16x8*)(lds + PG8_SB(b, h) + boff + n * 2048 + k * 1024); } while (0)
; #define PG8_MMA(ai, bj, At, Bt) do { __builtin_amdgcn_s_setprio(1); _Pragma("unroll") for (int m = 0; m < 4; ++m) _Pragma("unroll") for (int n = 0; n < 2; ++n) _Pragma("unroll") for (int k = 0; k < 2; ++k) \
;         acc[ai][bj][m][n] = __builtin_amdgcn_mfma_f32_16x16x32_bf16(Bt[n][k], At[m][k], acc[ai][bj][m][n], 0, 0, 0); __builtin_amdgcn_s_setprio(0); } while (0)
; #define PG8_WAIT_V(n) asm volatile("s_waitcnt vmcnt(" #n ")" ::: "memory")
; #define PG8_WAIT_L(n) asm volatile("s_waitcnt lgkmcnt(" #n ")" ::: "memory")
; #define PG8_BAR __builtin_amdgcn_s_barrier()
; #define PG8_SCHED __builtin_amdgcn_sched_barrier(0)
; template <class Epi, bool ALIGN_EPI, int K, int LDA, int LDB>
; __device__ __forceinline__ void gemm_phase(LAS unsigned char* lds, const int wid, const Gemm g, const StaticOrder& S, const Epi& E) {
;     ...
;         for (int t = 0; t < nt; t += 2) {
;             const bool last = (t == nt - 2);
;     ...
;             PG8_LDB(B0, 1, 0); PG8_LDB(B1, 1, 1); PG8_SCHED; PG8_LDA(At, 1, 0); PG8_STAGE(PG8_SA(0, 1), a2 + hA, voffA);
;             PG8_WAIT_V(8); PG8_WAIT_L(0); PG8_BAR; PG8_MMA(0, 0, At, B0); PG8_MMA(0, 1, At, B1); PG8_BAR; PG8_SCHED;
;             PG8_LDA(At, 1, 1); PG8_STAGE(PG8_SB(1, 0), b3, voffB); PG8_STAGE(PG8_SB(1, 1), b3 + hB, voffB); PG8_STAGE(PG8_SA(1, 0), a3, voffA);
;             PG8_WAIT_V(8); PG8_WAIT_L(0); PG8_BAR; PG8_MMA(1, 0, At, B0); PG8_MMA(1, 1, At, B1); PG8_BAR; PG8_SCHED;
	s_add_i32 s52, 0, 0x18000
	s_add_i32 s53, 0, 0x1c000
	v_add_u32_e32 v160, s52, v144
	v_add_u32_e32 v176, s53, v144
	ds_read_b128 v[148:151], v160
	ds_read_b128 v[152:155], v160 offset:1024
	ds_read_b128 v[156:159], v160 offset:2048
	ds_read_b128 v[160:163], v160 offset:3072
	ds_read_b128 v[164:167], v176
	ds_read_b128 v[168:171], v176 offset:1024
	ds_read_b128 v[172:175], v176 offset:2048
	ds_read_b128 v[176:179], v176 offset:3072
	s_add_u32 s26, s26, 0x40000
	s_addc_u32 s27, s27, 0
	s_mov_b32 m0, s31
	ds_read_b128 v[180:183], v147 offset:32768
	ds_read_b128 v[184:187], v147 offset:33792
	ds_read_b128 v[188:191], v147 offset:34816
	ds_read_b128 v[192:195], v147 offset:35840
	ds_read_b128 v[196:199], v147 offset:36864
	ds_read_b128 v[200:203], v147 offset:37888
	ds_read_b128 v[204:207], v147 offset:38912
	ds_read_b128 v[208:211], v147 offset:39936
	global_load_lds_dwordx4 v134, s[26:27]
	s_mov_b32 m0, s33
	s_nop 0
	global_load_lds_dwordx4 v130, s[26:27]
	s_waitcnt vmcnt(8)
	s_barrier
	s_setprio 1
	s_waitcnt lgkmcnt(0)
	v_mfma_f32_16x16x32_bf16 v[124:127], v[148:151], v[180:183], v[124:127]
	v_mfma_f32_16x16x32_bf16 v[120:123], v[156:159], v[180:183], v[120:123]
	v_mfma_f32_16x16x32_bf16 v[108:111], v[148:151], v[188:191], v[108:111]
	v_mfma_f32_16x16x32_bf16 v[104:107], v[156:159], v[188:191], v[104:107]
	v_mfma_f32_16x16x32_bf16 v[92:95], v[148:151], v[196:199], v[92:95]
	v_mfma_f32_16x16x32_bf16 v[88:91], v[156:159], v[196:199], v[88:91]
	v_mfma_f32_16x16x32_bf16 v[76:79], v[148:151], v[204:207], v[76:79]
	v_mfma_f32_16x16x32_bf16 v[72:75], v[156:159], v[204:207], v[72:75]
	v_mfma_f32_16x16x32_bf16 v[124:127], v[152:155], v[184:187], v[124:127]
	v_mfma_f32_16x16x32_bf16 v[120:123], v[160:163], v[184:187], v[120:123]
	v_mfma_f32_16x16x32_bf16 v[108:111], v[152:155], v[192:195], v[108:111]
	v_mfma_f32_16x16x32_bf16 v[104:107], v[160:163], v[192:195], v[104:107]
	v_mfma_f32_16x16x32_bf16 v[92:95], v[152:155], v[200:203], v[92:95]
	v_mfma_f32_16x16x32_bf16 v[88:91], v[160:163], v[200:203], v[88:91]
	v_mfma_f32_16x16x32_bf16 v[76:79], v[152:155], v[208:211], v[76:79]
	v_mfma_f32_16x16x32_bf16 v[72:75], v[160:163], v[208:211], v[72:75]
	v_mfma_f32_16x16x32_bf16 v[116:119], v[164:167], v[180:183], v[116:119]
	v_mfma_f32_16x16x32_bf16 v[112:115], v[172:175], v[180:183], v[112:115]
	v_mfma_f32_16x16x32_bf16 v[100:103], v[164:167], v[188:191], v[100:103]
	v_mfma_f32_16x16x32_bf16 v[96:99], v[172:175], v[188:191], v[96:99]
	v_mfma_f32_16x16x32_bf16 v[84:87], v[164:167], v[196:199], v[84:87]
	v_mfma_f32_16x16x32_bf16 v[80:83], v[172:175], v[196:199], v[80:83]
	v_mfma_f32_16x16x32_bf16 v[68:71], v[164:167], v[204:207], v[68:71]
	v_mfma_f32_16x16x32_bf16 v[64:67], v[172:175], v[204:207], v[64:67]
	v_mfma_f32_16x16x32_bf16 v[116:119], v[168:171], v[184:187], v[116:119]
	v_mfma_f32_16x16x32_bf16 v[112:115], v[176:179], v[184:187], v[112:115]
	v_mfma_f32_16x16x32_bf16 v[100:103], v[168:171], v[192:195], v[100:103]
	v_mfma_f32_16x16x32_bf16 v[96:99], v[176:179], v[192:195], v[96:99]
	v_mfma_f32_16x16x32_bf16 v[84:87], v[168:171], v[200:203], v[84:87]
	v_mfma_f32_16x16x32_bf16 v[80:83], v[176:179], v[200:203], v[80:83]
	v_mfma_f32_16x16x32_bf16 v[68:71], v[168:171], v[208:211], v[68:71]
	v_mfma_f32_16x16x32_bf16 v[64:67], v[176:179], v[208:211], v[64:67]
	s_setprio 0
	s_barrier
	s_add_i32 s26, s52, s3
	s_mov_b32 m0, s26
	ds_read_b128 v[180:183], v147 offset:49152
	ds_read_b128 v[184:187], v147 offset:50176
	ds_read_b128 v[188:191], v147 offset:51200
	ds_read_b128 v[192:195], v147 offset:52224
	ds_read_b128 v[196:199], v147 offset:53248
	ds_read_b128 v[200:203], v147 offset:54272
	ds_read_b128 v[204:207], v147 offset:55296
	ds_read_b128 v[208:211], v147 offset:56320
	global_load_lds_dwordx4 v132, s[98:99]
	s_add_i32 m0, s26, 0x2000
	s_add_u32 s24, s24, 0x40080
	s_addc_u32 s25, s25, 0
	s_add_i32 s26, s53, s3
	global_load_lds_dwordx4 v128, s[98:99]
	s_mov_b32 m0, s26
	s_nop 0
	global_load_lds_dwordx4 v132, s[24:25]
	s_add_i32 m0, s26, 0x2000
	s_nop 0
	global_load_lds_dwordx4 v128, s[24:25]
	s_mov_b32 m0, s38
	s_nop 0
	global_load_lds_dwordx4 v134, s[100:101]
	s_mov_b32 m0, s39
	s_nop 0
	global_load_lds_dwordx4 v130, s[100:101]
	s_waitcnt vmcnt(8)
	s_barrier
	s_setprio 1
	s_waitcnt lgkmcnt(0)
	v_mfma_f32_16x16x32_bf16 v[60:63], v[148:151], v[180:183], v[60:63]
	v_mfma_f32_16x16x32_bf16 v[56:59], v[156:159], v[180:183], v[56:59]
	v_mfma_f32_16x16x32_bf16 v[44:47], v[148:151], v[188:191], v[44:47]
	v_mfma_f32_16x16x32_bf16 v[40:43], v[156:159], v[188:191], v[40:43]
	v_mfma_f32_16x16x32_bf16 v[28:31], v[148:151], v[196:199], v[28:31]
	v_mfma_f32_16x16x32_bf16 v[24:27], v[156:159], v[196:199], v[24:27]
	v_mfma_f32_16x16x32_bf16 v[12:15], v[148:151], v[204:207], v[12:15]
	v_mfma_f32_16x16x32_bf16 v[8:11], v[156:159], v[204:207], v[8:11]
	v_mfma_f32_16x16x32_bf16 v[60:63], v[152:155], v[184:187], v[60:63]
	v_mfma_f32_16x16x32_bf16 v[56:59], v[160:163], v[184:187], v[56:59]
	v_mfma_f32_16x16x32_bf16 v[44:47], v[152:155], v[192:195], v[44:47]
	v_mfma_f32_16x16x32_bf16 v[40:43], v[160:163], v[192:195], v[40:43]
	v_mfma_f32_16x16x32_bf16 v[28:31], v[152:155], v[200:203], v[28:31]
	v_mfma_f32_16x16x32_bf16 v[24:27], v[160:163], v[200:203], v[24:27]
	v_mfma_f32_16x16x32_bf16 v[12:15], v[152:155], v[208:211], v[12:15]
	v_mfma_f32_16x16x32_bf16 v[8:11], v[160:163], v[208:211], v[8:11]
	v_mfma_f32_16x16x32_bf16 v[52:55], v[164:167], v[180:183], v[52:55]
	v_mfma_f32_16x16x32_bf16 v[48:51], v[172:175], v[180:183], v[48:51]
	v_mfma_f32_16x16x32_bf16 v[36:39], v[164:167], v[188:191], v[36:39]
	v_mfma_f32_16x16x32_bf16 v[32:35], v[172:175], v[188:191], v[32:35]
	v_mfma_f32_16x16x32_bf16 v[20:23], v[164:167], v[196:199], v[20:23]
	v_mfma_f32_16x16x32_bf16 v[16:19], v[172:175], v[196:199], v[16:19]
	v_mfma_f32_16x16x32_bf16 v[4:7], v[164:167], v[204:207], v[4:7]
	v_mfma_f32_16x16x32_bf16 v[0:3], v[172:175], v[204:207], v[0:3]
	v_mfma_f32_16x16x32_bf16 v[52:55], v[168:171], v[184:187], v[52:55]
	v_mfma_f32_16x16x32_bf16 v[48:51], v[176:179], v[184:187], v[48:51]
	v_mfma_f32_16x16x32_bf16 v[36:39], v[168:171], v[192:195], v[36:39]
	v_mfma_f32_16x16x32_bf16 v[32:35], v[176:179], v[192:195], v[32:35]
	v_mfma_f32_16x16x32_bf16 v[20:23], v[168:171], v[200:203], v[20:23]
	v_mfma_f32_16x16x32_bf16 v[16:19], v[176:179], v[200:203], v[16:19]
	v_mfma_f32_16x16x32_bf16 v[4:7], v[168:171], v[208:211], v[4:7]
	v_mfma_f32_16x16x32_bf16 v[0:3], v[176:179], v[208:211], v[0:3]
	s_setprio 0
	s_barrier
	s_add_i32 s55, s55, 2
	s_add_u32 s22, s22, 0x100
	s_addc_u32 s23, s23, 0
	s_add_u32 s51, s51, 0x100
	s_addc_u32 s54, s54, 0
	s_cmp_gt_u32 s55, 13
	s_cbranch_scc0 .LBB0_1052
	s_and_b64 vcc, exec, s[8:9]
	s_cbranch_vccz .LBB0_1055
	s_barrier

; #define PG8_STAGE(bufoff, gbase, voff) do { _Pragma("unroll") for (int _i = 0; _i < 2; ++_i) \
;         __builtin_amdgcn_global_load_lds((const unsigned*)((const char*)(gbase) + (voff)[_i]), (LAS unsigned*)(lds + (bufoff) + ldsw + _i * 8192), 16, 0, 0); } while (0)
; #define PG8_LDA(dst, b, h) do { _Pragma("unroll") for (int m = 0; m < 4; ++m) _Pragma("unroll") for (int k = 0; k < 2; ++k) dst[m][k] = *(const LAS bf16x8*)(lds + PG8_SA(b, h) + aoff + m * 2048 + k * 1024); } while (0)
; #define PG8_LDB(dst, b, h) do { _Pragma("unroll") for (int n = 0; n < 2; ++n) _Pragma("unroll") for (int k = 0; k < 2; ++k) dst[n][k] = *(const LAS bf16x8*)(lds + PG8_SB(b, h) + boff + n * 2048 + k * 1024); } while (0)
; #define PG8_MMA(ai, bj, At, Bt) do { __builtin_amdgcn_s_setprio(1); _Pragma("unroll") for (int m = 0; m < 4; ++m) _Pragma("unroll") for (int n = 0; n < 2; ++n) _Pragma("unroll") for (int k = 0; k < 2; ++k) \
;         acc[ai][bj][m][n] = __builtin_amdgcn_mfma_f32_16x16x32_bf16(Bt[n][k], At[m][k], acc[ai][bj][m][n], 0, 0, 0); __builtin_amdgcn_s_setprio(0); } while (0)
; template <class Epi, bool ALIGN_EPI, int K, int LDA, int LDB>
; __device__ __forceinline__ void gemm_phase(LAS unsigned char* lds, const int wid, const Gemm g, const StaticOrder& S, const Epi& E) {
;     ...
;         const bool has_next = S.next(ui + 1, nxt);
;         const char* nA = has_next ? (const char*)g.A + (size_t)nxt.pm * tA : cA; const char* nB = has_next ? (const char*)g.Bt + (size_t)nxt.pn * tB : cB;
;         for (int t = 0; t < nt; t += 2) {
;             const bool last = (t == nt - 2);
;             const char* a1 = cA + (size_t)(t + 1) * kstep;
;             const char* a2 = last ? nA : cA + (size_t)(t + 2) * kstep; const char* b2 = last ? nB : cB + (size_t)(t + 2) * kstep;
;             const char* a3 = a2 + kstep; const char* b3 = b2 + kstep;
;             PG8_LDB(B0, 0, 0); PG8_LDB(B1, 0, 1); PG8_SCHED; PG8_LDA(At, 0, 0); PG8_STAGE(PG8_SA(1, 1), a1 + hA, voffA);
;             PG8_WAIT_V(8); PG8_WAIT_L(0); PG8_BAR; PG8_MMA(0, 0, At, B0); PG8_MMA(0, 1, At, B1); PG8_BAR; PG8_SCHED;
;             PG8_LDA(At, 0, 1); PG8_STAGE(PG8_SB(0, 0), b2, voffB); PG8_STAGE(PG8_SB(0, 1), b2 + hB, voffB); PG8_STAGE(PG8_SA(0, 0), a2, voffA);
;             PG8_WAIT_V(8); PG8_WAIT_L(0); PG8_BAR; PG8_MMA(1, 0, At, B0); PG8_MMA(1, 1, At, B1); PG8_BAR; PG8_SCHED;
.LBB0_1136:
	s_add_u32 s65, s28, 0x100
	s_addc_u32 s66, s29, 0
	s_mov_b32 s67, -2
	s_add_u32 s28, s26, 0x100
	s_addc_u32 s29, s27, 0
	s_cmp_eq_u32 s67, 40
	s_cselect_b32 s35, s7, s29
	s_cselect_b32 s34, s6, s28
	s_cselect_b32 s31, s25, s66
	s_cselect_b32 s30, s24, s65
	s_add_i32 m0, s36, 0xc000
	global_load_lds_dwordx4 v156, s[26:27]
	s_add_i32 m0, s36, 0xe000
	s_nop 0
	global_load_lds_dwordx4 v158, s[26:27]
	s_waitcnt vmcnt(8)
	s_barrier
	s_setprio 1
	s_waitcnt lgkmcnt(0)
	v_mfma_f32_16x16x32_bf16 v[124:127], v[128:131], v[182:185], 0
	v_mfma_f32_16x16x32_bf16 v[116:119], v[136:139], v[182:185], 0
	v_mfma_f32_16x16x32_bf16 v[120:123], v[128:131], v[190:193], 0
	v_mfma_f32_16x16x32_bf16 v[112:115], v[136:139], v[190:193], 0
	v_mfma_f32_16x16x32_bf16 v[92:95], v[128:131], v[198:201], 0
	v_mfma_f32_16x16x32_bf16 v[88:91], v[136:139], v[198:201], 0
	v_mfma_f32_16x16x32_bf16 v[76:79], v[128:131], v[206:209], 0
	v_mfma_f32_16x16x32_bf16 v[72:75], v[136:139], v[206:209], 0
	v_mfma_f32_16x16x32_bf16 v[124:127], v[132:135], v[186:189], v[124:127]
	v_mfma_f32_16x16x32_bf16 v[116:119], v[140:143], v[186:189], v[116:119]
	v_mfma_f32_16x16x32_bf16 v[120:123], v[132:135], v[194:197], v[120:123]
	v_mfma_f32_16x16x32_bf16 v[112:115], v[140:143], v[194:197], v[112:115]
	v_mfma_f32_16x16x32_bf16 v[92:95], v[132:135], v[202:205], v[92:95]
	v_mfma_f32_16x16x32_bf16 v[88:91], v[140:143], v[202:205], v[88:91]
	v_mfma_f32_16x16x32_bf16 v[76:79], v[132:135], v[210:213], v[76:79]
	v_mfma_f32_16x16x32_bf16 v[72:75], v[140:143], v[210:213], v[72:75]
	v_mfma_f32_16x16x32_bf16 v[108:111], v[144:147], v[182:185], 0
	v_mfma_f32_16x16x32_bf16 v[104:107], v[168:171], v[182:185], 0
	v_mfma_f32_16x16x32_bf16 v[100:103], v[144:147], v[190:193], 0
	v_mfma_f32_16x16x32_bf16 v[96:99], v[168:171], v[190:193], 0
	v_mfma_f32_16x16x32_bf16 v[84:87], v[144:147], v[198:201], 0
	v_mfma_f32_16x16x32_bf16 v[80:83], v[168:171], v[198:201], 0
	v_mfma_f32_16x16x32_bf16 v[68:71], v[144:147], v[206:209], 0
	v_mfma_f32_16x16x32_bf16 v[64:67], v[168:171], v[206:209], 0
	v_mfma_f32_16x16x32_bf16 v[108:111], v[164:167], v[186:189], v[108:111]
	v_mfma_f32_16x16x32_bf16 v[104:107], v[178:181], v[186:189], v[104:107]
	v_mfma_f32_16x16x32_bf16 v[100:103], v[164:167], v[194:197], v[100:103]
	v_mfma_f32_16x16x32_bf16 v[96:99], v[178:181], v[194:197], v[96:99]
	v_mfma_f32_16x16x32_bf16 v[84:87], v[164:167], v[202:205], v[84:87]
	v_mfma_f32_16x16x32_bf16 v[80:83], v[178:181], v[202:205], v[80:83]
	v_mfma_f32_16x16x32_bf16 v[68:71], v[164:167], v[210:213], v[68:71]
	v_mfma_f32_16x16x32_bf16 v[64:67], v[178:181], v[210:213], v[64:67]
	s_setprio 0
	s_barrier
	s_add_u32 s98, s30, s12
	s_addc_u32 s99, s31, s13
	s_add_u32 s100, s34, s12
	s_addc_u32 s101, s35, s13
	s_add_i32 s26, s54, s33
	s_mov_b32 m0, s26
	ds_read_b128 v[182:185], v177 offset:16384
	ds_read_b128 v[186:189], v177 offset:17408
	ds_read_b128 v[190:193], v177 offset:18432
	ds_read_b128 v[194:197], v177 offset:19456
	ds_read_b128 v[198:201], v177 offset:20480
	ds_read_b128 v[202:205], v177 offset:21504
	ds_read_b128 v[206:209], v177 offset:22528
	ds_read_b128 v[210:213], v177 offset:23552
	global_load_lds_dwordx4 v150, s[30:31]
	s_add_i32 m0, s26, 0x2000
	s_add_u32 s26, s30, 0xb0000
	s_addc_u32 s27, s31, 0
	s_add_i32 s52, s55, s33
	global_load_lds_dwordx4 v154, s[30:31]
	s_mov_b32 m0, s52
	s_nop 0
	global_load_lds_dwordx4 v150, s[26:27]
	s_add_i32 m0, s52, 0x2000
	s_nop 0
	global_load_lds_dwordx4 v154, s[26:27]
	s_mov_b32 m0, s36
	s_nop 0
	global_load_lds_dwordx4 v148, s[34:35]
	s_mov_b32 m0, s37
	s_nop 0
	global_load_lds_dwordx4 v152, s[34:35]
	s_waitcnt vmcnt(8)
	s_barrier
	s_setprio 1
	s_waitcnt lgkmcnt(0)
	v_mfma_f32_16x16x32_bf16 v[60:63], v[128:131], v[182:185], 0
	v_mfma_f32_16x16x32_bf16 v[56:59], v[136:139], v[182:185], 0
	v_mfma_f32_16x16x32_bf16 v[44:47], v[128:131], v[190:193], 0
	v_mfma_f32_16x16x32_bf16 v[40:43], v[136:139], v[190:193], 0
	v_mfma_f32_16x16x32_bf16 v[36:39], v[128:131], v[198:201], 0
	v_mfma_f32_16x16x32_bf16 v[32:35], v[136:139], v[198:201], 0
	v_mfma_f32_16x16x32_bf16 v[20:23], v[128:131], v[206:209], 0
	v_mfma_f32_16x16x32_bf16 v[16:19], v[136:139], v[206:209], 0
	v_mfma_f32_16x16x32_bf16 v[60:63], v[132:135], v[186:189], v[60:63]
	v_mfma_f32_16x16x32_bf16 v[56:59], v[140:143], v[186:189], v[56:59]
	v_mfma_f32_16x16x32_bf16 v[44:47], v[132:135], v[194:197], v[44:47]
	v_mfma_f32_16x16x32_bf16 v[40:43], v[140:143], v[194:197], v[40:43]
	v_mfma_f32_16x16x32_bf16 v[36:39], v[132:135], v[202:205], v[36:39]
	v_mfma_f32_16x16x32_bf16 v[32:35], v[140:143], v[202:205], v[32:35]
	v_mfma_f32_16x16x32_bf16 v[20:23], v[132:135], v[210:213], v[20:23]
	v_mfma_f32_16x16x32_bf16 v[16:19], v[140:143], v[210:213], v[16:19]
	v_mfma_f32_16x16x32_bf16 v[52:55], v[144:147], v[182:185], 0
	v_mfma_f32_16x16x32_bf16 v[48:51], v[168:171], v[182:185], 0
	v_mfma_f32_16x16x32_bf16 v[28:31], v[144:147], v[190:193], 0
	v_mfma_f32_16x16x32_bf16 v[24:27], v[168:171], v[190:193], 0
	v_mfma_f32_16x16x32_bf16 v[12:15], v[144:147], v[198:201], 0
	v_mfma_f32_16x16x32_bf16 v[8:11], v[168:171], v[198:201], 0
	v_mfma_f32_16x16x32_bf16 v[4:7], v[144:147], v[206:209], 0
	v_mfma_f32_16x16x32_bf16 v[0:3], v[168:171], v[206:209], 0
	v_mfma_f32_16x16x32_bf16 v[52:55], v[164:167], v[186:189], v[52:55]
	v_mfma_f32_16x16x32_bf16 v[48:51], v[178:181], v[186:189], v[48:51]
	v_mfma_f32_16x16x32_bf16 v[28:31], v[164:167], v[194:197], v[28:31]
	v_mfma_f32_16x16x32_bf16 v[24:27], v[178:181], v[194:197], v[24:27]
	v_mfma_f32_16x16x32_bf16 v[12:15], v[164:167], v[202:205], v[12:15]
	v_mfma_f32_16x16x32_bf16 v[8:11], v[178:181], v[202:205], v[8:11]
	v_mfma_f32_16x16x32_bf16 v[4:7], v[164:167], v[210:213], v[4:7]
	v_mfma_f32_16x16x32_bf16 v[0:3], v[178:181], v[210:213], v[0:3]
	s_setprio 0
	s_barrier
; #define PG8_STAGE(bufoff, gbase, voff) do { _Pragma("unroll") for (int _i = 0; _i < 2; ++_i) \
;         __builtin_amdgcn_global_load_lds((const unsigned*)((const char*)(gbase) + (voff)[_i]), (LAS unsigned*)(lds + (bufoff) + ldsw + _i * 8192), 16, 0, 0); } while (0)
; #define PG8_LDA(dst, b, h) do { _Pragma("unroll") for (int m = 0; m < 4; ++m) _Pragma("unroll") for (int k = 0; k < 2; ++k) dst[m][k] = *(const LAS bf16x8*)(lds + PG8_SA(b, h) + aoff + m * 2048 + k * 1024); } while (0)
; #define PG8_LDB(dst, b, h) do { _Pragma("unroll") for (int n = 0; n < 2; ++n) _Pragma("unroll") for (int k = 0; k < 2; ++k) dst[n][k] = *(const LAS bf16x8*)(lds + PG8_SB(b, h) + boff + n * 2048 + k * 1024); } while (0)
; #define PG8_MMA(ai, bj, At, Bt) do { __builtin_amdgcn_s_setprio(1); _Pragma("unroll") for (int m = 0; m < 4; ++m) _Pragma("unroll") for (int n = 0; n < 2; ++n) _Pragma("unroll") for (int k = 0; k < 2; ++k) \
;         acc[ai][bj][m][n] = __builtin_amdgcn_mfma_f32_16x16x32_bf16(Bt[n][k], At[m][k], acc[ai][bj][m][n], 0, 0, 0); __builtin_amdgcn_s_setprio(0); } while (0)
; #define PG8_WAIT_V(n) asm volatile("s_waitcnt vmcnt(" #n ")" ::: "memory")
; #define PG8_WAIT_L(n) asm volatile("s_waitcnt lgkmcnt(" #n ")" ::: "memory")
; #define PG8_BAR __builtin_amdgcn_s_barrier()
; #define PG8_SCHED __builtin_amdgcn_sched_barrier(0)
; template <class Epi, bool ALIGN_EPI, int K, int LDA, int LDB>
; __device__ __forceinline__ void gemm_phase(LAS unsigned char* lds, const int wid, const Gemm g, const StaticOrder& S, const Epi& E) {
;     ...
;             PG8_LDB(B0, 1, 0); PG8_LDB(B1, 1, 1); PG8_SCHED; PG8_LDA(At, 1, 0); PG8_STAGE(PG8_SA(0, 1), a2 + hA, voffA);
;             PG8_WAIT_V(8); PG8_WAIT_L(0); PG8_BAR; PG8_MMA(0, 0, At, B0); PG8_MMA(0, 1, At, B1); PG8_BAR; PG8_SCHED;
;             PG8_LDA(At, 1, 1); PG8_STAGE(PG8_SB(1, 0), b3, voffB); PG8_STAGE(PG8_SB(1, 1), b3 + hB, voffB); PG8_STAGE(PG8_SA(1, 0), a3, voffA);
;             PG8_WAIT_V(8); PG8_WAIT_L(0); PG8_BAR; PG8_MMA(1, 0, At, B0); PG8_MMA(1, 1, At, B1); PG8_BAR; PG8_SCHED;
	s_add_i32 s52, 0, 0x18000
	s_add_i32 s53, 0, 0x1c000
	v_add_u32_e32 v140, s52, v174
	v_add_u32_e32 v178, s53, v174
	ds_read_b128 v[128:131], v140
	ds_read_b128 v[132:135], v140 offset:1024
	ds_read_b128 v[136:139], v140 offset:2048
	ds_read_b128 v[140:143], v140 offset:3072
	ds_read_b128 v[144:147], v178
	ds_read_b128 v[164:167], v178 offset:1024
	ds_read_b128 v[168:171], v178 offset:2048
	ds_read_b128 v[178:181], v178 offset:3072
	s_add_u32 s26, s34, 0xb0000
	s_addc_u32 s27, s35, 0
	s_mov_b32 m0, s38
	ds_read_b128 v[182:185], v177 offset:32768
	ds_read_b128 v[186:189], v177 offset:33792
	ds_read_b128 v[190:193], v177 offset:34816
	ds_read_b128 v[194:197], v177 offset:35840
	ds_read_b128 v[198:201], v177 offset:36864
	ds_read_b128 v[202:205], v177 offset:37888
	ds_read_b128 v[206:209], v177 offset:38912
	ds_read_b128 v[210:213], v177 offset:39936
	global_load_lds_dwordx4 v148, s[26:27]
	s_mov_b32 m0, s39
	s_nop 0
	global_load_lds_dwordx4 v152, s[26:27]
	s_waitcnt vmcnt(8)
	s_barrier
	s_setprio 1
	s_waitcnt lgkmcnt(0)
	v_mfma_f32_16x16x32_bf16 v[124:127], v[128:131], v[182:185], v[124:127]
	v_mfma_f32_16x16x32_bf16 v[116:119], v[136:139], v[182:185], v[116:119]
	v_mfma_f32_16x16x32_bf16 v[120:123], v[128:131], v[190:193], v[120:123]
	v_mfma_f32_16x16x32_bf16 v[112:115], v[136:139], v[190:193], v[112:115]
	v_mfma_f32_16x16x32_bf16 v[92:95], v[128:131], v[198:201], v[92:95]
	v_mfma_f32_16x16x32_bf16 v[88:91], v[136:139], v[198:201], v[88:91]
	v_mfma_f32_16x16x32_bf16 v[76:79], v[128:131], v[206:209], v[76:79]
	v_mfma_f32_16x16x32_bf16 v[72:75], v[136:139], v[206:209], v[72:75]
	v_mfma_f32_16x16x32_bf16 v[124:127], v[132:135], v[186:189], v[124:127]
	v_mfma_f32_16x16x32_bf16 v[116:119], v[140:143], v[186:189], v[116:119]
	v_mfma_f32_16x16x32_bf16 v[120:123], v[132:135], v[194:197], v[120:123]
	v_mfma_f32_16x16x32_bf16 v[112:115], v[140:143], v[194:197], v[112:115]
	v_mfma_f32_16x16x32_bf16 v[92:95], v[132:135], v[202:205], v[92:95]
	v_mfma_f32_16x16x32_bf16 v[88:91], v[140:143], v[202:205], v[88:91]
	v_mfma_f32_16x16x32_bf16 v[76:79], v[132:135], v[210:213], v[76:79]
	v_mfma_f32_16x16x32_bf16 v[72:75], v[140:143], v[210:213], v[72:75]
	v_mfma_f32_16x16x32_bf16 v[108:111], v[144:147], v[182:185], v[108:111]
	v_mfma_f32_16x16x32_bf16 v[104:107], v[168:171], v[182:185], v[104:107]
	v_mfma_f32_16x16x32_bf16 v[100:103], v[144:147], v[190:193], v[100:103]
	v_mfma_f32_16x16x32_bf16 v[96:99], v[168:171], v[190:193], v[96:99]
	v_mfma_f32_16x16x32_bf16 v[84:87], v[144:147], v[198:201], v[84:87]
	v_mfma_f32_16x16x32_bf16 v[80:83], v[168:171], v[198:201], v[80:83]
	v_mfma_f32_16x16x32_bf16 v[68:71], v[144:147], v[206:209], v[68:71]
	v_mfma_f32_16x16x32_bf16 v[64:67], v[168:171], v[206:209], v[64:67]
	v_mfma_f32_16x16x32_bf16 v[108:111], v[164:167], v[186:189], v[108:111]
	v_mfma_f32_16x16x32_bf16 v[104:107], v[178:181], v[186:189], v[104:107]
	v_mfma_f32_16x16x32_bf16 v[100:103], v[164:167], v[194:197], v[100:103]
	v_mfma_f32_16x16x32_bf16 v[96:99], v[178:181], v[194:197], v[96:99]
	v_mfma_f32_16x16x32_bf16 v[84:87], v[164:167], v[202:205], v[84:87]
	v_mfma_f32_16x16x32_bf16 v[80:83], v[178:181], v[202:205], v[80:83]
	v_mfma_f32_16x16x32_bf16 v[68:71], v[164:167], v[210:213], v[68:71]
	v_mfma_f32_16x16x32_bf16 v[64:67], v[178:181], v[210:213], v[64:67]
	s_setprio 0
	s_barrier
	s_add_i32 s26, s52, s33
	s_mov_b32 m0, s26
	ds_read_b128 v[182:185], v177 offset:49152
	ds_read_b128 v[186:189], v177 offset:50176
	ds_read_b128 v[190:193], v177 offset:51200
	ds_read_b128 v[194:197], v177 offset:52224
	ds_read_b128 v[198:201], v177 offset:53248
	ds_read_b128 v[202:205], v177 offset:54272
	ds_read_b128 v[206:209], v177 offset:55296
	ds_read_b128 v[210:213], v177 offset:56320
	global_load_lds_dwordx4 v150, s[98:99]
	s_add_i32 m0, s26, 0x2000
	s_add_u32 s26, s30, 0xb0080
	s_addc_u32 s27, s31, 0
	s_add_i32 s30, s53, s33
	global_load_lds_dwordx4 v154, s[98:99]
	s_mov_b32 m0, s30
	s_nop 0
	global_load_lds_dwordx4 v150, s[26:27]
	s_add_i32 m0, s30, 0x2000
	s_nop 0
	global_load_lds_dwordx4 v154, s[26:27]
	s_mov_b32 m0, s48
	s_nop 0
	global_load_lds_dwordx4 v148, s[100:101]
	s_mov_b32 m0, s49
	s_nop 0
	global_load_lds_dwordx4 v152, s[100:101]
	s_waitcnt vmcnt(8)
	s_barrier
	s_setprio 1
	s_waitcnt lgkmcnt(0)
	v_mfma_f32_16x16x32_bf16 v[60:63], v[128:131], v[182:185], v[60:63]
	v_mfma_f32_16x16x32_bf16 v[56:59], v[136:139], v[182:185], v[56:59]
	v_mfma_f32_16x16x32_bf16 v[44:47], v[128:131], v[190:193], v[44:47]
	v_mfma_f32_16x16x32_bf16 v[40:43], v[136:139], v[190:193], v[40:43]
	v_mfma_f32_16x16x32_bf16 v[36:39], v[128:131], v[198:201], v[36:39]
	v_mfma_f32_16x16x32_bf16 v[32:35], v[136:139], v[198:201], v[32:35]
	v_mfma_f32_16x16x32_bf16 v[20:23], v[128:131], v[206:209], v[20:23]
	v_mfma_f32_16x16x32_bf16 v[16:19], v[136:139], v[206:209], v[16:19]
	v_mfma_f32_16x16x32_bf16 v[60:63], v[132:135], v[186:189], v[60:63]
	v_mfma_f32_16x16x32_bf16 v[56:59], v[140:143], v[186:189], v[56:59]
	v_mfma_f32_16x16x32_bf16 v[44:47], v[132:135], v[194:197], v[44:47]
	v_mfma_f32_16x16x32_bf16 v[40:43], v[140:143], v[194:197], v[40:43]
	v_mfma_f32_16x16x32_bf16 v[36:39], v[132:135], v[202:205], v[36:39]
	v_mfma_f32_16x16x32_bf16 v[32:35], v[140:143], v[202:205], v[32:35]
	v_mfma_f32_16x16x32_bf16 v[20:23], v[132:135], v[210:213], v[20:23]
	v_mfma_f32_16x16x32_bf16 v[16:19], v[140:143], v[210:213], v[16:19]
	v_mfma_f32_16x16x32_bf16 v[52:55], v[144:147], v[182:185], v[52:55]
	v_mfma_f32_16x16x32_bf16 v[48:51], v[168:171], v[182:185], v[48:51]
	v_mfma_f32_16x16x32_bf16 v[28:31], v[144:147], v[190:193], v[28:31]
	v_mfma_f32_16x16x32_bf16 v[24:27], v[168:171], v[190:193], v[24:27]
	v_mfma_f32_16x16x32_bf16 v[12:15], v[144:147], v[198:201], v[12:15]
	v_mfma_f32_16x16x32_bf16 v[8:11], v[168:171], v[198:201], v[8:11]
	v_mfma_f32_16x16x32_bf16 v[4:7], v[144:147], v[206:209], v[4:7]
	v_mfma_f32_16x16x32_bf16 v[0:3], v[168:171], v[206:209], v[0:3]
	v_mfma_f32_16x16x32_bf16 v[52:55], v[164:167], v[186:189], v[52:55]
	v_mfma_f32_16x16x32_bf16 v[48:51], v[178:181], v[186:189], v[48:51]
	v_mfma_f32_16x16x32_bf16 v[28:31], v[164:167], v[194:197], v[28:31]
	v_mfma_f32_16x16x32_bf16 v[24:27], v[178:181], v[194:197], v[24:27]
	v_mfma_f32_16x16x32_bf16 v[12:15], v[164:167], v[202:205], v[12:15]
	v_mfma_f32_16x16x32_bf16 v[8:11], v[178:181], v[202:205], v[8:11]
	v_mfma_f32_16x16x32_bf16 v[4:7], v[164:167], v[210:213], v[4:7]
	v_mfma_f32_16x16x32_bf16 v[0:3], v[178:181], v[210:213], v[0:3]
	s_setprio 0
	s_barrier
	s_add_i32 s67, s67, 2
	s_add_u32 s65, s65, 0x100
	s_addc_u32 s66, s66, 0
	s_mov_b64 s[26:27], s[28:29]
; #define PG8_STAGE(bufoff, gbase, voff) do { _Pragma("unroll") for (int _i = 0; _i < 2; ++_i) \
;         __builtin_amdgcn_global_load_lds((const unsigned*)((const char*)(gbase) + (voff)[_i]), (LAS unsigned*)(lds + (bufoff) + ldsw + _i * 8192), 16, 0, 0); } while (0)
; #define PG8_LDA(dst, b, h) do { _Pragma("unroll") for (int m = 0; m < 4; ++m) _Pragma("unroll") for (int k = 0; k < 2; ++k) dst[m][k] = *(const LAS bf16x8*)(lds + PG8_SA(b, h) + aoff + m * 2048 + k * 1024); } while (0)
; #define PG8_LDB(dst, b, h) do { _Pragma("unroll") for (int n = 0; n < 2; ++n) _Pragma("unroll") for (int k = 0; k < 2; ++k) dst[n][k] = *(const LAS bf16x8*)(lds + PG8_SB(b, h) + boff + n * 2048 + k * 1024); } while (0)
; #define PG8_MMA(ai, bj, At, Bt) do { __builtin_amdgcn_s_setprio(1); _Pragma("unroll") for (int m = 0; m < 4; ++m) _Pragma("unroll") for (int n = 0; n < 2; ++n) _Pragma("unroll") for (int k = 0; k < 2; ++k) \
;         acc[ai][bj][m][n] = __builtin_amdgcn_mfma_f32_16x16x32_bf16(Bt[n][k], At[m][k], acc[ai][bj][m][n], 0, 0, 0); __builtin_amdgcn_s_setprio(0); } while (0)
; #define PG8_WAIT_V(n) asm volatile("s_waitcnt vmcnt(" #n ")" ::: "memory")
; #define PG8_WAIT_L(n) asm volatile("s_waitcnt lgkmcnt(" #n ")" ::: "memory")
; #define PG8_BAR __builtin_amdgcn_s_barrier()
; template <class Epi, bool ALIGN_EPI, int K, int LDA, int LDB>
; __device__ __forceinline__ void gemm_phase(LAS unsigned char* lds, const int wid, const Gemm g, const StaticOrder& S, const Epi& E) {
;     ...
;         for (int t = 0; t < nt; t += 2) {
;             const bool last = (t == nt - 2);
;             const char* a1 = cA + (size_t)(t + 1) * kstep;
;             const char* a2 = last ? nA : cA + (size_t)(t + 2) * kstep; const char* b2 = last ? nB : cB + (size_t)(t + 2) * kstep;
;             const char* a3 = a2 + kstep; const char* b3 = b2 + kstep;
;             PG8_LDB(B0, 0, 0); PG8_LDB(B1, 0, 1); PG8_SCHED; PG8_LDA(At, 0, 0); PG8_STAGE(PG8_SA(1, 1), a1 + hA, voffA);
;             PG8_WAIT_V(8); PG8_WAIT_L(0); PG8_BAR; PG8_MMA(0, 0, At, B0); PG8_MMA(0, 1, At, B1); PG8_BAR; PG8_SCHED;
;             PG8_LDA(At, 0, 1); PG8_STAGE(PG8_SB(0, 0), b2, voffB); PG8_STAGE(PG8_SB(0, 1), b2 + hB, voffB); PG8_STAGE(PG8_SA(0, 0), a2, voffA);
;             PG8_WAIT_V(8); PG8_WAIT_L(0); PG8_BAR; PG8_MMA(1, 0, At, B0); PG8_MMA(1, 1, At, B1); PG8_BAR; PG8_SCHED;
.LBB0_1137:
	ds_read_b128 v[128:131], v175
	ds_read_b128 v[132:135], v175 offset:1024
	ds_read_b128 v[136:139], v175 offset:2048
	ds_read_b128 v[140:143], v175 offset:3072
	ds_read_b128 v[144:147], v176
	ds_read_b128 v[164:167], v176 offset:1024
	ds_read_b128 v[168:171], v176 offset:2048
	ds_read_b128 v[178:181], v176 offset:3072
	s_add_u32 s28, s26, 0x100
	s_addc_u32 s29, s27, 0
	s_cmp_eq_u32 s67, 40
	s_cselect_b32 s35, s7, s29
	s_cselect_b32 s34, s6, s28
	s_cselect_b32 s31, s25, s66
	s_cselect_b32 s30, s24, s65
	s_add_i32 m0, s36, 0xc000
	ds_read_b128 v[182:185], v177
	ds_read_b128 v[186:189], v177 offset:1024
	ds_read_b128 v[190:193], v177 offset:2048
	ds_read_b128 v[194:197], v177 offset:3072
	ds_read_b128 v[198:201], v177 offset:4096
	ds_read_b128 v[202:205], v177 offset:5120
	ds_read_b128 v[206:209], v177 offset:6144
	ds_read_b128 v[210:213], v177 offset:7168
	global_load_lds_dwordx4 v156, s[26:27]
	s_add_i32 m0, s36, 0xe000
	s_nop 0
	global_load_lds_dwordx4 v158, s[26:27]
	s_waitcnt vmcnt(8)
	s_barrier
	s_setprio 1
	s_waitcnt lgkmcnt(0)
	v_mfma_f32_16x16x32_bf16 v[124:127], v[128:131], v[182:185], v[124:127]
	v_mfma_f32_16x16x32_bf16 v[116:119], v[136:139], v[182:185], v[116:119]
	v_mfma_f32_16x16x32_bf16 v[120:123], v[128:131], v[190:193], v[120:123]
	v_mfma_f32_16x16x32_bf16 v[112:115], v[136:139], v[190:193], v[112:115]
	v_mfma_f32_16x16x32_bf16 v[92:95], v[128:131], v[198:201], v[92:95]
	v_mfma_f32_16x16x32_bf16 v[88:91], v[136:139], v[198:201], v[88:91]
	v_mfma_f32_16x16x32_bf16 v[76:79], v[128:131], v[206:209], v[76:79]
	v_mfma_f32_16x16x32_bf16 v[72:75], v[136:139], v[206:209], v[72:75]
	v_mfma_f32_16x16x32_bf16 v[124:127], v[132:135], v[186:189], v[124:127]
	v_mfma_f32_16x16x32_bf16 v[116:119], v[140:143], v[186:189], v[116:119]
	v_mfma_f32_16x16x32_bf16 v[120:123], v[132:135], v[194:197], v[120:123]
	v_mfma_f32_16x16x32_bf16 v[112:115], v[140:143], v[194:197], v[112:115]
	v_mfma_f32_16x16x32_bf16 v[92:95], v[132:135], v[202:205], v[92:95]
	v_mfma_f32_16x16x32_bf16 v[88:91], v[140:143], v[202:205], v[88:91]
	v_mfma_f32_16x16x32_bf16 v[76:79], v[132:135], v[210:213], v[76:79]
	v_mfma_f32_16x16x32_bf16 v[72:75], v[140:143], v[210:213], v[72:75]
	v_mfma_f32_16x16x32_bf16 v[108:111], v[144:147], v[182:185], v[108:111]
	v_mfma_f32_16x16x32_bf16 v[104:107], v[168:171], v[182:185], v[104:107]
	v_mfma_f32_16x16x32_bf16 v[100:103], v[144:147], v[190:193], v[100:103]
	v_mfma_f32_16x16x32_bf16 v[96:99], v[168:171], v[190:193], v[96:99]
	v_mfma_f32_16x16x32_bf16 v[84:87], v[144:147], v[198:201], v[84:87]
	v_mfma_f32_16x16x32_bf16 v[80:83], v[168:171], v[198:201], v[80:83]
	v_mfma_f32_16x16x32_bf16 v[68:71], v[144:147], v[206:209], v[68:71]
	v_mfma_f32_16x16x32_bf16 v[64:67], v[168:171], v[206:209], v[64:67]
	v_mfma_f32_16x16x32_bf16 v[108:111], v[164:167], v[186:189], v[108:111]
	v_mfma_f32_16x16x32_bf16 v[104:107], v[178:181], v[186:189], v[104:107]
	v_mfma_f32_16x16x32_bf16 v[100:103], v[164:167], v[194:197], v[100:103]
	v_mfma_f32_16x16x32_bf16 v[96:99], v[178:181], v[194:197], v[96:99]
	v_mfma_f32_16x16x32_bf16 v[84:87], v[164:167], v[202:205], v[84:87]
	v_mfma_f32_16x16x32_bf16 v[80:83], v[178:181], v[202:205], v[80:83]
	v_mfma_f32_16x16x32_bf16 v[68:71], v[164:167], v[210:213], v[68:71]
	v_mfma_f32_16x16x32_bf16 v[64:67], v[178:181], v[210:213], v[64:67]
	s_setprio 0
	s_barrier
	s_add_u32 s98, s30, s12
	s_addc_u32 s99, s31, s13
	s_add_u32 s100, s34, s12
	s_addc_u32 s101, s35, s13
	s_add_i32 s26, s54, s33
	s_mov_b32 m0, s26
	ds_read_b128 v[182:185], v177 offset:16384
	ds_read_b128 v[186:189], v177 offset:17408
	ds_read_b128 v[190:193], v177 offset:18432
	ds_read_b128 v[194:197], v177 offset:19456
	ds_read_b128 v[198:201], v177 offset:20480
	ds_read_b128 v[202:205], v177 offset:21504
	ds_read_b128 v[206:209], v177 offset:22528
	ds_read_b128 v[210:213], v177 offset:23552
	global_load_lds_dwordx4 v150, s[30:31]
	s_add_i32 m0, s26, 0x2000
	s_add_u32 s26, s30, 0xb0000
	s_addc_u32 s27, s31, 0
	s_add_i32 s52, s55, s33
	global_load_lds_dwordx4 v154, s[30:31]
	s_mov_b32 m0, s52
	s_nop 0
	global_load_lds_dwordx4 v150, s[26:27]
	s_add_i32 m0, s52, 0x2000
	s_nop 0
	global_load_lds_dwordx4 v154, s[26:27]
	s_mov_b32 m0, s36
	s_nop 0
	global_load_lds_dwordx4 v148, s[34:35]
	s_mov_b32 m0, s37
	s_nop 0
	global_load_lds_dwordx4 v152, s[34:35]
	s_waitcnt vmcnt(8)
	s_barrier
	s_setprio 1
	s_waitcnt lgkmcnt(0)
	v_mfma_f32_16x16x32_bf16 v[60:63], v[128:131], v[182:185], v[60:63]
	v_mfma_f32_16x16x32_bf16 v[56:59], v[136:139], v[182:185], v[56:59]
	v_mfma_f32_16x16x32_bf16 v[44:47], v[128:131], v[190:193], v[44:47]
	v_mfma_f32_16x16x32_bf16 v[40:43], v[136:139], v[190:193], v[40:43]
	v_mfma_f32_16x16x32_bf16 v[36:39], v[128:131], v[198:201], v[36:39]
	v_mfma_f32_16x16x32_bf16 v[32:35], v[136:139], v[198:201], v[32:35]
	v_mfma_f32_16x16x32_bf16 v[20:23], v[128:131], v[206:209], v[20:23]
	v_mfma_f32_16x16x32_bf16 v[16:19], v[136:139], v[206:209], v[16:19]
	v_mfma_f32_16x16x32_bf16 v[60:63], v[132:135], v[186:189], v[60:63]
	v_mfma_f32_16x16x32_bf16 v[56:59], v[140:143], v[186:189], v[56:59]
	v_mfma_f32_16x16x32_bf16 v[44:47], v[132:135], v[194:197], v[44:47]
	v_mfma_f32_16x16x32_bf16 v[40:43], v[140:143], v[194:197], v[40:43]
	v_mfma_f32_16x16x32_bf16 v[36:39], v[132:135], v[202:205], v[36:39]
	v_mfma_f32_16x16x32_bf16 v[32:35], v[140:143], v[202:205], v[32:35]
	v_mfma_f32_16x16x32_bf16 v[20:23], v[132:135], v[210:213], v[20:23]
	v_mfma_f32_16x16x32_bf16 v[16:19], v[140:143], v[210:213], v[16:19]
	v_mfma_f32_16x16x32_bf16 v[52:55], v[144:147], v[182:185], v[52:55]
	v_mfma_f32_16x16x32_bf16 v[48:51], v[168:171], v[182:185], v[48:51]
	v_mfma_f32_16x16x32_bf16 v[28:31], v[144:147], v[190:193], v[28:31]
	v_mfma_f32_16x16x32_bf16 v[24:27], v[168:171], v[190:193], v[24:27]
	v_mfma_f32_16x16x32_bf16 v[12:15], v[144:147], v[198:201], v[12:15]
	v_mfma_f32_16x16x32_bf16 v[8:11], v[168:171], v[198:201], v[8:11]
	v_mfma_f32_16x16x32_bf16 v[4:7], v[144:147], v[206:209], v[4:7]
	v_mfma_f32_16x16x32_bf16 v[0:3], v[168:171], v[206:209], v[0:3]
	v_mfma_f32_16x16x32_bf16 v[52:55], v[164:167], v[186:189], v[52:55]
	v_mfma_f32_16x16x32_bf16 v[48:51], v[178:181], v[186:189], v[48:51]
	v_mfma_f32_16x16x32_bf16 v[28:31], v[164:167], v[194:197], v[28:31]
	v_mfma_f32_16x16x32_bf16 v[24:27], v[178:181], v[194:197], v[24:27]
	v_mfma_f32_16x16x32_bf16 v[12:15], v[164:167], v[202:205], v[12:15]
	v_mfma_f32_16x16x32_bf16 v[8:11], v[178:181], v[202:205], v[8:11]
	v_mfma_f32_16x16x32_bf16 v[4:7], v[164:167], v[210:213], v[4:7]
	v_mfma_f32_16x16x32_bf16 v[0:3], v[178:181], v[210:213], v[0:3]
	s_setprio 0
	s_barrier
; #define PG8_STAGE(bufoff, gbase, voff) do { _Pragma("unroll") for (int _i = 0; _i < 2; ++_i) \
;         __builtin_amdgcn_global_load_lds((const unsigned*)((const char*)(gbase) + (voff)[_i]), (LAS unsigned*)(lds + (bufoff) + ldsw + _i * 8192), 16, 0, 0); } while (0)
; #define PG8_LDA(dst, b, h) do { _Pragma("unroll") for (int m = 0; m < 4; ++m) _Pragma("unroll") for (int k = 0; k < 2; ++k) dst[m][k] = *(const LAS bf16x8*)(lds + PG8_SA(b, h) + aoff + m * 2048 + k * 1024); } while (0)
; #define PG8_LDB(dst, b, h) do { _Pragma("unroll") for (int n = 0; n < 2; ++n) _Pragma("unroll") for (int k = 0; k < 2; ++k) dst[n][k] = *(const LAS bf16x8*)(lds + PG8_SB(b, h) + boff + n * 2048 + k * 1024); } while (0)
; #define PG8_MMA(ai, bj, At, Bt) do { __builtin_amdgcn_s_setprio(1); _Pragma("unroll") for (int m = 0; m < 4; ++m) _Pragma("unroll") for (int n = 0; n < 2; ++n) _Pragma("unroll") for (int k = 0; k < 2; ++k) \
;         acc[ai][bj][m][n] = __builtin_amdgcn_mfma_f32_16x16x32_bf16(Bt[n][k], At[m][k], acc[ai][bj][m][n], 0, 0, 0); __builtin_amdgcn_s_setprio(0); } while (0)
; #define PG8_WAIT_V(n) asm volatile("s_waitcnt vmcnt(" #n ")" ::: "memory")
; #define PG8_WAIT_L(n) asm volatile("s_waitcnt lgkmcnt(" #n ")" ::: "memory")
; #define PG8_BAR __builtin_amdgcn_s_barrier()
; #define PG8_SCHED __builtin_amdgcn_sched_barrier(0)
; template <class Epi, bool ALIGN_EPI, int K, int LDA, int LDB>
; __device__ __forceinline__ void gemm_phase(LAS unsigned char* lds, const int wid, const Gemm g, const StaticOrder& S, const Epi& E) {
;     ...
;         for (int t = 0; t < nt; t += 2) {
;             const bool last = (t == nt - 2);
;     ...
;             PG8_LDB(B0, 1, 0); PG8_LDB(B1, 1, 1); PG8_SCHED; PG8_LDA(At, 1, 0); PG8_STAGE(PG8_SA(0, 1), a2 + hA, voffA);
;             PG8_WAIT_V(8); PG8_WAIT_L(0); PG8_BAR; PG8_MMA(0, 0, At, B0); PG8_MMA(0, 1, At, B1); PG8_BAR; PG8_SCHED;
;             PG8_LDA(At, 1, 1); PG8_STAGE(PG8_SB(1, 0), b3, voffB); PG8_STAGE(PG8_SB(1, 1), b3 + hB, voffB); PG8_STAGE(PG8_SA(1, 0), a3, voffA);
;             PG8_WAIT_V(8); PG8_WAIT_L(0); PG8_BAR; PG8_MMA(1, 0, At, B0); PG8_MMA(1, 1, At, B1); PG8_BAR; PG8_SCHED;
	s_add_i32 s52, 0, 0x18000
	s_add_i32 s53, 0, 0x1c000
	v_add_u32_e32 v140, s52, v174
	v_add_u32_e32 v178, s53, v174
	ds_read_b128 v[128:131], v140
	ds_read_b128 v[132:135], v140 offset:1024
	ds_read_b128 v[136:139], v140 offset:2048
	ds_read_b128 v[140:143], v140 offset:3072
	ds_read_b128 v[144:147], v178
	ds_read_b128 v[164:167], v178 offset:1024
	ds_read_b128 v[168:171], v178 offset:2048
	ds_read_b128 v[178:181], v178 offset:3072
	s_add_u32 s26, s34, 0xb0000
	s_addc_u32 s27, s35, 0
	s_mov_b32 m0, s38
	ds_read_b128 v[182:185], v177 offset:32768
	ds_read_b128 v[186:189], v177 offset:33792
	ds_read_b128 v[190:193], v177 offset:34816
	ds_read_b128 v[194:197], v177 offset:35840
	ds_read_b128 v[198:201], v177 offset:36864
	ds_read_b128 v[202:205], v177 offset:37888
	ds_read_b128 v[206:209], v177 offset:38912
	ds_read_b128 v[210:213], v177 offset:39936
	global_load_lds_dwordx4 v148, s[26:27]
	s_mov_b32 m0, s39
	s_nop 0
	global_load_lds_dwordx4 v152, s[26:27]
	s_waitcnt vmcnt(8)
	s_barrier
	s_setprio 1
	s_waitcnt lgkmcnt(0)
	v_mfma_f32_16x16x32_bf16 v[124:127], v[128:131], v[182:185], v[124:127]
	v_mfma_f32_16x16x32_bf16 v[116:119], v[136:139], v[182:185], v[116:119]
	v_mfma_f32_16x16x32_bf16 v[120:123], v[128:131], v[190:193], v[120:123]
	v_mfma_f32_16x16x32_bf16 v[112:115], v[136:139], v[190:193], v[112:115]
	v_mfma_f32_16x16x32_bf16 v[92:95], v[128:131], v[198:201], v[92:95]
	v_mfma_f32_16x16x32_bf16 v[88:91], v[136:139], v[198:201], v[88:91]
	v_mfma_f32_16x16x32_bf16 v[76:79], v[128:131], v[206:209], v[76:79]
	v_mfma_f32_16x16x32_bf16 v[72:75], v[136:139], v[206:209], v[72:75]
	v_mfma_f32_16x16x32_bf16 v[124:127], v[132:135], v[186:189], v[124:127]
	v_mfma_f32_16x16x32_bf16 v[116:119], v[140:143], v[186:189], v[116:119]
	v_mfma_f32_16x16x32_bf16 v[120:123], v[132:135], v[194:197], v[120:123]
	v_mfma_f32_16x16x32_bf16 v[112:115], v[140:143], v[194:197], v[112:115]
	v_mfma_f32_16x16x32_bf16 v[92:95], v[132:135], v[202:205], v[92:95]
	v_mfma_f32_16x16x32_bf16 v[88:91], v[140:143], v[202:205], v[88:91]
	v_mfma_f32_16x16x32_bf16 v[76:79], v[132:135], v[210:213], v[76:79]
	v_mfma_f32_16x16x32_bf16 v[72:75], v[140:143], v[210:213], v[72:75]
	v_mfma_f32_16x16x32_bf16 v[108:111], v[144:147], v[182:185], v[108:111]
	v_mfma_f32_16x16x32_bf16 v[104:107], v[168:171], v[182:185], v[104:107]
	v_mfma_f32_16x16x32_bf16 v[100:103], v[144:147], v[190:193], v[100:103]
	v_mfma_f32_16x16x32_bf16 v[96:99], v[168:171], v[190:193], v[96:99]
	v_mfma_f32_16x16x32_bf16 v[84:87], v[144:147], v[198:201], v[84:87]
	v_mfma_f32_16x16x32_bf16 v[80:83], v[168:171], v[198:201], v[80:83]
	v_mfma_f32_16x16x32_bf16 v[68:71], v[144:147], v[206:209], v[68:71]
	v_mfma_f32_16x16x32_bf16 v[64:67], v[168:171], v[206:209], v[64:67]
	v_mfma_f32_16x16x32_bf16 v[108:111], v[164:167], v[186:189], v[108:111]
	v_mfma_f32_16x16x32_bf16 v[104:107], v[178:181], v[186:189], v[104:107]
	v_mfma_f32_16x16x32_bf16 v[100:103], v[164:167], v[194:197], v[100:103]
	v_mfma_f32_16x16x32_bf16 v[96:99], v[178:181], v[194:197], v[96:99]
	v_mfma_f32_16x16x32_bf16 v[84:87], v[164:167], v[202:205], v[84:87]
	v_mfma_f32_16x16x32_bf16 v[80:83], v[178:181], v[202:205], v[80:83]
	v_mfma_f32_16x16x32_bf16 v[68:71], v[164:167], v[210:213], v[68:71]
	v_mfma_f32_16x16x32_bf16 v[64:67], v[178:181], v[210:213], v[64:67]
	s_setprio 0
	s_barrier
	s_add_i32 s26, s52, s33
	s_mov_b32 m0, s26
	ds_read_b128 v[182:185], v177 offset:49152
	ds_read_b128 v[186:189], v177 offset:50176
	ds_read_b128 v[190:193], v177 offset:51200
	ds_read_b128 v[194:197], v177 offset:52224
	ds_read_b128 v[198:201], v177 offset:53248
	ds_read_b128 v[202:205], v177 offset:54272
	ds_read_b128 v[206:209], v177 offset:55296
	ds_read_b128 v[210:213], v177 offset:56320
	global_load_lds_dwordx4 v150, s[98:99]
	s_add_i32 m0, s26, 0x2000
	s_add_u32 s26, s30, 0xb0080
	s_addc_u32 s27, s31, 0
	s_add_i32 s30, s53, s33
	global_load_lds_dwordx4 v154, s[98:99]
	s_mov_b32 m0, s30
	s_nop 0
	global_load_lds_dwordx4 v150, s[26:27]
	s_add_i32 m0, s30, 0x2000
	s_nop 0
	global_load_lds_dwordx4 v154, s[26:27]
	s_mov_b32 m0, s48
	s_nop 0
	global_load_lds_dwordx4 v148, s[100:101]
	s_mov_b32 m0, s49
	s_nop 0
	global_load_lds_dwordx4 v152, s[100:101]
	s_waitcnt vmcnt(8)
	s_barrier
	s_setprio 1
	s_waitcnt lgkmcnt(0)
	v_mfma_f32_16x16x32_bf16 v[60:63], v[128:131], v[182:185], v[60:63]
	v_mfma_f32_16x16x32_bf16 v[56:59], v[136:139], v[182:185], v[56:59]
	v_mfma_f32_16x16x32_bf16 v[44:47], v[128:131], v[190:193], v[44:47]
	v_mfma_f32_16x16x32_bf16 v[40:43], v[136:139], v[190:193], v[40:43]
	v_mfma_f32_16x16x32_bf16 v[36:39], v[128:131], v[198:201], v[36:39]
	v_mfma_f32_16x16x32_bf16 v[32:35], v[136:139], v[198:201], v[32:35]
	v_mfma_f32_16x16x32_bf16 v[20:23], v[128:131], v[206:209], v[20:23]
	v_mfma_f32_16x16x32_bf16 v[16:19], v[136:139], v[206:209], v[16:19]
	v_mfma_f32_16x16x32_bf16 v[60:63], v[132:135], v[186:189], v[60:63]
	v_mfma_f32_16x16x32_bf16 v[56:59], v[140:143], v[186:189], v[56:59]
	v_mfma_f32_16x16x32_bf16 v[44:47], v[132:135], v[194:197], v[44:47]
	v_mfma_f32_16x16x32_bf16 v[40:43], v[140:143], v[194:197], v[40:43]
	v_mfma_f32_16x16x32_bf16 v[36:39], v[132:135], v[202:205], v[36:39]
	v_mfma_f32_16x16x32_bf16 v[32:35], v[140:143], v[202:205], v[32:35]
	v_mfma_f32_16x16x32_bf16 v[20:23], v[132:135], v[210:213], v[20:23]
	v_mfma_f32_16x16x32_bf16 v[16:19], v[140:143], v[210:213], v[16:19]
	v_mfma_f32_16x16x32_bf16 v[52:55], v[144:147], v[182:185], v[52:55]
	v_mfma_f32_16x16x32_bf16 v[48:51], v[168:171], v[182:185], v[48:51]
	v_mfma_f32_16x16x32_bf16 v[28:31], v[144:147], v[190:193], v[28:31]
	v_mfma_f32_16x16x32_bf16 v[24:27], v[168:171], v[190:193], v[24:27]
	v_mfma_f32_16x16x32_bf16 v[12:15], v[144:147], v[198:201], v[12:15]
	v_mfma_f32_16x16x32_bf16 v[8:11], v[168:171], v[198:201], v[8:11]
	v_mfma_f32_16x16x32_bf16 v[4:7], v[144:147], v[206:209], v[4:7]
	v_mfma_f32_16x16x32_bf16 v[0:3], v[168:171], v[206:209], v[0:3]
	v_mfma_f32_16x16x32_bf16 v[52:55], v[164:167], v[186:189], v[52:55]
	v_mfma_f32_16x16x32_bf16 v[48:51], v[178:181], v[186:189], v[48:51]
	v_mfma_f32_16x16x32_bf16 v[28:31], v[164:167], v[194:197], v[28:31]
	v_mfma_f32_16x16x32_bf16 v[24:27], v[178:181], v[194:197], v[24:27]
	v_mfma_f32_16x16x32_bf16 v[12:15], v[164:167], v[202:205], v[12:15]
	v_mfma_f32_16x16x32_bf16 v[8:11], v[178:181], v[202:205], v[8:11]
	v_mfma_f32_16x16x32_bf16 v[4:7], v[164:167], v[210:213], v[4:7]
	v_mfma_f32_16x16x32_bf16 v[0:3], v[178:181], v[210:213], v[0:3]
	s_setprio 0
	s_barrier
	s_add_i32 s67, s67, 2
	s_add_u32 s65, s65, 0x100
	s_addc_u32 s66, s66, 0
	s_cmp_gt_u32 s67, 41
	s_mov_b64 s[26:27], s[28:29]
	s_cbranch_scc0 .LBB0_1137
	s_and_b64 vcc, exec, s[14:15]
	s_cbranch_vccz .LBB0_1140
	s_barrier

; #define PG8_STAGE(bufoff, gbase, voff) do { _Pragma("unroll") for (int _i = 0; _i < 2; ++_i) \
;         __builtin_amdgcn_global_load_lds((const unsigned*)((const char*)(gbase) + (voff)[_i]), (LAS unsigned*)(lds + (bufoff) + ldsw + _i * 8192), 16, 0, 0); } while (0)
; #define PG8_LDA(dst, b, h) do { _Pragma("unroll") for (int m = 0; m < 4; ++m) _Pragma("unroll") for (int k = 0; k < 2; ++k) dst[m][k] = *(const LAS bf16x8*)(lds + PG8_SA(b, h) + aoff + m * 2048 + k * 1024); } while (0)
; #define PG8_LDB(dst, b, h) do { _Pragma("unroll") for (int n = 0; n < 2; ++n) _Pragma("unroll") for (int k = 0; k < 2; ++k) dst[n][k] = *(const LAS bf16x8*)(lds + PG8_SB(b, h) + boff + n * 2048 + k * 1024); } while (0)
; #define PG8_MMA(ai, bj, At, Bt) do { __builtin_amdgcn_s_setprio(1); _Pragma("unroll") for (int m = 0; m < 4; ++m) _Pragma("unroll") for (int n = 0; n < 2; ++n) _Pragma("unroll") for (int k = 0; k < 2; ++k) \
;         acc[ai][bj][m][n] = __builtin_amdgcn_mfma_f32_16x16x32_bf16(Bt[n][k], At[m][k], acc[ai][bj][m][n], 0, 0, 0); __builtin_amdgcn_s_setprio(0); } while (0)
; template <class Epi, bool ALIGN_EPI, int K, int LDA, int LDB>
; __device__ __forceinline__ void gemm_phase(LAS unsigned char* lds, const int wid, const Gemm g, const StaticOrder& S, const Epi& E) {
;     ...
;         const bool has_next = S.next(ui + 1, nxt);
;         const char* nA = has_next ? (const char*)g.A + (size_t)nxt.pm * tA : cA; const char* nB = has_next ? (const char*)g.Bt + (size_t)nxt.pn * tB : cB;
;         for (int t = 0; t < nt; t += 2) {
;             const bool last = (t == nt - 2);
;             const char* a1 = cA + (size_t)(t + 1) * kstep;
;             const char* a2 = last ? nA : cA + (size_t)(t + 2) * kstep; const char* b2 = last ? nB : cB + (size_t)(t + 2) * kstep;
;             const char* a3 = a2 + kstep; const char* b3 = b2 + kstep;
;             PG8_LDB(B0, 0, 0); PG8_LDB(B1, 0, 1); PG8_SCHED; PG8_LDA(At, 0, 0); PG8_STAGE(PG8_SA(1, 1), a1 + hA, voffA);
;             PG8_WAIT_V(8); PG8_WAIT_L(0); PG8_BAR; PG8_MMA(0, 0, At, B0); PG8_MMA(0, 1, At, B1); PG8_BAR; PG8_SCHED;
;             PG8_LDA(At, 0, 1); PG8_STAGE(PG8_SB(0, 0), b2, voffB); PG8_STAGE(PG8_SB(0, 1), b2 + hB, voffB); PG8_STAGE(PG8_SA(0, 0), a2, voffA);
;             PG8_WAIT_V(8); PG8_WAIT_L(0); PG8_BAR; PG8_MMA(1, 0, At, B0); PG8_MMA(1, 1, At, B1); PG8_BAR; PG8_SCHED;
.LBB0_1278:
	s_ashr_i32 s25, s24, 31
	s_lshl_b64 s[26:27], s[24:25], 19
	v_readlane_b32 s7, v254, 0
	s_add_u32 s26, s7, s26
	v_readlane_b32 s7, v254, 1
	s_addc_u32 s27, s7, s27
	s_and_b64 s[28:29], s[4:5], exec
	s_cselect_b32 s7, s27, s35
	s_cselect_b32 s25, s26, s34
	s_ashr_i32 s23, s22, 31
	s_lshl_b64 s[28:29], s[22:23], 19
	s_add_u32 s28, s0, s28
	s_addc_u32 s29, s1, s29
	s_and_b64 s[38:39], s[4:5], exec
	s_cselect_b32 s23, s29, s37
	s_cselect_b32 s42, s28, s36
	s_add_u32 s34, s34, 0x40080
	s_addc_u32 s35, s35, 0
	s_add_u32 s59, s36, 0x100
	s_addc_u32 s60, s37, 0
	s_mov_b32 s61, -2
	s_add_u32 s36, s34, 0xfffc0080
	s_addc_u32 s37, s35, -1
	s_cmp_eq_u32 s61, 12
	s_cselect_b32 s39, s7, s37
	s_cselect_b32 s38, s25, s36
	s_cselect_b32 s37, s23, s60
	s_cselect_b32 s36, s42, s59
	s_add_i32 m0, s31, 0xc000
	global_load_lds_dwordx4 v136, s[34:35]
	s_add_i32 m0, s31, 0xe000
	s_nop 0
	global_load_lds_dwordx4 v138, s[34:35]
	s_waitcnt vmcnt(8)
	s_barrier
	s_setprio 1
	s_waitcnt lgkmcnt(0)
	v_mfma_f32_16x16x32_bf16 v[124:127], v[144:147], v[182:185], 0
	v_mfma_f32_16x16x32_bf16 v[120:123], v[158:161], v[182:185], 0
	v_mfma_f32_16x16x32_bf16 v[108:111], v[144:147], v[190:193], 0
	v_mfma_f32_16x16x32_bf16 v[104:107], v[158:161], v[190:193], 0
	v_mfma_f32_16x16x32_bf16 v[92:95], v[144:147], v[198:201], 0
	v_mfma_f32_16x16x32_bf16 v[88:91], v[158:161], v[198:201], 0
	v_mfma_f32_16x16x32_bf16 v[76:79], v[144:147], v[206:209], 0
	v_mfma_f32_16x16x32_bf16 v[72:75], v[158:161], v[206:209], 0
	v_mfma_f32_16x16x32_bf16 v[124:127], v[154:157], v[186:189], v[124:127]
	v_mfma_f32_16x16x32_bf16 v[120:123], v[162:165], v[186:189], v[120:123]
	v_mfma_f32_16x16x32_bf16 v[108:111], v[154:157], v[194:197], v[108:111]
	v_mfma_f32_16x16x32_bf16 v[104:107], v[162:165], v[194:197], v[104:107]
	v_mfma_f32_16x16x32_bf16 v[92:95], v[154:157], v[202:205], v[92:95]
	v_mfma_f32_16x16x32_bf16 v[88:91], v[162:165], v[202:205], v[88:91]
	v_mfma_f32_16x16x32_bf16 v[76:79], v[154:157], v[210:213], v[76:79]
	v_mfma_f32_16x16x32_bf16 v[72:75], v[162:165], v[210:213], v[72:75]
	v_mfma_f32_16x16x32_bf16 v[116:119], v[166:169], v[182:185], 0
	v_mfma_f32_16x16x32_bf16 v[112:115], v[174:177], v[182:185], 0
	v_mfma_f32_16x16x32_bf16 v[100:103], v[166:169], v[190:193], 0
	v_mfma_f32_16x16x32_bf16 v[96:99], v[174:177], v[190:193], 0
	v_mfma_f32_16x16x32_bf16 v[84:87], v[166:169], v[198:201], 0
	v_mfma_f32_16x16x32_bf16 v[80:83], v[174:177], v[198:201], 0
	v_mfma_f32_16x16x32_bf16 v[68:71], v[166:169], v[206:209], 0
	v_mfma_f32_16x16x32_bf16 v[64:67], v[174:177], v[206:209], 0
	v_mfma_f32_16x16x32_bf16 v[116:119], v[170:173], v[186:189], v[116:119]
	v_mfma_f32_16x16x32_bf16 v[112:115], v[178:181], v[186:189], v[112:115]
	v_mfma_f32_16x16x32_bf16 v[100:103], v[170:173], v[194:197], v[100:103]
	v_mfma_f32_16x16x32_bf16 v[96:99], v[178:181], v[194:197], v[96:99]
	v_mfma_f32_16x16x32_bf16 v[84:87], v[170:173], v[202:205], v[84:87]
	v_mfma_f32_16x16x32_bf16 v[80:83], v[178:181], v[202:205], v[80:83]
	v_mfma_f32_16x16x32_bf16 v[68:71], v[170:173], v[210:213], v[68:71]
	v_mfma_f32_16x16x32_bf16 v[64:67], v[178:181], v[210:213], v[64:67]
	s_setprio 0
	s_barrier
	s_add_u32 s98, s36, s12
	s_addc_u32 s99, s37, s13
	s_add_u32 s100, s38, s12
	s_addc_u32 s101, s39, s13
	s_add_i32 s52, s57, s3
	s_mov_b32 m0, s52
	ds_read_b128 v[182:185], v153 offset:16384
	ds_read_b128 v[186:189], v153 offset:17408
	ds_read_b128 v[190:193], v153 offset:18432
	ds_read_b128 v[194:197], v153 offset:19456
	ds_read_b128 v[198:201], v153 offset:20480
	ds_read_b128 v[202:205], v153 offset:21504
	ds_read_b128 v[206:209], v153 offset:22528
	ds_read_b128 v[210:213], v153 offset:23552
	global_load_lds_dwordx4 v130, s[36:37]
	s_add_i32 m0, s52, 0x2000
	s_add_u32 s62, s36, 0x40000
	s_addc_u32 s63, s37, 0
	s_add_i32 s52, s58, s3
	global_load_lds_dwordx4 v134, s[36:37]
	s_mov_b32 m0, s52
	s_nop 0
	global_load_lds_dwordx4 v130, s[62:63]
	s_add_i32 m0, s52, 0x2000
	s_nop 0
	global_load_lds_dwordx4 v134, s[62:63]
	s_mov_b32 m0, s31
	s_nop 0
	global_load_lds_dwordx4 v128, s[38:39]
	s_mov_b32 m0, s33
	s_nop 0
	global_load_lds_dwordx4 v132, s[38:39]
	s_waitcnt vmcnt(8)
	s_barrier
	s_setprio 1
	s_waitcnt lgkmcnt(0)
	v_mfma_f32_16x16x32_bf16 v[60:63], v[144:147], v[182:185], 0
	v_mfma_f32_16x16x32_bf16 v[56:59], v[158:161], v[182:185], 0
	v_mfma_f32_16x16x32_bf16 v[44:47], v[144:147], v[190:193], 0
	v_mfma_f32_16x16x32_bf16 v[40:43], v[158:161], v[190:193], 0
	v_mfma_f32_16x16x32_bf16 v[28:31], v[144:147], v[198:201], 0
	v_mfma_f32_16x16x32_bf16 v[24:27], v[158:161], v[198:201], 0
	v_mfma_f32_16x16x32_bf16 v[12:15], v[144:147], v[206:209], 0
	v_mfma_f32_16x16x32_bf16 v[8:11], v[158:161], v[206:209], 0
	v_mfma_f32_16x16x32_bf16 v[60:63], v[154:157], v[186:189], v[60:63]
	v_mfma_f32_16x16x32_bf16 v[56:59], v[162:165], v[186:189], v[56:59]
	v_mfma_f32_16x16x32_bf16 v[44:47], v[154:157], v[194:197], v[44:47]
	v_mfma_f32_16x16x32_bf16 v[40:43], v[162:165], v[194:197], v[40:43]
	v_mfma_f32_16x16x32_bf16 v[28:31], v[154:157], v[202:205], v[28:31]
	v_mfma_f32_16x16x32_bf16 v[24:27], v[162:165], v[202:205], v[24:27]
	v_mfma_f32_16x16x32_bf16 v[12:15], v[154:157], v[210:213], v[12:15]
	v_mfma_f32_16x16x32_bf16 v[8:11], v[162:165], v[210:213], v[8:11]
	v_mfma_f32_16x16x32_bf16 v[52:55], v[166:169], v[182:185], 0
	v_mfma_f32_16x16x32_bf16 v[48:51], v[174:177], v[182:185], 0
	v_mfma_f32_16x16x32_bf16 v[36:39], v[166:169], v[190:193], 0
	v_mfma_f32_16x16x32_bf16 v[32:35], v[174:177], v[190:193], 0
	v_mfma_f32_16x16x32_bf16 v[20:23], v[166:169], v[198:201], 0
	v_mfma_f32_16x16x32_bf16 v[16:19], v[174:177], v[198:201], 0
	v_mfma_f32_16x16x32_bf16 v[4:7], v[166:169], v[206:209], 0
	v_mfma_f32_16x16x32_bf16 v[0:3], v[174:177], v[206:209], 0
	v_mfma_f32_16x16x32_bf16 v[52:55], v[170:173], v[186:189], v[52:55]
	v_mfma_f32_16x16x32_bf16 v[48:51], v[178:181], v[186:189], v[48:51]
	v_mfma_f32_16x16x32_bf16 v[36:39], v[170:173], v[194:197], v[36:39]
	v_mfma_f32_16x16x32_bf16 v[32:35], v[178:181], v[194:197], v[32:35]
	v_mfma_f32_16x16x32_bf16 v[20:23], v[170:173], v[202:205], v[20:23]
	v_mfma_f32_16x16x32_bf16 v[16:19], v[178:181], v[202:205], v[16:19]
	v_mfma_f32_16x16x32_bf16 v[4:7], v[170:173], v[210:213], v[4:7]
	v_mfma_f32_16x16x32_bf16 v[0:3], v[178:181], v[210:213], v[0:3]
	s_setprio 0
	s_barrier
; #define PG8_STAGE(bufoff, gbase, voff) do { _Pragma("unroll") for (int _i = 0; _i < 2; ++_i) \
;         __builtin_amdgcn_global_load_lds((const unsigned*)((const char*)(gbase) + (voff)[_i]), (LAS unsigned*)(lds + (bufoff) + ldsw + _i * 8192), 16, 0, 0); } while (0)
; #define PG8_LDA(dst, b, h) do { _Pragma("unroll") for (int m = 0; m < 4; ++m) _Pragma("unroll") for (int k = 0; k < 2; ++k) dst[m][k] = *(const LAS bf16x8*)(lds + PG8_SA(b, h) + aoff + m * 2048 + k * 1024); } while (0)
; #define PG8_LDB(dst, b, h) do { _Pragma("unroll") for (int n = 0; n < 2; ++n) _Pragma("unroll") for (int k = 0; k < 2; ++k) dst[n][k] = *(const LAS bf16x8*)(lds + PG8_SB(b, h) + boff + n * 2048 + k * 1024); } while (0)
; #define PG8_MMA(ai, bj, At, Bt) do { __builtin_amdgcn_s_setprio(1); _Pragma("unroll") for (int m = 0; m < 4; ++m) _Pragma("unroll") for (int n = 0; n < 2; ++n) _Pragma("unroll") for (int k = 0; k < 2; ++k) \
;         acc[ai][bj][m][n] = __builtin_amdgcn_mfma_f32_16x16x32_bf16(Bt[n][k], At[m][k], acc[ai][bj][m][n], 0, 0, 0); __builtin_amdgcn_s_setprio(0); } while (0)
; #define PG8_WAIT_V(n) asm volatile("s_waitcnt vmcnt(" #n ")" ::: "memory")
; #define PG8_WAIT_L(n) asm volatile("s_waitcnt lgkmcnt(" #n ")" ::: "memory")
; #define PG8_BAR __builtin_amdgcn_s_barrier()
; #define PG8_SCHED __builtin_amdgcn_sched_barrier(0)
; template <class Epi, bool ALIGN_EPI, int K, int LDA, int LDB>
; __device__ __forceinline__ void gemm_phase(LAS unsigned char* lds, const int wid, const Gemm g, const StaticOrder& S, const Epi& E) {
;     ...
;             PG8_LDB(B0, 1, 0); PG8_LDB(B1, 1, 1); PG8_SCHED; PG8_LDA(At, 1, 0); PG8_STAGE(PG8_SA(0, 1), a2 + hA, voffA);
;             PG8_WAIT_V(8); PG8_WAIT_L(0); PG8_BAR; PG8_MMA(0, 0, At, B0); PG8_MMA(0, 1, At, B1); PG8_BAR; PG8_SCHED;
;             PG8_LDA(At, 1, 1); PG8_STAGE(PG8_SB(1, 0), b3, voffB); PG8_STAGE(PG8_SB(1, 1), b3 + hB, voffB); PG8_STAGE(PG8_SA(1, 0), a3, voffA);
;             PG8_WAIT_V(8); PG8_WAIT_L(0); PG8_BAR; PG8_MMA(1, 0, At, B0); PG8_MMA(1, 1, At, B1); PG8_BAR; PG8_SCHED;
	s_add_i32 s52, 0, 0x18000
	s_add_i32 s53, 0, 0x1c000
	v_add_u32_e32 v162, s52, v150
	v_add_u32_e32 v178, s53, v150
	ds_read_b128 v[144:147], v162
	ds_read_b128 v[154:157], v162 offset:1024
	ds_read_b128 v[158:161], v162 offset:2048
	ds_read_b128 v[162:165], v162 offset:3072
	ds_read_b128 v[166:169], v178
	ds_read_b128 v[170:173], v178 offset:1024
	ds_read_b128 v[174:177], v178 offset:2048
	ds_read_b128 v[178:181], v178 offset:3072
	s_add_u32 s38, s38, 0x40000
	s_addc_u32 s39, s39, 0
	s_mov_b32 m0, s40
	ds_read_b128 v[182:185], v153 offset:32768
	ds_read_b128 v[186:189], v153 offset:33792
	ds_read_b128 v[190:193], v153 offset:34816
	ds_read_b128 v[194:197], v153 offset:35840
	ds_read_b128 v[198:201], v153 offset:36864
	ds_read_b128 v[202:205], v153 offset:37888
	ds_read_b128 v[206:209], v153 offset:38912
	ds_read_b128 v[210:213], v153 offset:39936
	global_load_lds_dwordx4 v128, s[38:39]
	s_mov_b32 m0, s41
	s_nop 0
	global_load_lds_dwordx4 v132, s[38:39]
	s_waitcnt vmcnt(8)
	s_barrier
	s_setprio 1
	s_waitcnt lgkmcnt(0)
	v_mfma_f32_16x16x32_bf16 v[124:127], v[144:147], v[182:185], v[124:127]
	v_mfma_f32_16x16x32_bf16 v[120:123], v[158:161], v[182:185], v[120:123]
	v_mfma_f32_16x16x32_bf16 v[108:111], v[144:147], v[190:193], v[108:111]
	v_mfma_f32_16x16x32_bf16 v[104:107], v[158:161], v[190:193], v[104:107]
	v_mfma_f32_16x16x32_bf16 v[92:95], v[144:147], v[198:201], v[92:95]
	v_mfma_f32_16x16x32_bf16 v[88:91], v[158:161], v[198:201], v[88:91]
	v_mfma_f32_16x16x32_bf16 v[76:79], v[144:147], v[206:209], v[76:79]
	v_mfma_f32_16x16x32_bf16 v[72:75], v[158:161], v[206:209], v[72:75]
	v_mfma_f32_16x16x32_bf16 v[124:127], v[154:157], v[186:189], v[124:127]
	v_mfma_f32_16x16x32_bf16 v[120:123], v[162:165], v[186:189], v[120:123]
	v_mfma_f32_16x16x32_bf16 v[108:111], v[154:157], v[194:197], v[108:111]
	v_mfma_f32_16x16x32_bf16 v[104:107], v[162:165], v[194:197], v[104:107]
	v_mfma_f32_16x16x32_bf16 v[92:95], v[154:157], v[202:205], v[92:95]
	v_mfma_f32_16x16x32_bf16 v[88:91], v[162:165], v[202:205], v[88:91]
	v_mfma_f32_16x16x32_bf16 v[76:79], v[154:157], v[210:213], v[76:79]
	v_mfma_f32_16x16x32_bf16 v[72:75], v[162:165], v[210:213], v[72:75]
	v_mfma_f32_16x16x32_bf16 v[116:119], v[166:169], v[182:185], v[116:119]
	v_mfma_f32_16x16x32_bf16 v[112:115], v[174:177], v[182:185], v[112:115]
	v_mfma_f32_16x16x32_bf16 v[100:103], v[166:169], v[190:193], v[100:103]
	v_mfma_f32_16x16x32_bf16 v[96:99], v[174:177], v[190:193], v[96:99]
	v_mfma_f32_16x16x32_bf16 v[84:87], v[166:169], v[198:201], v[84:87]
	v_mfma_f32_16x16x32_bf16 v[80:83], v[174:177], v[198:201], v[80:83]
	v_mfma_f32_16x16x32_bf16 v[68:71], v[166:169], v[206:209], v[68:71]
	v_mfma_f32_16x16x32_bf16 v[64:67], v[174:177], v[206:209], v[64:67]
	v_mfma_f32_16x16x32_bf16 v[116:119], v[170:173], v[186:189], v[116:119]
	v_mfma_f32_16x16x32_bf16 v[112:115], v[178:181], v[186:189], v[112:115]
	v_mfma_f32_16x16x32_bf16 v[100:103], v[170:173], v[194:197], v[100:103]
	v_mfma_f32_16x16x32_bf16 v[96:99], v[178:181], v[194:197], v[96:99]
	v_mfma_f32_16x16x32_bf16 v[84:87], v[170:173], v[202:205], v[84:87]
	v_mfma_f32_16x16x32_bf16 v[80:83], v[178:181], v[202:205], v[80:83]
	v_mfma_f32_16x16x32_bf16 v[68:71], v[170:173], v[210:213], v[68:71]
	v_mfma_f32_16x16x32_bf16 v[64:67], v[178:181], v[210:213], v[64:67]
	s_setprio 0
	s_barrier
	s_add_i32 s38, s52, s3
	s_mov_b32 m0, s38
	ds_read_b128 v[182:185], v153 offset:49152
	ds_read_b128 v[186:189], v153 offset:50176
	ds_read_b128 v[190:193], v153 offset:51200
	ds_read_b128 v[194:197], v153 offset:52224
	ds_read_b128 v[198:201], v153 offset:53248
	ds_read_b128 v[202:205], v153 offset:54272
	ds_read_b128 v[206:209], v153 offset:55296
	ds_read_b128 v[210:213], v153 offset:56320
	global_load_lds_dwordx4 v130, s[98:99]
	s_add_i32 m0, s38, 0x2000
	s_add_u32 s36, s36, 0x40080
	s_addc_u32 s37, s37, 0
	s_add_i32 s38, s53, s3
	global_load_lds_dwordx4 v134, s[98:99]
	s_mov_b32 m0, s38
	s_nop 0
	global_load_lds_dwordx4 v130, s[36:37]
	s_add_i32 m0, s38, 0x2000
	s_nop 0
	global_load_lds_dwordx4 v134, s[36:37]
	s_mov_b32 m0, s55
	s_nop 0
	global_load_lds_dwordx4 v128, s[100:101]
	s_mov_b32 m0, s56
	s_nop 0
	global_load_lds_dwordx4 v132, s[100:101]
	s_waitcnt vmcnt(8)
	s_barrier
	s_setprio 1
	s_waitcnt lgkmcnt(0)
	v_mfma_f32_16x16x32_bf16 v[60:63], v[144:147], v[182:185], v[60:63]
	v_mfma_f32_16x16x32_bf16 v[56:59], v[158:161], v[182:185], v[56:59]
	v_mfma_f32_16x16x32_bf16 v[44:47], v[144:147], v[190:193], v[44:47]
	v_mfma_f32_16x16x32_bf16 v[40:43], v[158:161], v[190:193], v[40:43]
	v_mfma_f32_16x16x32_bf16 v[28:31], v[144:147], v[198:201], v[28:31]
	v_mfma_f32_16x16x32_bf16 v[24:27], v[158:161], v[198:201], v[24:27]
	v_mfma_f32_16x16x32_bf16 v[12:15], v[144:147], v[206:209], v[12:15]
	v_mfma_f32_16x16x32_bf16 v[8:11], v[158:161], v[206:209], v[8:11]
	v_mfma_f32_16x16x32_bf16 v[60:63], v[154:157], v[186:189], v[60:63]
	v_mfma_f32_16x16x32_bf16 v[56:59], v[162:165], v[186:189], v[56:59]
	v_mfma_f32_16x16x32_bf16 v[44:47], v[154:157], v[194:197], v[44:47]
	v_mfma_f32_16x16x32_bf16 v[40:43], v[162:165], v[194:197], v[40:43]
	v_mfma_f32_16x16x32_bf16 v[28:31], v[154:157], v[202:205], v[28:31]
	v_mfma_f32_16x16x32_bf16 v[24:27], v[162:165], v[202:205], v[24:27]
	v_mfma_f32_16x16x32_bf16 v[12:15], v[154:157], v[210:213], v[12:15]
	v_mfma_f32_16x16x32_bf16 v[8:11], v[162:165], v[210:213], v[8:11]
	v_mfma_f32_16x16x32_bf16 v[52:55], v[166:169], v[182:185], v[52:55]
	v_mfma_f32_16x16x32_bf16 v[48:51], v[174:177], v[182:185], v[48:51]
	v_mfma_f32_16x16x32_bf16 v[36:39], v[166:169], v[190:193], v[36:39]
	v_mfma_f32_16x16x32_bf16 v[32:35], v[174:177], v[190:193], v[32:35]
	v_mfma_f32_16x16x32_bf16 v[20:23], v[166:169], v[198:201], v[20:23]
	v_mfma_f32_16x16x32_bf16 v[16:19], v[174:177], v[198:201], v[16:19]
	v_mfma_f32_16x16x32_bf16 v[4:7], v[166:169], v[206:209], v[4:7]
	v_mfma_f32_16x16x32_bf16 v[0:3], v[174:177], v[206:209], v[0:3]
	v_mfma_f32_16x16x32_bf16 v[52:55], v[170:173], v[186:189], v[52:55]
	v_mfma_f32_16x16x32_bf16 v[48:51], v[178:181], v[186:189], v[48:51]
	v_mfma_f32_16x16x32_bf16 v[36:39], v[170:173], v[194:197], v[36:39]
	v_mfma_f32_16x16x32_bf16 v[32:35], v[178:181], v[194:197], v[32:35]
	v_mfma_f32_16x16x32_bf16 v[20:23], v[170:173], v[202:205], v[20:23]
	v_mfma_f32_16x16x32_bf16 v[16:19], v[178:181], v[202:205], v[16:19]
	v_mfma_f32_16x16x32_bf16 v[4:7], v[170:173], v[210:213], v[4:7]
	v_mfma_f32_16x16x32_bf16 v[0:3], v[178:181], v[210:213], v[0:3]
	s_setprio 0
	s_barrier
	s_add_i32 s61, s61, 2
	s_add_u32 s34, s34, 0x100
	s_addc_u32 s35, s35, 0
	s_add_u32 s59, s59, 0x100
	s_addc_u32 s60, s60, 0
; #define PG8_STAGE(bufoff, gbase, voff) do { _Pragma("unroll") for (int _i = 0; _i < 2; ++_i) \
;         __builtin_amdgcn_global_load_lds((const unsigned*)((const char*)(gbase) + (voff)[_i]), (LAS unsigned*)(lds + (bufoff) + ldsw + _i * 8192), 16, 0, 0); } while (0)
; #define PG8_LDA(dst, b, h) do { _Pragma("unroll") for (int m = 0; m < 4; ++m) _Pragma("unroll") for (int k = 0; k < 2; ++k) dst[m][k] = *(const LAS bf16x8*)(lds + PG8_SA(b, h) + aoff + m * 2048 + k * 1024); } while (0)
; #define PG8_LDB(dst, b, h) do { _Pragma("unroll") for (int n = 0; n < 2; ++n) _Pragma("unroll") for (int k = 0; k < 2; ++k) dst[n][k] = *(const LAS bf16x8*)(lds + PG8_SB(b, h) + boff + n * 2048 + k * 1024); } while (0)
; #define PG8_MMA(ai, bj, At, Bt) do { __builtin_amdgcn_s_setprio(1); _Pragma("unroll") for (int m = 0; m < 4; ++m) _Pragma("unroll") for (int n = 0; n < 2; ++n) _Pragma("unroll") for (int k = 0; k < 2; ++k) \
;         acc[ai][bj][m][n] = __builtin_amdgcn_mfma_f32_16x16x32_bf16(Bt[n][k], At[m][k], acc[ai][bj][m][n], 0, 0, 0); __builtin_amdgcn_s_setprio(0); } while (0)
; #define PG8_WAIT_V(n) asm volatile("s_waitcnt vmcnt(" #n ")" ::: "memory")
; #define PG8_WAIT_L(n) asm volatile("s_waitcnt lgkmcnt(" #n ")" ::: "memory")
; #define PG8_BAR __builtin_amdgcn_s_barrier()
; template <class Epi, bool ALIGN_EPI, int K, int LDA, int LDB>
; __device__ __forceinline__ void gemm_phase(LAS unsigned char* lds, const int wid, const Gemm g, const StaticOrder& S, const Epi& E) {
;     ...
;         for (int t = 0; t < nt; t += 2) {
;             const bool last = (t == nt - 2);
;             const char* a1 = cA + (size_t)(t + 1) * kstep;
;             const char* a2 = last ? nA : cA + (size_t)(t + 2) * kstep; const char* b2 = last ? nB : cB + (size_t)(t + 2) * kstep;
;             const char* a3 = a2 + kstep; const char* b3 = b2 + kstep;
;             PG8_LDB(B0, 0, 0); PG8_LDB(B1, 0, 1); PG8_SCHED; PG8_LDA(At, 0, 0); PG8_STAGE(PG8_SA(1, 1), a1 + hA, voffA);
;             PG8_WAIT_V(8); PG8_WAIT_L(0); PG8_BAR; PG8_MMA(0, 0, At, B0); PG8_MMA(0, 1, At, B1); PG8_BAR; PG8_SCHED;
;             PG8_LDA(At, 0, 1); PG8_STAGE(PG8_SB(0, 0), b2, voffB); PG8_STAGE(PG8_SB(0, 1), b2 + hB, voffB); PG8_STAGE(PG8_SA(0, 0), a2, voffA);
;             PG8_WAIT_V(8); PG8_WAIT_L(0); PG8_BAR; PG8_MMA(1, 0, At, B0); PG8_MMA(1, 1, At, B1); PG8_BAR; PG8_SCHED;
.LBB0_1279:
	ds_read_b128 v[144:147], v151
	ds_read_b128 v[154:157], v151 offset:1024
	ds_read_b128 v[158:161], v151 offset:2048
	ds_read_b128 v[162:165], v151 offset:3072
	ds_read_b128 v[166:169], v152
	ds_read_b128 v[170:173], v152 offset:1024
	ds_read_b128 v[174:177], v152 offset:2048
	ds_read_b128 v[178:181], v152 offset:3072
	s_add_u32 s36, s34, 0xfffc0080
	s_addc_u32 s37, s35, -1
	s_cmp_eq_u32 s61, 12
	s_cselect_b32 s39, s7, s37
	s_cselect_b32 s38, s25, s36
	s_cselect_b32 s37, s23, s60
	s_cselect_b32 s36, s42, s59
	s_add_i32 m0, s31, 0xc000
	ds_read_b128 v[182:185], v153
	ds_read_b128 v[186:189], v153 offset:1024
	ds_read_b128 v[190:193], v153 offset:2048
	ds_read_b128 v[194:197], v153 offset:3072
	ds_read_b128 v[198:201], v153 offset:4096
	ds_read_b128 v[202:205], v153 offset:5120
	ds_read_b128 v[206:209], v153 offset:6144
	ds_read_b128 v[210:213], v153 offset:7168
	global_load_lds_dwordx4 v136, s[34:35]
	s_add_i32 m0, s31, 0xe000
	s_nop 0
	global_load_lds_dwordx4 v138, s[34:35]
	s_waitcnt vmcnt(8)
	s_barrier
	s_setprio 1
	s_waitcnt lgkmcnt(0)
	v_mfma_f32_16x16x32_bf16 v[124:127], v[144:147], v[182:185], v[124:127]
	v_mfma_f32_16x16x32_bf16 v[120:123], v[158:161], v[182:185], v[120:123]
	v_mfma_f32_16x16x32_bf16 v[108:111], v[144:147], v[190:193], v[108:111]
	v_mfma_f32_16x16x32_bf16 v[104:107], v[158:161], v[190:193], v[104:107]
	v_mfma_f32_16x16x32_bf16 v[92:95], v[144:147], v[198:201], v[92:95]
	v_mfma_f32_16x16x32_bf16 v[88:91], v[158:161], v[198:201], v[88:91]
	v_mfma_f32_16x16x32_bf16 v[76:79], v[144:147], v[206:209], v[76:79]
	v_mfma_f32_16x16x32_bf16 v[72:75], v[158:161], v[206:209], v[72:75]
	v_mfma_f32_16x16x32_bf16 v[124:127], v[154:157], v[186:189], v[124:127]
	v_mfma_f32_16x16x32_bf16 v[120:123], v[162:165], v[186:189], v[120:123]
	v_mfma_f32_16x16x32_bf16 v[108:111], v[154:157], v[194:197], v[108:111]
	v_mfma_f32_16x16x32_bf16 v[104:107], v[162:165], v[194:197], v[104:107]
	v_mfma_f32_16x16x32_bf16 v[92:95], v[154:157], v[202:205], v[92:95]
	v_mfma_f32_16x16x32_bf16 v[88:91], v[162:165], v[202:205], v[88:91]
	v_mfma_f32_16x16x32_bf16 v[76:79], v[154:157], v[210:213], v[76:79]
	v_mfma_f32_16x16x32_bf16 v[72:75], v[162:165], v[210:213], v[72:75]
	v_mfma_f32_16x16x32_bf16 v[116:119], v[166:169], v[182:185], v[116:119]
	v_mfma_f32_16x16x32_bf16 v[112:115], v[174:177], v[182:185], v[112:115]
	v_mfma_f32_16x16x32_bf16 v[100:103], v[166:169], v[190:193], v[100:103]
	v_mfma_f32_16x16x32_bf16 v[96:99], v[174:177], v[190:193], v[96:99]
	v_mfma_f32_16x16x32_bf16 v[84:87], v[166:169], v[198:201], v[84:87]
	v_mfma_f32_16x16x32_bf16 v[80:83], v[174:177], v[198:201], v[80:83]
	v_mfma_f32_16x16x32_bf16 v[68:71], v[166:169], v[206:209], v[68:71]
	v_mfma_f32_16x16x32_bf16 v[64:67], v[174:177], v[206:209], v[64:67]
	v_mfma_f32_16x16x32_bf16 v[116:119], v[170:173], v[186:189], v[116:119]
	v_mfma_f32_16x16x32_bf16 v[112:115], v[178:181], v[186:189], v[112:115]
	v_mfma_f32_16x16x32_bf16 v[100:103], v[170:173], v[194:197], v[100:103]
	v_mfma_f32_16x16x32_bf16 v[96:99], v[178:181], v[194:197], v[96:99]
	v_mfma_f32_16x16x32_bf16 v[84:87], v[170:173], v[202:205], v[84:87]
	v_mfma_f32_16x16x32_bf16 v[80:83], v[178:181], v[202:205], v[80:83]
	v_mfma_f32_16x16x32_bf16 v[68:71], v[170:173], v[210:213], v[68:71]
	v_mfma_f32_16x16x32_bf16 v[64:67], v[178:181], v[210:213], v[64:67]
	s_setprio 0
	s_barrier
	s_add_u32 s98, s36, s12
	s_addc_u32 s99, s37, s13
	s_add_u32 s100, s38, s12
	s_addc_u32 s101, s39, s13
	s_add_i32 s52, s57, s3
	s_mov_b32 m0, s52
	ds_read_b128 v[182:185], v153 offset:16384
	ds_read_b128 v[186:189], v153 offset:17408
	ds_read_b128 v[190:193], v153 offset:18432
	ds_read_b128 v[194:197], v153 offset:19456
	ds_read_b128 v[198:201], v153 offset:20480
	ds_read_b128 v[202:205], v153 offset:21504
	ds_read_b128 v[206:209], v153 offset:22528
	ds_read_b128 v[210:213], v153 offset:23552
	global_load_lds_dwordx4 v130, s[36:37]
	s_add_i32 m0, s52, 0x2000
	s_add_u32 s62, s36, 0x40000
	s_addc_u32 s63, s37, 0
	s_add_i32 s52, s58, s3
	global_load_lds_dwordx4 v134, s[36:37]
	s_mov_b32 m0, s52
	s_nop 0
	global_load_lds_dwordx4 v130, s[62:63]
	s_add_i32 m0, s52, 0x2000
	s_nop 0
	global_load_lds_dwordx4 v134, s[62:63]
	s_mov_b32 m0, s31
	s_nop 0
	global_load_lds_dwordx4 v128, s[38:39]
	s_mov_b32 m0, s33
	s_nop 0
	global_load_lds_dwordx4 v132, s[38:39]
	s_waitcnt vmcnt(8)
	s_barrier
	s_setprio 1
	s_waitcnt lgkmcnt(0)
	v_mfma_f32_16x16x32_bf16 v[60:63], v[144:147], v[182:185], v[60:63]
	v_mfma_f32_16x16x32_bf16 v[56:59], v[158:161], v[182:185], v[56:59]
	v_mfma_f32_16x16x32_bf16 v[44:47], v[144:147], v[190:193], v[44:47]
	v_mfma_f32_16x16x32_bf16 v[40:43], v[158:161], v[190:193], v[40:43]
	v_mfma_f32_16x16x32_bf16 v[28:31], v[144:147], v[198:201], v[28:31]
	v_mfma_f32_16x16x32_bf16 v[24:27], v[158:161], v[198:201], v[24:27]
	v_mfma_f32_16x16x32_bf16 v[12:15], v[144:147], v[206:209], v[12:15]
	v_mfma_f32_16x16x32_bf16 v[8:11], v[158:161], v[206:209], v[8:11]
	v_mfma_f32_16x16x32_bf16 v[60:63], v[154:157], v[186:189], v[60:63]
	v_mfma_f32_16x16x32_bf16 v[56:59], v[162:165], v[186:189], v[56:59]
	v_mfma_f32_16x16x32_bf16 v[44:47], v[154:157], v[194:197], v[44:47]
	v_mfma_f32_16x16x32_bf16 v[40:43], v[162:165], v[194:197], v[40:43]
	v_mfma_f32_16x16x32_bf16 v[28:31], v[154:157], v[202:205], v[28:31]
	v_mfma_f32_16x16x32_bf16 v[24:27], v[162:165], v[202:205], v[24:27]
	v_mfma_f32_16x16x32_bf16 v[12:15], v[154:157], v[210:213], v[12:15]
	v_mfma_f32_16x16x32_bf16 v[8:11], v[162:165], v[210:213], v[8:11]
	v_mfma_f32_16x16x32_bf16 v[52:55], v[166:169], v[182:185], v[52:55]
	v_mfma_f32_16x16x32_bf16 v[48:51], v[174:177], v[182:185], v[48:51]
	v_mfma_f32_16x16x32_bf16 v[36:39], v[166:169], v[190:193], v[36:39]
	v_mfma_f32_16x16x32_bf16 v[32:35], v[174:177], v[190:193], v[32:35]
	v_mfma_f32_16x16x32_bf16 v[20:23], v[166:169], v[198:201], v[20:23]
	v_mfma_f32_16x16x32_bf16 v[16:19], v[174:177], v[198:201], v[16:19]
	v_mfma_f32_16x16x32_bf16 v[4:7], v[166:169], v[206:209], v[4:7]
	v_mfma_f32_16x16x32_bf16 v[0:3], v[174:177], v[206:209], v[0:3]
	v_mfma_f32_16x16x32_bf16 v[52:55], v[170:173], v[186:189], v[52:55]
	v_mfma_f32_16x16x32_bf16 v[48:51], v[178:181], v[186:189], v[48:51]
	v_mfma_f32_16x16x32_bf16 v[36:39], v[170:173], v[194:197], v[36:39]
	v_mfma_f32_16x16x32_bf16 v[32:35], v[178:181], v[194:197], v[32:35]
	v_mfma_f32_16x16x32_bf16 v[20:23], v[170:173], v[202:205], v[20:23]
	v_mfma_f32_16x16x32_bf16 v[16:19], v[178:181], v[202:205], v[16:19]
	v_mfma_f32_16x16x32_bf16 v[4:7], v[170:173], v[210:213], v[4:7]
	v_mfma_f32_16x16x32_bf16 v[0:3], v[178:181], v[210:213], v[0:3]
	s_setprio 0
	s_barrier
; #define PG8_STAGE(bufoff, gbase, voff) do { _Pragma("unroll") for (int _i = 0; _i < 2; ++_i) \
;         __builtin_amdgcn_global_load_lds((const unsigned*)((const char*)(gbase) + (voff)[_i]), (LAS unsigned*)(lds + (bufoff) + ldsw + _i * 8192), 16, 0, 0); } while (0)
; #define PG8_LDA(dst, b, h) do { _Pragma("unroll") for (int m = 0; m < 4; ++m) _Pragma("unroll") for (int k = 0; k < 2; ++k) dst[m][k] = *(const LAS bf16x8*)(lds + PG8_SA(b, h) + aoff + m * 2048 + k * 1024); } while (0)
; #define PG8_LDB(dst, b, h) do { _Pragma("unroll") for (int n = 0; n < 2; ++n) _Pragma("unroll") for (int k = 0; k < 2; ++k) dst[n][k] = *(const LAS bf16x8*)(lds + PG8_SB(b, h) + boff + n * 2048 + k * 1024); } while (0)
; #define PG8_MMA(ai, bj, At, Bt) do { __builtin_amdgcn_s_setprio(1); _Pragma("unroll") for (int m = 0; m < 4; ++m) _Pragma("unroll") for (int n = 0; n < 2; ++n) _Pragma("unroll") for (int k = 0; k < 2; ++k) \
;         acc[ai][bj][m][n] = __builtin_amdgcn_mfma_f32_16x16x32_bf16(Bt[n][k], At[m][k], acc[ai][bj][m][n], 0, 0, 0); __builtin_amdgcn_s_setprio(0); } while (0)
; #define PG8_WAIT_V(n) asm volatile("s_waitcnt vmcnt(" #n ")" ::: "memory")
; #define PG8_WAIT_L(n) asm volatile("s_waitcnt lgkmcnt(" #n ")" ::: "memory")
; #define PG8_BAR __builtin_amdgcn_s_barrier()
; #define PG8_SCHED __builtin_amdgcn_sched_barrier(0)
; template <class Epi, bool ALIGN_EPI, int K, int LDA, int LDB>
; __device__ __forceinline__ void gemm_phase(LAS unsigned char* lds, const int wid, const Gemm g, const StaticOrder& S, const Epi& E) {
;     ...
;         for (int t = 0; t < nt; t += 2) {
;             const bool last = (t == nt - 2);
;     ...
;             PG8_LDB(B0, 1, 0); PG8_LDB(B1, 1, 1); PG8_SCHED; PG8_LDA(At, 1, 0); PG8_STAGE(PG8_SA(0, 1), a2 + hA, voffA);
;             PG8_WAIT_V(8); PG8_WAIT_L(0); PG8_BAR; PG8_MMA(0, 0, At, B0); PG8_MMA(0, 1, At, B1); PG8_BAR; PG8_SCHED;
;             PG8_LDA(At, 1, 1); PG8_STAGE(PG8_SB(1, 0), b3, voffB); PG8_STAGE(PG8_SB(1, 1), b3 + hB, voffB); PG8_STAGE(PG8_SA(1, 0), a3, voffA);
;             PG8_WAIT_V(8); PG8_WAIT_L(0); PG8_BAR; PG8_MMA(1, 0, At, B0); PG8_MMA(1, 1, At, B1); PG8_BAR; PG8_SCHED;
	s_add_i32 s52, 0, 0x18000
	s_add_i32 s53, 0, 0x1c000
	v_add_u32_e32 v162, s52, v150
	v_add_u32_e32 v178, s53, v150
	ds_read_b128 v[144:147], v162
	ds_read_b128 v[154:157], v162 offset:1024
	ds_read_b128 v[158:161], v162 offset:2048
	ds_read_b128 v[162:165], v162 offset:3072
	ds_read_b128 v[166:169], v178
	ds_read_b128 v[170:173], v178 offset:1024
	ds_read_b128 v[174:177], v178 offset:2048
	ds_read_b128 v[178:181], v178 offset:3072
	s_add_u32 s38, s38, 0x40000
	s_addc_u32 s39, s39, 0
	s_mov_b32 m0, s40
	ds_read_b128 v[182:185], v153 offset:32768
	ds_read_b128 v[186:189], v153 offset:33792
	ds_read_b128 v[190:193], v153 offset:34816
	ds_read_b128 v[194:197], v153 offset:35840
	ds_read_b128 v[198:201], v153 offset:36864
	ds_read_b128 v[202:205], v153 offset:37888
	ds_read_b128 v[206:209], v153 offset:38912
	ds_read_b128 v[210:213], v153 offset:39936
	global_load_lds_dwordx4 v128, s[38:39]
	s_mov_b32 m0, s41
	s_nop 0
	global_load_lds_dwordx4 v132, s[38:39]
	s_waitcnt vmcnt(8)
	s_barrier
	s_setprio 1
	s_waitcnt lgkmcnt(0)
	v_mfma_f32_16x16x32_bf16 v[124:127], v[144:147], v[182:185], v[124:127]
	v_mfma_f32_16x16x32_bf16 v[120:123], v[158:161], v[182:185], v[120:123]
	v_mfma_f32_16x16x32_bf16 v[108:111], v[144:147], v[190:193], v[108:111]
	v_mfma_f32_16x16x32_bf16 v[104:107], v[158:161], v[190:193], v[104:107]
	v_mfma_f32_16x16x32_bf16 v[92:95], v[144:147], v[198:201], v[92:95]
	v_mfma_f32_16x16x32_bf16 v[88:91], v[158:161], v[198:201], v[88:91]
	v_mfma_f32_16x16x32_bf16 v[76:79], v[144:147], v[206:209], v[76:79]
	v_mfma_f32_16x16x32_bf16 v[72:75], v[158:161], v[206:209], v[72:75]
	v_mfma_f32_16x16x32_bf16 v[124:127], v[154:157], v[186:189], v[124:127]
	v_mfma_f32_16x16x32_bf16 v[120:123], v[162:165], v[186:189], v[120:123]
	v_mfma_f32_16x16x32_bf16 v[108:111], v[154:157], v[194:197], v[108:111]
	v_mfma_f32_16x16x32_bf16 v[104:107], v[162:165], v[194:197], v[104:107]
	v_mfma_f32_16x16x32_bf16 v[92:95], v[154:157], v[202:205], v[92:95]
	v_mfma_f32_16x16x32_bf16 v[88:91], v[162:165], v[202:205], v[88:91]
	v_mfma_f32_16x16x32_bf16 v[76:79], v[154:157], v[210:213], v[76:79]
	v_mfma_f32_16x16x32_bf16 v[72:75], v[162:165], v[210:213], v[72:75]
	v_mfma_f32_16x16x32_bf16 v[116:119], v[166:169], v[182:185], v[116:119]
	v_mfma_f32_16x16x32_bf16 v[112:115], v[174:177], v[182:185], v[112:115]
	v_mfma_f32_16x16x32_bf16 v[100:103], v[166:169], v[190:193], v[100:103]
	v_mfma_f32_16x16x32_bf16 v[96:99], v[174:177], v[190:193], v[96:99]
	v_mfma_f32_16x16x32_bf16 v[84:87], v[166:169], v[198:201], v[84:87]
	v_mfma_f32_16x16x32_bf16 v[80:83], v[174:177], v[198:201], v[80:83]
	v_mfma_f32_16x16x32_bf16 v[68:71], v[166:169], v[206:209], v[68:71]
	v_mfma_f32_16x16x32_bf16 v[64:67], v[174:177], v[206:209], v[64:67]
	v_mfma_f32_16x16x32_bf16 v[116:119], v[170:173], v[186:189], v[116:119]
	v_mfma_f32_16x16x32_bf16 v[112:115], v[178:181], v[186:189], v[112:115]
	v_mfma_f32_16x16x32_bf16 v[100:103], v[170:173], v[194:197], v[100:103]
	v_mfma_f32_16x16x32_bf16 v[96:99], v[178:181], v[194:197], v[96:99]
	v_mfma_f32_16x16x32_bf16 v[84:87], v[170:173], v[202:205], v[84:87]
	v_mfma_f32_16x16x32_bf16 v[80:83], v[178:181], v[202:205], v[80:83]
	v_mfma_f32_16x16x32_bf16 v[68:71], v[170:173], v[210:213], v[68:71]
	v_mfma_f32_16x16x32_bf16 v[64:67], v[178:181], v[210:213], v[64:67]
	s_setprio 0
	s_barrier
	s_add_i32 s38, s52, s3
	s_mov_b32 m0, s38
	ds_read_b128 v[182:185], v153 offset:49152
	ds_read_b128 v[186:189], v153 offset:50176
	ds_read_b128 v[190:193], v153 offset:51200
	ds_read_b128 v[194:197], v153 offset:52224
	ds_read_b128 v[198:201], v153 offset:53248
	ds_read_b128 v[202:205], v153 offset:54272
	ds_read_b128 v[206:209], v153 offset:55296
	ds_read_b128 v[210:213], v153 offset:56320
	global_load_lds_dwordx4 v130, s[98:99]
	s_add_i32 m0, s38, 0x2000
	s_add_u32 s36, s36, 0x40080
	s_addc_u32 s37, s37, 0
	s_add_i32 s38, s53, s3
	global_load_lds_dwordx4 v134, s[98:99]
	s_mov_b32 m0, s38
	s_nop 0
	global_load_lds_dwordx4 v130, s[36:37]
	s_add_i32 m0, s38, 0x2000
	s_nop 0
	global_load_lds_dwordx4 v134, s[36:37]
	s_mov_b32 m0, s55
	s_nop 0
	global_load_lds_dwordx4 v128, s[100:101]
	s_mov_b32 m0, s56
	s_nop 0
	global_load_lds_dwordx4 v132, s[100:101]
	s_waitcnt vmcnt(8)
	s_barrier
	s_setprio 1
	s_waitcnt lgkmcnt(0)
	v_mfma_f32_16x16x32_bf16 v[60:63], v[144:147], v[182:185], v[60:63]
	v_mfma_f32_16x16x32_bf16 v[56:59], v[158:161], v[182:185], v[56:59]
	v_mfma_f32_16x16x32_bf16 v[44:47], v[144:147], v[190:193], v[44:47]
	v_mfma_f32_16x16x32_bf16 v[40:43], v[158:161], v[190:193], v[40:43]
	v_mfma_f32_16x16x32_bf16 v[28:31], v[144:147], v[198:201], v[28:31]
	v_mfma_f32_16x16x32_bf16 v[24:27], v[158:161], v[198:201], v[24:27]
	v_mfma_f32_16x16x32_bf16 v[12:15], v[144:147], v[206:209], v[12:15]
	v_mfma_f32_16x16x32_bf16 v[8:11], v[158:161], v[206:209], v[8:11]
	v_mfma_f32_16x16x32_bf16 v[60:63], v[154:157], v[186:189], v[60:63]
	v_mfma_f32_16x16x32_bf16 v[56:59], v[162:165], v[186:189], v[56:59]
	v_mfma_f32_16x16x32_bf16 v[44:47], v[154:157], v[194:197], v[44:47]
	v_mfma_f32_16x16x32_bf16 v[40:43], v[162:165], v[194:197], v[40:43]
	v_mfma_f32_16x16x32_bf16 v[28:31], v[154:157], v[202:205], v[28:31]
	v_mfma_f32_16x16x32_bf16 v[24:27], v[162:165], v[202:205], v[24:27]
	v_mfma_f32_16x16x32_bf16 v[12:15], v[154:157], v[210:213], v[12:15]
	v_mfma_f32_16x16x32_bf16 v[8:11], v[162:165], v[210:213], v[8:11]
	v_mfma_f32_16x16x32_bf16 v[52:55], v[166:169], v[182:185], v[52:55]
	v_mfma_f32_16x16x32_bf16 v[48:51], v[174:177], v[182:185], v[48:51]
	v_mfma_f32_16x16x32_bf16 v[36:39], v[166:169], v[190:193], v[36:39]
	v_mfma_f32_16x16x32_bf16 v[32:35], v[174:177], v[190:193], v[32:35]
	v_mfma_f32_16x16x32_bf16 v[20:23], v[166:169], v[198:201], v[20:23]
	v_mfma_f32_16x16x32_bf16 v[16:19], v[174:177], v[198:201], v[16:19]
	v_mfma_f32_16x16x32_bf16 v[4:7], v[166:169], v[206:209], v[4:7]
	v_mfma_f32_16x16x32_bf16 v[0:3], v[174:177], v[206:209], v[0:3]
	v_mfma_f32_16x16x32_bf16 v[52:55], v[170:173], v[186:189], v[52:55]
	v_mfma_f32_16x16x32_bf16 v[48:51], v[178:181], v[186:189], v[48:51]
	v_mfma_f32_16x16x32_bf16 v[36:39], v[170:173], v[194:197], v[36:39]
	v_mfma_f32_16x16x32_bf16 v[32:35], v[178:181], v[194:197], v[32:35]
	v_mfma_f32_16x16x32_bf16 v[20:23], v[170:173], v[202:205], v[20:23]
	v_mfma_f32_16x16x32_bf16 v[16:19], v[178:181], v[202:205], v[16:19]
	v_mfma_f32_16x16x32_bf16 v[4:7], v[170:173], v[210:213], v[4:7]
	v_mfma_f32_16x16x32_bf16 v[0:3], v[178:181], v[210:213], v[0:3]
	s_setprio 0
	s_barrier
	s_add_i32 s61, s61, 2
	s_add_u32 s34, s34, 0x100
	s_addc_u32 s35, s35, 0
	s_add_u32 s59, s59, 0x100
	s_addc_u32 s60, s60, 0
	s_cmp_gt_u32 s61, 13
	s_cbranch_scc0 .LBB0_1279
	s_and_b64 vcc, exec, s[10:11]
	s_cbranch_vccz .LBB0_1282
	s_barrier

; #define PG8_STAGE(bufoff, gbase, voff) do { _Pragma("unroll") for (int _i = 0; _i < 2; ++_i) \
;         __builtin_amdgcn_global_load_lds((const unsigned*)((const char*)(gbase) + (voff)[_i]), (LAS unsigned*)(lds + (bufoff) + ldsw + _i * 8192), 16, 0, 0); } while (0)
; #define PG8_LDA(dst, b, h) do { _Pragma("unroll") for (int m = 0; m < 4; ++m) _Pragma("unroll") for (int k = 0; k < 2; ++k) dst[m][k] = *(const LAS bf16x8*)(lds + PG8_SA(b, h) + aoff + m * 2048 + k * 1024); } while (0)
; #define PG8_LDB(dst, b, h) do { _Pragma("unroll") for (int n = 0; n < 2; ++n) _Pragma("unroll") for (int k = 0; k < 2; ++k) dst[n][k] = *(const LAS bf16x8*)(lds + PG8_SB(b, h) + boff + n * 2048 + k * 1024); } while (0)
; #define PG8_MMA(ai, bj, At, Bt) do { __builtin_amdgcn_s_setprio(1); _Pragma("unroll") for (int m = 0; m < 4; ++m) _Pragma("unroll") for (int n = 0; n < 2; ++n) _Pragma("unroll") for (int k = 0; k < 2; ++k) \
;         acc[ai][bj][m][n] = __builtin_amdgcn_mfma_f32_16x16x32_bf16(Bt[n][k], At[m][k], acc[ai][bj][m][n], 0, 0, 0); __builtin_amdgcn_s_setprio(0); } while (0)
; template <class Epi, bool ALIGN_EPI, int K, int LDA, int LDB>
; __device__ __forceinline__ void gemm_phase(LAS unsigned char* lds, const int wid, const Gemm g, const StaticOrder& S, const Epi& E) {
;     ...
;         const bool has_next = S.next(ui + 1, nxt);
;         const char* nA = has_next ? (const char*)g.A + (size_t)nxt.pm * tA : cA; const char* nB = has_next ? (const char*)g.Bt + (size_t)nxt.pn * tB : cB;
;         for (int t = 0; t < nt; t += 2) {
;             const bool last = (t == nt - 2);
;             const char* a1 = cA + (size_t)(t + 1) * kstep;
;             const char* a2 = last ? nA : cA + (size_t)(t + 2) * kstep; const char* b2 = last ? nB : cB + (size_t)(t + 2) * kstep;
;             const char* a3 = a2 + kstep; const char* b3 = b2 + kstep;
;             PG8_LDB(B0, 0, 0); PG8_LDB(B1, 0, 1); PG8_SCHED; PG8_LDA(At, 0, 0); PG8_STAGE(PG8_SA(1, 1), a1 + hA, voffA);
;             PG8_WAIT_V(8); PG8_WAIT_L(0); PG8_BAR; PG8_MMA(0, 0, At, B0); PG8_MMA(0, 1, At, B1); PG8_BAR; PG8_SCHED;
;             PG8_LDA(At, 0, 1); PG8_STAGE(PG8_SB(0, 0), b2, voffB); PG8_STAGE(PG8_SB(0, 1), b2 + hB, voffB); PG8_STAGE(PG8_SA(0, 0), a2, voffA);
;             PG8_WAIT_V(8); PG8_WAIT_L(0); PG8_BAR; PG8_MMA(1, 0, At, B0); PG8_MMA(1, 1, At, B1); PG8_BAR; PG8_SCHED;
.LBB0_1476:
	s_ashr_i32 s25, s24, 31
	s_lshl_b64 s[26:27], s[24:25], 19
	v_readlane_b32 s23, v254, 0
	s_add_u32 s26, s23, s26
	v_readlane_b32 s23, v254, 1
	s_addc_u32 s27, s23, s27
	s_and_b64 s[28:29], s[4:5], exec
	s_cselect_b32 s25, s27, s35
	s_cselect_b32 s42, s26, s34
	s_ashr_i32 s23, s22, 31
	s_lshl_b64 s[28:29], s[22:23], 19
	s_add_u32 s28, s1, s28
	s_addc_u32 s29, s3, s29
	s_and_b64 s[38:39], s[4:5], exec
	s_cselect_b32 s23, s29, s37
	s_cselect_b32 s66, s28, s36
	s_add_u32 s34, s34, 0x40080
	s_addc_u32 s35, s35, 0
	s_add_u32 s67, s36, 0x100
	s_addc_u32 s68, s37, 0
	s_mov_b32 s69, -2
	s_add_u32 s36, s34, 0xfffc0080
	s_addc_u32 s37, s35, -1
	s_cmp_eq_u32 s69, 12
	s_cselect_b32 s39, s25, s37
	s_cselect_b32 s38, s42, s36
	s_cselect_b32 s37, s23, s68
	s_cselect_b32 s36, s66, s67
	s_add_i32 m0, s40, 0xc000
	global_load_lds_dwordx4 v156, s[34:35]
	s_add_i32 m0, s40, 0xe000
	s_nop 0
	global_load_lds_dwordx4 v158, s[34:35]
	s_waitcnt vmcnt(8)
	s_barrier
	s_setprio 1
	s_waitcnt lgkmcnt(0)
	v_mfma_f32_16x16x32_bf16 v[124:127], v[128:131], v[182:185], 0
	v_mfma_f32_16x16x32_bf16 v[116:119], v[136:139], v[182:185], 0
	v_mfma_f32_16x16x32_bf16 v[120:123], v[128:131], v[190:193], 0
	v_mfma_f32_16x16x32_bf16 v[112:115], v[136:139], v[190:193], 0
	v_mfma_f32_16x16x32_bf16 v[92:95], v[128:131], v[198:201], 0
	v_mfma_f32_16x16x32_bf16 v[88:91], v[136:139], v[198:201], 0
	v_mfma_f32_16x16x32_bf16 v[76:79], v[128:131], v[206:209], 0
	v_mfma_f32_16x16x32_bf16 v[72:75], v[136:139], v[206:209], 0
	v_mfma_f32_16x16x32_bf16 v[124:127], v[132:135], v[186:189], v[124:127]
	v_mfma_f32_16x16x32_bf16 v[116:119], v[140:143], v[186:189], v[116:119]
	v_mfma_f32_16x16x32_bf16 v[120:123], v[132:135], v[194:197], v[120:123]
	v_mfma_f32_16x16x32_bf16 v[112:115], v[140:143], v[194:197], v[112:115]
	v_mfma_f32_16x16x32_bf16 v[92:95], v[132:135], v[202:205], v[92:95]
	v_mfma_f32_16x16x32_bf16 v[88:91], v[140:143], v[202:205], v[88:91]
	v_mfma_f32_16x16x32_bf16 v[76:79], v[132:135], v[210:213], v[76:79]
	v_mfma_f32_16x16x32_bf16 v[72:75], v[140:143], v[210:213], v[72:75]
	v_mfma_f32_16x16x32_bf16 v[108:111], v[144:147], v[182:185], 0
	v_mfma_f32_16x16x32_bf16 v[104:107], v[168:171], v[182:185], 0
	v_mfma_f32_16x16x32_bf16 v[100:103], v[144:147], v[190:193], 0
	v_mfma_f32_16x16x32_bf16 v[96:99], v[168:171], v[190:193], 0
	v_mfma_f32_16x16x32_bf16 v[84:87], v[144:147], v[198:201], 0
	v_mfma_f32_16x16x32_bf16 v[80:83], v[168:171], v[198:201], 0
	v_mfma_f32_16x16x32_bf16 v[68:71], v[144:147], v[206:209], 0
	v_mfma_f32_16x16x32_bf16 v[64:67], v[168:171], v[206:209], 0
	v_mfma_f32_16x16x32_bf16 v[108:111], v[164:167], v[186:189], v[108:111]
	v_mfma_f32_16x16x32_bf16 v[104:107], v[178:181], v[186:189], v[104:107]
	v_mfma_f32_16x16x32_bf16 v[100:103], v[164:167], v[194:197], v[100:103]
	v_mfma_f32_16x16x32_bf16 v[96:99], v[178:181], v[194:197], v[96:99]
	v_mfma_f32_16x16x32_bf16 v[84:87], v[164:167], v[202:205], v[84:87]
	v_mfma_f32_16x16x32_bf16 v[80:83], v[178:181], v[202:205], v[80:83]
	v_mfma_f32_16x16x32_bf16 v[68:71], v[164:167], v[210:213], v[68:71]
	v_mfma_f32_16x16x32_bf16 v[64:67], v[178:181], v[210:213], v[64:67]
	s_setprio 0
	s_barrier
	s_add_u32 s98, s36, s12
	s_addc_u32 s99, s37, s13
	s_add_u32 s100, s38, s12
	s_addc_u32 s101, s39, s13
	s_add_i32 s52, s58, s33
	s_mov_b32 m0, s52
	ds_read_b128 v[182:185], v177 offset:16384
	ds_read_b128 v[186:189], v177 offset:17408
	ds_read_b128 v[190:193], v177 offset:18432
	ds_read_b128 v[194:197], v177 offset:19456
	ds_read_b128 v[198:201], v177 offset:20480
	ds_read_b128 v[202:205], v177 offset:21504
	ds_read_b128 v[206:209], v177 offset:22528
	ds_read_b128 v[210:213], v177 offset:23552
	global_load_lds_dwordx4 v150, s[36:37]
	s_add_i32 m0, s52, 0x2000
	s_add_u32 s70, s36, 0x40000
	s_addc_u32 s71, s37, 0
	s_add_i32 s52, s59, s33
	global_load_lds_dwordx4 v154, s[36:37]
	s_mov_b32 m0, s52
	s_nop 0
	global_load_lds_dwordx4 v150, s[70:71]
	s_add_i32 m0, s52, 0x2000
	s_nop 0
	global_load_lds_dwordx4 v154, s[70:71]
	s_mov_b32 m0, s40
	s_nop 0
	global_load_lds_dwordx4 v148, s[38:39]
	s_mov_b32 m0, s41
	s_nop 0
	global_load_lds_dwordx4 v152, s[38:39]
	s_waitcnt vmcnt(8)
	s_barrier
	s_setprio 1
	s_waitcnt lgkmcnt(0)
	v_mfma_f32_16x16x32_bf16 v[60:63], v[128:131], v[182:185], 0
	v_mfma_f32_16x16x32_bf16 v[56:59], v[136:139], v[182:185], 0
	v_mfma_f32_16x16x32_bf16 v[44:47], v[128:131], v[190:193], 0
	v_mfma_f32_16x16x32_bf16 v[40:43], v[136:139], v[190:193], 0
	v_mfma_f32_16x16x32_bf16 v[36:39], v[128:131], v[198:201], 0
	v_mfma_f32_16x16x32_bf16 v[32:35], v[136:139], v[198:201], 0
	v_mfma_f32_16x16x32_bf16 v[20:23], v[128:131], v[206:209], 0
	v_mfma_f32_16x16x32_bf16 v[16:19], v[136:139], v[206:209], 0
	v_mfma_f32_16x16x32_bf16 v[60:63], v[132:135], v[186:189], v[60:63]
	v_mfma_f32_16x16x32_bf16 v[56:59], v[140:143], v[186:189], v[56:59]
	v_mfma_f32_16x16x32_bf16 v[44:47], v[132:135], v[194:197], v[44:47]
	v_mfma_f32_16x16x32_bf16 v[40:43], v[140:143], v[194:197], v[40:43]
	v_mfma_f32_16x16x32_bf16 v[36:39], v[132:135], v[202:205], v[36:39]
	v_mfma_f32_16x16x32_bf16 v[32:35], v[140:143], v[202:205], v[32:35]
	v_mfma_f32_16x16x32_bf16 v[20:23], v[132:135], v[210:213], v[20:23]
	v_mfma_f32_16x16x32_bf16 v[16:19], v[140:143], v[210:213], v[16:19]
	v_mfma_f32_16x16x32_bf16 v[52:55], v[144:147], v[182:185], 0
	v_mfma_f32_16x16x32_bf16 v[48:51], v[168:171], v[182:185], 0
	v_mfma_f32_16x16x32_bf16 v[28:31], v[144:147], v[190:193], 0
	v_mfma_f32_16x16x32_bf16 v[24:27], v[168:171], v[190:193], 0
	v_mfma_f32_16x16x32_bf16 v[12:15], v[144:147], v[198:201], 0
	v_mfma_f32_16x16x32_bf16 v[8:11], v[168:171], v[198:201], 0
	v_mfma_f32_16x16x32_bf16 v[4:7], v[144:147], v[206:209], 0
	v_mfma_f32_16x16x32_bf16 v[0:3], v[168:171], v[206:209], 0
	v_mfma_f32_16x16x32_bf16 v[52:55], v[164:167], v[186:189], v[52:55]
	v_mfma_f32_16x16x32_bf16 v[48:51], v[178:181], v[186:189], v[48:51]
	v_mfma_f32_16x16x32_bf16 v[28:31], v[164:167], v[194:197], v[28:31]
	v_mfma_f32_16x16x32_bf16 v[24:27], v[178:181], v[194:197], v[24:27]
	v_mfma_f32_16x16x32_bf16 v[12:15], v[164:167], v[202:205], v[12:15]
	v_mfma_f32_16x16x32_bf16 v[8:11], v[178:181], v[202:205], v[8:11]
	v_mfma_f32_16x16x32_bf16 v[4:7], v[164:167], v[210:213], v[4:7]
	v_mfma_f32_16x16x32_bf16 v[0:3], v[178:181], v[210:213], v[0:3]
	s_setprio 0
	s_barrier
; #define PG8_STAGE(bufoff, gbase, voff) do { _Pragma("unroll") for (int _i = 0; _i < 2; ++_i) \
;         __builtin_amdgcn_global_load_lds((const unsigned*)((const char*)(gbase) + (voff)[_i]), (LAS unsigned*)(lds + (bufoff) + ldsw + _i * 8192), 16, 0, 0); } while (0)
; #define PG8_LDA(dst, b, h) do { _Pragma("unroll") for (int m = 0; m < 4; ++m) _Pragma("unroll") for (int k = 0; k < 2; ++k) dst[m][k] = *(const LAS bf16x8*)(lds + PG8_SA(b, h) + aoff + m * 2048 + k * 1024); } while (0)
; #define PG8_LDB(dst, b, h) do { _Pragma("unroll") for (int n = 0; n < 2; ++n) _Pragma("unroll") for (int k = 0; k < 2; ++k) dst[n][k] = *(const LAS bf16x8*)(lds + PG8_SB(b, h) + boff + n * 2048 + k * 1024); } while (0)
; #define PG8_MMA(ai, bj, At, Bt) do { __builtin_amdgcn_s_setprio(1); _Pragma("unroll") for (int m = 0; m < 4; ++m) _Pragma("unroll") for (int n = 0; n < 2; ++n) _Pragma("unroll") for (int k = 0; k < 2; ++k) \
;         acc[ai][bj][m][n] = __builtin_amdgcn_mfma_f32_16x16x32_bf16(Bt[n][k], At[m][k], acc[ai][bj][m][n], 0, 0, 0); __builtin_amdgcn_s_setprio(0); } while (0)
; #define PG8_WAIT_V(n) asm volatile("s_waitcnt vmcnt(" #n ")" ::: "memory")
; #define PG8_WAIT_L(n) asm volatile("s_waitcnt lgkmcnt(" #n ")" ::: "memory")
; #define PG8_BAR __builtin_amdgcn_s_barrier()
; #define PG8_SCHED __builtin_amdgcn_sched_barrier(0)
; template <class Epi, bool ALIGN_EPI, int K, int LDA, int LDB>
; __device__ __forceinline__ void gemm_phase(LAS unsigned char* lds, const int wid, const Gemm g, const StaticOrder& S, const Epi& E) {
;     ...
;             PG8_LDB(B0, 1, 0); PG8_LDB(B1, 1, 1); PG8_SCHED; PG8_LDA(At, 1, 0); PG8_STAGE(PG8_SA(0, 1), a2 + hA, voffA);
;             PG8_WAIT_V(8); PG8_WAIT_L(0); PG8_BAR; PG8_MMA(0, 0, At, B0); PG8_MMA(0, 1, At, B1); PG8_BAR; PG8_SCHED;
;             PG8_LDA(At, 1, 1); PG8_STAGE(PG8_SB(1, 0), b3, voffB); PG8_STAGE(PG8_SB(1, 1), b3 + hB, voffB); PG8_STAGE(PG8_SA(1, 0), a3, voffA);
;             PG8_WAIT_V(8); PG8_WAIT_L(0); PG8_BAR; PG8_MMA(1, 0, At, B0); PG8_MMA(1, 1, At, B1); PG8_BAR; PG8_SCHED;
	s_add_i32 s52, 0, 0x18000
	s_add_i32 s53, 0, 0x1c000
	v_add_u32_e32 v140, s52, v174
	v_add_u32_e32 v178, s53, v174
	ds_read_b128 v[128:131], v140
	ds_read_b128 v[132:135], v140 offset:1024
	ds_read_b128 v[136:139], v140 offset:2048
	ds_read_b128 v[140:143], v140 offset:3072
	ds_read_b128 v[144:147], v178
	ds_read_b128 v[164:167], v178 offset:1024
	ds_read_b128 v[168:171], v178 offset:2048
	ds_read_b128 v[178:181], v178 offset:3072
	s_add_u32 s38, s38, 0x40000
	s_addc_u32 s39, s39, 0
	s_mov_b32 m0, s43
	ds_read_b128 v[182:185], v177 offset:32768
	ds_read_b128 v[186:189], v177 offset:33792
	ds_read_b128 v[190:193], v177 offset:34816
	ds_read_b128 v[194:197], v177 offset:35840
	ds_read_b128 v[198:201], v177 offset:36864
	ds_read_b128 v[202:205], v177 offset:37888
	ds_read_b128 v[206:209], v177 offset:38912
	ds_read_b128 v[210:213], v177 offset:39936
	global_load_lds_dwordx4 v148, s[38:39]
	s_mov_b32 m0, s48
	s_nop 0
	global_load_lds_dwordx4 v152, s[38:39]
	s_waitcnt vmcnt(8)
	s_barrier
	s_setprio 1
	s_waitcnt lgkmcnt(0)
	v_mfma_f32_16x16x32_bf16 v[124:127], v[128:131], v[182:185], v[124:127]
	v_mfma_f32_16x16x32_bf16 v[116:119], v[136:139], v[182:185], v[116:119]
	v_mfma_f32_16x16x32_bf16 v[120:123], v[128:131], v[190:193], v[120:123]
	v_mfma_f32_16x16x32_bf16 v[112:115], v[136:139], v[190:193], v[112:115]
	v_mfma_f32_16x16x32_bf16 v[92:95], v[128:131], v[198:201], v[92:95]
	v_mfma_f32_16x16x32_bf16 v[88:91], v[136:139], v[198:201], v[88:91]
	v_mfma_f32_16x16x32_bf16 v[76:79], v[128:131], v[206:209], v[76:79]
	v_mfma_f32_16x16x32_bf16 v[72:75], v[136:139], v[206:209], v[72:75]
	v_mfma_f32_16x16x32_bf16 v[124:127], v[132:135], v[186:189], v[124:127]
	v_mfma_f32_16x16x32_bf16 v[116:119], v[140:143], v[186:189], v[116:119]
	v_mfma_f32_16x16x32_bf16 v[120:123], v[132:135], v[194:197], v[120:123]
	v_mfma_f32_16x16x32_bf16 v[112:115], v[140:143], v[194:197], v[112:115]
	v_mfma_f32_16x16x32_bf16 v[92:95], v[132:135], v[202:205], v[92:95]
	v_mfma_f32_16x16x32_bf16 v[88:91], v[140:143], v[202:205], v[88:91]
	v_mfma_f32_16x16x32_bf16 v[76:79], v[132:135], v[210:213], v[76:79]
	v_mfma_f32_16x16x32_bf16 v[72:75], v[140:143], v[210:213], v[72:75]
	v_mfma_f32_16x16x32_bf16 v[108:111], v[144:147], v[182:185], v[108:111]
	v_mfma_f32_16x16x32_bf16 v[104:107], v[168:171], v[182:185], v[104:107]
	v_mfma_f32_16x16x32_bf16 v[100:103], v[144:147], v[190:193], v[100:103]
	v_mfma_f32_16x16x32_bf16 v[96:99], v[168:171], v[190:193], v[96:99]
	v_mfma_f32_16x16x32_bf16 v[84:87], v[144:147], v[198:201], v[84:87]
	v_mfma_f32_16x16x32_bf16 v[80:83], v[168:171], v[198:201], v[80:83]
	v_mfma_f32_16x16x32_bf16 v[68:71], v[144:147], v[206:209], v[68:71]
	v_mfma_f32_16x16x32_bf16 v[64:67], v[168:171], v[206:209], v[64:67]
	v_mfma_f32_16x16x32_bf16 v[108:111], v[164:167], v[186:189], v[108:111]
	v_mfma_f32_16x16x32_bf16 v[104:107], v[178:181], v[186:189], v[104:107]
	v_mfma_f32_16x16x32_bf16 v[100:103], v[164:167], v[194:197], v[100:103]
	v_mfma_f32_16x16x32_bf16 v[96:99], v[178:181], v[194:197], v[96:99]
	v_mfma_f32_16x16x32_bf16 v[84:87], v[164:167], v[202:205], v[84:87]
	v_mfma_f32_16x16x32_bf16 v[80:83], v[178:181], v[202:205], v[80:83]
	v_mfma_f32_16x16x32_bf16 v[68:71], v[164:167], v[210:213], v[68:71]
	v_mfma_f32_16x16x32_bf16 v[64:67], v[178:181], v[210:213], v[64:67]
	s_setprio 0
	s_barrier
	s_add_i32 s38, s52, s33
	s_mov_b32 m0, s38
	ds_read_b128 v[182:185], v177 offset:49152
	ds_read_b128 v[186:189], v177 offset:50176
	ds_read_b128 v[190:193], v177 offset:51200
	ds_read_b128 v[194:197], v177 offset:52224
	ds_read_b128 v[198:201], v177 offset:53248
	ds_read_b128 v[202:205], v177 offset:54272
	ds_read_b128 v[206:209], v177 offset:55296
	ds_read_b128 v[210:213], v177 offset:56320
	global_load_lds_dwordx4 v150, s[98:99]
	s_add_i32 m0, s38, 0x2000
	s_add_u32 s36, s36, 0x40080
	s_addc_u32 s37, s37, 0
	s_add_i32 s38, s53, s33
	global_load_lds_dwordx4 v154, s[98:99]
	s_mov_b32 m0, s38
	s_nop 0
	global_load_lds_dwordx4 v150, s[36:37]
	s_add_i32 m0, s38, 0x2000
	s_nop 0
	global_load_lds_dwordx4 v154, s[36:37]
	s_mov_b32 m0, s55
	s_nop 0
	global_load_lds_dwordx4 v148, s[100:101]
	s_mov_b32 m0, s56
	s_nop 0
	global_load_lds_dwordx4 v152, s[100:101]
	s_waitcnt vmcnt(8)
	s_barrier
	s_setprio 1
	s_waitcnt lgkmcnt(0)
	v_mfma_f32_16x16x32_bf16 v[60:63], v[128:131], v[182:185], v[60:63]
	v_mfma_f32_16x16x32_bf16 v[56:59], v[136:139], v[182:185], v[56:59]
	v_mfma_f32_16x16x32_bf16 v[44:47], v[128:131], v[190:193], v[44:47]
	v_mfma_f32_16x16x32_bf16 v[40:43], v[136:139], v[190:193], v[40:43]
	v_mfma_f32_16x16x32_bf16 v[36:39], v[128:131], v[198:201], v[36:39]
	v_mfma_f32_16x16x32_bf16 v[32:35], v[136:139], v[198:201], v[32:35]
	v_mfma_f32_16x16x32_bf16 v[20:23], v[128:131], v[206:209], v[20:23]
	v_mfma_f32_16x16x32_bf16 v[16:19], v[136:139], v[206:209], v[16:19]
	v_mfma_f32_16x16x32_bf16 v[60:63], v[132:135], v[186:189], v[60:63]
	v_mfma_f32_16x16x32_bf16 v[56:59], v[140:143], v[186:189], v[56:59]
	v_mfma_f32_16x16x32_bf16 v[44:47], v[132:135], v[194:197], v[44:47]
	v_mfma_f32_16x16x32_bf16 v[40:43], v[140:143], v[194:197], v[40:43]
	v_mfma_f32_16x16x32_bf16 v[36:39], v[132:135], v[202:205], v[36:39]
	v_mfma_f32_16x16x32_bf16 v[32:35], v[140:143], v[202:205], v[32:35]
	v_mfma_f32_16x16x32_bf16 v[20:23], v[132:135], v[210:213], v[20:23]
	v_mfma_f32_16x16x32_bf16 v[16:19], v[140:143], v[210:213], v[16:19]
	v_mfma_f32_16x16x32_bf16 v[52:55], v[144:147], v[182:185], v[52:55]
	v_mfma_f32_16x16x32_bf16 v[48:51], v[168:171], v[182:185], v[48:51]
	v_mfma_f32_16x16x32_bf16 v[28:31], v[144:147], v[190:193], v[28:31]
	v_mfma_f32_16x16x32_bf16 v[24:27], v[168:171], v[190:193], v[24:27]
	v_mfma_f32_16x16x32_bf16 v[12:15], v[144:147], v[198:201], v[12:15]
	v_mfma_f32_16x16x32_bf16 v[8:11], v[168:171], v[198:201], v[8:11]
	v_mfma_f32_16x16x32_bf16 v[4:7], v[144:147], v[206:209], v[4:7]
	v_mfma_f32_16x16x32_bf16 v[0:3], v[168:171], v[206:209], v[0:3]
	v_mfma_f32_16x16x32_bf16 v[52:55], v[164:167], v[186:189], v[52:55]
	v_mfma_f32_16x16x32_bf16 v[48:51], v[178:181], v[186:189], v[48:51]
	v_mfma_f32_16x16x32_bf16 v[28:31], v[164:167], v[194:197], v[28:31]
	v_mfma_f32_16x16x32_bf16 v[24:27], v[178:181], v[194:197], v[24:27]
	v_mfma_f32_16x16x32_bf16 v[12:15], v[164:167], v[202:205], v[12:15]
	v_mfma_f32_16x16x32_bf16 v[8:11], v[178:181], v[202:205], v[8:11]
	v_mfma_f32_16x16x32_bf16 v[4:7], v[164:167], v[210:213], v[4:7]
	v_mfma_f32_16x16x32_bf16 v[0:3], v[178:181], v[210:213], v[0:3]
	s_setprio 0
	s_barrier
	s_add_i32 s69, s69, 2
	s_add_u32 s34, s34, 0x100
	s_addc_u32 s35, s35, 0
	s_add_u32 s67, s67, 0x100
	s_addc_u32 s68, s68, 0
; #define PG8_STAGE(bufoff, gbase, voff) do { _Pragma("unroll") for (int _i = 0; _i < 2; ++_i) \
;         __builtin_amdgcn_global_load_lds((const unsigned*)((const char*)(gbase) + (voff)[_i]), (LAS unsigned*)(lds + (bufoff) + ldsw + _i * 8192), 16, 0, 0); } while (0)
; #define PG8_LDA(dst, b, h) do { _Pragma("unroll") for (int m = 0; m < 4; ++m) _Pragma("unroll") for (int k = 0; k < 2; ++k) dst[m][k] = *(const LAS bf16x8*)(lds + PG8_SA(b, h) + aoff + m * 2048 + k * 1024); } while (0)
; #define PG8_LDB(dst, b, h) do { _Pragma("unroll") for (int n = 0; n < 2; ++n) _Pragma("unroll") for (int k = 0; k < 2; ++k) dst[n][k] = *(const LAS bf16x8*)(lds + PG8_SB(b, h) + boff + n * 2048 + k * 1024); } while (0)
; #define PG8_MMA(ai, bj, At, Bt) do { __builtin_amdgcn_s_setprio(1); _Pragma("unroll") for (int m = 0; m < 4; ++m) _Pragma("unroll") for (int n = 0; n < 2; ++n) _Pragma("unroll") for (int k = 0; k < 2; ++k) \
;         acc[ai][bj][m][n] = __builtin_amdgcn_mfma_f32_16x16x32_bf16(Bt[n][k], At[m][k], acc[ai][bj][m][n], 0, 0, 0); __builtin_amdgcn_s_setprio(0); } while (0)
; #define PG8_WAIT_V(n) asm volatile("s_waitcnt vmcnt(" #n ")" ::: "memory")
; #define PG8_WAIT_L(n) asm volatile("s_waitcnt lgkmcnt(" #n ")" ::: "memory")
; #define PG8_BAR __builtin_amdgcn_s_barrier()
; template <class Epi, bool ALIGN_EPI, int K, int LDA, int LDB>
; __device__ __forceinline__ void gemm_phase(LAS unsigned char* lds, const int wid, const Gemm g, const StaticOrder& S, const Epi& E) {
;     ...
;         for (int t = 0; t < nt; t += 2) {
;             const bool last = (t == nt - 2);
;             const char* a1 = cA + (size_t)(t + 1) * kstep;
;             const char* a2 = last ? nA : cA + (size_t)(t + 2) * kstep; const char* b2 = last ? nB : cB + (size_t)(t + 2) * kstep;
;             const char* a3 = a2 + kstep; const char* b3 = b2 + kstep;
;             PG8_LDB(B0, 0, 0); PG8_LDB(B1, 0, 1); PG8_SCHED; PG8_LDA(At, 0, 0); PG8_STAGE(PG8_SA(1, 1), a1 + hA, voffA);
;             PG8_WAIT_V(8); PG8_WAIT_L(0); PG8_BAR; PG8_MMA(0, 0, At, B0); PG8_MMA(0, 1, At, B1); PG8_BAR; PG8_SCHED;
;             PG8_LDA(At, 0, 1); PG8_STAGE(PG8_SB(0, 0), b2, voffB); PG8_STAGE(PG8_SB(0, 1), b2 + hB, voffB); PG8_STAGE(PG8_SA(0, 0), a2, voffA);
;             PG8_WAIT_V(8); PG8_WAIT_L(0); PG8_BAR; PG8_MMA(1, 0, At, B0); PG8_MMA(1, 1, At, B1); PG8_BAR; PG8_SCHED;
.LBB0_1477:
	ds_read_b128 v[128:131], v175
	ds_read_b128 v[132:135], v175 offset:1024
	ds_read_b128 v[136:139], v175 offset:2048
	ds_read_b128 v[140:143], v175 offset:3072
	ds_read_b128 v[144:147], v176
	ds_read_b128 v[164:167], v176 offset:1024
	ds_read_b128 v[168:171], v176 offset:2048
	ds_read_b128 v[178:181], v176 offset:3072
	s_add_u32 s36, s34, 0xfffc0080
	s_addc_u32 s37, s35, -1
	s_cmp_eq_u32 s69, 12
	s_cselect_b32 s39, s25, s37
	s_cselect_b32 s38, s42, s36
	s_cselect_b32 s37, s23, s68
	s_cselect_b32 s36, s66, s67
	s_add_i32 m0, s40, 0xc000
	ds_read_b128 v[182:185], v177
	ds_read_b128 v[186:189], v177 offset:1024
	ds_read_b128 v[190:193], v177 offset:2048
	ds_read_b128 v[194:197], v177 offset:3072
	ds_read_b128 v[198:201], v177 offset:4096
	ds_read_b128 v[202:205], v177 offset:5120
	ds_read_b128 v[206:209], v177 offset:6144
	ds_read_b128 v[210:213], v177 offset:7168
	global_load_lds_dwordx4 v156, s[34:35]
	s_add_i32 m0, s40, 0xe000
	s_nop 0
	global_load_lds_dwordx4 v158, s[34:35]
	s_waitcnt vmcnt(8)
	s_barrier
	s_setprio 1
	s_waitcnt lgkmcnt(0)
	v_mfma_f32_16x16x32_bf16 v[124:127], v[128:131], v[182:185], v[124:127]
	v_mfma_f32_16x16x32_bf16 v[116:119], v[136:139], v[182:185], v[116:119]
	v_mfma_f32_16x16x32_bf16 v[120:123], v[128:131], v[190:193], v[120:123]
	v_mfma_f32_16x16x32_bf16 v[112:115], v[136:139], v[190:193], v[112:115]
	v_mfma_f32_16x16x32_bf16 v[92:95], v[128:131], v[198:201], v[92:95]
	v_mfma_f32_16x16x32_bf16 v[88:91], v[136:139], v[198:201], v[88:91]
	v_mfma_f32_16x16x32_bf16 v[76:79], v[128:131], v[206:209], v[76:79]
	v_mfma_f32_16x16x32_bf16 v[72:75], v[136:139], v[206:209], v[72:75]
	v_mfma_f32_16x16x32_bf16 v[124:127], v[132:135], v[186:189], v[124:127]
	v_mfma_f32_16x16x32_bf16 v[116:119], v[140:143], v[186:189], v[116:119]
	v_mfma_f32_16x16x32_bf16 v[120:123], v[132:135], v[194:197], v[120:123]
	v_mfma_f32_16x16x32_bf16 v[112:115], v[140:143], v[194:197], v[112:115]
	v_mfma_f32_16x16x32_bf16 v[92:95], v[132:135], v[202:205], v[92:95]
	v_mfma_f32_16x16x32_bf16 v[88:91], v[140:143], v[202:205], v[88:91]
	v_mfma_f32_16x16x32_bf16 v[76:79], v[132:135], v[210:213], v[76:79]
	v_mfma_f32_16x16x32_bf16 v[72:75], v[140:143], v[210:213], v[72:75]
	v_mfma_f32_16x16x32_bf16 v[108:111], v[144:147], v[182:185], v[108:111]
	v_mfma_f32_16x16x32_bf16 v[104:107], v[168:171], v[182:185], v[104:107]
	v_mfma_f32_16x16x32_bf16 v[100:103], v[144:147], v[190:193], v[100:103]
	v_mfma_f32_16x16x32_bf16 v[96:99], v[168:171], v[190:193], v[96:99]
	v_mfma_f32_16x16x32_bf16 v[84:87], v[144:147], v[198:201], v[84:87]
	v_mfma_f32_16x16x32_bf16 v[80:83], v[168:171], v[198:201], v[80:83]
	v_mfma_f32_16x16x32_bf16 v[68:71], v[144:147], v[206:209], v[68:71]
	v_mfma_f32_16x16x32_bf16 v[64:67], v[168:171], v[206:209], v[64:67]
	v_mfma_f32_16x16x32_bf16 v[108:111], v[164:167], v[186:189], v[108:111]
	v_mfma_f32_16x16x32_bf16 v[104:107], v[178:181], v[186:189], v[104:107]
	v_mfma_f32_16x16x32_bf16 v[100:103], v[164:167], v[194:197], v[100:103]
	v_mfma_f32_16x16x32_bf16 v[96:99], v[178:181], v[194:197], v[96:99]
	v_mfma_f32_16x16x32_bf16 v[84:87], v[164:167], v[202:205], v[84:87]
	v_mfma_f32_16x16x32_bf16 v[80:83], v[178:181], v[202:205], v[80:83]
	v_mfma_f32_16x16x32_bf16 v[68:71], v[164:167], v[210:213], v[68:71]
	v_mfma_f32_16x16x32_bf16 v[64:67], v[178:181], v[210:213], v[64:67]
	s_setprio 0
	s_barrier
	s_add_u32 s98, s36, s12
	s_addc_u32 s99, s37, s13
	s_add_u32 s100, s38, s12
	s_addc_u32 s101, s39, s13
	s_add_i32 s52, s58, s33
	s_mov_b32 m0, s52
	ds_read_b128 v[182:185], v177 offset:16384
	ds_read_b128 v[186:189], v177 offset:17408
	ds_read_b128 v[190:193], v177 offset:18432
	ds_read_b128 v[194:197], v177 offset:19456
	ds_read_b128 v[198:201], v177 offset:20480
	ds_read_b128 v[202:205], v177 offset:21504
	ds_read_b128 v[206:209], v177 offset:22528
	ds_read_b128 v[210:213], v177 offset:23552
	global_load_lds_dwordx4 v150, s[36:37]
	s_add_i32 m0, s52, 0x2000
	s_add_u32 s70, s36, 0x40000
	s_addc_u32 s71, s37, 0
	s_add_i32 s52, s59, s33
	global_load_lds_dwordx4 v154, s[36:37]
	s_mov_b32 m0, s52
	s_nop 0
	global_load_lds_dwordx4 v150, s[70:71]
	s_add_i32 m0, s52, 0x2000
	s_nop 0
	global_load_lds_dwordx4 v154, s[70:71]
	s_mov_b32 m0, s40
	s_nop 0
	global_load_lds_dwordx4 v148, s[38:39]
	s_mov_b32 m0, s41
	s_nop 0
	global_load_lds_dwordx4 v152, s[38:39]
	s_waitcnt vmcnt(8)
	s_barrier
	s_setprio 1
	s_waitcnt lgkmcnt(0)
	v_mfma_f32_16x16x32_bf16 v[60:63], v[128:131], v[182:185], v[60:63]
	v_mfma_f32_16x16x32_bf16 v[56:59], v[136:139], v[182:185], v[56:59]
	v_mfma_f32_16x16x32_bf16 v[44:47], v[128:131], v[190:193], v[44:47]
	v_mfma_f32_16x16x32_bf16 v[40:43], v[136:139], v[190:193], v[40:43]
	v_mfma_f32_16x16x32_bf16 v[36:39], v[128:131], v[198:201], v[36:39]
	v_mfma_f32_16x16x32_bf16 v[32:35], v[136:139], v[198:201], v[32:35]
	v_mfma_f32_16x16x32_bf16 v[20:23], v[128:131], v[206:209], v[20:23]
	v_mfma_f32_16x16x32_bf16 v[16:19], v[136:139], v[206:209], v[16:19]
	v_mfma_f32_16x16x32_bf16 v[60:63], v[132:135], v[186:189], v[60:63]
	v_mfma_f32_16x16x32_bf16 v[56:59], v[140:143], v[186:189], v[56:59]
	v_mfma_f32_16x16x32_bf16 v[44:47], v[132:135], v[194:197], v[44:47]
	v_mfma_f32_16x16x32_bf16 v[40:43], v[140:143], v[194:197], v[40:43]
	v_mfma_f32_16x16x32_bf16 v[36:39], v[132:135], v[202:205], v[36:39]
	v_mfma_f32_16x16x32_bf16 v[32:35], v[140:143], v[202:205], v[32:35]
	v_mfma_f32_16x16x32_bf16 v[20:23], v[132:135], v[210:213], v[20:23]
	v_mfma_f32_16x16x32_bf16 v[16:19], v[140:143], v[210:213], v[16:19]
	v_mfma_f32_16x16x32_bf16 v[52:55], v[144:147], v[182:185], v[52:55]
	v_mfma_f32_16x16x32_bf16 v[48:51], v[168:171], v[182:185], v[48:51]
	v_mfma_f32_16x16x32_bf16 v[28:31], v[144:147], v[190:193], v[28:31]
	v_mfma_f32_16x16x32_bf16 v[24:27], v[168:171], v[190:193], v[24:27]
	v_mfma_f32_16x16x32_bf16 v[12:15], v[144:147], v[198:201], v[12:15]
	v_mfma_f32_16x16x32_bf16 v[8:11], v[168:171], v[198:201], v[8:11]
	v_mfma_f32_16x16x32_bf16 v[4:7], v[144:147], v[206:209], v[4:7]
	v_mfma_f32_16x16x32_bf16 v[0:3], v[168:171], v[206:209], v[0:3]
	v_mfma_f32_16x16x32_bf16 v[52:55], v[164:167], v[186:189], v[52:55]
	v_mfma_f32_16x16x32_bf16 v[48:51], v[178:181], v[186:189], v[48:51]
	v_mfma_f32_16x16x32_bf16 v[28:31], v[164:167], v[194:197], v[28:31]
	v_mfma_f32_16x16x32_bf16 v[24:27], v[178:181], v[194:197], v[24:27]
	v_mfma_f32_16x16x32_bf16 v[12:15], v[164:167], v[202:205], v[12:15]
	v_mfma_f32_16x16x32_bf16 v[8:11], v[178:181], v[202:205], v[8:11]
	v_mfma_f32_16x16x32_bf16 v[4:7], v[164:167], v[210:213], v[4:7]
	v_mfma_f32_16x16x32_bf16 v[0:3], v[178:181], v[210:213], v[0:3]
	s_setprio 0
	s_barrier
; #define PG8_STAGE(bufoff, gbase, voff) do { _Pragma("unroll") for (int _i = 0; _i < 2; ++_i) \
;         __builtin_amdgcn_global_load_lds((const unsigned*)((const char*)(gbase) + (voff)[_i]), (LAS unsigned*)(lds + (bufoff) + ldsw + _i * 8192), 16, 0, 0); } while (0)
; #define PG8_LDA(dst, b, h) do { _Pragma("unroll") for (int m = 0; m < 4; ++m) _Pragma("unroll") for (int k = 0; k < 2; ++k) dst[m][k] = *(const LAS bf16x8*)(lds + PG8_SA(b, h) + aoff + m * 2048 + k * 1024); } while (0)
; #define PG8_LDB(dst, b, h) do { _Pragma("unroll") for (int n = 0; n < 2; ++n) _Pragma("unroll") for (int k = 0; k < 2; ++k) dst[n][k] = *(const LAS bf16x8*)(lds + PG8_SB(b, h) + boff + n * 2048 + k * 1024); } while (0)
; #define PG8_MMA(ai, bj, At, Bt) do { __builtin_amdgcn_s_setprio(1); _Pragma("unroll") for (int m = 0; m < 4; ++m) _Pragma("unroll") for (int n = 0; n < 2; ++n) _Pragma("unroll") for (int k = 0; k < 2; ++k) \
;         acc[ai][bj][m][n] = __builtin_amdgcn_mfma_f32_16x16x32_bf16(Bt[n][k], At[m][k], acc[ai][bj][m][n], 0, 0, 0); __builtin_amdgcn_s_setprio(0); } while (0)
; #define PG8_WAIT_V(n) asm volatile("s_waitcnt vmcnt(" #n ")" ::: "memory")
; #define PG8_WAIT_L(n) asm volatile("s_waitcnt lgkmcnt(" #n ")" ::: "memory")
; #define PG8_BAR __builtin_amdgcn_s_barrier()
; #define PG8_SCHED __builtin_amdgcn_sched_barrier(0)
; template <class Epi, bool ALIGN_EPI, int K, int LDA, int LDB>
; __device__ __forceinline__ void gemm_phase(LAS unsigned char* lds, const int wid, const Gemm g, const StaticOrder& S, const Epi& E) {
;     ...
;             PG8_LDB(B0, 1, 0); PG8_LDB(B1, 1, 1); PG8_SCHED; PG8_LDA(At, 1, 0); PG8_STAGE(PG8_SA(0, 1), a2 + hA, voffA);
;             PG8_WAIT_V(8); PG8_WAIT_L(0); PG8_BAR; PG8_MMA(0, 0, At, B0); PG8_MMA(0, 1, At, B1); PG8_BAR; PG8_SCHED;
;             PG8_LDA(At, 1, 1); PG8_STAGE(PG8_SB(1, 0), b3, voffB); PG8_STAGE(PG8_SB(1, 1), b3 + hB, voffB); PG8_STAGE(PG8_SA(1, 0), a3, voffA);
;             PG8_WAIT_V(8); PG8_WAIT_L(0); PG8_BAR; PG8_MMA(1, 0, At, B0); PG8_MMA(1, 1, At, B1); PG8_BAR; PG8_SCHED;
;         }
;         if constexpr (ALIGN_EPI) { if (wr == 0) PG8_BAR; }
	s_add_i32 s52, 0, 0x18000
	s_add_i32 s53, 0, 0x1c000
	v_add_u32_e32 v140, s52, v174
	v_add_u32_e32 v178, s53, v174
	ds_read_b128 v[128:131], v140
	ds_read_b128 v[132:135], v140 offset:1024
	ds_read_b128 v[136:139], v140 offset:2048
	ds_read_b128 v[140:143], v140 offset:3072
	ds_read_b128 v[144:147], v178
	ds_read_b128 v[164:167], v178 offset:1024
	ds_read_b128 v[168:171], v178 offset:2048
	ds_read_b128 v[178:181], v178 offset:3072
	s_add_u32 s38, s38, 0x40000
	s_addc_u32 s39, s39, 0
	s_mov_b32 m0, s43
	ds_read_b128 v[182:185], v177 offset:32768
	ds_read_b128 v[186:189], v177 offset:33792
	ds_read_b128 v[190:193], v177 offset:34816
	ds_read_b128 v[194:197], v177 offset:35840
	ds_read_b128 v[198:201], v177 offset:36864
	ds_read_b128 v[202:205], v177 offset:37888
	ds_read_b128 v[206:209], v177 offset:38912
	ds_read_b128 v[210:213], v177 offset:39936
	global_load_lds_dwordx4 v148, s[38:39]
	s_mov_b32 m0, s48
	s_nop 0
	global_load_lds_dwordx4 v152, s[38:39]
	s_waitcnt vmcnt(8)
	s_barrier
	s_setprio 1
	s_waitcnt lgkmcnt(0)
	v_mfma_f32_16x16x32_bf16 v[124:127], v[128:131], v[182:185], v[124:127]
	v_mfma_f32_16x16x32_bf16 v[116:119], v[136:139], v[182:185], v[116:119]
	v_mfma_f32_16x16x32_bf16 v[120:123], v[128:131], v[190:193], v[120:123]
	v_mfma_f32_16x16x32_bf16 v[112:115], v[136:139], v[190:193], v[112:115]
	v_mfma_f32_16x16x32_bf16 v[92:95], v[128:131], v[198:201], v[92:95]
	v_mfma_f32_16x16x32_bf16 v[88:91], v[136:139], v[198:201], v[88:91]
	v_mfma_f32_16x16x32_bf16 v[76:79], v[128:131], v[206:209], v[76:79]
	v_mfma_f32_16x16x32_bf16 v[72:75], v[136:139], v[206:209], v[72:75]
	v_mfma_f32_16x16x32_bf16 v[124:127], v[132:135], v[186:189], v[124:127]
	v_mfma_f32_16x16x32_bf16 v[116:119], v[140:143], v[186:189], v[116:119]
	v_mfma_f32_16x16x32_bf16 v[120:123], v[132:135], v[194:197], v[120:123]
	v_mfma_f32_16x16x32_bf16 v[112:115], v[140:143], v[194:197], v[112:115]
	v_mfma_f32_16x16x32_bf16 v[92:95], v[132:135], v[202:205], v[92:95]
	v_mfma_f32_16x16x32_bf16 v[88:91], v[140:143], v[202:205], v[88:91]
	v_mfma_f32_16x16x32_bf16 v[76:79], v[132:135], v[210:213], v[76:79]
	v_mfma_f32_16x16x32_bf16 v[72:75], v[140:143], v[210:213], v[72:75]
	v_mfma_f32_16x16x32_bf16 v[108:111], v[144:147], v[182:185], v[108:111]
	v_mfma_f32_16x16x32_bf16 v[104:107], v[168:171], v[182:185], v[104:107]
	v_mfma_f32_16x16x32_bf16 v[100:103], v[144:147], v[190:193], v[100:103]
	v_mfma_f32_16x16x32_bf16 v[96:99], v[168:171], v[190:193], v[96:99]
	v_mfma_f32_16x16x32_bf16 v[84:87], v[144:147], v[198:201], v[84:87]
	v_mfma_f32_16x16x32_bf16 v[80:83], v[168:171], v[198:201], v[80:83]
	v_mfma_f32_16x16x32_bf16 v[68:71], v[144:147], v[206:209], v[68:71]
	v_mfma_f32_16x16x32_bf16 v[64:67], v[168:171], v[206:209], v[64:67]
	v_mfma_f32_16x16x32_bf16 v[108:111], v[164:167], v[186:189], v[108:111]
	v_mfma_f32_16x16x32_bf16 v[104:107], v[178:181], v[186:189], v[104:107]
	v_mfma_f32_16x16x32_bf16 v[100:103], v[164:167], v[194:197], v[100:103]
	v_mfma_f32_16x16x32_bf16 v[96:99], v[178:181], v[194:197], v[96:99]
	v_mfma_f32_16x16x32_bf16 v[84:87], v[164:167], v[202:205], v[84:87]
	v_mfma_f32_16x16x32_bf16 v[80:83], v[178:181], v[202:205], v[80:83]
	v_mfma_f32_16x16x32_bf16 v[68:71], v[164:167], v[210:213], v[68:71]
	v_mfma_f32_16x16x32_bf16 v[64:67], v[178:181], v[210:213], v[64:67]
	s_setprio 0
	s_barrier
	s_add_i32 s38, s52, s33
	s_mov_b32 m0, s38
	ds_read_b128 v[182:185], v177 offset:49152
	ds_read_b128 v[186:189], v177 offset:50176
	ds_read_b128 v[190:193], v177 offset:51200
	ds_read_b128 v[194:197], v177 offset:52224
	ds_read_b128 v[198:201], v177 offset:53248
	ds_read_b128 v[202:205], v177 offset:54272
	ds_read_b128 v[206:209], v177 offset:55296
	ds_read_b128 v[210:213], v177 offset:56320
	global_load_lds_dwordx4 v150, s[98:99]
	s_add_i32 m0, s38, 0x2000
	s_add_u32 s36, s36, 0x40080
	s_addc_u32 s37, s37, 0
	s_add_i32 s38, s53, s33
	global_load_lds_dwordx4 v154, s[98:99]
	s_mov_b32 m0, s38
	s_nop 0
	global_load_lds_dwordx4 v150, s[36:37]
	s_add_i32 m0, s38, 0x2000
	s_nop 0
	global_load_lds_dwordx4 v154, s[36:37]
	s_mov_b32 m0, s55
	s_nop 0
	global_load_lds_dwordx4 v148, s[100:101]
	s_mov_b32 m0, s56
	s_nop 0
	global_load_lds_dwordx4 v152, s[100:101]
	s_waitcnt vmcnt(8)
	s_barrier
	s_setprio 1
	s_waitcnt lgkmcnt(0)
	v_mfma_f32_16x16x32_bf16 v[60:63], v[128:131], v[182:185], v[60:63]
	v_mfma_f32_16x16x32_bf16 v[56:59], v[136:139], v[182:185], v[56:59]
	v_mfma_f32_16x16x32_bf16 v[44:47], v[128:131], v[190:193], v[44:47]
	v_mfma_f32_16x16x32_bf16 v[40:43], v[136:139], v[190:193], v[40:43]
	v_mfma_f32_16x16x32_bf16 v[36:39], v[128:131], v[198:201], v[36:39]
	v_mfma_f32_16x16x32_bf16 v[32:35], v[136:139], v[198:201], v[32:35]
	v_mfma_f32_16x16x32_bf16 v[20:23], v[128:131], v[206:209], v[20:23]
	v_mfma_f32_16x16x32_bf16 v[16:19], v[136:139], v[206:209], v[16:19]
	v_mfma_f32_16x16x32_bf16 v[60:63], v[132:135], v[186:189], v[60:63]
	v_mfma_f32_16x16x32_bf16 v[56:59], v[140:143], v[186:189], v[56:59]
	v_mfma_f32_16x16x32_bf16 v[44:47], v[132:135], v[194:197], v[44:47]
	v_mfma_f32_16x16x32_bf16 v[40:43], v[140:143], v[194:197], v[40:43]
	v_mfma_f32_16x16x32_bf16 v[36:39], v[132:135], v[202:205], v[36:39]
	v_mfma_f32_16x16x32_bf16 v[32:35], v[140:143], v[202:205], v[32:35]
	v_mfma_f32_16x16x32_bf16 v[20:23], v[132:135], v[210:213], v[20:23]
	v_mfma_f32_16x16x32_bf16 v[16:19], v[140:143], v[210:213], v[16:19]
	v_mfma_f32_16x16x32_bf16 v[52:55], v[144:147], v[182:185], v[52:55]
	v_mfma_f32_16x16x32_bf16 v[48:51], v[168:171], v[182:185], v[48:51]
	v_mfma_f32_16x16x32_bf16 v[28:31], v[144:147], v[190:193], v[28:31]
	v_mfma_f32_16x16x32_bf16 v[24:27], v[168:171], v[190:193], v[24:27]
	v_mfma_f32_16x16x32_bf16 v[12:15], v[144:147], v[198:201], v[12:15]
	v_mfma_f32_16x16x32_bf16 v[8:11], v[168:171], v[198:201], v[8:11]
	v_mfma_f32_16x16x32_bf16 v[4:7], v[144:147], v[206:209], v[4:7]
	v_mfma_f32_16x16x32_bf16 v[0:3], v[168:171], v[206:209], v[0:3]
	v_mfma_f32_16x16x32_bf16 v[52:55], v[164:167], v[186:189], v[52:55]
	v_mfma_f32_16x16x32_bf16 v[48:51], v[178:181], v[186:189], v[48:51]
	v_mfma_f32_16x16x32_bf16 v[28:31], v[164:167], v[194:197], v[28:31]
	v_mfma_f32_16x16x32_bf16 v[24:27], v[178:181], v[194:197], v[24:27]
	v_mfma_f32_16x16x32_bf16 v[12:15], v[164:167], v[202:205], v[12:15]
	v_mfma_f32_16x16x32_bf16 v[8:11], v[178:181], v[202:205], v[8:11]
	v_mfma_f32_16x16x32_bf16 v[4:7], v[164:167], v[210:213], v[4:7]
	v_mfma_f32_16x16x32_bf16 v[0:3], v[178:181], v[210:213], v[0:3]
	s_setprio 0
	s_barrier
	s_add_i32 s69, s69, 2
	s_add_u32 s34, s34, 0x100
	s_addc_u32 s35, s35, 0
	s_add_u32 s67, s67, 0x100
	s_addc_u32 s68, s68, 0
	s_cmp_gt_u32 s69, 13
	s_cbranch_scc0 .LBB0_1477
	s_and_b64 vcc, exec, s[14:15]
	s_cbranch_vccz .LBB0_1480
	s_barrier

; #define PG8_STAGE(bufoff, gbase, voff) do { _Pragma("unroll") for (int _i = 0; _i < 2; ++_i) \
;         __builtin_amdgcn_global_load_lds((const unsigned*)((const char*)(gbase) + (voff)[_i]), (LAS unsigned*)(lds + (bufoff) + ldsw + _i * 8192), 16, 0, 0); } while (0)
; #define PG8_LDA(dst, b, h) do { _Pragma("unroll") for (int m = 0; m < 4; ++m) _Pragma("unroll") for (int k = 0; k < 2; ++k) dst[m][k] = *(const LAS bf16x8*)(lds + PG8_SA(b, h) + aoff + m * 2048 + k * 1024); } while (0)
; #define PG8_LDB(dst, b, h) do { _Pragma("unroll") for (int n = 0; n < 2; ++n) _Pragma("unroll") for (int k = 0; k < 2; ++k) dst[n][k] = *(const LAS bf16x8*)(lds + PG8_SB(b, h) + boff + n * 2048 + k * 1024); } while (0)
; #define PG8_MMA(ai, bj, At, Bt) do { __builtin_amdgcn_s_setprio(1); _Pragma("unroll") for (int m = 0; m < 4; ++m) _Pragma("unroll") for (int n = 0; n < 2; ++n) _Pragma("unroll") for (int k = 0; k < 2; ++k) \
;         acc[ai][bj][m][n] = __builtin_amdgcn_mfma_f32_16x16x32_bf16(Bt[n][k], At[m][k], acc[ai][bj][m][n], 0, 0, 0); __builtin_amdgcn_s_setprio(0); } while (0)
; #define PG8_WAIT_V(n) asm volatile("s_waitcnt vmcnt(" #n ")" ::: "memory")
; #define PG8_WAIT_L(n) asm volatile("s_waitcnt lgkmcnt(" #n ")" ::: "memory")
; #define PG8_BAR __builtin_amdgcn_s_barrier()
; #define PG8_SCHED __builtin_amdgcn_sched_barrier(0)
; template <class Epi, bool ALIGN_EPI, int K, int LDA, int LDB>
; __device__ __forceinline__ void gemm_phase(LAS unsigned char* lds, const int wid, const Gemm g, const StaticOrder& S, const Epi& E) {
;     ...
;             const bool last = (t == nt - 2);
;             const char* a1 = cA + (size_t)(t + 1) * kstep;
;             const char* a2 = last ? nA : cA + (size_t)(t + 2) * kstep; const char* b2 = last ? nB : cB + (size_t)(t + 2) * kstep;
;             const char* a3 = a2 + kstep; const char* b3 = b2 + kstep;
;             PG8_LDB(B0, 0, 0); PG8_LDB(B1, 0, 1); PG8_SCHED; PG8_LDA(At, 0, 0); PG8_STAGE(PG8_SA(1, 1), a1 + hA, voffA);
;             PG8_WAIT_V(8); PG8_WAIT_L(0); PG8_BAR; PG8_MMA(0, 0, At, B0); PG8_MMA(0, 1, At, B1); PG8_BAR; PG8_SCHED;
;             PG8_LDA(At, 0, 1); PG8_STAGE(PG8_SB(0, 0), b2, voffB); PG8_STAGE(PG8_SB(0, 1), b2 + hB, voffB); PG8_STAGE(PG8_SA(0, 0), a2, voffA);
;             PG8_WAIT_V(8); PG8_WAIT_L(0); PG8_BAR; PG8_MMA(1, 0, At, B0); PG8_MMA(1, 1, At, B1); PG8_BAR; PG8_SCHED;
.LBB0_1696:
	s_add_u32 s61, s28, 0x100
	s_addc_u32 s62, s29, 0
	s_mov_b32 s63, -2
	s_add_u32 s28, s26, 0x100
	s_addc_u32 s29, s27, 0
	s_cmp_eq_u32 s63, 40
	s_cselect_b32 s35, s7, s29
	s_cselect_b32 s34, s6, s28
	s_cselect_b32 s31, s25, s62
	s_cselect_b32 s30, s24, s61
	s_add_i32 m0, s36, 0xc000
	global_load_lds_dwordx4 v152, s[26:27]
	s_add_i32 m0, s36, 0xe000
	s_nop 0
	global_load_lds_dwordx4 v154, s[26:27]
	s_waitcnt vmcnt(8)
	s_barrier
	s_setprio 1
	s_waitcnt lgkmcnt(0)
	v_mfma_f32_16x16x32_bf16 v[140:143], v[120:123], v[182:185], 0
	v_mfma_f32_16x16x32_bf16 v[136:139], v[128:131], v[182:185], 0
	v_mfma_f32_16x16x32_bf16 v[108:111], v[120:123], v[190:193], 0
	v_mfma_f32_16x16x32_bf16 v[104:107], v[128:131], v[190:193], 0
	v_mfma_f32_16x16x32_bf16 v[92:95], v[120:123], v[198:201], 0
	v_mfma_f32_16x16x32_bf16 v[88:91], v[128:131], v[198:201], 0
	v_mfma_f32_16x16x32_bf16 v[76:79], v[120:123], v[206:209], 0
	v_mfma_f32_16x16x32_bf16 v[72:75], v[128:131], v[206:209], 0
	v_mfma_f32_16x16x32_bf16 v[140:143], v[124:127], v[186:189], v[140:143]
	v_mfma_f32_16x16x32_bf16 v[136:139], v[132:135], v[186:189], v[136:139]
	v_mfma_f32_16x16x32_bf16 v[108:111], v[124:127], v[194:197], v[108:111]
	v_mfma_f32_16x16x32_bf16 v[104:107], v[132:135], v[194:197], v[104:107]
	v_mfma_f32_16x16x32_bf16 v[92:95], v[124:127], v[202:205], v[92:95]
	v_mfma_f32_16x16x32_bf16 v[88:91], v[132:135], v[202:205], v[88:91]
	v_mfma_f32_16x16x32_bf16 v[76:79], v[124:127], v[210:213], v[76:79]
	v_mfma_f32_16x16x32_bf16 v[72:75], v[132:135], v[210:213], v[72:75]
	v_mfma_f32_16x16x32_bf16 v[116:119], v[160:163], v[182:185], 0
	v_mfma_f32_16x16x32_bf16 v[112:115], v[174:177], v[182:185], 0
	v_mfma_f32_16x16x32_bf16 v[100:103], v[160:163], v[190:193], 0
	v_mfma_f32_16x16x32_bf16 v[96:99], v[174:177], v[190:193], 0
	v_mfma_f32_16x16x32_bf16 v[84:87], v[160:163], v[198:201], 0
	v_mfma_f32_16x16x32_bf16 v[80:83], v[174:177], v[198:201], 0
	v_mfma_f32_16x16x32_bf16 v[68:71], v[160:163], v[206:209], 0
	v_mfma_f32_16x16x32_bf16 v[64:67], v[174:177], v[206:209], 0
	v_mfma_f32_16x16x32_bf16 v[116:119], v[170:173], v[186:189], v[116:119]
	v_mfma_f32_16x16x32_bf16 v[112:115], v[178:181], v[186:189], v[112:115]
	v_mfma_f32_16x16x32_bf16 v[100:103], v[170:173], v[194:197], v[100:103]
	v_mfma_f32_16x16x32_bf16 v[96:99], v[178:181], v[194:197], v[96:99]
	v_mfma_f32_16x16x32_bf16 v[84:87], v[170:173], v[202:205], v[84:87]
	v_mfma_f32_16x16x32_bf16 v[80:83], v[178:181], v[202:205], v[80:83]
	v_mfma_f32_16x16x32_bf16 v[68:71], v[170:173], v[210:213], v[68:71]
	v_mfma_f32_16x16x32_bf16 v[64:67], v[178:181], v[210:213], v[64:67]
	s_setprio 0
	s_barrier
	s_add_u32 s98, s30, s12
	s_addc_u32 s99, s31, s13
	s_add_u32 s100, s34, s12
	s_addc_u32 s101, s35, s13
	s_add_i32 s26, s54, s33
	s_mov_b32 m0, s26
	ds_read_b128 v[182:185], v169 offset:16384
	ds_read_b128 v[186:189], v169 offset:17408
	ds_read_b128 v[190:193], v169 offset:18432
	ds_read_b128 v[194:197], v169 offset:19456
	ds_read_b128 v[198:201], v169 offset:20480
	ds_read_b128 v[202:205], v169 offset:21504
	ds_read_b128 v[206:209], v169 offset:22528
	ds_read_b128 v[210:213], v169 offset:23552
	global_load_lds_dwordx4 v146, s[30:31]
	s_add_i32 m0, s26, 0x2000
	s_add_u32 s26, s30, 0xb0000
	s_addc_u32 s27, s31, 0
	s_add_i32 s52, s55, s33
	global_load_lds_dwordx4 v150, s[30:31]
	s_mov_b32 m0, s52
	s_nop 0
	global_load_lds_dwordx4 v146, s[26:27]
	s_add_i32 m0, s52, 0x2000
	s_nop 0
	global_load_lds_dwordx4 v150, s[26:27]
	s_mov_b32 m0, s36
	s_nop 0
	global_load_lds_dwordx4 v144, s[34:35]
	s_mov_b32 m0, s37
	s_nop 0
	global_load_lds_dwordx4 v148, s[34:35]
	s_waitcnt vmcnt(8)
	s_barrier
	s_setprio 1
	s_waitcnt lgkmcnt(0)
	v_mfma_f32_16x16x32_bf16 v[60:63], v[120:123], v[182:185], 0
	v_mfma_f32_16x16x32_bf16 v[56:59], v[128:131], v[182:185], 0
	v_mfma_f32_16x16x32_bf16 v[44:47], v[120:123], v[190:193], 0
	v_mfma_f32_16x16x32_bf16 v[40:43], v[128:131], v[190:193], 0
	v_mfma_f32_16x16x32_bf16 v[28:31], v[120:123], v[198:201], 0
	v_mfma_f32_16x16x32_bf16 v[24:27], v[128:131], v[198:201], 0
	v_mfma_f32_16x16x32_bf16 v[12:15], v[120:123], v[206:209], 0
	v_mfma_f32_16x16x32_bf16 v[8:11], v[128:131], v[206:209], 0
	v_mfma_f32_16x16x32_bf16 v[60:63], v[124:127], v[186:189], v[60:63]
	v_mfma_f32_16x16x32_bf16 v[56:59], v[132:135], v[186:189], v[56:59]
	v_mfma_f32_16x16x32_bf16 v[44:47], v[124:127], v[194:197], v[44:47]
	v_mfma_f32_16x16x32_bf16 v[40:43], v[132:135], v[194:197], v[40:43]
	v_mfma_f32_16x16x32_bf16 v[28:31], v[124:127], v[202:205], v[28:31]
	v_mfma_f32_16x16x32_bf16 v[24:27], v[132:135], v[202:205], v[24:27]
	v_mfma_f32_16x16x32_bf16 v[12:15], v[124:127], v[210:213], v[12:15]
	v_mfma_f32_16x16x32_bf16 v[8:11], v[132:135], v[210:213], v[8:11]
	v_mfma_f32_16x16x32_bf16 v[52:55], v[160:163], v[182:185], 0
	v_mfma_f32_16x16x32_bf16 v[48:51], v[174:177], v[182:185], 0
	v_mfma_f32_16x16x32_bf16 v[36:39], v[160:163], v[190:193], 0
	v_mfma_f32_16x16x32_bf16 v[32:35], v[174:177], v[190:193], 0
	v_mfma_f32_16x16x32_bf16 v[20:23], v[160:163], v[198:201], 0
	v_mfma_f32_16x16x32_bf16 v[16:19], v[174:177], v[198:201], 0
	v_mfma_f32_16x16x32_bf16 v[4:7], v[160:163], v[206:209], 0
	v_mfma_f32_16x16x32_bf16 v[0:3], v[174:177], v[206:209], 0
	v_mfma_f32_16x16x32_bf16 v[52:55], v[170:173], v[186:189], v[52:55]
	v_mfma_f32_16x16x32_bf16 v[48:51], v[178:181], v[186:189], v[48:51]
	v_mfma_f32_16x16x32_bf16 v[36:39], v[170:173], v[194:197], v[36:39]
	v_mfma_f32_16x16x32_bf16 v[32:35], v[178:181], v[194:197], v[32:35]
	v_mfma_f32_16x16x32_bf16 v[20:23], v[170:173], v[202:205], v[20:23]
	v_mfma_f32_16x16x32_bf16 v[16:19], v[178:181], v[202:205], v[16:19]
	v_mfma_f32_16x16x32_bf16 v[4:7], v[170:173], v[210:213], v[4:7]
	v_mfma_f32_16x16x32_bf16 v[0:3], v[178:181], v[210:213], v[0:3]
	s_setprio 0
	s_barrier
; #define PG8_STAGE(bufoff, gbase, voff) do { _Pragma("unroll") for (int _i = 0; _i < 2; ++_i) \
;         __builtin_amdgcn_global_load_lds((const unsigned*)((const char*)(gbase) + (voff)[_i]), (LAS unsigned*)(lds + (bufoff) + ldsw + _i * 8192), 16, 0, 0); } while (0)
; #define PG8_LDA(dst, b, h) do { _Pragma("unroll") for (int m = 0; m < 4; ++m) _Pragma("unroll") for (int k = 0; k < 2; ++k) dst[m][k] = *(const LAS bf16x8*)(lds + PG8_SA(b, h) + aoff + m * 2048 + k * 1024); } while (0)
; #define PG8_LDB(dst, b, h) do { _Pragma("unroll") for (int n = 0; n < 2; ++n) _Pragma("unroll") for (int k = 0; k < 2; ++k) dst[n][k] = *(const LAS bf16x8*)(lds + PG8_SB(b, h) + boff + n * 2048 + k * 1024); } while (0)
; #define PG8_MMA(ai, bj, At, Bt) do { __builtin_amdgcn_s_setprio(1); _Pragma("unroll") for (int m = 0; m < 4; ++m) _Pragma("unroll") for (int n = 0; n < 2; ++n) _Pragma("unroll") for (int k = 0; k < 2; ++k) \
;         acc[ai][bj][m][n] = __builtin_amdgcn_mfma_f32_16x16x32_bf16(Bt[n][k], At[m][k], acc[ai][bj][m][n], 0, 0, 0); __builtin_amdgcn_s_setprio(0); } while (0)
; #define PG8_WAIT_V(n) asm volatile("s_waitcnt vmcnt(" #n ")" ::: "memory")
; #define PG8_WAIT_L(n) asm volatile("s_waitcnt lgkmcnt(" #n ")" ::: "memory")
; #define PG8_BAR __builtin_amdgcn_s_barrier()
; #define PG8_SCHED __builtin_amdgcn_sched_barrier(0)
; template <class Epi, bool ALIGN_EPI, int K, int LDA, int LDB>
; __device__ __forceinline__ void gemm_phase(LAS unsigned char* lds, const int wid, const Gemm g, const StaticOrder& S, const Epi& E) {
;     ...
;             PG8_LDB(B0, 1, 0); PG8_LDB(B1, 1, 1); PG8_SCHED; PG8_LDA(At, 1, 0); PG8_STAGE(PG8_SA(0, 1), a2 + hA, voffA);
;             PG8_WAIT_V(8); PG8_WAIT_L(0); PG8_BAR; PG8_MMA(0, 0, At, B0); PG8_MMA(0, 1, At, B1); PG8_BAR; PG8_SCHED;
;             PG8_LDA(At, 1, 1); PG8_STAGE(PG8_SB(1, 0), b3, voffB); PG8_STAGE(PG8_SB(1, 1), b3 + hB, voffB); PG8_STAGE(PG8_SA(1, 0), a3, voffA);
;             PG8_WAIT_V(8); PG8_WAIT_L(0); PG8_BAR; PG8_MMA(1, 0, At, B0); PG8_MMA(1, 1, At, B1); PG8_BAR; PG8_SCHED;
	s_add_i32 s52, 0, 0x18000
	s_add_i32 s53, 0, 0x1c000
	v_add_u32_e32 v132, s52, v166
	v_add_u32_e32 v178, s53, v166
	ds_read_b128 v[120:123], v132
	ds_read_b128 v[124:127], v132 offset:1024
	ds_read_b128 v[128:131], v132 offset:2048
	ds_read_b128 v[132:135], v132 offset:3072
	ds_read_b128 v[160:163], v178
	ds_read_b128 v[170:173], v178 offset:1024
	ds_read_b128 v[174:177], v178 offset:2048
	ds_read_b128 v[178:181], v178 offset:3072
	s_add_u32 s26, s34, 0xb0000
	s_addc_u32 s27, s35, 0
	s_mov_b32 m0, s38
	ds_read_b128 v[182:185], v169 offset:32768
	ds_read_b128 v[186:189], v169 offset:33792
	ds_read_b128 v[190:193], v169 offset:34816
	ds_read_b128 v[194:197], v169 offset:35840
	ds_read_b128 v[198:201], v169 offset:36864
	ds_read_b128 v[202:205], v169 offset:37888
	ds_read_b128 v[206:209], v169 offset:38912
	ds_read_b128 v[210:213], v169 offset:39936
	global_load_lds_dwordx4 v144, s[26:27]
	s_mov_b32 m0, s39
	s_nop 0
	global_load_lds_dwordx4 v148, s[26:27]
	s_waitcnt vmcnt(8)
	s_barrier
	s_setprio 1
	s_waitcnt lgkmcnt(0)
	v_mfma_f32_16x16x32_bf16 v[140:143], v[120:123], v[182:185], v[140:143]
	v_mfma_f32_16x16x32_bf16 v[136:139], v[128:131], v[182:185], v[136:139]
	v_mfma_f32_16x16x32_bf16 v[108:111], v[120:123], v[190:193], v[108:111]
	v_mfma_f32_16x16x32_bf16 v[104:107], v[128:131], v[190:193], v[104:107]
	v_mfma_f32_16x16x32_bf16 v[92:95], v[120:123], v[198:201], v[92:95]
	v_mfma_f32_16x16x32_bf16 v[88:91], v[128:131], v[198:201], v[88:91]
	v_mfma_f32_16x16x32_bf16 v[76:79], v[120:123], v[206:209], v[76:79]
	v_mfma_f32_16x16x32_bf16 v[72:75], v[128:131], v[206:209], v[72:75]
	v_mfma_f32_16x16x32_bf16 v[140:143], v[124:127], v[186:189], v[140:143]
	v_mfma_f32_16x16x32_bf16 v[136:139], v[132:135], v[186:189], v[136:139]
	v_mfma_f32_16x16x32_bf16 v[108:111], v[124:127], v[194:197], v[108:111]
	v_mfma_f32_16x16x32_bf16 v[104:107], v[132:135], v[194:197], v[104:107]
	v_mfma_f32_16x16x32_bf16 v[92:95], v[124:127], v[202:205], v[92:95]
	v_mfma_f32_16x16x32_bf16 v[88:91], v[132:135], v[202:205], v[88:91]
	v_mfma_f32_16x16x32_bf16 v[76:79], v[124:127], v[210:213], v[76:79]
	v_mfma_f32_16x16x32_bf16 v[72:75], v[132:135], v[210:213], v[72:75]
	v_mfma_f32_16x16x32_bf16 v[116:119], v[160:163], v[182:185], v[116:119]
	v_mfma_f32_16x16x32_bf16 v[112:115], v[174:177], v[182:185], v[112:115]
	v_mfma_f32_16x16x32_bf16 v[100:103], v[160:163], v[190:193], v[100:103]
	v_mfma_f32_16x16x32_bf16 v[96:99], v[174:177], v[190:193], v[96:99]
	v_mfma_f32_16x16x32_bf16 v[84:87], v[160:163], v[198:201], v[84:87]
	v_mfma_f32_16x16x32_bf16 v[80:83], v[174:177], v[198:201], v[80:83]
	v_mfma_f32_16x16x32_bf16 v[68:71], v[160:163], v[206:209], v[68:71]
	v_mfma_f32_16x16x32_bf16 v[64:67], v[174:177], v[206:209], v[64:67]
	v_mfma_f32_16x16x32_bf16 v[116:119], v[170:173], v[186:189], v[116:119]
	v_mfma_f32_16x16x32_bf16 v[112:115], v[178:181], v[186:189], v[112:115]
	v_mfma_f32_16x16x32_bf16 v[100:103], v[170:173], v[194:197], v[100:103]
	v_mfma_f32_16x16x32_bf16 v[96:99], v[178:181], v[194:197], v[96:99]
	v_mfma_f32_16x16x32_bf16 v[84:87], v[170:173], v[202:205], v[84:87]
	v_mfma_f32_16x16x32_bf16 v[80:83], v[178:181], v[202:205], v[80:83]
	v_mfma_f32_16x16x32_bf16 v[68:71], v[170:173], v[210:213], v[68:71]
	v_mfma_f32_16x16x32_bf16 v[64:67], v[178:181], v[210:213], v[64:67]
	s_setprio 0
	s_barrier
	s_add_i32 s26, s52, s33
	s_mov_b32 m0, s26
	ds_read_b128 v[182:185], v169 offset:49152
	ds_read_b128 v[186:189], v169 offset:50176
	ds_read_b128 v[190:193], v169 offset:51200
	ds_read_b128 v[194:197], v169 offset:52224
	ds_read_b128 v[198:201], v169 offset:53248
	ds_read_b128 v[202:205], v169 offset:54272
	ds_read_b128 v[206:209], v169 offset:55296
	ds_read_b128 v[210:213], v169 offset:56320
	global_load_lds_dwordx4 v146, s[98:99]
	s_add_i32 m0, s26, 0x2000
	s_add_u32 s26, s30, 0xb0080
	s_addc_u32 s27, s31, 0
	s_add_i32 s30, s53, s33
	global_load_lds_dwordx4 v150, s[98:99]
	s_mov_b32 m0, s30
	s_nop 0
	global_load_lds_dwordx4 v146, s[26:27]
	s_add_i32 m0, s30, 0x2000
	s_nop 0
	global_load_lds_dwordx4 v150, s[26:27]
	s_mov_b32 m0, s48
	s_nop 0
	global_load_lds_dwordx4 v144, s[100:101]
	s_mov_b32 m0, s49
	s_nop 0
	global_load_lds_dwordx4 v148, s[100:101]
	s_waitcnt vmcnt(8)
	s_barrier
	s_setprio 1
	s_waitcnt lgkmcnt(0)
	v_mfma_f32_16x16x32_bf16 v[60:63], v[120:123], v[182:185], v[60:63]
	v_mfma_f32_16x16x32_bf16 v[56:59], v[128:131], v[182:185], v[56:59]
	v_mfma_f32_16x16x32_bf16 v[44:47], v[120:123], v[190:193], v[44:47]
	v_mfma_f32_16x16x32_bf16 v[40:43], v[128:131], v[190:193], v[40:43]
	v_mfma_f32_16x16x32_bf16 v[28:31], v[120:123], v[198:201], v[28:31]
	v_mfma_f32_16x16x32_bf16 v[24:27], v[128:131], v[198:201], v[24:27]
	v_mfma_f32_16x16x32_bf16 v[12:15], v[120:123], v[206:209], v[12:15]
	v_mfma_f32_16x16x32_bf16 v[8:11], v[128:131], v[206:209], v[8:11]
	v_mfma_f32_16x16x32_bf16 v[60:63], v[124:127], v[186:189], v[60:63]
	v_mfma_f32_16x16x32_bf16 v[56:59], v[132:135], v[186:189], v[56:59]
	v_mfma_f32_16x16x32_bf16 v[44:47], v[124:127], v[194:197], v[44:47]
	v_mfma_f32_16x16x32_bf16 v[40:43], v[132:135], v[194:197], v[40:43]
	v_mfma_f32_16x16x32_bf16 v[28:31], v[124:127], v[202:205], v[28:31]
	v_mfma_f32_16x16x32_bf16 v[24:27], v[132:135], v[202:205], v[24:27]
	v_mfma_f32_16x16x32_bf16 v[12:15], v[124:127], v[210:213], v[12:15]
	v_mfma_f32_16x16x32_bf16 v[8:11], v[132:135], v[210:213], v[8:11]
	v_mfma_f32_16x16x32_bf16 v[52:55], v[160:163], v[182:185], v[52:55]
	v_mfma_f32_16x16x32_bf16 v[48:51], v[174:177], v[182:185], v[48:51]
	v_mfma_f32_16x16x32_bf16 v[36:39], v[160:163], v[190:193], v[36:39]
	v_mfma_f32_16x16x32_bf16 v[32:35], v[174:177], v[190:193], v[32:35]
	v_mfma_f32_16x16x32_bf16 v[20:23], v[160:163], v[198:201], v[20:23]
	v_mfma_f32_16x16x32_bf16 v[16:19], v[174:177], v[198:201], v[16:19]
	v_mfma_f32_16x16x32_bf16 v[4:7], v[160:163], v[206:209], v[4:7]
	v_mfma_f32_16x16x32_bf16 v[0:3], v[174:177], v[206:209], v[0:3]
	v_mfma_f32_16x16x32_bf16 v[52:55], v[170:173], v[186:189], v[52:55]
	v_mfma_f32_16x16x32_bf16 v[48:51], v[178:181], v[186:189], v[48:51]
	v_mfma_f32_16x16x32_bf16 v[36:39], v[170:173], v[194:197], v[36:39]
	v_mfma_f32_16x16x32_bf16 v[32:35], v[178:181], v[194:197], v[32:35]
	v_mfma_f32_16x16x32_bf16 v[20:23], v[170:173], v[202:205], v[20:23]
	v_mfma_f32_16x16x32_bf16 v[16:19], v[178:181], v[202:205], v[16:19]
	v_mfma_f32_16x16x32_bf16 v[4:7], v[170:173], v[210:213], v[4:7]
	v_mfma_f32_16x16x32_bf16 v[0:3], v[178:181], v[210:213], v[0:3]
	s_setprio 0
	s_barrier
	s_add_i32 s63, s63, 2
	s_add_u32 s61, s61, 0x100
	s_addc_u32 s62, s62, 0
	s_mov_b64 s[26:27], s[28:29]
; #define PG8_STAGE(bufoff, gbase, voff) do { _Pragma("unroll") for (int _i = 0; _i < 2; ++_i) \
;         __builtin_amdgcn_global_load_lds((const unsigned*)((const char*)(gbase) + (voff)[_i]), (LAS unsigned*)(lds + (bufoff) + ldsw + _i * 8192), 16, 0, 0); } while (0)
; #define PG8_LDA(dst, b, h) do { _Pragma("unroll") for (int m = 0; m < 4; ++m) _Pragma("unroll") for (int k = 0; k < 2; ++k) dst[m][k] = *(const LAS bf16x8*)(lds + PG8_SA(b, h) + aoff + m * 2048 + k * 1024); } while (0)
; #define PG8_LDB(dst, b, h) do { _Pragma("unroll") for (int n = 0; n < 2; ++n) _Pragma("unroll") for (int k = 0; k < 2; ++k) dst[n][k] = *(const LAS bf16x8*)(lds + PG8_SB(b, h) + boff + n * 2048 + k * 1024); } while (0)
; #define PG8_MMA(ai, bj, At, Bt) do { __builtin_amdgcn_s_setprio(1); _Pragma("unroll") for (int m = 0; m < 4; ++m) _Pragma("unroll") for (int n = 0; n < 2; ++n) _Pragma("unroll") for (int k = 0; k < 2; ++k) \
;         acc[ai][bj][m][n] = __builtin_amdgcn_mfma_f32_16x16x32_bf16(Bt[n][k], At[m][k], acc[ai][bj][m][n], 0, 0, 0); __builtin_amdgcn_s_setprio(0); } while (0)
; #define PG8_WAIT_V(n) asm volatile("s_waitcnt vmcnt(" #n ")" ::: "memory")
; #define PG8_WAIT_L(n) asm volatile("s_waitcnt lgkmcnt(" #n ")" ::: "memory")
; #define PG8_BAR __builtin_amdgcn_s_barrier()
; #define PG8_SCHED __builtin_amdgcn_sched_barrier(0)
; template <class Epi, bool ALIGN_EPI, int K, int LDA, int LDB>
; __device__ __forceinline__ void gemm_phase(LAS unsigned char* lds, const int wid, const Gemm g, const StaticOrder& S, const Epi& E) {
;     ...
;             const bool last = (t == nt - 2);
;             const char* a1 = cA + (size_t)(t + 1) * kstep;
;             const char* a2 = last ? nA : cA + (size_t)(t + 2) * kstep; const char* b2 = last ? nB : cB + (size_t)(t + 2) * kstep;
;             const char* a3 = a2 + kstep; const char* b3 = b2 + kstep;
;             PG8_LDB(B0, 0, 0); PG8_LDB(B1, 0, 1); PG8_SCHED; PG8_LDA(At, 0, 0); PG8_STAGE(PG8_SA(1, 1), a1 + hA, voffA);
;             PG8_WAIT_V(8); PG8_WAIT_L(0); PG8_BAR; PG8_MMA(0, 0, At, B0); PG8_MMA(0, 1, At, B1); PG8_BAR; PG8_SCHED;
;             PG8_LDA(At, 0, 1); PG8_STAGE(PG8_SB(0, 0), b2, voffB); PG8_STAGE(PG8_SB(0, 1), b2 + hB, voffB); PG8_STAGE(PG8_SA(0, 0), a2, voffA);
;             PG8_WAIT_V(8); PG8_WAIT_L(0); PG8_BAR; PG8_MMA(1, 0, At, B0); PG8_MMA(1, 1, At, B1); PG8_BAR; PG8_SCHED;
.LBB0_1697:
	ds_read_b128 v[120:123], v167
	ds_read_b128 v[124:127], v167 offset:1024
	ds_read_b128 v[128:131], v167 offset:2048
	ds_read_b128 v[132:135], v167 offset:3072
	ds_read_b128 v[160:163], v168
	ds_read_b128 v[170:173], v168 offset:1024
	ds_read_b128 v[174:177], v168 offset:2048
	ds_read_b128 v[178:181], v168 offset:3072
	s_add_u32 s28, s26, 0x100
	s_addc_u32 s29, s27, 0
	s_cmp_eq_u32 s63, 40
	s_cselect_b32 s35, s7, s29
	s_cselect_b32 s34, s6, s28
	s_cselect_b32 s31, s25, s62
	s_cselect_b32 s30, s24, s61
	s_add_i32 m0, s36, 0xc000
	ds_read_b128 v[182:185], v169
	ds_read_b128 v[186:189], v169 offset:1024
	ds_read_b128 v[190:193], v169 offset:2048
	ds_read_b128 v[194:197], v169 offset:3072
	ds_read_b128 v[198:201], v169 offset:4096
	ds_read_b128 v[202:205], v169 offset:5120
	ds_read_b128 v[206:209], v169 offset:6144
	ds_read_b128 v[210:213], v169 offset:7168
	global_load_lds_dwordx4 v152, s[26:27]
	s_add_i32 m0, s36, 0xe000
	s_nop 0
	global_load_lds_dwordx4 v154, s[26:27]
	s_waitcnt vmcnt(8)
	s_barrier
	s_setprio 1
	s_waitcnt lgkmcnt(0)
	v_mfma_f32_16x16x32_bf16 v[140:143], v[120:123], v[182:185], v[140:143]
	v_mfma_f32_16x16x32_bf16 v[136:139], v[128:131], v[182:185], v[136:139]
	v_mfma_f32_16x16x32_bf16 v[108:111], v[120:123], v[190:193], v[108:111]
	v_mfma_f32_16x16x32_bf16 v[104:107], v[128:131], v[190:193], v[104:107]
	v_mfma_f32_16x16x32_bf16 v[92:95], v[120:123], v[198:201], v[92:95]
	v_mfma_f32_16x16x32_bf16 v[88:91], v[128:131], v[198:201], v[88:91]
	v_mfma_f32_16x16x32_bf16 v[76:79], v[120:123], v[206:209], v[76:79]
	v_mfma_f32_16x16x32_bf16 v[72:75], v[128:131], v[206:209], v[72:75]
	v_mfma_f32_16x16x32_bf16 v[140:143], v[124:127], v[186:189], v[140:143]
	v_mfma_f32_16x16x32_bf16 v[136:139], v[132:135], v[186:189], v[136:139]
	v_mfma_f32_16x16x32_bf16 v[108:111], v[124:127], v[194:197], v[108:111]
	v_mfma_f32_16x16x32_bf16 v[104:107], v[132:135], v[194:197], v[104:107]
	v_mfma_f32_16x16x32_bf16 v[92:95], v[124:127], v[202:205], v[92:95]
	v_mfma_f32_16x16x32_bf16 v[88:91], v[132:135], v[202:205], v[88:91]
	v_mfma_f32_16x16x32_bf16 v[76:79], v[124:127], v[210:213], v[76:79]
	v_mfma_f32_16x16x32_bf16 v[72:75], v[132:135], v[210:213], v[72:75]
	v_mfma_f32_16x16x32_bf16 v[116:119], v[160:163], v[182:185], v[116:119]
	v_mfma_f32_16x16x32_bf16 v[112:115], v[174:177], v[182:185], v[112:115]
	v_mfma_f32_16x16x32_bf16 v[100:103], v[160:163], v[190:193], v[100:103]
	v_mfma_f32_16x16x32_bf16 v[96:99], v[174:177], v[190:193], v[96:99]
	v_mfma_f32_16x16x32_bf16 v[84:87], v[160:163], v[198:201], v[84:87]
	v_mfma_f32_16x16x32_bf16 v[80:83], v[174:177], v[198:201], v[80:83]
	v_mfma_f32_16x16x32_bf16 v[68:71], v[160:163], v[206:209], v[68:71]
	v_mfma_f32_16x16x32_bf16 v[64:67], v[174:177], v[206:209], v[64:67]
	v_mfma_f32_16x16x32_bf16 v[116:119], v[170:173], v[186:189], v[116:119]
	v_mfma_f32_16x16x32_bf16 v[112:115], v[178:181], v[186:189], v[112:115]
	v_mfma_f32_16x16x32_bf16 v[100:103], v[170:173], v[194:197], v[100:103]
	v_mfma_f32_16x16x32_bf16 v[96:99], v[178:181], v[194:197], v[96:99]
	v_mfma_f32_16x16x32_bf16 v[84:87], v[170:173], v[202:205], v[84:87]
	v_mfma_f32_16x16x32_bf16 v[80:83], v[178:181], v[202:205], v[80:83]
	v_mfma_f32_16x16x32_bf16 v[68:71], v[170:173], v[210:213], v[68:71]
	v_mfma_f32_16x16x32_bf16 v[64:67], v[178:181], v[210:213], v[64:67]
	s_setprio 0
	s_barrier
	s_add_u32 s98, s30, s12
	s_addc_u32 s99, s31, s13
	s_add_u32 s100, s34, s12
	s_addc_u32 s101, s35, s13
	s_add_i32 s26, s54, s33
	s_mov_b32 m0, s26
	ds_read_b128 v[182:185], v169 offset:16384
	ds_read_b128 v[186:189], v169 offset:17408
	ds_read_b128 v[190:193], v169 offset:18432
	ds_read_b128 v[194:197], v169 offset:19456
	ds_read_b128 v[198:201], v169 offset:20480
	ds_read_b128 v[202:205], v169 offset:21504
	ds_read_b128 v[206:209], v169 offset:22528
	ds_read_b128 v[210:213], v169 offset:23552
	global_load_lds_dwordx4 v146, s[30:31]
	s_add_i32 m0, s26, 0x2000
	s_add_u32 s26, s30, 0xb0000
	s_addc_u32 s27, s31, 0
	s_add_i32 s52, s55, s33
	global_load_lds_dwordx4 v150, s[30:31]
	s_mov_b32 m0, s52
	s_nop 0
	global_load_lds_dwordx4 v146, s[26:27]
	s_add_i32 m0, s52, 0x2000
	s_nop 0
	global_load_lds_dwordx4 v150, s[26:27]
	s_mov_b32 m0, s36
	s_nop 0
	global_load_lds_dwordx4 v144, s[34:35]
	s_mov_b32 m0, s37
	s_nop 0
	global_load_lds_dwordx4 v148, s[34:35]
	s_waitcnt vmcnt(8)
	s_barrier
	s_setprio 1
	s_waitcnt lgkmcnt(0)
	v_mfma_f32_16x16x32_bf16 v[60:63], v[120:123], v[182:185], v[60:63]
	v_mfma_f32_16x16x32_bf16 v[56:59], v[128:131], v[182:185], v[56:59]
	v_mfma_f32_16x16x32_bf16 v[44:47], v[120:123], v[190:193], v[44:47]
	v_mfma_f32_16x16x32_bf16 v[40:43], v[128:131], v[190:193], v[40:43]
	v_mfma_f32_16x16x32_bf16 v[28:31], v[120:123], v[198:201], v[28:31]
	v_mfma_f32_16x16x32_bf16 v[24:27], v[128:131], v[198:201], v[24:27]
	v_mfma_f32_16x16x32_bf16 v[12:15], v[120:123], v[206:209], v[12:15]
	v_mfma_f32_16x16x32_bf16 v[8:11], v[128:131], v[206:209], v[8:11]
	v_mfma_f32_16x16x32_bf16 v[60:63], v[124:127], v[186:189], v[60:63]
	v_mfma_f32_16x16x32_bf16 v[56:59], v[132:135], v[186:189], v[56:59]
	v_mfma_f32_16x16x32_bf16 v[44:47], v[124:127], v[194:197], v[44:47]
	v_mfma_f32_16x16x32_bf16 v[40:43], v[132:135], v[194:197], v[40:43]
	v_mfma_f32_16x16x32_bf16 v[28:31], v[124:127], v[202:205], v[28:31]
	v_mfma_f32_16x16x32_bf16 v[24:27], v[132:135], v[202:205], v[24:27]
	v_mfma_f32_16x16x32_bf16 v[12:15], v[124:127], v[210:213], v[12:15]
	v_mfma_f32_16x16x32_bf16 v[8:11], v[132:135], v[210:213], v[8:11]
	v_mfma_f32_16x16x32_bf16 v[52:55], v[160:163], v[182:185], v[52:55]
	v_mfma_f32_16x16x32_bf16 v[48:51], v[174:177], v[182:185], v[48:51]
	v_mfma_f32_16x16x32_bf16 v[36:39], v[160:163], v[190:193], v[36:39]
	v_mfma_f32_16x16x32_bf16 v[32:35], v[174:177], v[190:193], v[32:35]
	v_mfma_f32_16x16x32_bf16 v[20:23], v[160:163], v[198:201], v[20:23]
	v_mfma_f32_16x16x32_bf16 v[16:19], v[174:177], v[198:201], v[16:19]
	v_mfma_f32_16x16x32_bf16 v[4:7], v[160:163], v[206:209], v[4:7]
	v_mfma_f32_16x16x32_bf16 v[0:3], v[174:177], v[206:209], v[0:3]
	v_mfma_f32_16x16x32_bf16 v[52:55], v[170:173], v[186:189], v[52:55]
	v_mfma_f32_16x16x32_bf16 v[48:51], v[178:181], v[186:189], v[48:51]
	v_mfma_f32_16x16x32_bf16 v[36:39], v[170:173], v[194:197], v[36:39]
	v_mfma_f32_16x16x32_bf16 v[32:35], v[178:181], v[194:197], v[32:35]
	v_mfma_f32_16x16x32_bf16 v[20:23], v[170:173], v[202:205], v[20:23]
	v_mfma_f32_16x16x32_bf16 v[16:19], v[178:181], v[202:205], v[16:19]
	v_mfma_f32_16x16x32_bf16 v[4:7], v[170:173], v[210:213], v[4:7]
	v_mfma_f32_16x16x32_bf16 v[0:3], v[178:181], v[210:213], v[0:3]
	s_setprio 0
	s_barrier
; #define PG8_STAGE(bufoff, gbase, voff) do { _Pragma("unroll") for (int _i = 0; _i < 2; ++_i) \
;         __builtin_amdgcn_global_load_lds((const unsigned*)((const char*)(gbase) + (voff)[_i]), (LAS unsigned*)(lds + (bufoff) + ldsw + _i * 8192), 16, 0, 0); } while (0)
; #define PG8_LDA(dst, b, h) do { _Pragma("unroll") for (int m = 0; m < 4; ++m) _Pragma("unroll") for (int k = 0; k < 2; ++k) dst[m][k] = *(const LAS bf16x8*)(lds + PG8_SA(b, h) + aoff + m * 2048 + k * 1024); } while (0)
; #define PG8_LDB(dst, b, h) do { _Pragma("unroll") for (int n = 0; n < 2; ++n) _Pragma("unroll") for (int k = 0; k < 2; ++k) dst[n][k] = *(const LAS bf16x8*)(lds + PG8_SB(b, h) + boff + n * 2048 + k * 1024); } while (0)
; #define PG8_MMA(ai, bj, At, Bt) do { __builtin_amdgcn_s_setprio(1); _Pragma("unroll") for (int m = 0; m < 4; ++m) _Pragma("unroll") for (int n = 0; n < 2; ++n) _Pragma("unroll") for (int k = 0; k < 2; ++k) \
;         acc[ai][bj][m][n] = __builtin_amdgcn_mfma_f32_16x16x32_bf16(Bt[n][k], At[m][k], acc[ai][bj][m][n], 0, 0, 0); __builtin_amdgcn_s_setprio(0); } while (0)
; #define PG8_WAIT_V(n) asm volatile("s_waitcnt vmcnt(" #n ")" ::: "memory")
; #define PG8_WAIT_L(n) asm volatile("s_waitcnt lgkmcnt(" #n ")" ::: "memory")
; #define PG8_BAR __builtin_amdgcn_s_barrier()
; #define PG8_SCHED __builtin_amdgcn_sched_barrier(0)
; template <class Epi, bool ALIGN_EPI, int K, int LDA, int LDB>
; __device__ __forceinline__ void gemm_phase(LAS unsigned char* lds, const int wid, const Gemm g, const StaticOrder& S, const Epi& E) {
;     ...
;             PG8_LDB(B0, 1, 0); PG8_LDB(B1, 1, 1); PG8_SCHED; PG8_LDA(At, 1, 0); PG8_STAGE(PG8_SA(0, 1), a2 + hA, voffA);
;             PG8_WAIT_V(8); PG8_WAIT_L(0); PG8_BAR; PG8_MMA(0, 0, At, B0); PG8_MMA(0, 1, At, B1); PG8_BAR; PG8_SCHED;
;             PG8_LDA(At, 1, 1); PG8_STAGE(PG8_SB(1, 0), b3, voffB); PG8_STAGE(PG8_SB(1, 1), b3 + hB, voffB); PG8_STAGE(PG8_SA(1, 0), a3, voffA);
;             PG8_WAIT_V(8); PG8_WAIT_L(0); PG8_BAR; PG8_MMA(1, 0, At, B0); PG8_MMA(1, 1, At, B1); PG8_BAR; PG8_SCHED;
;         }
;         if constexpr (ALIGN_EPI) { if (wr == 0) PG8_BAR; }
	s_add_i32 s52, 0, 0x18000
	s_add_i32 s53, 0, 0x1c000
	v_add_u32_e32 v132, s52, v166
	v_add_u32_e32 v178, s53, v166
	ds_read_b128 v[120:123], v132
	ds_read_b128 v[124:127], v132 offset:1024
	ds_read_b128 v[128:131], v132 offset:2048
	ds_read_b128 v[132:135], v132 offset:3072
	ds_read_b128 v[160:163], v178
	ds_read_b128 v[170:173], v178 offset:1024
	ds_read_b128 v[174:177], v178 offset:2048
	ds_read_b128 v[178:181], v178 offset:3072
	s_add_u32 s26, s34, 0xb0000
	s_addc_u32 s27, s35, 0
	s_mov_b32 m0, s38
	ds_read_b128 v[182:185], v169 offset:32768
	ds_read_b128 v[186:189], v169 offset:33792
	ds_read_b128 v[190:193], v169 offset:34816
	ds_read_b128 v[194:197], v169 offset:35840
	ds_read_b128 v[198:201], v169 offset:36864
	ds_read_b128 v[202:205], v169 offset:37888
	ds_read_b128 v[206:209], v169 offset:38912
	ds_read_b128 v[210:213], v169 offset:39936
	global_load_lds_dwordx4 v144, s[26:27]
	s_mov_b32 m0, s39
	s_nop 0
	global_load_lds_dwordx4 v148, s[26:27]
	s_waitcnt vmcnt(8)
	s_barrier
	s_setprio 1
	s_waitcnt lgkmcnt(0)
	v_mfma_f32_16x16x32_bf16 v[140:143], v[120:123], v[182:185], v[140:143]
	v_mfma_f32_16x16x32_bf16 v[136:139], v[128:131], v[182:185], v[136:139]
	v_mfma_f32_16x16x32_bf16 v[108:111], v[120:123], v[190:193], v[108:111]
	v_mfma_f32_16x16x32_bf16 v[104:107], v[128:131], v[190:193], v[104:107]
	v_mfma_f32_16x16x32_bf16 v[92:95], v[120:123], v[198:201], v[92:95]
	v_mfma_f32_16x16x32_bf16 v[88:91], v[128:131], v[198:201], v[88:91]
	v_mfma_f32_16x16x32_bf16 v[76:79], v[120:123], v[206:209], v[76:79]
	v_mfma_f32_16x16x32_bf16 v[72:75], v[128:131], v[206:209], v[72:75]
	v_mfma_f32_16x16x32_bf16 v[140:143], v[124:127], v[186:189], v[140:143]
	v_mfma_f32_16x16x32_bf16 v[136:139], v[132:135], v[186:189], v[136:139]
	v_mfma_f32_16x16x32_bf16 v[108:111], v[124:127], v[194:197], v[108:111]
	v_mfma_f32_16x16x32_bf16 v[104:107], v[132:135], v[194:197], v[104:107]
	v_mfma_f32_16x16x32_bf16 v[92:95], v[124:127], v[202:205], v[92:95]
	v_mfma_f32_16x16x32_bf16 v[88:91], v[132:135], v[202:205], v[88:91]
	v_mfma_f32_16x16x32_bf16 v[76:79], v[124:127], v[210:213], v[76:79]
	v_mfma_f32_16x16x32_bf16 v[72:75], v[132:135], v[210:213], v[72:75]
	v_mfma_f32_16x16x32_bf16 v[116:119], v[160:163], v[182:185], v[116:119]
	v_mfma_f32_16x16x32_bf16 v[112:115], v[174:177], v[182:185], v[112:115]
	v_mfma_f32_16x16x32_bf16 v[100:103], v[160:163], v[190:193], v[100:103]
	v_mfma_f32_16x16x32_bf16 v[96:99], v[174:177], v[190:193], v[96:99]
	v_mfma_f32_16x16x32_bf16 v[84:87], v[160:163], v[198:201], v[84:87]
	v_mfma_f32_16x16x32_bf16 v[80:83], v[174:177], v[198:201], v[80:83]
	v_mfma_f32_16x16x32_bf16 v[68:71], v[160:163], v[206:209], v[68:71]
	v_mfma_f32_16x16x32_bf16 v[64:67], v[174:177], v[206:209], v[64:67]
	v_mfma_f32_16x16x32_bf16 v[116:119], v[170:173], v[186:189], v[116:119]
	v_mfma_f32_16x16x32_bf16 v[112:115], v[178:181], v[186:189], v[112:115]
	v_mfma_f32_16x16x32_bf16 v[100:103], v[170:173], v[194:197], v[100:103]
	v_mfma_f32_16x16x32_bf16 v[96:99], v[178:181], v[194:197], v[96:99]
	v_mfma_f32_16x16x32_bf16 v[84:87], v[170:173], v[202:205], v[84:87]
	v_mfma_f32_16x16x32_bf16 v[80:83], v[178:181], v[202:205], v[80:83]
	v_mfma_f32_16x16x32_bf16 v[68:71], v[170:173], v[210:213], v[68:71]
	v_mfma_f32_16x16x32_bf16 v[64:67], v[178:181], v[210:213], v[64:67]
	s_setprio 0
	s_barrier
	s_add_i32 s26, s52, s33
	s_mov_b32 m0, s26
	ds_read_b128 v[182:185], v169 offset:49152
	ds_read_b128 v[186:189], v169 offset:50176
	ds_read_b128 v[190:193], v169 offset:51200
	ds_read_b128 v[194:197], v169 offset:52224
	ds_read_b128 v[198:201], v169 offset:53248
	ds_read_b128 v[202:205], v169 offset:54272
	ds_read_b128 v[206:209], v169 offset:55296
	ds_read_b128 v[210:213], v169 offset:56320
	global_load_lds_dwordx4 v146, s[98:99]
	s_add_i32 m0, s26, 0x2000
	s_add_u32 s26, s30, 0xb0080
	s_addc_u32 s27, s31, 0
	s_add_i32 s30, s53, s33
	global_load_lds_dwordx4 v150, s[98:99]
	s_mov_b32 m0, s30
	s_nop 0
	global_load_lds_dwordx4 v146, s[26:27]
	s_add_i32 m0, s30, 0x2000
	s_nop 0
	global_load_lds_dwordx4 v150, s[26:27]
	s_mov_b32 m0, s48
	s_nop 0
	global_load_lds_dwordx4 v144, s[100:101]
	s_mov_b32 m0, s49
	s_nop 0
	global_load_lds_dwordx4 v148, s[100:101]
	s_waitcnt vmcnt(8)
	s_barrier
	s_setprio 1
	s_waitcnt lgkmcnt(0)
	v_mfma_f32_16x16x32_bf16 v[60:63], v[120:123], v[182:185], v[60:63]
	v_mfma_f32_16x16x32_bf16 v[56:59], v[128:131], v[182:185], v[56:59]
	v_mfma_f32_16x16x32_bf16 v[44:47], v[120:123], v[190:193], v[44:47]
	v_mfma_f32_16x16x32_bf16 v[40:43], v[128:131], v[190:193], v[40:43]
	v_mfma_f32_16x16x32_bf16 v[28:31], v[120:123], v[198:201], v[28:31]
	v_mfma_f32_16x16x32_bf16 v[24:27], v[128:131], v[198:201], v[24:27]
	v_mfma_f32_16x16x32_bf16 v[12:15], v[120:123], v[206:209], v[12:15]
	v_mfma_f32_16x16x32_bf16 v[8:11], v[128:131], v[206:209], v[8:11]
	v_mfma_f32_16x16x32_bf16 v[60:63], v[124:127], v[186:189], v[60:63]
	v_mfma_f32_16x16x32_bf16 v[56:59], v[132:135], v[186:189], v[56:59]
	v_mfma_f32_16x16x32_bf16 v[44:47], v[124:127], v[194:197], v[44:47]
	v_mfma_f32_16x16x32_bf16 v[40:43], v[132:135], v[194:197], v[40:43]
	v_mfma_f32_16x16x32_bf16 v[28:31], v[124:127], v[202:205], v[28:31]
	v_mfma_f32_16x16x32_bf16 v[24:27], v[132:135], v[202:205], v[24:27]
	v_mfma_f32_16x16x32_bf16 v[12:15], v[124:127], v[210:213], v[12:15]
	v_mfma_f32_16x16x32_bf16 v[8:11], v[132:135], v[210:213], v[8:11]
	v_mfma_f32_16x16x32_bf16 v[52:55], v[160:163], v[182:185], v[52:55]
	v_mfma_f32_16x16x32_bf16 v[48:51], v[174:177], v[182:185], v[48:51]
	v_mfma_f32_16x16x32_bf16 v[36:39], v[160:163], v[190:193], v[36:39]
	v_mfma_f32_16x16x32_bf16 v[32:35], v[174:177], v[190:193], v[32:35]
	v_mfma_f32_16x16x32_bf16 v[20:23], v[160:163], v[198:201], v[20:23]
	v_mfma_f32_16x16x32_bf16 v[16:19], v[174:177], v[198:201], v[16:19]
	v_mfma_f32_16x16x32_bf16 v[4:7], v[160:163], v[206:209], v[4:7]
	v_mfma_f32_16x16x32_bf16 v[0:3], v[174:177], v[206:209], v[0:3]
	v_mfma_f32_16x16x32_bf16 v[52:55], v[170:173], v[186:189], v[52:55]
	v_mfma_f32_16x16x32_bf16 v[48:51], v[178:181], v[186:189], v[48:51]
	v_mfma_f32_16x16x32_bf16 v[36:39], v[170:173], v[194:197], v[36:39]
	v_mfma_f32_16x16x32_bf16 v[32:35], v[178:181], v[194:197], v[32:35]
	v_mfma_f32_16x16x32_bf16 v[20:23], v[170:173], v[202:205], v[20:23]
	v_mfma_f32_16x16x32_bf16 v[16:19], v[178:181], v[202:205], v[16:19]
	v_mfma_f32_16x16x32_bf16 v[4:7], v[170:173], v[210:213], v[4:7]
	v_mfma_f32_16x16x32_bf16 v[0:3], v[178:181], v[210:213], v[0:3]
	s_setprio 0
	s_barrier
	s_add_i32 s63, s63, 2
	s_add_u32 s61, s61, 0x100
	s_addc_u32 s62, s62, 0
	s_cmp_gt_u32 s63, 41
	s_mov_b64 s[26:27], s[28:29]
	s_cbranch_scc0 .LBB0_1697
	s_and_b64 vcc, exec, s[14:15]
	s_cbranch_vccz .LBB0_1700
	s_barrier
